# v17flat2global
# baseline (speedup 1.0000x reference)
; __device__ __forceinline__ unsigned cvt_pk_bf16(float lo, float hi) { unsigned r; asm volatile("v_cvt_pk_bf16_f32 %0, %1, %2" : "=v"(r) : "v"(lo), "v"(hi)); return r; }
; __device__ __forceinline__ void transpose_w(LAS unsigned char* lds, const float* __restrict__ src, int ld_src, int K, int Npad, bf16_t* __restrict__ dst, int mode, const float* __restrict__ scale) {
;     ...
;         for (int i = 0; i < 32; ++i) { float x = col >= 0 ? v[i] : 0.f; if (scale) x *= scale[k0 + kq + 2 * i]; t[(kq + 2 * i) * 257 + n] = x; }
;         __syncthreads();
; #pragma unroll
;         for (int j = 0; j < 4; ++j) { const int c = tid + 512 * j, nn = c >> 3, kc = (c & 7) * 8; float w[8];
; #pragma unroll
;             for (int e = 0; e < 8; ++e) w[e] = t[(kc + e) * 257 + nn];
;             u32x4 o; o.x = cvt_pk_bf16(w[0], w[1]); o.y = cvt_pk_bf16(w[2], w[3]); o.z = cvt_pk_bf16(w[4], w[5]); o.w = cvt_pk_bf16(w[6], w[7]);
;             *(u32x4*)(dst + (size_t)(n0 + nn) * K + k0 + kc) = o; }
;         __syncthreads();
.LBB0_34:
	ds_write_b32 v21, v2 offset:63736
	s_waitcnt lgkmcnt(0)
	s_barrier
	ds_read_b32 v2, v17 offset:1028
	ds_read_b32 v8, v17 offset:4112
	ds_read_b32 v9, v17 offset:7196
	ds_read_b32 v24, v17 offset:5140
	ds_read_b32 v7, v17 offset:2056
	ds_read_b32 v6, v17
	ds_read_b32 v25, v17 offset:3084
	ds_read_b32 v26, v17 offset:6168
	s_ashr_i32 s1, s0, 31
	s_waitcnt lgkmcnt(2)
	v_cvt_pk_bf16_f32 v6, v6, v2
	v_add_u32_e32 v2, s27, v13
	v_lshl_add_u64 v[22:23], s[0:1], 1, v[4:5]
	s_waitcnt lgkmcnt(1)
	v_cvt_pk_bf16_f32 v7, v7, v25
	v_cvt_pk_bf16_f32 v8, v8, v24
	v_mad_u64_u32 v[24:25], s[0:1], v2, s23, 0
	s_waitcnt lgkmcnt(0)
	v_cvt_pk_bf16_f32 v9, v26, v9
	v_ashrrev_i32_e32 v26, 31, v2
	v_mov_b32_e32 v2, v25
	v_mad_u64_u32 v[26:27], s[0:1], v26, s23, v[2:3]
	v_mov_b32_e32 v25, v26
	v_lshl_add_u64 v[24:25], v[24:25], 1, v[22:23]
	v_add_u32_e32 v2, s27, v14
	ds_read_b32 v28, v18 offset:1028
	ds_read_b32 v29, v18 offset:3084
	ds_read_b32 v30, v18 offset:5140
	ds_read_b32 v31, v18 offset:7196
	ds_read_b32 v32, v18 offset:6168
	ds_read_b32 v33, v18 offset:4112
	ds_read_b32 v34, v18 offset:2056
	ds_read_b32 v35, v18
	global_store_dwordx4 v[24:25], v[6:9], off
	v_mad_u64_u32 v[24:25], s[0:1], v2, s23, 0
	v_ashrrev_i32_e32 v26, 31, v2
	v_mov_b32_e32 v2, v25
	v_mad_u64_u32 v[26:27], s[0:1], v26, s23, v[2:3]
	v_mov_b32_e32 v25, v26
	v_lshl_add_u64 v[24:25], v[24:25], 1, v[22:23]
	v_add_u32_e32 v2, s27, v15
	s_waitcnt lgkmcnt(0)
	v_cvt_pk_bf16_f32 v6, v35, v28
	v_cvt_pk_bf16_f32 v7, v34, v29
	v_cvt_pk_bf16_f32 v8, v33, v30
	v_cvt_pk_bf16_f32 v9, v32, v31
	ds_read_b32 v28, v19 offset:1028
	ds_read_b32 v29, v19 offset:3084
	ds_read_b32 v30, v19 offset:5140
	ds_read_b32 v31, v19 offset:7196
	ds_read_b32 v32, v19 offset:6168
	ds_read_b32 v33, v19 offset:4112
	ds_read_b32 v34, v19 offset:2056
	ds_read_b32 v35, v19
	global_store_dwordx4 v[24:25], v[6:9], off
	v_mad_u64_u32 v[24:25], s[0:1], v2, s23, 0
	v_ashrrev_i32_e32 v26, 31, v2
	v_mov_b32_e32 v2, v25
	v_mad_u64_u32 v[26:27], s[0:1], v26, s23, v[2:3]
	v_mov_b32_e32 v25, v26
	v_lshl_add_u64 v[24:25], v[24:25], 1, v[22:23]
	v_add_u32_e32 v2, s27, v16
	s_waitcnt lgkmcnt(0)
	v_cvt_pk_bf16_f32 v6, v35, v28
	v_cvt_pk_bf16_f32 v7, v34, v29
	v_cvt_pk_bf16_f32 v8, v33, v30
	v_cvt_pk_bf16_f32 v9, v32, v31
	ds_read_b32 v28, v20 offset:1028
	ds_read_b32 v29, v20 offset:3084
	ds_read_b32 v30, v20 offset:5140
	ds_read_b32 v31, v20 offset:7196
	ds_read_b32 v32, v20 offset:6168
	ds_read_b32 v33, v20 offset:4112
	ds_read_b32 v34, v20 offset:2056
	ds_read_b32 v35, v20
	global_store_dwordx4 v[24:25], v[6:9], off
	v_mad_u64_u32 v[24:25], s[0:1], v2, s23, 0
	v_ashrrev_i32_e32 v26, 31, v2
	v_mov_b32_e32 v2, v25
	v_mad_u64_u32 v[26:27], s[0:1], v26, s23, v[2:3]
	v_mov_b32_e32 v25, v26
	v_readlane_b32 s4, v253, 11
	v_lshl_add_u64 v[22:23], v[24:25], 1, v[22:23]
	v_readlane_b32 s5, v253, 12
	s_waitcnt lgkmcnt(0)
	v_cvt_pk_bf16_f32 v6, v35, v28
	v_cvt_pk_bf16_f32 v7, v34, v29
	v_cvt_pk_bf16_f32 v8, v33, v30
	v_cvt_pk_bf16_f32 v9, v32, v31
	global_store_dwordx4 v[22:23], v[6:9], off
	s_waitcnt lgkmcnt(0)
	s_barrier
	s_load_dwordx2 s[0:1], s[4:5], 0x98
	s_waitcnt lgkmcnt(0)
	s_add_i32 s35, s0, s35
	s_cmp_lt_i32 s35, s34
	s_cbranch_scc0 .LBB0_6

; __device__ __forceinline__ void transpose_w8(LAS unsigned char* lds, const float* __restrict__ src, int ld_src, int K, int N, int col0, unsigned char* __restrict__ dst8, const float* __restrict__ scale) {
;     ...
;         for (int i = 0; i < 32; ++i) t[(kq + 2 * i) * 257 + n] = v[i] * (scale ? 32.f * scale[k0 + kq + 2 * i] : 16.f);
;         __syncthreads();
; #pragma unroll
;         for (int j = 0; j < 2; ++j) { const int c = tid + 512 * j, nn = c >> 2, kc = (c & 3) * 16; float w[16];
; #pragma unroll
;             for (int e = 0; e < 16; ++e) w[e] = t[(kc + e) * 257 + nn];
;             u32x4 o;
; #pragma unroll
;             for (int q = 0; q < 4; ++q) { int x = __builtin_amdgcn_cvt_pk_fp8_f32(w[4 * q], w[4 * q + 1], 0, false); x = __builtin_amdgcn_cvt_pk_fp8_f32(w[4 * q + 2], w[4 * q + 3], x, true); o[q] = (unsigned)x; }
;             *(u32x4*)(dst8 + (size_t)(n0 + nn) * K + k0 + kc) = o; }
;         __syncthreads();
.LBB0_114:
	v_mul_f32_e32 v6, v52, v9
	ds_write_b32 v51, v8 offset:61680
	ds_write_b32 v51, v6 offset:63736
	s_waitcnt lgkmcnt(0)
	s_barrier
	ds_read_b32 v7, v49
	ds_read_b32 v8, v49 offset:1028
	ds_read_b32 v12, v49 offset:2056
	ds_read_b32 v16, v49 offset:3084
	ds_read_b32 v9, v49 offset:4112
	ds_read_b32 v17, v49 offset:5140
	ds_read_b32 v18, v49 offset:6168
	ds_read_b32 v19, v49 offset:7196
	ds_read_b32 v20, v49 offset:8224
	ds_read_b32 v21, v49 offset:9252
	ds_read_b32 v22, v49 offset:10280
	ds_read_b32 v23, v49 offset:11308
	ds_read_b32 v24, v49 offset:12336
	ds_read_b32 v25, v49 offset:13364
	ds_read_b32 v26, v49 offset:14392
	ds_read_b32 v27, v49 offset:15420
	v_mov_b32_e32 v6, 0
	s_waitcnt lgkmcnt(14)
	v_cvt_pk_fp8_f32 v6, v7, v8
	v_mov_b32_e32 v7, 0
	s_waitcnt lgkmcnt(10)
	v_cvt_pk_fp8_f32 v7, v9, v17
	v_mov_b32_e32 v8, 0
	v_mov_b32_e32 v9, 0
	s_waitcnt lgkmcnt(6)
	v_cvt_pk_fp8_f32 v8, v20, v21
	s_waitcnt lgkmcnt(2)
	v_cvt_pk_fp8_f32 v9, v24, v25
	v_cvt_pk_fp8_f32 v6, v12, v16 op_sel:[0,0,1]
	v_cvt_pk_fp8_f32 v7, v18, v19 op_sel:[0,0,1]
	v_cvt_pk_fp8_f32 v8, v22, v23 op_sel:[0,0,1]
	s_waitcnt lgkmcnt(0)
	v_cvt_pk_fp8_f32 v9, v26, v27 op_sel:[0,0,1]
	v_add_u32_e32 v16, s28, v47
	s_ashr_i32 s31, s30, 31
	v_ashrrev_i32_e32 v17, 31, v16
	v_lshl_add_u64 v[14:15], v[2:3], 0, s[30:31]
	v_lshlrev_b64 v[16:17], 11, v[16:17]
	v_lshl_add_u64 v[16:17], v[14:15], 0, v[16:17]
	global_store_dwordx4 v[16:17], v[6:9], off
	ds_read_b32 v7, v50
	ds_read_b32 v8, v50 offset:1028
	ds_read_b32 v12, v50 offset:2056
	ds_read_b32 v16, v50 offset:3084
	ds_read_b32 v9, v50 offset:4112
	ds_read_b32 v17, v50 offset:5140
	ds_read_b32 v18, v50 offset:6168
	ds_read_b32 v19, v50 offset:7196
	ds_read_b32 v20, v50 offset:8224
	ds_read_b32 v21, v50 offset:9252
	ds_read_b32 v22, v50 offset:10280
	ds_read_b32 v23, v50 offset:11308
	ds_read_b32 v24, v50 offset:12336
	ds_read_b32 v25, v50 offset:13364
	ds_read_b32 v26, v50 offset:14392
	ds_read_b32 v27, v50 offset:15420
	v_mov_b32_e32 v6, 0
	s_waitcnt lgkmcnt(0)
	v_cvt_pk_fp8_f32 v6, v7, v8
	v_mov_b32_e32 v7, 0
	v_cvt_pk_fp8_f32 v7, v9, v17
	v_mov_b32_e32 v8, 0
	v_mov_b32_e32 v9, 0
	v_cvt_pk_fp8_f32 v8, v20, v21
	v_cvt_pk_fp8_f32 v9, v24, v25
	v_cvt_pk_fp8_f32 v6, v12, v16 op_sel:[0,0,1]
	v_cvt_pk_fp8_f32 v7, v18, v19 op_sel:[0,0,1]
	v_cvt_pk_fp8_f32 v8, v22, v23 op_sel:[0,0,1]
	v_cvt_pk_fp8_f32 v9, v26, v27 op_sel:[0,0,1]
	v_add_u32_e32 v16, s28, v48
	v_ashrrev_i32_e32 v17, 31, v16
	v_lshlrev_b64 v[16:17], 11, v[16:17]
	v_lshl_add_u64 v[14:15], v[14:15], 0, v[16:17]
	s_mov_b32 s0, s96
	global_store_dwordx4 v[14:15], v[6:9], off
	s_waitcnt lgkmcnt(0)
	s_barrier
	s_add_i32 s2, s0, s2
	s_cmpk_lt_i32 s2, 0x100
	s_cbranch_scc0 .LBB0_178

; __device__ __forceinline__ void transpose_w8(LAS unsigned char* lds, const float* __restrict__ src, int ld_src, int K, int N, int col0, unsigned char* __restrict__ dst8, const float* __restrict__ scale) {
;     ...
;         for (int i = 0; i < 32; ++i) t[(kq + 2 * i) * 257 + n] = v[i] * (scale ? 32.f * scale[k0 + kq + 2 * i] : 16.f);
;         __syncthreads();
; #pragma unroll
;         for (int j = 0; j < 2; ++j) { const int c = tid + 512 * j, nn = c >> 2, kc = (c & 3) * 16; float w[16];
; #pragma unroll
;             for (int e = 0; e < 16; ++e) w[e] = t[(kc + e) * 257 + nn];
;             u32x4 o;
; #pragma unroll
;             for (int q = 0; q < 4; ++q) { int x = __builtin_amdgcn_cvt_pk_fp8_f32(w[4 * q], w[4 * q + 1], 0, false); x = __builtin_amdgcn_cvt_pk_fp8_f32(w[4 * q + 2], w[4 * q + 3], x, true); o[q] = (unsigned)x; }
;             *(u32x4*)(dst8 + (size_t)(n0 + nn) * K + k0 + kc) = o; }
;         __syncthreads();
.LBB0_181:
	v_mul_f32_e32 v4, v50, v7
	ds_write_b32 v49, v6 offset:61680
	ds_write_b32 v49, v4 offset:63736
	s_waitcnt lgkmcnt(0)
	s_barrier
	ds_read_b32 v5, v47
	ds_read_b32 v6, v47 offset:1028
	ds_read_b32 v12, v47 offset:2056
	ds_read_b32 v14, v47 offset:3084
	ds_read_b32 v7, v47 offset:4112
	ds_read_b32 v15, v47 offset:5140
	ds_read_b32 v16, v47 offset:6168
	ds_read_b32 v17, v47 offset:7196
	ds_read_b32 v18, v47 offset:8224
	ds_read_b32 v19, v47 offset:9252
	ds_read_b32 v20, v47 offset:10280
	ds_read_b32 v21, v47 offset:11308
	ds_read_b32 v22, v47 offset:12336
	ds_read_b32 v23, v47 offset:13364
	ds_read_b32 v24, v47 offset:14392
	ds_read_b32 v25, v47 offset:15420
	v_mov_b32_e32 v4, v11
	s_waitcnt lgkmcnt(14)
	v_cvt_pk_fp8_f32 v4, v5, v6
	v_mov_b32_e32 v5, v11
	s_waitcnt lgkmcnt(10)
	v_cvt_pk_fp8_f32 v5, v7, v15
	v_mov_b32_e32 v6, v11
	v_mov_b32_e32 v7, v11
	s_waitcnt lgkmcnt(6)
	v_cvt_pk_fp8_f32 v6, v18, v19
	s_waitcnt lgkmcnt(2)
	v_cvt_pk_fp8_f32 v7, v22, v23
	v_cvt_pk_fp8_f32 v4, v12, v14 op_sel:[0,0,1]
	v_cvt_pk_fp8_f32 v5, v16, v17 op_sel:[0,0,1]
	v_cvt_pk_fp8_f32 v6, v20, v21 op_sel:[0,0,1]
	s_waitcnt lgkmcnt(0)
	v_cvt_pk_fp8_f32 v7, v24, v25 op_sel:[0,0,1]
	v_add_u32_e32 v14, s14, v45
	s_ashr_i32 s29, s28, 31
	v_ashrrev_i32_e32 v15, 31, v14
	v_lshl_add_u64 v[8:9], v[2:3], 0, s[28:29]
	v_lshlrev_b64 v[14:15], 11, v[14:15]
	v_lshl_add_u64 v[14:15], v[8:9], 0, v[14:15]
	global_store_dwordx4 v[14:15], v[4:7], off
	ds_read_b32 v5, v48
	ds_read_b32 v6, v48 offset:1028
	ds_read_b32 v12, v48 offset:2056
	ds_read_b32 v14, v48 offset:3084
	ds_read_b32 v7, v48 offset:4112
	ds_read_b32 v15, v48 offset:5140
	ds_read_b32 v16, v48 offset:6168
	ds_read_b32 v17, v48 offset:7196
	ds_read_b32 v18, v48 offset:8224
	ds_read_b32 v19, v48 offset:9252
	ds_read_b32 v20, v48 offset:10280
	ds_read_b32 v21, v48 offset:11308
	ds_read_b32 v22, v48 offset:12336
	ds_read_b32 v23, v48 offset:13364
	ds_read_b32 v24, v48 offset:14392
	ds_read_b32 v25, v48 offset:15420
	v_mov_b32_e32 v4, v11
	s_waitcnt lgkmcnt(0)
	v_cvt_pk_fp8_f32 v4, v5, v6
	v_mov_b32_e32 v5, v11
	v_cvt_pk_fp8_f32 v5, v7, v15
	v_mov_b32_e32 v6, v11
	v_mov_b32_e32 v7, v11
	v_cvt_pk_fp8_f32 v6, v18, v19
	v_cvt_pk_fp8_f32 v7, v22, v23
	v_cvt_pk_fp8_f32 v4, v12, v14 op_sel:[0,0,1]
	v_cvt_pk_fp8_f32 v5, v16, v17 op_sel:[0,0,1]
	v_cvt_pk_fp8_f32 v6, v20, v21 op_sel:[0,0,1]
	v_cvt_pk_fp8_f32 v7, v24, v25 op_sel:[0,0,1]
	v_add_u32_e32 v14, s14, v46
	v_ashrrev_i32_e32 v15, 31, v14
	v_lshlrev_b64 v[14:15], 11, v[14:15]
	v_lshl_add_u64 v[8:9], v[8:9], 0, v[14:15]
	s_mov_b32 s0, s96
	global_store_dwordx4 v[8:9], v[4:7], off
	s_waitcnt lgkmcnt(0)
	s_barrier
	s_add_i32 s2, s0, s2
	s_cmpk_lt_i32 s2, 0x300
	s_cbranch_scc0 .LBB0_245

; __device__ __forceinline__ int obid() { int t = blockIdx.x; asm volatile("" : "+s"(t)); return t; }
; __device__ __forceinline__ int ogdim() { int t = gridDim.x; asm volatile("" : "+s"(t)); return t; }
; __device__ __forceinline__ void transpose_w8(LAS unsigned char* lds, const float* __restrict__ src, int ld_src, int K, int N, int col0, unsigned char* __restrict__ dst8, const float* __restrict__ scale) {
;     ...
;     for (int id = obid(); id < ntiles; id += ogdim()) {
;         const int n0 = (id % ntn) * 256, k0 = (id / ntn) * 64;
;         const int n = tid & 255, kq = tid >> 8;
;         float v[32];
;         const float* sp = src + (size_t)(k0 + kq) * ld_src + col0 + n0 + n;
; #pragma unroll
;         for (int i = 0; i < 32; ++i) v[i] = sp[(size_t)(2 * i) * ld_src];
; #pragma unroll
;         for (int i = 0; i < 32; ++i) t[(kq + 2 * i) * 257 + n] = v[i] * (scale ? 32.f * scale[k0 + kq + 2 * i] : 16.f);
.LBB0_247:
	s_ashr_i32 s1, s0, 31
	s_lshr_b32 s1, s1, 29
	s_add_i32 s1, s0, s1
	s_and_b32 s10, s1, 0xfffff8
	s_lshl_b32 s1, s1, 3
	s_sub_i32 s11, s0, s10
	s_and_b32 s10, s1, 0xffffffc0
	v_add_u32_e32 v22, s10, v12
	v_ashrrev_i32_e32 v23, 31, v22
	s_lshl_b32 s12, s11, 8
	v_lshlrev_b64 v[22:23], 13, v[22:23]
	s_ashr_i32 s13, s12, 31
	v_add_u32_e32 v26, s12, v16
	v_add_u32_e32 v28, s12, v17
	v_lshl_add_u64 v[22:23], s[2:3], 0, v[22:23]
	s_ashr_i32 s11, s10, 31
	v_ashrrev_i32_e32 v27, 31, v26
	v_ashrrev_i32_e32 v29, 31, v28
	v_lshl_add_u64 v[22:23], s[12:13], 2, v[22:23]
	s_movk_i32 s5, 0x4000
	v_lshl_add_u64 v[24:25], v[14:15], 0, s[10:11]
	v_lshlrev_b64 v[26:27], 10, v[26:27]
	v_lshlrev_b64 v[28:29], 10, v[28:29]
	v_lshl_add_u64 v[22:23], v[22:23], 0, v[10:11]
	v_lshl_add_u64 v[26:27], v[24:25], 0, v[26:27]
	v_lshl_add_u64 v[24:25], v[24:25], 0, v[28:29]
	v_add_co_u32_e32 v28, vcc, s5, v22
	global_load_dword v21, v[22:23], off
	s_nop 0
	v_addc_co_u32_e32 v29, vcc, 0, v23, vcc
	v_add_co_u32_e32 v30, vcc, s65, v22
	v_mov_b32_e32 v2, v11
	s_nop 0
	v_addc_co_u32_e32 v31, vcc, 0, v23, vcc
	v_add_co_u32_e32 v32, vcc, s66, v22
	v_mov_b32_e32 v3, v11
	s_nop 0
	v_addc_co_u32_e32 v33, vcc, 0, v23, vcc
	v_add_co_u32_e32 v34, vcc, s67, v22
	v_mov_b32_e32 v4, v11
	s_nop 0
	v_addc_co_u32_e32 v35, vcc, 0, v23, vcc
	v_add_co_u32_e32 v36, vcc, s68, v22
	v_mov_b32_e32 v5, v11
	s_nop 0
	v_addc_co_u32_e32 v37, vcc, 0, v23, vcc
	v_add_co_u32_e32 v38, vcc, s69, v22
	v_mov_b32_e32 v6, v11
	s_nop 0
	v_addc_co_u32_e32 v39, vcc, 0, v23, vcc
	v_add_co_u32_e32 v40, vcc, s70, v22
	v_mov_b32_e32 v7, v11
	s_nop 0
	v_addc_co_u32_e32 v41, vcc, 0, v23, vcc
	v_add_co_u32_e32 v42, vcc, s71, v22
	v_mov_b32_e32 v8, v11
	s_nop 0
	v_addc_co_u32_e32 v43, vcc, 0, v23, vcc
	v_add_co_u32_e32 v44, vcc, s72, v22
	v_mov_b32_e32 v9, v11
	s_nop 0
	v_addc_co_u32_e32 v45, vcc, 0, v23, vcc
	v_add_co_u32_e32 v46, vcc, s73, v22
	s_waitcnt lgkmcnt(0)
	s_mov_b32 s4, s96
	v_addc_co_u32_e32 v47, vcc, 0, v23, vcc
	v_add_co_u32_e32 v48, vcc, s74, v22
	s_waitcnt vmcnt(0)
	v_mul_f32_e32 v21, 0x41800000, v21
	v_addc_co_u32_e32 v49, vcc, 0, v23, vcc
	v_add_co_u32_e32 v50, vcc, s75, v22
	s_nop 1
	v_addc_co_u32_e32 v51, vcc, 0, v23, vcc
	v_add_co_u32_e32 v52, vcc, s38, v22
	s_nop 1
	v_addc_co_u32_e32 v53, vcc, 0, v23, vcc
	v_add_co_u32_e32 v54, vcc, s76, v22
	s_nop 1
	v_addc_co_u32_e32 v55, vcc, 0, v23, vcc
	v_add_co_u32_e32 v56, vcc, s77, v22
	s_nop 1
	v_addc_co_u32_e32 v57, vcc, 0, v23, vcc
	v_add_co_u32_e32 v58, vcc, s78, v22
	s_nop 1
	v_addc_co_u32_e32 v59, vcc, 0, v23, vcc
	v_add_co_u32_e32 v60, vcc, s79, v22
	s_nop 1
	v_addc_co_u32_e32 v61, vcc, 0, v23, vcc
	v_add_co_u32_e32 v62, vcc, s80, v22
	s_nop 1
	v_addc_co_u32_e32 v63, vcc, 0, v23, vcc
	v_add_co_u32_e32 v64, vcc, s81, v22
	s_nop 1
	v_addc_co_u32_e32 v65, vcc, 0, v23, vcc
	v_add_co_u32_e32 v66, vcc, s82, v22
	s_nop 1
	v_addc_co_u32_e32 v67, vcc, 0, v23, vcc
	v_add_co_u32_e32 v68, vcc, s83, v22
	s_nop 1
	v_addc_co_u32_e32 v69, vcc, 0, v23, vcc
	v_add_co_u32_e32 v70, vcc, s84, v22
	s_nop 1
	v_addc_co_u32_e32 v71, vcc, 0, v23, vcc
	v_add_co_u32_e32 v72, vcc, s85, v22
	s_nop 1
	v_addc_co_u32_e32 v73, vcc, 0, v23, vcc
	v_add_co_u32_e32 v74, vcc, s86, v22
	s_nop 1
	v_addc_co_u32_e32 v75, vcc, 0, v23, vcc
	v_add_co_u32_e32 v76, vcc, s87, v22
	s_nop 1
	v_addc_co_u32_e32 v77, vcc, 0, v23, vcc
	v_add_co_u32_e32 v78, vcc, s40, v22
	s_nop 1
	v_addc_co_u32_e32 v79, vcc, 0, v23, vcc
	v_add_co_u32_e32 v80, vcc, s88, v22
	s_nop 1
	v_addc_co_u32_e32 v81, vcc, 0, v23, vcc
	v_add_co_u32_e32 v82, vcc, s89, v22
	s_nop 1
	v_addc_co_u32_e32 v83, vcc, 0, v23, vcc
	v_add_co_u32_e32 v84, vcc, s90, v22
	s_nop 1
	v_addc_co_u32_e32 v85, vcc, 0, v23, vcc
	v_add_co_u32_e32 v86, vcc, s91, v22
	s_nop 1
	v_addc_co_u32_e32 v87, vcc, 0, v23, vcc
	v_add_co_u32_e32 v22, vcc, s92, v22
	s_nop 1
	v_addc_co_u32_e32 v23, vcc, 0, v23, vcc
	global_load_dword v28, v[28:29], off
	s_nop 0
	global_load_dword v29, v[30:31], off
	s_nop 0
	global_load_dword v30, v[32:33], off
	global_load_dword v31, v[34:35], off
	s_nop 0
	global_load_dword v32, v[36:37], off
	global_load_dword v33, v[38:39], off
	global_load_dword v34, v[40:41], off
	global_load_dword v35, v[42:43], off
	s_nop 0
	global_load_dword v36, v[44:45], off
	global_load_dword v37, v[46:47], off
	global_load_dword v38, v[48:49], off
	global_load_dword v39, v[50:51], off
	global_load_dword v40, v[52:53], off
	global_load_dword v41, v[54:55], off
	global_load_dword v42, v[56:57], off
	global_load_dword v43, v[58:59], off
	global_load_dword v44, v[60:61], off
	global_load_dword v45, v[62:63], off
	global_load_dword v46, v[64:65], off
	global_load_dword v47, v[66:67], off
	global_load_dword v48, v[68:69], off
	global_load_dword v49, v[70:71], off
	global_load_dword v50, v[72:73], off
	global_load_dword v51, v[74:75], off
	global_load_dword v52, v[76:77], off
	global_load_dword v53, v[78:79], off
	global_load_dword v54, v[80:81], off
	global_load_dword v55, v[82:83], off
	global_load_dword v56, v[84:85], off
	global_load_dword v57, v[86:87], off
	s_nop 0
	global_load_dword v22, v[22:23], off
	ds_write_b32 v18, v21
	s_waitcnt vmcnt(30)
; __device__ __forceinline__ void transpose_w8(LAS unsigned char* lds, const float* __restrict__ src, int ld_src, int K, int N, int col0, unsigned char* __restrict__ dst8, const float* __restrict__ scale) {
;     ...
;         for (int i = 0; i < 32; ++i) t[(kq + 2 * i) * 257 + n] = v[i] * (scale ? 32.f * scale[k0 + kq + 2 * i] : 16.f);
;         __syncthreads();
; #pragma unroll
;         for (int j = 0; j < 2; ++j) { const int c = tid + 512 * j, nn = c >> 2, kc = (c & 3) * 16; float w[16];
; #pragma unroll
;             for (int e = 0; e < 16; ++e) w[e] = t[(kc + e) * 257 + nn];
;             u32x4 o;
; #pragma unroll
;             for (int q = 0; q < 4; ++q) { int x = __builtin_amdgcn_cvt_pk_fp8_f32(w[4 * q], w[4 * q + 1], 0, false); x = __builtin_amdgcn_cvt_pk_fp8_f32(w[4 * q + 2], w[4 * q + 3], x, true); o[q] = (unsigned)x; }
;             *(u32x4*)(dst8 + (size_t)(n0 + nn) * K + k0 + kc) = o; }
;         __syncthreads();
	v_mul_f32_e32 v21, 0x41800000, v28
	s_waitcnt vmcnt(29)
	v_mul_f32_e32 v23, 0x41800000, v29
	s_waitcnt vmcnt(28)
	v_mul_f32_e32 v28, 0x41800000, v30
	s_waitcnt vmcnt(27)
	v_mul_f32_e32 v29, 0x41800000, v31
	s_waitcnt vmcnt(26)
	v_mul_f32_e32 v30, 0x41800000, v32
	s_waitcnt vmcnt(25)
	v_mul_f32_e32 v31, 0x41800000, v33
	s_waitcnt vmcnt(24)
	v_mul_f32_e32 v32, 0x41800000, v34
	s_waitcnt vmcnt(23)
	v_mul_f32_e32 v33, 0x41800000, v35
	s_waitcnt vmcnt(22)
	v_mul_f32_e32 v34, 0x41800000, v36
	s_waitcnt vmcnt(21)
	v_mul_f32_e32 v35, 0x41800000, v37
	s_waitcnt vmcnt(20)
	v_mul_f32_e32 v36, 0x41800000, v38
	s_waitcnt vmcnt(19)
	v_mul_f32_e32 v37, 0x41800000, v39
	s_waitcnt vmcnt(18)
	v_mul_f32_e32 v38, 0x41800000, v40
	s_waitcnt vmcnt(17)
	v_mul_f32_e32 v39, 0x41800000, v41
	s_waitcnt vmcnt(16)
	v_mul_f32_e32 v40, 0x41800000, v42
	s_waitcnt vmcnt(15)
	v_mul_f32_e32 v41, 0x41800000, v43
	s_waitcnt vmcnt(14)
	v_mul_f32_e32 v42, 0x41800000, v44
	s_waitcnt vmcnt(13)
	v_mul_f32_e32 v43, 0x41800000, v45
	s_waitcnt vmcnt(12)
	v_mul_f32_e32 v44, 0x41800000, v46
	s_waitcnt vmcnt(11)
	v_mul_f32_e32 v45, 0x41800000, v47
	s_waitcnt vmcnt(10)
	v_mul_f32_e32 v46, 0x41800000, v48
	s_waitcnt vmcnt(9)
	v_mul_f32_e32 v47, 0x41800000, v49
	s_waitcnt vmcnt(8)
	v_mul_f32_e32 v48, 0x41800000, v50
	s_waitcnt vmcnt(7)
	v_mul_f32_e32 v49, 0x41800000, v51
	s_waitcnt vmcnt(6)
	v_mul_f32_e32 v50, 0x41800000, v52
	s_waitcnt vmcnt(5)
	v_mul_f32_e32 v51, 0x41800000, v53
	s_waitcnt vmcnt(4)
	v_mul_f32_e32 v52, 0x41800000, v54
	s_waitcnt vmcnt(3)
	v_mul_f32_e32 v53, 0x41800000, v55
	s_waitcnt vmcnt(2)
	v_mul_f32_e32 v54, 0x41800000, v56
	s_waitcnt vmcnt(1)
	v_mul_f32_e32 v55, 0x41800000, v57
	s_waitcnt vmcnt(0)
	v_mul_f32_e32 v22, 0x41800000, v22
	ds_write_b32 v18, v21 offset:2056
	ds_write_b32 v18, v23 offset:4112
	ds_write_b32 v18, v28 offset:6168
	ds_write_b32 v18, v29 offset:8224
	ds_write_b32 v18, v30 offset:10280
	ds_write_b32 v18, v31 offset:12336
	ds_write_b32 v18, v32 offset:14392
	ds_write_b32 v18, v33 offset:16448
	ds_write_b32 v18, v34 offset:18504
	ds_write_b32 v18, v35 offset:20560
	ds_write_b32 v18, v36 offset:22616
	ds_write_b32 v18, v37 offset:24672
	ds_write_b32 v18, v38 offset:26728
	ds_write_b32 v18, v39 offset:28784
	ds_write_b32 v18, v40 offset:30840
	ds_write_b32 v18, v41 offset:32896
	ds_write_b32 v18, v42 offset:34952
	ds_write_b32 v18, v43 offset:37008
	ds_write_b32 v18, v44 offset:39064
	ds_write_b32 v18, v45 offset:41120
	ds_write_b32 v18, v46 offset:43176
	ds_write_b32 v18, v47 offset:45232
	ds_write_b32 v18, v48 offset:47288
	ds_write_b32 v18, v49 offset:49344
	ds_write_b32 v18, v50 offset:51400
	ds_write_b32 v18, v51 offset:53456
	ds_write_b32 v18, v52 offset:55512
	ds_write_b32 v18, v53 offset:57568
	ds_write_b32 v18, v54 offset:59624
	ds_write_b32 v18, v55 offset:61680
	ds_write_b32 v18, v22 offset:63736
	s_waitcnt lgkmcnt(0)
	s_barrier
	ds_read_b32 v21, v19
	ds_read_b32 v22, v19 offset:1028
	ds_read_b32 v23, v19 offset:2056
	ds_read_b32 v28, v19 offset:3084
	ds_read_b32 v29, v19 offset:4112
	ds_read_b32 v30, v19 offset:5140
	ds_read_b32 v31, v19 offset:6168
	ds_read_b32 v32, v19 offset:7196
	ds_read_b32 v33, v19 offset:8224
	ds_read_b32 v34, v19 offset:9252
	ds_read_b32 v35, v19 offset:10280
	ds_read_b32 v36, v19 offset:11308
	ds_read_b32 v37, v19 offset:12336
	ds_read_b32 v38, v19 offset:13364
	ds_read_b32 v39, v19 offset:14392
	ds_read_b32 v40, v19 offset:15420
	ds_read_b32 v41, v20
	ds_read_b32 v42, v20 offset:1028
	ds_read_b32 v43, v20 offset:2056
	ds_read_b32 v44, v20 offset:3084
	ds_read_b32 v45, v20 offset:4112
	ds_read_b32 v46, v20 offset:5140
	ds_read_b32 v47, v20 offset:6168
	ds_read_b32 v48, v20 offset:7196
	ds_read_b32 v49, v20 offset:8224
	ds_read_b32 v50, v20 offset:9252
	ds_read_b32 v51, v20 offset:10280
	ds_read_b32 v52, v20 offset:11308
	ds_read_b32 v53, v20 offset:12336
	ds_read_b32 v54, v20 offset:13364
	ds_read_b32 v55, v20 offset:14392
	ds_read_b32 v56, v20 offset:15420
	s_waitcnt lgkmcnt(14)
	v_cvt_pk_fp8_f32 v2, v21, v22
	v_cvt_pk_fp8_f32 v3, v29, v30
	v_cvt_pk_fp8_f32 v4, v33, v34
	v_cvt_pk_fp8_f32 v5, v37, v38
	v_cvt_pk_fp8_f32 v6, v41, v42
	s_waitcnt lgkmcnt(10)
	v_cvt_pk_fp8_f32 v7, v45, v46
	s_waitcnt lgkmcnt(6)
	v_cvt_pk_fp8_f32 v8, v49, v50
	s_waitcnt lgkmcnt(2)
	v_cvt_pk_fp8_f32 v9, v53, v54
	v_cvt_pk_fp8_f32 v2, v23, v28 op_sel:[0,0,1]
	v_cvt_pk_fp8_f32 v3, v31, v32 op_sel:[0,0,1]
	v_cvt_pk_fp8_f32 v4, v35, v36 op_sel:[0,0,1]
	v_cvt_pk_fp8_f32 v5, v39, v40 op_sel:[0,0,1]
	v_cvt_pk_fp8_f32 v6, v43, v44 op_sel:[0,0,1]
	v_cvt_pk_fp8_f32 v7, v47, v48 op_sel:[0,0,1]
	v_cvt_pk_fp8_f32 v8, v51, v52 op_sel:[0,0,1]
	s_waitcnt lgkmcnt(0)
	v_cvt_pk_fp8_f32 v9, v55, v56 op_sel:[0,0,1]
	global_store_dwordx4 v[26:27], v[2:5], off
	global_store_dwordx4 v[24:25], v[6:9], off
	s_waitcnt lgkmcnt(0)
	s_barrier
	s_add_i32 s0, s4, s0
	s_cmpk_lt_i32 s0, 0x80
	s_cbranch_scc1 .LBB0_247
	s_branch .LBB0_110

; __device__ __forceinline__ u32x4 pack8(f32x4 v0, f32x4 v1) { u32x4 w; w.x = cvt_pk_bf16(v0[0], v0[1]); w.y = cvt_pk_bf16(v0[2], v0[3]); w.z = cvt_pk_bf16(v1[0], v1[1]); w.w = cvt_pk_bf16(v1[2], v1[3]); return w; }
; __device__ __forceinline__ void unpack8(u32x4 w, f32x4& a, f32x4& b) { a = (f32x4){bf_lo(w.x), bf_hi(w.x), bf_lo(w.y), bf_hi(w.y)}; b = (f32x4){bf_lo(w.z), bf_hi(w.z), bf_lo(w.w), bf_hi(w.w)}; }
;     __device__ __forceinline__ void operator()(const f32x4 (&acc)[2][2][4][2], const Unit& u, int wr, int wc, int fr, int fq) const {
;         const unsigned char* gate_ = gate; bf16_t* mg_ = mg; const int first_ = first; const float as_ = ascale;
;         epi_perm2<LB>(acc, u, wr, wc, fr, fq,
;             [=](int row, int col) __attribute__((always_inline)) { LB L; L.g = *(const u32x2*)(gate_ + (size_t)row * (NP * 2) + col);
;                 L.m = first_ ? (u32x4){0u, 0u, 0u, 0u} : *(const u32x4*)(mg_ + (size_t)row * DM + col); return L; },
;             [=](int row, int col, f32x4 v0, f32x4 v1, const LB& L) __attribute__((always_inline)) {
;                 f32x4 g0, g1, p0, p1; gate_unpack8(L.g, g0, g1); unpack8(L.m, p0, p1);
;                 v0 = v0 * (g0 * as_) + p0; v1 = v1 * (g1 * as_) + p1;
;                 *(u32x4*)(mg_ + (size_t)row * DM + col) = pack8(v0, v1); });
;     }
.LBB0_286:
	v_mov_b32_e32 v130, v199
	s_mov_b32 s12, 0x3a800000
	v_and_b32_e32 v131, 15, v130
	v_ashrrev_i32_e32 v132, 2, v130
	v_lshrrev_b32_e32 v130, 1, v130
	v_and_b32_e32 v130, 0x78, v130
	v_lshl_or_b32 v130, s0, 8, v130
	v_readlane_b32 s0, v253, 38
	v_and_or_b32 v131, v132, s61, v131
	v_readlane_b32 s1, v253, 39
	v_lshl_add_u32 v132, s82, 8, v131
	v_ashrrev_i32_e32 v131, 31, v130
	v_mov_b64_e32 v[134:135], s[0:1]
	v_mad_i64_i32 v[136:137], s[0:1], v132, s31, v[134:135]
	v_lshl_add_u64 v[136:137], v[136:137], 0, v[130:131]
	global_load_dwordx2 v[158:159], v[136:137], off
	global_load_dwordx2 v[154:155], v[136:137], off offset:128
	v_or_b32_e32 v150, 16, v132
	v_mad_i64_i32 v[136:137], s[0:1], v150, s31, v[134:135]
	v_lshl_add_u64 v[136:137], v[136:137], 0, v[130:131]
	global_load_dwordx2 v[152:153], v[136:137], off
	global_load_dwordx2 v[148:149], v[136:137], off offset:128
	v_or_b32_e32 v144, 32, v132
	v_mad_i64_i32 v[136:137], s[0:1], v144, s31, v[134:135]
	v_lshl_add_u64 v[136:137], v[136:137], 0, v[130:131]
	global_load_dwordx2 v[146:147], v[136:137], off
	global_load_dwordx2 v[142:143], v[136:137], off offset:128
	v_ashrrev_i32_e32 v133, 31, v132
	v_lshlrev_b64 v[138:139], 12, v[132:133]
	v_or_b32_e32 v136, 48, v132
	v_lshl_add_u64 v[156:157], s[74:75], 0, v[138:139]
	v_mad_i64_i32 v[138:139], s[0:1], v136, s31, v[134:135]
	v_lshl_add_u64 v[138:139], v[138:139], 0, v[130:131]
	global_load_dwordx2 v[140:141], v[138:139], off
	s_nop 0
	global_load_dwordx2 v[138:139], v[138:139], off offset:128
	v_ashrrev_i32_e32 v151, 31, v150
	v_ashrrev_i32_e32 v145, 31, v144
	v_ashrrev_i32_e32 v137, 31, v136
	s_mov_b64 s[82:83], -1
	s_andn2_b64 vcc, exec, s[40:41]
	s_waitcnt vmcnt(0) lgkmcnt(0)
	v_cvt_f32_ubyte1_e32 v161, v158
	v_cvt_f32_ubyte0_e32 v160, v158
	v_pk_mul_f32 v[160:161], v[160:161], s[30:31] op_sel_hi:[1,0]
	v_cvt_f32_ubyte1_e32 v169, v159
	v_cvt_f32_ubyte0_e32 v168, v159
	v_cvt_f32_ubyte3_e32 v167, v158
	v_cvt_f32_ubyte2_e32 v166, v158
	v_cvt_f32_ubyte3_e32 v173, v159
	v_cvt_f32_ubyte2_e32 v172, v159
	v_pk_mul_f32 v[168:169], v[168:169], s[30:31] op_sel_hi:[1,0]
	v_pk_mul_f32 v[160:161], v[160:161], s[12:13] op_sel_hi:[1,0]
	v_pk_mul_f32 v[166:167], v[166:167], s[30:31] op_sel_hi:[1,0]
	v_pk_mul_f32 v[158:159], v[172:173], s[30:31] op_sel_hi:[1,0]
	v_pk_fma_f32 v[126:127], v[126:127], v[160:161], 0 op_sel_hi:[1,1,0]
	v_pk_mul_f32 v[160:161], v[168:169], s[12:13] op_sel_hi:[1,0]
	v_pk_mul_f32 v[166:167], v[166:167], s[12:13] op_sel_hi:[1,0]
	v_pk_mul_f32 v[158:159], v[158:159], s[12:13] op_sel_hi:[1,0]
	v_pk_fma_f32 v[122:123], v[122:123], v[160:161], 0 op_sel_hi:[1,1,0]
	v_pk_fma_f32 v[128:129], v[128:129], v[166:167], 0 op_sel_hi:[1,1,0]
	v_pk_fma_f32 v[158:159], v[124:125], v[158:159], 0 op_sel_hi:[1,1,0]
	v_cvt_pk_bf16_f32 v124, v126, v127
	v_cvt_pk_bf16_f32 v125, v128, v129
	v_cvt_pk_bf16_f32 v126, v122, v123
	v_lshlrev_b64 v[122:123], 1, v[130:131]
	v_cvt_pk_bf16_f32 v127, v158, v159
	v_lshl_add_u64 v[128:129], v[156:157], 0, v[122:123]
	global_store_dwordx4 v[128:129], v[124:127], off
	v_cvt_f32_ubyte1_e32 v157, v155
	v_cvt_f32_ubyte0_e32 v156, v155
	v_cvt_f32_ubyte1_e32 v125, v154
	v_cvt_f32_ubyte0_e32 v124, v154
	v_cvt_f32_ubyte3_e32 v127, v154
	v_cvt_f32_ubyte2_e32 v126, v154
	v_pk_mul_f32 v[126:127], v[126:127], s[30:31] op_sel_hi:[1,0]
	v_pk_mul_f32 v[124:125], v[124:125], s[30:31] op_sel_hi:[1,0]
	v_cvt_f32_ubyte3_e32 v159, v155
	v_cvt_f32_ubyte2_e32 v158, v155
	v_pk_mul_f32 v[154:155], v[158:159], s[30:31] op_sel_hi:[1,0]
	v_pk_mul_f32 v[156:157], v[156:157], s[30:31] op_sel_hi:[1,0]
	v_pk_mul_f32 v[124:125], v[124:125], s[12:13] op_sel_hi:[1,0]
	v_pk_mul_f32 v[126:127], v[126:127], s[12:13] op_sel_hi:[1,0]
	v_pk_fma_f32 v[118:119], v[118:119], v[124:125], 0 op_sel_hi:[1,1,0]
	v_pk_fma_f32 v[120:121], v[120:121], v[126:127], 0 op_sel_hi:[1,1,0]
	v_pk_mul_f32 v[124:125], v[156:157], s[12:13] op_sel_hi:[1,0]
	v_pk_mul_f32 v[126:127], v[154:155], s[12:13] op_sel_hi:[1,0]
	s_nop 0
	v_pk_fma_f32 v[126:127], v[116:117], v[126:127], 0 op_sel_hi:[1,1,0]
	v_pk_fma_f32 v[116:117], v[114:115], v[124:125], 0 op_sel_hi:[1,1,0]
	v_cvt_pk_bf16_f32 v114, v118, v119
	v_cvt_pk_bf16_f32 v115, v120, v121
	v_cvt_f32_ubyte1_e32 v119, v153
	v_cvt_pk_bf16_f32 v116, v116, v117
	v_cvt_pk_bf16_f32 v117, v126, v127
	global_store_dwordx4 v[128:129], v[114:117], off offset:256
	v_cvt_f32_ubyte0_e32 v118, v153
	v_cvt_f32_ubyte3_e32 v121, v153
	v_cvt_f32_ubyte1_e32 v115, v152
	v_cvt_f32_ubyte0_e32 v114, v152
	v_cvt_f32_ubyte3_e32 v117, v152
	v_cvt_f32_ubyte2_e32 v116, v152
	v_pk_mul_f32 v[116:117], v[116:117], s[30:31] op_sel_hi:[1,0]
	v_pk_mul_f32 v[114:115], v[114:115], s[30:31] op_sel_hi:[1,0]
	v_cvt_f32_ubyte2_e32 v120, v153
	v_pk_mul_f32 v[120:121], v[120:121], s[30:31] op_sel_hi:[1,0]
	v_pk_mul_f32 v[118:119], v[118:119], s[30:31] op_sel_hi:[1,0]
	v_pk_mul_f32 v[114:115], v[114:115], s[12:13] op_sel_hi:[1,0]
	v_pk_mul_f32 v[116:117], v[116:117], s[12:13] op_sel_hi:[1,0]
	v_pk_fma_f32 v[110:111], v[110:111], v[114:115], 0 op_sel_hi:[1,1,0]
	v_pk_fma_f32 v[112:113], v[112:113], v[116:117], 0 op_sel_hi:[1,1,0]
	v_pk_mul_f32 v[114:115], v[118:119], s[12:13] op_sel_hi:[1,0]
	v_pk_mul_f32 v[116:117], v[120:121], s[12:13] op_sel_hi:[1,0]
	s_nop 0
	v_pk_fma_f32 v[116:117], v[108:109], v[116:117], 0 op_sel_hi:[1,1,0]
	v_pk_fma_f32 v[108:109], v[106:107], v[114:115], 0 op_sel_hi:[1,1,0]
	v_cvt_pk_bf16_f32 v106, v110, v111
	v_lshlrev_b64 v[110:111], 12, v[150:151]
	v_lshl_add_u64 v[110:111], s[74:75], 0, v[110:111]
	v_cvt_pk_bf16_f32 v107, v112, v113
	v_cvt_pk_bf16_f32 v108, v108, v109
	v_cvt_pk_bf16_f32 v109, v116, v117
	v_lshl_add_u64 v[110:111], v[110:111], 0, v[122:123]
; __device__ __forceinline__ u32x4 pack8(f32x4 v0, f32x4 v1) { u32x4 w; w.x = cvt_pk_bf16(v0[0], v0[1]); w.y = cvt_pk_bf16(v0[2], v0[3]); w.z = cvt_pk_bf16(v1[0], v1[1]); w.w = cvt_pk_bf16(v1[2], v1[3]); return w; }
; __device__ __forceinline__ void unpack8(u32x4 w, f32x4& a, f32x4& b) { a = (f32x4){bf_lo(w.x), bf_hi(w.x), bf_lo(w.y), bf_hi(w.y)}; b = (f32x4){bf_lo(w.z), bf_hi(w.z), bf_lo(w.w), bf_hi(w.w)}; }
;     __device__ __forceinline__ void operator()(const f32x4 (&acc)[2][2][4][2], const Unit& u, int wr, int wc, int fr, int fq) const {
;         const unsigned char* gate_ = gate; bf16_t* mg_ = mg; const int first_ = first; const float as_ = ascale;
;         epi_perm2<LB>(acc, u, wr, wc, fr, fq,
;             [=](int row, int col) __attribute__((always_inline)) { LB L; L.g = *(const u32x2*)(gate_ + (size_t)row * (NP * 2) + col);
;                 L.m = first_ ? (u32x4){0u, 0u, 0u, 0u} : *(const u32x4*)(mg_ + (size_t)row * DM + col); return L; },
;             [=](int row, int col, f32x4 v0, f32x4 v1, const LB& L) __attribute__((always_inline)) {
;                 f32x4 g0, g1, p0, p1; gate_unpack8(L.g, g0, g1); unpack8(L.m, p0, p1);
;                 v0 = v0 * (g0 * as_) + p0; v1 = v1 * (g1 * as_) + p1;
;                 *(u32x4*)(mg_ + (size_t)row * DM + col) = pack8(v0, v1); });
;     }
	global_store_dwordx4 v[110:111], v[106:109], off
	v_cvt_f32_ubyte1_e32 v113, v149
	v_cvt_f32_ubyte0_e32 v112, v149
	v_cvt_f32_ubyte1_e32 v107, v148
	v_cvt_f32_ubyte0_e32 v106, v148
	v_cvt_f32_ubyte3_e32 v109, v148
	v_cvt_f32_ubyte2_e32 v108, v148
	v_pk_mul_f32 v[108:109], v[108:109], s[30:31] op_sel_hi:[1,0]
	v_pk_mul_f32 v[106:107], v[106:107], s[30:31] op_sel_hi:[1,0]
	v_cvt_f32_ubyte3_e32 v115, v149
	v_cvt_f32_ubyte2_e32 v114, v149
	v_pk_mul_f32 v[114:115], v[114:115], s[30:31] op_sel_hi:[1,0]
	v_pk_mul_f32 v[112:113], v[112:113], s[30:31] op_sel_hi:[1,0]
	v_pk_mul_f32 v[106:107], v[106:107], s[12:13] op_sel_hi:[1,0]
	v_pk_mul_f32 v[108:109], v[108:109], s[12:13] op_sel_hi:[1,0]
	v_pk_fma_f32 v[102:103], v[102:103], v[106:107], 0 op_sel_hi:[1,1,0]
	v_pk_fma_f32 v[104:105], v[104:105], v[108:109], 0 op_sel_hi:[1,1,0]
	v_pk_mul_f32 v[106:107], v[112:113], s[12:13] op_sel_hi:[1,0]
	v_pk_mul_f32 v[108:109], v[114:115], s[12:13] op_sel_hi:[1,0]
	s_nop 0
	v_pk_fma_f32 v[108:109], v[100:101], v[108:109], 0 op_sel_hi:[1,1,0]
	v_pk_fma_f32 v[100:101], v[98:99], v[106:107], 0 op_sel_hi:[1,1,0]
	v_cvt_pk_bf16_f32 v98, v102, v103
	v_cvt_pk_bf16_f32 v99, v104, v105
	v_cvt_f32_ubyte1_e32 v103, v147
	v_cvt_pk_bf16_f32 v100, v100, v101
	v_cvt_pk_bf16_f32 v101, v108, v109
	global_store_dwordx4 v[110:111], v[98:101], off offset:256
	v_cvt_f32_ubyte0_e32 v102, v147
	v_cvt_f32_ubyte3_e32 v105, v147
	v_cvt_f32_ubyte1_e32 v99, v146
	v_cvt_f32_ubyte0_e32 v98, v146
	v_cvt_f32_ubyte3_e32 v101, v146
	v_cvt_f32_ubyte2_e32 v100, v146
	v_pk_mul_f32 v[100:101], v[100:101], s[30:31] op_sel_hi:[1,0]
	v_pk_mul_f32 v[98:99], v[98:99], s[30:31] op_sel_hi:[1,0]
	v_cvt_f32_ubyte2_e32 v104, v147
	v_pk_mul_f32 v[104:105], v[104:105], s[30:31] op_sel_hi:[1,0]
	v_pk_mul_f32 v[102:103], v[102:103], s[30:31] op_sel_hi:[1,0]
	v_pk_mul_f32 v[98:99], v[98:99], s[12:13] op_sel_hi:[1,0]
	v_pk_mul_f32 v[100:101], v[100:101], s[12:13] op_sel_hi:[1,0]
	v_pk_fma_f32 v[94:95], v[94:95], v[98:99], 0 op_sel_hi:[1,1,0]
	v_pk_fma_f32 v[96:97], v[96:97], v[100:101], 0 op_sel_hi:[1,1,0]
	v_pk_mul_f32 v[98:99], v[102:103], s[12:13] op_sel_hi:[1,0]
	v_pk_mul_f32 v[100:101], v[104:105], s[12:13] op_sel_hi:[1,0]
	s_nop 0
	v_pk_fma_f32 v[100:101], v[92:93], v[100:101], 0 op_sel_hi:[1,1,0]
	v_pk_fma_f32 v[92:93], v[90:91], v[98:99], 0 op_sel_hi:[1,1,0]
	v_cvt_pk_bf16_f32 v90, v94, v95
	v_lshlrev_b64 v[94:95], 12, v[144:145]
	v_lshl_add_u64 v[94:95], s[74:75], 0, v[94:95]
	v_cvt_pk_bf16_f32 v91, v96, v97
	v_cvt_pk_bf16_f32 v92, v92, v93
	v_cvt_pk_bf16_f32 v93, v100, v101
	v_lshl_add_u64 v[94:95], v[94:95], 0, v[122:123]
	global_store_dwordx4 v[94:95], v[90:93], off
	v_cvt_f32_ubyte1_e32 v97, v143
	v_cvt_f32_ubyte0_e32 v96, v143
	v_cvt_f32_ubyte1_e32 v91, v142
	v_cvt_f32_ubyte0_e32 v90, v142
	v_cvt_f32_ubyte3_e32 v93, v142
	v_cvt_f32_ubyte2_e32 v92, v142
	v_pk_mul_f32 v[92:93], v[92:93], s[30:31] op_sel_hi:[1,0]
	v_pk_mul_f32 v[90:91], v[90:91], s[30:31] op_sel_hi:[1,0]
	v_cvt_f32_ubyte3_e32 v99, v143
	v_cvt_f32_ubyte2_e32 v98, v143
	v_pk_mul_f32 v[98:99], v[98:99], s[30:31] op_sel_hi:[1,0]
	v_pk_mul_f32 v[96:97], v[96:97], s[30:31] op_sel_hi:[1,0]
	v_pk_mul_f32 v[90:91], v[90:91], s[12:13] op_sel_hi:[1,0]
	v_pk_mul_f32 v[92:93], v[92:93], s[12:13] op_sel_hi:[1,0]
	v_pk_fma_f32 v[86:87], v[86:87], v[90:91], 0 op_sel_hi:[1,1,0]
	v_pk_fma_f32 v[88:89], v[88:89], v[92:93], 0 op_sel_hi:[1,1,0]
	v_pk_mul_f32 v[90:91], v[96:97], s[12:13] op_sel_hi:[1,0]
	v_pk_mul_f32 v[92:93], v[98:99], s[12:13] op_sel_hi:[1,0]
	s_nop 0
	v_pk_fma_f32 v[92:93], v[84:85], v[92:93], 0 op_sel_hi:[1,1,0]
	v_pk_fma_f32 v[84:85], v[82:83], v[90:91], 0 op_sel_hi:[1,1,0]
	v_cvt_pk_bf16_f32 v82, v86, v87
	v_cvt_pk_bf16_f32 v83, v88, v89
	v_cvt_f32_ubyte1_e32 v87, v141
	v_cvt_pk_bf16_f32 v84, v84, v85
	v_cvt_pk_bf16_f32 v85, v92, v93
	global_store_dwordx4 v[94:95], v[82:85], off offset:256
	v_cvt_f32_ubyte0_e32 v86, v141
	v_cvt_f32_ubyte3_e32 v89, v141
	v_cvt_f32_ubyte1_e32 v83, v140
	v_cvt_f32_ubyte0_e32 v82, v140
	v_cvt_f32_ubyte3_e32 v85, v140
	v_cvt_f32_ubyte2_e32 v84, v140
	v_pk_mul_f32 v[84:85], v[84:85], s[30:31] op_sel_hi:[1,0]
	v_pk_mul_f32 v[82:83], v[82:83], s[30:31] op_sel_hi:[1,0]
	v_cvt_f32_ubyte2_e32 v88, v141
	v_pk_mul_f32 v[88:89], v[88:89], s[30:31] op_sel_hi:[1,0]
	v_pk_mul_f32 v[86:87], v[86:87], s[30:31] op_sel_hi:[1,0]
	v_pk_mul_f32 v[82:83], v[82:83], s[12:13] op_sel_hi:[1,0]
	v_pk_mul_f32 v[84:85], v[84:85], s[12:13] op_sel_hi:[1,0]
	v_pk_fma_f32 v[78:79], v[78:79], v[82:83], 0 op_sel_hi:[1,1,0]
	v_pk_fma_f32 v[80:81], v[80:81], v[84:85], 0 op_sel_hi:[1,1,0]
	v_pk_mul_f32 v[82:83], v[86:87], s[12:13] op_sel_hi:[1,0]
	v_pk_mul_f32 v[84:85], v[88:89], s[12:13] op_sel_hi:[1,0]
	s_nop 0
	v_pk_fma_f32 v[84:85], v[76:77], v[84:85], 0 op_sel_hi:[1,1,0]
	v_pk_fma_f32 v[76:77], v[74:75], v[82:83], 0 op_sel_hi:[1,1,0]
	v_cvt_pk_bf16_f32 v74, v78, v79
	v_lshlrev_b64 v[78:79], 12, v[136:137]
	v_lshl_add_u64 v[78:79], s[74:75], 0, v[78:79]
	v_cvt_pk_bf16_f32 v75, v80, v81
	v_cvt_pk_bf16_f32 v76, v76, v77
	v_cvt_pk_bf16_f32 v77, v84, v85
	v_lshl_add_u64 v[78:79], v[78:79], 0, v[122:123]
	global_store_dwordx4 v[78:79], v[74:77], off
	v_cvt_f32_ubyte1_e32 v81, v139
	v_cvt_f32_ubyte0_e32 v80, v139
	v_cvt_f32_ubyte1_e32 v75, v138
	v_cvt_f32_ubyte0_e32 v74, v138
	v_cvt_f32_ubyte3_e32 v77, v138
	v_cvt_f32_ubyte2_e32 v76, v138
	v_pk_mul_f32 v[76:77], v[76:77], s[30:31] op_sel_hi:[1,0]
	v_pk_mul_f32 v[74:75], v[74:75], s[30:31] op_sel_hi:[1,0]
	v_cvt_f32_ubyte3_e32 v83, v139
	v_cvt_f32_ubyte2_e32 v82, v139
	v_pk_mul_f32 v[82:83], v[82:83], s[30:31] op_sel_hi:[1,0]
	v_pk_mul_f32 v[80:81], v[80:81], s[30:31] op_sel_hi:[1,0]
; __device__ __forceinline__ u32x4 pack8(f32x4 v0, f32x4 v1) { u32x4 w; w.x = cvt_pk_bf16(v0[0], v0[1]); w.y = cvt_pk_bf16(v0[2], v0[3]); w.z = cvt_pk_bf16(v1[0], v1[1]); w.w = cvt_pk_bf16(v1[2], v1[3]); return w; }
; __device__ __forceinline__ void unpack8(u32x4 w, f32x4& a, f32x4& b) { a = (f32x4){bf_lo(w.x), bf_hi(w.x), bf_lo(w.y), bf_hi(w.y)}; b = (f32x4){bf_lo(w.z), bf_hi(w.z), bf_lo(w.w), bf_hi(w.w)}; }
; template <class LT, class FL, class FP>
; __device__ __forceinline__ void epi_perm2(const f32x4 (&acc)[2][2][4][2], const Unit& u, int wr, int wc, int fr, int fq, const FL& loadf, const FP& procf) {
; #pragma unroll
;     for (int ai = 0; ai < 2; ++ai) {
;         LT L[4][2];
; #pragma unroll
;         for (int m = 0; m < 4; ++m)
; #pragma unroll
;             for (int bj = 0; bj < 2; ++bj) L[m][bj] = loadf(u.pm * BM + ai * HALF + wr * 64 + m * 16 + fr, u.pn * BM + bj * HALF + wc * 32 + 8 * fq);
; #pragma unroll
;         for (int m = 0; m < 4; ++m)
; #pragma unroll
;             for (int bj = 0; bj < 2; ++bj) procf(u.pm * BM + ai * HALF + wr * 64 + m * 16 + fr, u.pn * BM + bj * HALF + wc * 32 + 8 * fq, acc[ai][bj][m][0], acc[ai][bj][m][1], L[m][bj]);
;     }
; }
;     __device__ __forceinline__ void operator()(const f32x4 (&acc)[2][2][4][2], const Unit& u, int wr, int wc, int fr, int fq) const {
;         const unsigned char* gate_ = gate; bf16_t* mg_ = mg; const int first_ = first; const float as_ = ascale;
;         epi_perm2<LB>(acc, u, wr, wc, fr, fq,
;             [=](int row, int col) __attribute__((always_inline)) { LB L; L.g = *(const u32x2*)(gate_ + (size_t)row * (NP * 2) + col);
;                 L.m = first_ ? (u32x4){0u, 0u, 0u, 0u} : *(const u32x4*)(mg_ + (size_t)row * DM + col); return L; },
;             [=](int row, int col, f32x4 v0, f32x4 v1, const LB& L) __attribute__((always_inline)) {
;                 f32x4 g0, g1, p0, p1; gate_unpack8(L.g, g0, g1); unpack8(L.m, p0, p1);
;                 v0 = v0 * (g0 * as_) + p0; v1 = v1 * (g1 * as_) + p1;
;                 *(u32x4*)(mg_ + (size_t)row * DM + col) = pack8(v0, v1); });
;     }
	v_pk_mul_f32 v[74:75], v[74:75], s[12:13] op_sel_hi:[1,0]
	v_pk_mul_f32 v[76:77], v[76:77], s[12:13] op_sel_hi:[1,0]
	v_pk_fma_f32 v[70:71], v[70:71], v[74:75], 0 op_sel_hi:[1,1,0]
	v_pk_fma_f32 v[72:73], v[72:73], v[76:77], 0 op_sel_hi:[1,1,0]
	v_pk_mul_f32 v[74:75], v[80:81], s[12:13] op_sel_hi:[1,0]
	v_pk_mul_f32 v[76:77], v[82:83], s[12:13] op_sel_hi:[1,0]
	v_add_u32_e32 v82, 0x90, v132
	v_pk_fma_f32 v[76:77], v[68:69], v[76:77], 0 op_sel_hi:[1,1,0]
	v_pk_fma_f32 v[68:69], v[66:67], v[74:75], 0 op_sel_hi:[1,1,0]
	v_cvt_pk_bf16_f32 v66, v70, v71
	v_cvt_pk_bf16_f32 v67, v72, v73
	v_add_u32_e32 v74, 0xa0, v132
	v_cvt_pk_bf16_f32 v68, v68, v69
	v_cvt_pk_bf16_f32 v69, v76, v77
	global_store_dwordx4 v[78:79], v[66:69], off offset:256
	v_ashrrev_i32_e32 v83, 31, v82
	v_ashrrev_i32_e32 v75, 31, v74
	v_add_u32_e32 v66, 0x80, v132
	v_ashrrev_i32_e32 v67, 31, v66
	v_mad_i64_i32 v[68:69], s[0:1], v66, s31, v[134:135]
	v_lshlrev_b64 v[66:67], 12, v[66:67]
	v_lshl_add_u64 v[76:77], s[74:75], 0, v[66:67]
	v_lshl_add_u64 v[66:67], v[68:69], 0, v[130:131]
	global_load_dwordx2 v[78:79], v[66:67], off
	global_load_dwordx2 v[80:81], v[66:67], off offset:128
	v_mad_i64_i32 v[66:67], s[0:1], v82, s31, v[134:135]
	v_lshl_add_u64 v[66:67], v[66:67], 0, v[130:131]
	global_load_dwordx2 v[84:85], v[66:67], off
	global_load_dwordx2 v[86:87], v[66:67], off offset:128
	v_mad_i64_i32 v[66:67], s[0:1], v74, s31, v[134:135]
	v_lshl_add_u64 v[66:67], v[66:67], 0, v[130:131]
	global_load_dwordx2 v[88:89], v[66:67], off
	global_load_dwordx2 v[72:73], v[66:67], off offset:128
	v_add_u32_e32 v68, 0xb0, v132
	v_mad_i64_i32 v[66:67], s[0:1], v68, s31, v[134:135]
	v_lshl_add_u64 v[66:67], v[66:67], 0, v[130:131]
	global_load_dwordx2 v[70:71], v[66:67], off
	s_nop 0
	global_load_dwordx2 v[66:67], v[66:67], off offset:128
	v_ashrrev_i32_e32 v69, 31, v68
	s_waitcnt vmcnt(0) lgkmcnt(0)
	v_cvt_f32_ubyte1_e32 v91, v78
	v_cvt_f32_ubyte0_e32 v90, v78
	v_pk_mul_f32 v[90:91], v[90:91], s[30:31] op_sel_hi:[1,0]
	v_cvt_f32_ubyte1_e32 v95, v79
	v_cvt_f32_ubyte0_e32 v94, v79
	v_cvt_f32_ubyte3_e32 v97, v79
	v_cvt_f32_ubyte2_e32 v96, v79
	v_cvt_f32_ubyte3_e32 v93, v78
	v_cvt_f32_ubyte2_e32 v92, v78
	v_pk_mul_f32 v[78:79], v[96:97], s[30:31] op_sel_hi:[1,0]
	v_pk_mul_f32 v[94:95], v[94:95], s[30:31] op_sel_hi:[1,0]
	v_pk_mul_f32 v[90:91], v[90:91], s[12:13] op_sel_hi:[1,0]
	v_pk_mul_f32 v[92:93], v[92:93], s[30:31] op_sel_hi:[1,0]
	v_pk_fma_f32 v[62:63], v[62:63], v[90:91], 0 op_sel_hi:[1,1,0]
	v_pk_mul_f32 v[90:91], v[94:95], s[12:13] op_sel_hi:[1,0]
	v_pk_mul_f32 v[78:79], v[78:79], s[12:13] op_sel_hi:[1,0]
	v_pk_mul_f32 v[92:93], v[92:93], s[12:13] op_sel_hi:[1,0]
	v_pk_fma_f32 v[78:79], v[60:61], v[78:79], 0 op_sel_hi:[1,1,0]
	v_pk_fma_f32 v[60:61], v[58:59], v[90:91], 0 op_sel_hi:[1,1,0]
	v_pk_fma_f32 v[64:65], v[64:65], v[92:93], 0 op_sel_hi:[1,1,0]
	v_cvt_pk_bf16_f32 v58, v62, v63
	v_lshl_add_u64 v[62:63], v[76:77], 0, v[122:123]
	v_cvt_pk_bf16_f32 v59, v64, v65
	v_cvt_pk_bf16_f32 v60, v60, v61
	v_cvt_pk_bf16_f32 v61, v78, v79
	global_store_dwordx4 v[62:63], v[58:61], off
	v_cvt_f32_ubyte1_e32 v65, v81
	v_cvt_f32_ubyte0_e32 v64, v81
	v_cvt_f32_ubyte1_e32 v59, v80
	v_cvt_f32_ubyte0_e32 v58, v80
	v_cvt_f32_ubyte3_e32 v61, v80
	v_cvt_f32_ubyte2_e32 v60, v80
	v_pk_mul_f32 v[60:61], v[60:61], s[30:31] op_sel_hi:[1,0]
	v_pk_mul_f32 v[58:59], v[58:59], s[30:31] op_sel_hi:[1,0]
	v_cvt_f32_ubyte3_e32 v77, v81
	v_cvt_f32_ubyte2_e32 v76, v81
	v_pk_mul_f32 v[76:77], v[76:77], s[30:31] op_sel_hi:[1,0]
	v_pk_mul_f32 v[64:65], v[64:65], s[30:31] op_sel_hi:[1,0]
	v_pk_mul_f32 v[58:59], v[58:59], s[12:13] op_sel_hi:[1,0]
	v_pk_mul_f32 v[60:61], v[60:61], s[12:13] op_sel_hi:[1,0]
	v_pk_fma_f32 v[54:55], v[54:55], v[58:59], 0 op_sel_hi:[1,1,0]
	v_pk_fma_f32 v[56:57], v[56:57], v[60:61], 0 op_sel_hi:[1,1,0]
	v_pk_mul_f32 v[58:59], v[64:65], s[12:13] op_sel_hi:[1,0]
	v_pk_mul_f32 v[60:61], v[76:77], s[12:13] op_sel_hi:[1,0]
	s_nop 0
	v_pk_fma_f32 v[60:61], v[52:53], v[60:61], 0 op_sel_hi:[1,1,0]
	v_pk_fma_f32 v[52:53], v[50:51], v[58:59], 0 op_sel_hi:[1,1,0]
	v_cvt_pk_bf16_f32 v50, v54, v55
	v_cvt_pk_bf16_f32 v51, v56, v57
	v_cvt_f32_ubyte1_e32 v55, v85
	v_cvt_pk_bf16_f32 v52, v52, v53
	v_cvt_pk_bf16_f32 v53, v60, v61
	global_store_dwordx4 v[62:63], v[50:53], off offset:256
	v_cvt_f32_ubyte0_e32 v54, v85
	v_cvt_f32_ubyte3_e32 v57, v85
	v_cvt_f32_ubyte1_e32 v51, v84
	v_cvt_f32_ubyte0_e32 v50, v84
	v_cvt_f32_ubyte3_e32 v53, v84
	v_cvt_f32_ubyte2_e32 v52, v84
	v_pk_mul_f32 v[52:53], v[52:53], s[30:31] op_sel_hi:[1,0]
	v_pk_mul_f32 v[50:51], v[50:51], s[30:31] op_sel_hi:[1,0]
	v_cvt_f32_ubyte2_e32 v56, v85
	v_pk_mul_f32 v[56:57], v[56:57], s[30:31] op_sel_hi:[1,0]
	v_pk_mul_f32 v[54:55], v[54:55], s[30:31] op_sel_hi:[1,0]
	v_pk_mul_f32 v[50:51], v[50:51], s[12:13] op_sel_hi:[1,0]
	v_pk_mul_f32 v[52:53], v[52:53], s[12:13] op_sel_hi:[1,0]
	v_pk_fma_f32 v[46:47], v[46:47], v[50:51], 0 op_sel_hi:[1,1,0]
	v_pk_fma_f32 v[48:49], v[48:49], v[52:53], 0 op_sel_hi:[1,1,0]
	v_pk_mul_f32 v[50:51], v[54:55], s[12:13] op_sel_hi:[1,0]
	v_pk_mul_f32 v[52:53], v[56:57], s[12:13] op_sel_hi:[1,0]
	s_nop 0
	v_pk_fma_f32 v[52:53], v[44:45], v[52:53], 0 op_sel_hi:[1,1,0]
	v_pk_fma_f32 v[44:45], v[42:43], v[50:51], 0 op_sel_hi:[1,1,0]
	v_cvt_pk_bf16_f32 v42, v46, v47
	v_lshlrev_b64 v[46:47], 12, v[82:83]
	v_lshl_add_u64 v[46:47], s[74:75], 0, v[46:47]
	v_cvt_pk_bf16_f32 v43, v48, v49
	v_cvt_pk_bf16_f32 v44, v44, v45
	v_cvt_pk_bf16_f32 v45, v52, v53
	v_lshl_add_u64 v[46:47], v[46:47], 0, v[122:123]
	global_store_dwordx4 v[46:47], v[42:45], off
	v_cvt_f32_ubyte1_e32 v49, v87
	v_cvt_f32_ubyte0_e32 v48, v87
	v_cvt_f32_ubyte1_e32 v43, v86
; __device__ __forceinline__ int otid() { int t = threadIdx.x; asm volatile("" : "+v"(t)); return t; }
; #define PG8_BAR __builtin_amdgcn_s_barrier()
; __device__ __forceinline__ u32x4 pack8(f32x4 v0, f32x4 v1) { u32x4 w; w.x = cvt_pk_bf16(v0[0], v0[1]); w.y = cvt_pk_bf16(v0[2], v0[3]); w.z = cvt_pk_bf16(v1[0], v1[1]); w.w = cvt_pk_bf16(v1[2], v1[3]); return w; }
; __device__ __forceinline__ void unpack8(u32x4 w, f32x4& a, f32x4& b) { a = (f32x4){bf_lo(w.x), bf_hi(w.x), bf_lo(w.y), bf_hi(w.y)}; b = (f32x4){bf_lo(w.z), bf_hi(w.z), bf_lo(w.w), bf_hi(w.w)}; }
;     ...
;         if (wr == 0) PG8_BAR;
;         { const int t2_ = otid(), w2_ = t2_ >> 6, l2_ = t2_ & 63; E(acc, cur, w2_ >> 2, w2_ & 3, l2_ & 15, l2_ >> 4); }
;         if (!has_next) break;
; #pragma unroll
;         for (int a = 0; a < 2; ++a)
; #pragma unroll
;             for (int b = 0; b < 2; ++b)
; #pragma unroll
;                 for (int m = 0; m < 4; ++m)
; #pragma unroll
;                     for (int n = 0; n < 2; ++n) acc[a][b][m][n] = (f32x4){0.f, 0.f, 0.f, 0.f};
;         cur = nxt; cA = nA; cB = nB; ++ui;
;         if (wr == 1) PG8_BAR;
;     }
;     __device__ __forceinline__ void operator()(const f32x4 (&acc)[2][2][4][2], const Unit& u, int wr, int wc, int fr, int fq) const {
;         const unsigned char* gate_ = gate; bf16_t* mg_ = mg; const int first_ = first; const float as_ = ascale;
;         epi_perm2<LB>(acc, u, wr, wc, fr, fq,
;             [=](int row, int col) __attribute__((always_inline)) { LB L; L.g = *(const u32x2*)(gate_ + (size_t)row * (NP * 2) + col);
;                 L.m = first_ ? (u32x4){0u, 0u, 0u, 0u} : *(const u32x4*)(mg_ + (size_t)row * DM + col); return L; },
;             [=](int row, int col, f32x4 v0, f32x4 v1, const LB& L) __attribute__((always_inline)) {
;                 f32x4 g0, g1, p0, p1; gate_unpack8(L.g, g0, g1); unpack8(L.m, p0, p1);
;                 v0 = v0 * (g0 * as_) + p0; v1 = v1 * (g1 * as_) + p1;
;                 *(u32x4*)(mg_ + (size_t)row * DM + col) = pack8(v0, v1); });
;     }
	v_cvt_f32_ubyte0_e32 v42, v86
	v_cvt_f32_ubyte3_e32 v45, v86
	v_cvt_f32_ubyte2_e32 v44, v86
	v_pk_mul_f32 v[44:45], v[44:45], s[30:31] op_sel_hi:[1,0]
	v_pk_mul_f32 v[42:43], v[42:43], s[30:31] op_sel_hi:[1,0]
	v_cvt_f32_ubyte3_e32 v51, v87
	v_cvt_f32_ubyte2_e32 v50, v87
	v_pk_mul_f32 v[50:51], v[50:51], s[30:31] op_sel_hi:[1,0]
	v_pk_mul_f32 v[48:49], v[48:49], s[30:31] op_sel_hi:[1,0]
	v_pk_mul_f32 v[42:43], v[42:43], s[12:13] op_sel_hi:[1,0]
	v_pk_mul_f32 v[44:45], v[44:45], s[12:13] op_sel_hi:[1,0]
	v_pk_fma_f32 v[38:39], v[38:39], v[42:43], 0 op_sel_hi:[1,1,0]
	v_pk_fma_f32 v[40:41], v[40:41], v[44:45], 0 op_sel_hi:[1,1,0]
	v_pk_mul_f32 v[42:43], v[48:49], s[12:13] op_sel_hi:[1,0]
	v_pk_mul_f32 v[44:45], v[50:51], s[12:13] op_sel_hi:[1,0]
	s_nop 0
	v_pk_fma_f32 v[44:45], v[36:37], v[44:45], 0 op_sel_hi:[1,1,0]
	v_pk_fma_f32 v[36:37], v[34:35], v[42:43], 0 op_sel_hi:[1,1,0]
	v_cvt_pk_bf16_f32 v34, v38, v39
	v_cvt_pk_bf16_f32 v35, v40, v41
	v_cvt_f32_ubyte1_e32 v39, v89
	v_cvt_pk_bf16_f32 v36, v36, v37
	v_cvt_pk_bf16_f32 v37, v44, v45
	global_store_dwordx4 v[46:47], v[34:37], off offset:256
	v_cvt_f32_ubyte0_e32 v38, v89
	v_cvt_f32_ubyte3_e32 v41, v89
	v_cvt_f32_ubyte1_e32 v35, v88
	v_cvt_f32_ubyte0_e32 v34, v88
	v_cvt_f32_ubyte3_e32 v37, v88
	v_cvt_f32_ubyte2_e32 v36, v88
	v_pk_mul_f32 v[36:37], v[36:37], s[30:31] op_sel_hi:[1,0]
	v_pk_mul_f32 v[34:35], v[34:35], s[30:31] op_sel_hi:[1,0]
	v_cvt_f32_ubyte2_e32 v40, v89
	v_pk_mul_f32 v[40:41], v[40:41], s[30:31] op_sel_hi:[1,0]
	v_pk_mul_f32 v[38:39], v[38:39], s[30:31] op_sel_hi:[1,0]
	v_pk_mul_f32 v[34:35], v[34:35], s[12:13] op_sel_hi:[1,0]
	v_pk_mul_f32 v[36:37], v[36:37], s[12:13] op_sel_hi:[1,0]
	v_pk_fma_f32 v[30:31], v[30:31], v[34:35], 0 op_sel_hi:[1,1,0]
	v_pk_fma_f32 v[32:33], v[32:33], v[36:37], 0 op_sel_hi:[1,1,0]
	v_pk_mul_f32 v[34:35], v[38:39], s[12:13] op_sel_hi:[1,0]
	v_pk_mul_f32 v[36:37], v[40:41], s[12:13] op_sel_hi:[1,0]
	s_nop 0
	v_pk_fma_f32 v[36:37], v[28:29], v[36:37], 0 op_sel_hi:[1,1,0]
	v_pk_fma_f32 v[28:29], v[26:27], v[34:35], 0 op_sel_hi:[1,1,0]
	v_cvt_pk_bf16_f32 v26, v30, v31
	v_lshlrev_b64 v[30:31], 12, v[74:75]
	v_lshl_add_u64 v[30:31], s[74:75], 0, v[30:31]
	v_cvt_pk_bf16_f32 v27, v32, v33
	v_cvt_pk_bf16_f32 v28, v28, v29
	v_cvt_pk_bf16_f32 v29, v36, v37
	v_lshl_add_u64 v[30:31], v[30:31], 0, v[122:123]
	global_store_dwordx4 v[30:31], v[26:29], off
	v_cvt_f32_ubyte1_e32 v33, v73
	v_cvt_f32_ubyte0_e32 v32, v73
	v_cvt_f32_ubyte1_e32 v27, v72
	v_cvt_f32_ubyte0_e32 v26, v72
	v_cvt_f32_ubyte3_e32 v29, v72
	v_cvt_f32_ubyte2_e32 v28, v72
	v_pk_mul_f32 v[28:29], v[28:29], s[30:31] op_sel_hi:[1,0]
	v_pk_mul_f32 v[26:27], v[26:27], s[30:31] op_sel_hi:[1,0]
	v_cvt_f32_ubyte3_e32 v35, v73
	v_cvt_f32_ubyte2_e32 v34, v73
	v_pk_mul_f32 v[34:35], v[34:35], s[30:31] op_sel_hi:[1,0]
	v_pk_mul_f32 v[32:33], v[32:33], s[30:31] op_sel_hi:[1,0]
	v_pk_mul_f32 v[26:27], v[26:27], s[12:13] op_sel_hi:[1,0]
	v_pk_mul_f32 v[28:29], v[28:29], s[12:13] op_sel_hi:[1,0]
	v_pk_fma_f32 v[22:23], v[22:23], v[26:27], 0 op_sel_hi:[1,1,0]
	v_pk_fma_f32 v[24:25], v[24:25], v[28:29], 0 op_sel_hi:[1,1,0]
	v_pk_mul_f32 v[26:27], v[32:33], s[12:13] op_sel_hi:[1,0]
	v_pk_mul_f32 v[28:29], v[34:35], s[12:13] op_sel_hi:[1,0]
	s_nop 0
	v_pk_fma_f32 v[28:29], v[20:21], v[28:29], 0 op_sel_hi:[1,1,0]
	v_pk_fma_f32 v[20:21], v[18:19], v[26:27], 0 op_sel_hi:[1,1,0]
	v_cvt_pk_bf16_f32 v18, v22, v23
	v_cvt_pk_bf16_f32 v19, v24, v25
	v_cvt_f32_ubyte1_e32 v23, v71
	v_cvt_pk_bf16_f32 v20, v20, v21
	v_cvt_pk_bf16_f32 v21, v28, v29
	global_store_dwordx4 v[30:31], v[18:21], off offset:256
	v_cvt_f32_ubyte0_e32 v22, v71
	v_cvt_f32_ubyte3_e32 v25, v71
	v_cvt_f32_ubyte1_e32 v19, v70
	v_cvt_f32_ubyte0_e32 v18, v70
	v_cvt_f32_ubyte3_e32 v21, v70
	v_cvt_f32_ubyte2_e32 v20, v70
	v_pk_mul_f32 v[20:21], v[20:21], s[30:31] op_sel_hi:[1,0]
	v_pk_mul_f32 v[18:19], v[18:19], s[30:31] op_sel_hi:[1,0]
	v_cvt_f32_ubyte2_e32 v24, v71
	v_pk_mul_f32 v[24:25], v[24:25], s[30:31] op_sel_hi:[1,0]
	v_pk_mul_f32 v[22:23], v[22:23], s[30:31] op_sel_hi:[1,0]
	v_pk_mul_f32 v[18:19], v[18:19], s[12:13] op_sel_hi:[1,0]
	v_pk_mul_f32 v[20:21], v[20:21], s[12:13] op_sel_hi:[1,0]
	v_pk_fma_f32 v[14:15], v[14:15], v[18:19], 0 op_sel_hi:[1,1,0]
	v_pk_fma_f32 v[16:17], v[16:17], v[20:21], 0 op_sel_hi:[1,1,0]
	v_pk_mul_f32 v[18:19], v[22:23], s[12:13] op_sel_hi:[1,0]
	v_pk_mul_f32 v[20:21], v[24:25], s[12:13] op_sel_hi:[1,0]
	s_nop 0
	v_pk_fma_f32 v[20:21], v[12:13], v[20:21], 0 op_sel_hi:[1,1,0]
	v_pk_fma_f32 v[12:13], v[10:11], v[18:19], 0 op_sel_hi:[1,1,0]
	v_cvt_pk_bf16_f32 v10, v14, v15
	v_lshlrev_b64 v[14:15], 12, v[68:69]
	v_lshl_add_u64 v[14:15], s[74:75], 0, v[14:15]
	v_cvt_pk_bf16_f32 v11, v16, v17
	v_cvt_pk_bf16_f32 v12, v12, v13
	v_cvt_pk_bf16_f32 v13, v20, v21
	v_lshl_add_u64 v[14:15], v[14:15], 0, v[122:123]
	global_store_dwordx4 v[14:15], v[10:13], off
	v_cvt_f32_ubyte1_e32 v17, v67
	v_cvt_f32_ubyte0_e32 v16, v67
	v_cvt_f32_ubyte1_e32 v11, v66
	v_cvt_f32_ubyte0_e32 v10, v66
	v_cvt_f32_ubyte3_e32 v13, v66
	v_cvt_f32_ubyte2_e32 v12, v66
	v_pk_mul_f32 v[12:13], v[12:13], s[30:31] op_sel_hi:[1,0]
	v_pk_mul_f32 v[10:11], v[10:11], s[30:31] op_sel_hi:[1,0]
	v_cvt_f32_ubyte3_e32 v19, v67
	v_cvt_f32_ubyte2_e32 v18, v67
	v_pk_mul_f32 v[18:19], v[18:19], s[30:31] op_sel_hi:[1,0]
	v_pk_mul_f32 v[16:17], v[16:17], s[30:31] op_sel_hi:[1,0]
	v_pk_mul_f32 v[10:11], v[10:11], s[12:13] op_sel_hi:[1,0]
	v_pk_mul_f32 v[12:13], v[12:13], s[12:13] op_sel_hi:[1,0]
	v_pk_fma_f32 v[6:7], v[6:7], v[10:11], 0 op_sel_hi:[1,1,0]
	v_pk_fma_f32 v[8:9], v[8:9], v[12:13], 0 op_sel_hi:[1,1,0]
	v_pk_mul_f32 v[10:11], v[16:17], s[12:13] op_sel_hi:[1,0]
	v_pk_mul_f32 v[12:13], v[18:19], s[12:13] op_sel_hi:[1,0]
	s_nop 0
	v_pk_fma_f32 v[12:13], v[4:5], v[12:13], 0 op_sel_hi:[1,1,0]
	v_pk_fma_f32 v[4:5], v[2:3], v[10:11], 0 op_sel_hi:[1,1,0]
	v_cvt_pk_bf16_f32 v2, v6, v7
	v_cvt_pk_bf16_f32 v3, v8, v9
	s_nop 0
	v_cvt_pk_bf16_f32 v4, v4, v5
	v_cvt_pk_bf16_f32 v5, v12, v13
	global_store_dwordx4 v[14:15], v[2:5], off offset:256
	s_cbranch_vccnz .LBB0_275
	v_readlane_b32 s0, v254, 60
	v_readlane_b32 s1, v254, 61
	s_andn2_b64 vcc, exec, s[0:1]
	s_cbranch_vccnz .LBB0_274
	s_barrier
	s_branch .LBB0_274

; __device__ __forceinline__ u32x4 pack8(f32x4 v0, f32x4 v1) { u32x4 w; w.x = cvt_pk_bf16(v0[0], v0[1]); w.y = cvt_pk_bf16(v0[2], v0[3]); w.z = cvt_pk_bf16(v1[0], v1[1]); w.w = cvt_pk_bf16(v1[2], v1[3]); return w; }
; __device__ __forceinline__ void unpack8(u32x4 w, f32x4& a, f32x4& b) { a = (f32x4){bf_lo(w.x), bf_hi(w.x), bf_lo(w.y), bf_hi(w.y)}; b = (f32x4){bf_lo(w.z), bf_hi(w.z), bf_lo(w.w), bf_hi(w.w)}; }
; template <class LT, class FL, class FP>
; __device__ __forceinline__ void epi_perm2(const f32x4 (&acc)[2][2][4][2], const Unit& u, int wr, int wc, int fr, int fq, const FL& loadf, const FP& procf) {
; #pragma unroll
;     for (int ai = 0; ai < 2; ++ai) {
;         LT L[4][2];
; #pragma unroll
;         for (int m = 0; m < 4; ++m)
; #pragma unroll
;             for (int bj = 0; bj < 2; ++bj) L[m][bj] = loadf(u.pm * BM + ai * HALF + wr * 64 + m * 16 + fr, u.pn * BM + bj * HALF + wc * 32 + 8 * fq);
; #pragma unroll
;         for (int m = 0; m < 4; ++m)
; #pragma unroll
;             for (int bj = 0; bj < 2; ++bj) procf(u.pm * BM + ai * HALF + wr * 64 + m * 16 + fr, u.pn * BM + bj * HALF + wc * 32 + 8 * fq, acc[ai][bj][m][0], acc[ai][bj][m][1], L[m][bj]);
;     }
; }
;     __device__ __forceinline__ void operator()(const f32x4 (&acc)[2][2][4][2], const Unit& u, int wr, int wc, int fr, int fq) const {
;         const unsigned char* gate_ = gate; bf16_t* mg_ = mg; const int first_ = first; const float as_ = ascale;
;         epi_perm2<LB>(acc, u, wr, wc, fr, fq,
;             [=](int row, int col) __attribute__((always_inline)) { LB L; L.g = *(const u32x2*)(gate_ + (size_t)row * (NP * 2) + col);
;                 L.m = first_ ? (u32x4){0u, 0u, 0u, 0u} : *(const u32x4*)(mg_ + (size_t)row * DM + col); return L; },
;             [=](int row, int col, f32x4 v0, f32x4 v1, const LB& L) __attribute__((always_inline)) {
;                 f32x4 g0, g1, p0, p1; gate_unpack8(L.g, g0, g1); unpack8(L.m, p0, p1);
;                 v0 = v0 * (g0 * as_) + p0; v1 = v1 * (g1 * as_) + p1;
;                 *(u32x4*)(mg_ + (size_t)row * DM + col) = pack8(v0, v1); });
;     }
.LBB0_313:
	v_mov_b32_e32 v130, v199
	v_mov_b64_e32 v[170:171], s[66:67]
	v_and_b32_e32 v131, 15, v130
	v_ashrrev_i32_e32 v132, 2, v130
	v_lshrrev_b32_e32 v130, 1, v130
	v_and_or_b32 v131, v132, s61, v131
	v_and_b32_e32 v130, 0x78, v130
	v_lshl_add_u32 v168, s49, 8, v131
	v_lshl_or_b32 v166, s48, 8, v130
	v_mad_i64_i32 v[130:131], s[34:35], v168, s31, v[170:171]
	v_ashrrev_i32_e32 v167, 31, v166
	v_ashrrev_i32_e32 v169, 31, v168
	v_lshl_add_u64 v[130:131], v[130:131], 0, v[166:167]
	v_lshlrev_b64 v[132:133], 12, v[168:169]
	global_load_dwordx2 v[202:203], v[130:131], off
	v_lshl_add_u64 v[132:133], s[74:75], 0, v[132:133]
	v_lshlrev_b64 v[172:173], 1, v[166:167]
	v_lshl_add_u64 v[190:191], v[132:133], 0, v[172:173]
	global_load_dwordx4 v[158:161], v[190:191], off
	global_load_dwordx2 v[200:201], v[130:131], off offset:128
	global_load_dwordx4 v[154:157], v[190:191], off offset:256
	v_or_b32_e32 v130, 16, v168
	v_mad_i64_i32 v[132:133], s[34:35], v130, s31, v[170:171]
	v_ashrrev_i32_e32 v131, 31, v130
	v_lshl_add_u64 v[132:133], v[132:133], 0, v[166:167]
	v_lshlrev_b64 v[130:131], 12, v[130:131]
	global_load_dwordx2 v[192:193], v[132:133], off
	v_lshl_add_u64 v[130:131], s[74:75], 0, v[130:131]
	v_lshl_add_u64 v[182:183], v[130:131], 0, v[172:173]
	global_load_dwordx4 v[150:153], v[182:183], off
	global_load_dwordx2 v[188:189], v[132:133], off offset:128
	global_load_dwordx4 v[146:149], v[182:183], off offset:256
	v_or_b32_e32 v130, 32, v168
	v_mad_i64_i32 v[132:133], s[34:35], v130, s31, v[170:171]
	v_ashrrev_i32_e32 v131, 31, v130
	v_lshl_add_u64 v[132:133], v[132:133], 0, v[166:167]
	v_lshlrev_b64 v[130:131], 12, v[130:131]
	global_load_dwordx2 v[184:185], v[132:133], off
	v_lshl_add_u64 v[130:131], s[74:75], 0, v[130:131]
	v_lshl_add_u64 v[174:175], v[130:131], 0, v[172:173]
	global_load_dwordx4 v[138:141], v[174:175], off
	global_load_dwordx2 v[178:179], v[132:133], off offset:128
	s_nop 0
	global_load_dwordx4 v[130:133], v[174:175], off offset:256
	v_or_b32_e32 v134, 48, v168
	v_mad_i64_i32 v[136:137], s[34:35], v134, s31, v[170:171]
	v_ashrrev_i32_e32 v135, 31, v134
	v_lshl_add_u64 v[136:137], v[136:137], 0, v[166:167]
	v_lshlrev_b64 v[134:135], 12, v[134:135]
	global_load_dwordx2 v[186:187], v[136:137], off
	v_lshl_add_u64 v[134:135], s[74:75], 0, v[134:135]
	v_lshl_add_u64 v[176:177], v[134:135], 0, v[172:173]
	global_load_dwordx4 v[142:145], v[176:177], off
	global_load_dwordx2 v[180:181], v[136:137], off offset:128
	s_nop 0
	global_load_dwordx4 v[134:137], v[176:177], off offset:256
	s_mov_b64 s[42:43], -1
	s_and_b64 vcc, exec, s[40:41]
	s_movk_i32 s60, 0xc00
	s_waitcnt vmcnt(0) lgkmcnt(0)
	v_cvt_f32_ubyte3_e32 v195, v202
	v_cvt_f32_ubyte2_e32 v194, v202
	v_cvt_f32_ubyte3_e32 v207, v203
	v_cvt_f32_ubyte2_e32 v206, v203
	v_cvt_f32_ubyte1_e32 v209, v203
	v_cvt_f32_ubyte0_e32 v208, v203
	v_cvt_f32_ubyte1_e32 v197, v202
	v_cvt_f32_ubyte0_e32 v196, v202
	v_pk_mul_f32 v[194:195], v[194:195], s[30:31] op_sel_hi:[1,0]
	v_pk_mul_f32 v[202:203], v[208:209], s[30:31] op_sel_hi:[1,0]
	v_pk_mul_f32 v[206:207], v[206:207], s[30:31] op_sel_hi:[1,0]
	v_lshlrev_b32_e32 v208, 16, v158
	v_and_b32_e32 v209, 0xffff0000, v158
	v_lshlrev_b32_e32 v158, 16, v159
	v_and_b32_e32 v159, 0xffff0000, v159
	v_lshlrev_b32_e32 v210, 16, v160
	v_and_b32_e32 v211, 0xffff0000, v160
	v_lshlrev_b32_e32 v160, 16, v161
	v_and_b32_e32 v161, 0xffff0000, v161
	v_pk_mul_f32 v[196:197], v[196:197], s[30:31] op_sel_hi:[1,0]
	v_pk_fma_f32 v[128:129], v[128:129], v[194:195], v[158:159]
	v_pk_fma_f32 v[158:159], v[124:125], v[206:207], v[160:161]
	v_pk_fma_f32 v[124:125], v[122:123], v[202:203], v[210:211]
	v_pk_fma_f32 v[126:127], v[126:127], v[196:197], v[208:209]
	v_lshlrev_b32_e32 v160, 16, v156
	v_cvt_pk_bf16_f32 v122, v126, v127
	v_cvt_pk_bf16_f32 v123, v128, v129
	v_cvt_pk_bf16_f32 v124, v124, v125
	v_cvt_pk_bf16_f32 v125, v158, v159
	global_store_dwordx4 v[190:191], v[122:125], off
	v_cvt_f32_ubyte3_e32 v127, v201
	v_cvt_f32_ubyte2_e32 v126, v201
	v_cvt_f32_ubyte3_e32 v123, v200
	v_cvt_f32_ubyte2_e32 v122, v200
	v_cvt_f32_ubyte1_e32 v125, v200
	v_cvt_f32_ubyte0_e32 v124, v200
	v_cvt_f32_ubyte1_e32 v129, v201
	v_cvt_f32_ubyte0_e32 v128, v201
	v_pk_mul_f32 v[124:125], v[124:125], s[30:31] op_sel_hi:[1,0]
	v_pk_mul_f32 v[122:123], v[122:123], s[30:31] op_sel_hi:[1,0]
	v_pk_mul_f32 v[128:129], v[128:129], s[30:31] op_sel_hi:[1,0]
	v_pk_mul_f32 v[126:127], v[126:127], s[30:31] op_sel_hi:[1,0]
	v_lshlrev_b32_e32 v158, 16, v154
	v_and_b32_e32 v159, 0xffff0000, v154
	v_lshlrev_b32_e32 v154, 16, v155
	v_and_b32_e32 v155, 0xffff0000, v155
	v_and_b32_e32 v161, 0xffff0000, v156
	v_lshlrev_b32_e32 v156, 16, v157
	v_and_b32_e32 v157, 0xffff0000, v157
	v_pk_fma_f32 v[120:121], v[120:121], v[122:123], v[154:155]
	v_pk_fma_f32 v[118:119], v[118:119], v[124:125], v[158:159]
	v_pk_fma_f32 v[122:123], v[116:117], v[126:127], v[156:157]
	v_pk_fma_f32 v[116:117], v[114:115], v[128:129], v[160:161]
	v_cvt_pk_bf16_f32 v114, v118, v119
	v_cvt_pk_bf16_f32 v115, v120, v121
	v_cvt_f32_ubyte3_e32 v119, v193
	v_cvt_pk_bf16_f32 v116, v116, v117
	v_cvt_pk_bf16_f32 v117, v122, v123
	global_store_dwordx4 v[190:191], v[114:117], off offset:256
	v_cvt_f32_ubyte2_e32 v118, v193
	v_cvt_f32_ubyte1_e32 v121, v193
	v_cvt_f32_ubyte3_e32 v115, v192
	v_cvt_f32_ubyte2_e32 v114, v192
	v_cvt_f32_ubyte0_e32 v120, v193
	v_cvt_f32_ubyte1_e32 v117, v192
	v_cvt_f32_ubyte0_e32 v116, v192
	v_pk_mul_f32 v[114:115], v[114:115], s[30:31] op_sel_hi:[1,0]
	v_pk_mul_f32 v[120:121], v[120:121], s[30:31] op_sel_hi:[1,0]
	v_pk_mul_f32 v[118:119], v[118:119], s[30:31] op_sel_hi:[1,0]
	v_lshlrev_b32_e32 v124, 16, v151
; __device__ __forceinline__ u32x4 pack8(f32x4 v0, f32x4 v1) { u32x4 w; w.x = cvt_pk_bf16(v0[0], v0[1]); w.y = cvt_pk_bf16(v0[2], v0[3]); w.z = cvt_pk_bf16(v1[0], v1[1]); w.w = cvt_pk_bf16(v1[2], v1[3]); return w; }
; __device__ __forceinline__ void unpack8(u32x4 w, f32x4& a, f32x4& b) { a = (f32x4){bf_lo(w.x), bf_hi(w.x), bf_lo(w.y), bf_hi(w.y)}; b = (f32x4){bf_lo(w.z), bf_hi(w.z), bf_lo(w.w), bf_hi(w.w)}; }
;     __device__ __forceinline__ void operator()(const f32x4 (&acc)[2][2][4][2], const Unit& u, int wr, int wc, int fr, int fq) const {
;         const unsigned char* gate_ = gate; bf16_t* mg_ = mg; const int first_ = first; const float as_ = ascale;
;         epi_perm2<LB>(acc, u, wr, wc, fr, fq,
;             [=](int row, int col) __attribute__((always_inline)) { LB L; L.g = *(const u32x2*)(gate_ + (size_t)row * (NP * 2) + col);
;                 L.m = first_ ? (u32x4){0u, 0u, 0u, 0u} : *(const u32x4*)(mg_ + (size_t)row * DM + col); return L; },
;             [=](int row, int col, f32x4 v0, f32x4 v1, const LB& L) __attribute__((always_inline)) {
;                 f32x4 g0, g1, p0, p1; gate_unpack8(L.g, g0, g1); unpack8(L.m, p0, p1);
;                 v0 = v0 * (g0 * as_) + p0; v1 = v1 * (g1 * as_) + p1;
;                 *(u32x4*)(mg_ + (size_t)row * DM + col) = pack8(v0, v1); });
;     }
	v_and_b32_e32 v125, 0xffff0000, v151
	v_lshlrev_b32_e32 v126, 16, v152
	v_and_b32_e32 v127, 0xffff0000, v152
	v_lshlrev_b32_e32 v128, 16, v153
	v_and_b32_e32 v129, 0xffff0000, v153
	v_pk_mul_f32 v[116:117], v[116:117], s[30:31] op_sel_hi:[1,0]
	v_lshlrev_b32_e32 v122, 16, v150
	v_and_b32_e32 v123, 0xffff0000, v150
	v_pk_fma_f32 v[112:113], v[112:113], v[114:115], v[124:125]
	v_pk_fma_f32 v[114:115], v[108:109], v[118:119], v[128:129]
	v_pk_fma_f32 v[108:109], v[106:107], v[120:121], v[126:127]
	v_pk_fma_f32 v[110:111], v[110:111], v[116:117], v[122:123]
	v_lshlrev_b32_e32 v116, 16, v147
	v_cvt_pk_bf16_f32 v106, v110, v111
	v_cvt_pk_bf16_f32 v107, v112, v113
	v_cvt_pk_bf16_f32 v108, v108, v109
	v_cvt_pk_bf16_f32 v109, v114, v115
	global_store_dwordx4 v[182:183], v[106:109], off
	v_cvt_f32_ubyte3_e32 v111, v189
	v_cvt_f32_ubyte2_e32 v110, v189
	v_cvt_f32_ubyte3_e32 v107, v188
	v_cvt_f32_ubyte2_e32 v106, v188
	v_cvt_f32_ubyte1_e32 v109, v188
	v_cvt_f32_ubyte0_e32 v108, v188
	v_cvt_f32_ubyte1_e32 v113, v189
	v_cvt_f32_ubyte0_e32 v112, v189
	v_pk_mul_f32 v[108:109], v[108:109], s[30:31] op_sel_hi:[1,0]
	v_pk_mul_f32 v[106:107], v[106:107], s[30:31] op_sel_hi:[1,0]
	v_pk_mul_f32 v[112:113], v[112:113], s[30:31] op_sel_hi:[1,0]
	v_pk_mul_f32 v[110:111], v[110:111], s[30:31] op_sel_hi:[1,0]
	v_lshlrev_b32_e32 v114, 16, v146
	v_and_b32_e32 v115, 0xffff0000, v146
	v_and_b32_e32 v117, 0xffff0000, v147
	v_lshlrev_b32_e32 v118, 16, v148
	v_and_b32_e32 v119, 0xffff0000, v148
	v_lshlrev_b32_e32 v120, 16, v149
	v_and_b32_e32 v121, 0xffff0000, v149
	v_pk_fma_f32 v[104:105], v[104:105], v[106:107], v[116:117]
	v_pk_fma_f32 v[102:103], v[102:103], v[108:109], v[114:115]
	v_pk_fma_f32 v[106:107], v[100:101], v[110:111], v[120:121]
	v_pk_fma_f32 v[100:101], v[98:99], v[112:113], v[118:119]
	v_cvt_pk_bf16_f32 v98, v102, v103
	v_cvt_pk_bf16_f32 v99, v104, v105
	v_cvt_f32_ubyte3_e32 v103, v185
	v_cvt_pk_bf16_f32 v100, v100, v101
	v_cvt_pk_bf16_f32 v101, v106, v107
	global_store_dwordx4 v[182:183], v[98:101], off offset:256
	v_cvt_f32_ubyte2_e32 v102, v185
	v_cvt_f32_ubyte1_e32 v105, v185
	v_cvt_f32_ubyte3_e32 v99, v184
	v_cvt_f32_ubyte2_e32 v98, v184
	v_cvt_f32_ubyte0_e32 v104, v185
	v_cvt_f32_ubyte1_e32 v101, v184
	v_cvt_f32_ubyte0_e32 v100, v184
	v_pk_mul_f32 v[98:99], v[98:99], s[30:31] op_sel_hi:[1,0]
	v_pk_mul_f32 v[104:105], v[104:105], s[30:31] op_sel_hi:[1,0]
	v_pk_mul_f32 v[102:103], v[102:103], s[30:31] op_sel_hi:[1,0]
	v_lshlrev_b32_e32 v108, 16, v139
	v_and_b32_e32 v109, 0xffff0000, v139
	v_lshlrev_b32_e32 v110, 16, v140
	v_and_b32_e32 v111, 0xffff0000, v140
	v_lshlrev_b32_e32 v112, 16, v141
	v_and_b32_e32 v113, 0xffff0000, v141
	v_pk_mul_f32 v[100:101], v[100:101], s[30:31] op_sel_hi:[1,0]
	v_lshlrev_b32_e32 v106, 16, v138
	v_and_b32_e32 v107, 0xffff0000, v138
	v_pk_fma_f32 v[96:97], v[96:97], v[98:99], v[108:109]
	v_pk_fma_f32 v[98:99], v[92:93], v[102:103], v[112:113]
	v_pk_fma_f32 v[92:93], v[90:91], v[104:105], v[110:111]
	v_pk_fma_f32 v[94:95], v[94:95], v[100:101], v[106:107]
	v_lshlrev_b32_e32 v100, 16, v131
	v_cvt_pk_bf16_f32 v90, v94, v95
	v_cvt_pk_bf16_f32 v91, v96, v97
	v_cvt_pk_bf16_f32 v92, v92, v93
	v_cvt_pk_bf16_f32 v93, v98, v99
	global_store_dwordx4 v[174:175], v[90:93], off
	v_cvt_f32_ubyte3_e32 v95, v179
	v_cvt_f32_ubyte2_e32 v94, v179
	v_cvt_f32_ubyte3_e32 v91, v178
	v_cvt_f32_ubyte2_e32 v90, v178
	v_cvt_f32_ubyte1_e32 v93, v178
	v_cvt_f32_ubyte0_e32 v92, v178
	v_cvt_f32_ubyte1_e32 v97, v179
	v_cvt_f32_ubyte0_e32 v96, v179
	v_pk_mul_f32 v[92:93], v[92:93], s[30:31] op_sel_hi:[1,0]
	v_pk_mul_f32 v[90:91], v[90:91], s[30:31] op_sel_hi:[1,0]
	v_pk_mul_f32 v[96:97], v[96:97], s[30:31] op_sel_hi:[1,0]
	v_pk_mul_f32 v[94:95], v[94:95], s[30:31] op_sel_hi:[1,0]
	v_lshlrev_b32_e32 v98, 16, v130
	v_and_b32_e32 v99, 0xffff0000, v130
	v_and_b32_e32 v101, 0xffff0000, v131
	v_lshlrev_b32_e32 v102, 16, v132
	v_and_b32_e32 v103, 0xffff0000, v132
	v_lshlrev_b32_e32 v104, 16, v133
	v_and_b32_e32 v105, 0xffff0000, v133
	v_pk_fma_f32 v[88:89], v[88:89], v[90:91], v[100:101]
	v_pk_fma_f32 v[86:87], v[86:87], v[92:93], v[98:99]
	v_pk_fma_f32 v[90:91], v[84:85], v[94:95], v[104:105]
	v_pk_fma_f32 v[84:85], v[82:83], v[96:97], v[102:103]
	v_cvt_pk_bf16_f32 v82, v86, v87
	v_cvt_pk_bf16_f32 v83, v88, v89
	v_cvt_f32_ubyte3_e32 v87, v187
	v_cvt_pk_bf16_f32 v84, v84, v85
	v_cvt_pk_bf16_f32 v85, v90, v91
	global_store_dwordx4 v[174:175], v[82:85], off offset:256
	v_cvt_f32_ubyte2_e32 v86, v187
	v_cvt_f32_ubyte1_e32 v89, v187
	v_cvt_f32_ubyte3_e32 v83, v186
	v_cvt_f32_ubyte2_e32 v82, v186
	v_cvt_f32_ubyte0_e32 v88, v187
	v_cvt_f32_ubyte1_e32 v85, v186
	v_cvt_f32_ubyte0_e32 v84, v186
	v_pk_mul_f32 v[82:83], v[82:83], s[30:31] op_sel_hi:[1,0]
	v_pk_mul_f32 v[88:89], v[88:89], s[30:31] op_sel_hi:[1,0]
	v_pk_mul_f32 v[86:87], v[86:87], s[30:31] op_sel_hi:[1,0]
	v_lshlrev_b32_e32 v92, 16, v143
	v_and_b32_e32 v93, 0xffff0000, v143
	v_lshlrev_b32_e32 v94, 16, v144
	v_and_b32_e32 v95, 0xffff0000, v144
	v_lshlrev_b32_e32 v96, 16, v145
	v_and_b32_e32 v97, 0xffff0000, v145
	v_pk_mul_f32 v[84:85], v[84:85], s[30:31] op_sel_hi:[1,0]
	v_lshlrev_b32_e32 v90, 16, v142
	v_and_b32_e32 v91, 0xffff0000, v142
	v_pk_fma_f32 v[80:81], v[80:81], v[82:83], v[92:93]
	v_pk_fma_f32 v[82:83], v[76:77], v[86:87], v[96:97]
	v_pk_fma_f32 v[76:77], v[74:75], v[88:89], v[94:95]
	v_pk_fma_f32 v[78:79], v[78:79], v[84:85], v[90:91]
	v_lshlrev_b32_e32 v84, 16, v135
	v_cvt_pk_bf16_f32 v74, v78, v79
	v_cvt_pk_bf16_f32 v75, v80, v81
	v_cvt_pk_bf16_f32 v76, v76, v77
	v_cvt_pk_bf16_f32 v77, v82, v83
	global_store_dwordx4 v[176:177], v[74:77], off
	v_cvt_f32_ubyte3_e32 v79, v181
	v_cvt_f32_ubyte2_e32 v78, v181
; __device__ __forceinline__ u32x4 pack8(f32x4 v0, f32x4 v1) { u32x4 w; w.x = cvt_pk_bf16(v0[0], v0[1]); w.y = cvt_pk_bf16(v0[2], v0[3]); w.z = cvt_pk_bf16(v1[0], v1[1]); w.w = cvt_pk_bf16(v1[2], v1[3]); return w; }
; __device__ __forceinline__ void unpack8(u32x4 w, f32x4& a, f32x4& b) { a = (f32x4){bf_lo(w.x), bf_hi(w.x), bf_lo(w.y), bf_hi(w.y)}; b = (f32x4){bf_lo(w.z), bf_hi(w.z), bf_lo(w.w), bf_hi(w.w)}; }
; template <class LT, class FL, class FP>
; __device__ __forceinline__ void epi_perm2(const f32x4 (&acc)[2][2][4][2], const Unit& u, int wr, int wc, int fr, int fq, const FL& loadf, const FP& procf) {
; #pragma unroll
;     for (int ai = 0; ai < 2; ++ai) {
;         LT L[4][2];
; #pragma unroll
;         for (int m = 0; m < 4; ++m)
; #pragma unroll
;             for (int bj = 0; bj < 2; ++bj) L[m][bj] = loadf(u.pm * BM + ai * HALF + wr * 64 + m * 16 + fr, u.pn * BM + bj * HALF + wc * 32 + 8 * fq);
; #pragma unroll
;         for (int m = 0; m < 4; ++m)
; #pragma unroll
;             for (int bj = 0; bj < 2; ++bj) procf(u.pm * BM + ai * HALF + wr * 64 + m * 16 + fr, u.pn * BM + bj * HALF + wc * 32 + 8 * fq, acc[ai][bj][m][0], acc[ai][bj][m][1], L[m][bj]);
;     }
; }
;     __device__ __forceinline__ void operator()(const f32x4 (&acc)[2][2][4][2], const Unit& u, int wr, int wc, int fr, int fq) const {
;         const unsigned char* gate_ = gate; bf16_t* mg_ = mg; const int first_ = first; const float as_ = ascale;
;         epi_perm2<LB>(acc, u, wr, wc, fr, fq,
;             [=](int row, int col) __attribute__((always_inline)) { LB L; L.g = *(const u32x2*)(gate_ + (size_t)row * (NP * 2) + col);
;                 L.m = first_ ? (u32x4){0u, 0u, 0u, 0u} : *(const u32x4*)(mg_ + (size_t)row * DM + col); return L; },
;             [=](int row, int col, f32x4 v0, f32x4 v1, const LB& L) __attribute__((always_inline)) {
;                 f32x4 g0, g1, p0, p1; gate_unpack8(L.g, g0, g1); unpack8(L.m, p0, p1);
;                 v0 = v0 * (g0 * as_) + p0; v1 = v1 * (g1 * as_) + p1;
;                 *(u32x4*)(mg_ + (size_t)row * DM + col) = pack8(v0, v1); });
;     }
	v_cvt_f32_ubyte3_e32 v75, v180
	v_cvt_f32_ubyte2_e32 v74, v180
	v_cvt_f32_ubyte1_e32 v77, v180
	v_cvt_f32_ubyte0_e32 v76, v180
	v_cvt_f32_ubyte1_e32 v81, v181
	v_cvt_f32_ubyte0_e32 v80, v181
	v_pk_mul_f32 v[76:77], v[76:77], s[30:31] op_sel_hi:[1,0]
	v_pk_mul_f32 v[74:75], v[74:75], s[30:31] op_sel_hi:[1,0]
	v_pk_mul_f32 v[80:81], v[80:81], s[30:31] op_sel_hi:[1,0]
	v_pk_mul_f32 v[78:79], v[78:79], s[30:31] op_sel_hi:[1,0]
	v_lshlrev_b32_e32 v82, 16, v134
	v_and_b32_e32 v83, 0xffff0000, v134
	v_and_b32_e32 v85, 0xffff0000, v135
	v_lshlrev_b32_e32 v86, 16, v136
	v_and_b32_e32 v87, 0xffff0000, v136
	v_lshlrev_b32_e32 v88, 16, v137
	v_and_b32_e32 v89, 0xffff0000, v137
	v_pk_fma_f32 v[72:73], v[72:73], v[74:75], v[84:85]
	v_pk_fma_f32 v[70:71], v[70:71], v[76:77], v[82:83]
	v_pk_fma_f32 v[74:75], v[68:69], v[78:79], v[88:89]
	v_pk_fma_f32 v[68:69], v[66:67], v[80:81], v[86:87]
	v_cvt_pk_bf16_f32 v66, v70, v71
	v_cvt_pk_bf16_f32 v67, v72, v73
	s_nop 0
	v_cvt_pk_bf16_f32 v68, v68, v69
	v_cvt_pk_bf16_f32 v69, v74, v75
	global_store_dwordx4 v[176:177], v[66:69], off offset:256
	s_nop 1
	v_add_u32_e32 v66, 0x80, v168
	v_mad_i64_i32 v[68:69], s[34:35], v66, s31, v[170:171]
	v_ashrrev_i32_e32 v67, 31, v66
	v_lshl_add_u64 v[68:69], v[68:69], 0, v[166:167]
	v_lshlrev_b64 v[66:67], 12, v[66:67]
	global_load_dwordx2 v[112:113], v[68:69], off
	v_lshl_add_u64 v[66:67], s[74:75], 0, v[66:67]
	v_lshl_add_u64 v[114:115], v[66:67], 0, v[172:173]
	global_load_dwordx4 v[100:103], v[114:115], off
	global_load_dwordx2 v[116:117], v[68:69], off offset:128
	global_load_dwordx4 v[104:107], v[114:115], off offset:256
	v_add_u32_e32 v66, 0x90, v168
	v_mad_i64_i32 v[68:69], s[34:35], v66, s31, v[170:171]
	v_ashrrev_i32_e32 v67, 31, v66
	v_lshl_add_u64 v[68:69], v[68:69], 0, v[166:167]
	v_lshlrev_b64 v[66:67], 12, v[66:67]
	global_load_dwordx2 v[118:119], v[68:69], off
	v_lshl_add_u64 v[66:67], s[74:75], 0, v[66:67]
	v_lshl_add_u64 v[96:97], v[66:67], 0, v[172:173]
	global_load_dwordx4 v[108:111], v[96:97], off
	global_load_dwordx2 v[120:121], v[68:69], off offset:128
	global_load_dwordx4 v[82:85], v[96:97], off offset:256
	v_add_u32_e32 v66, 0xa0, v168
	v_mad_i64_i32 v[68:69], s[34:35], v66, s31, v[170:171]
	v_ashrrev_i32_e32 v67, 31, v66
	v_lshl_add_u64 v[68:69], v[68:69], 0, v[166:167]
	v_lshlrev_b64 v[66:67], 12, v[66:67]
	global_load_dwordx2 v[98:99], v[68:69], off
	v_lshl_add_u64 v[66:67], s[74:75], 0, v[66:67]
	v_lshl_add_u64 v[90:91], v[66:67], 0, v[172:173]
	global_load_dwordx4 v[78:81], v[90:91], off
	global_load_dwordx2 v[94:95], v[68:69], off offset:128
	global_load_dwordx4 v[74:77], v[90:91], off offset:256
	v_add_u32_e32 v66, 0xb0, v168
	v_mad_i64_i32 v[68:69], s[34:35], v66, s31, v[170:171]
	v_ashrrev_i32_e32 v67, 31, v66
	v_lshl_add_u64 v[68:69], v[68:69], 0, v[166:167]
	v_lshlrev_b64 v[66:67], 12, v[66:67]
	global_load_dwordx2 v[92:93], v[68:69], off
	v_lshl_add_u64 v[66:67], s[74:75], 0, v[66:67]
	v_lshl_add_u64 v[86:87], v[66:67], 0, v[172:173]
	global_load_dwordx4 v[70:73], v[86:87], off
	global_load_dwordx2 v[88:89], v[68:69], off offset:128
	s_nop 0
	global_load_dwordx4 v[66:69], v[86:87], off offset:256
	s_waitcnt vmcnt(0) lgkmcnt(0)
	v_cvt_f32_ubyte3_e32 v123, v112
	v_cvt_f32_ubyte2_e32 v122, v112
	v_cvt_f32_ubyte1_e32 v125, v112
	v_cvt_f32_ubyte0_e32 v124, v112
	v_cvt_f32_ubyte3_e32 v127, v113
	v_cvt_f32_ubyte2_e32 v126, v113
	v_cvt_f32_ubyte1_e32 v129, v113
	v_cvt_f32_ubyte0_e32 v128, v113
	v_pk_mul_f32 v[124:125], v[124:125], s[30:31] op_sel_hi:[1,0]
	v_pk_mul_f32 v[122:123], v[122:123], s[30:31] op_sel_hi:[1,0]
	v_pk_mul_f32 v[112:113], v[128:129], s[30:31] op_sel_hi:[1,0]
	v_pk_mul_f32 v[126:127], v[126:127], s[30:31] op_sel_hi:[1,0]
	v_lshlrev_b32_e32 v128, 16, v100
	v_and_b32_e32 v129, 0xffff0000, v100
	v_lshlrev_b32_e32 v100, 16, v101
	v_and_b32_e32 v101, 0xffff0000, v101
	v_lshlrev_b32_e32 v130, 16, v102
	v_and_b32_e32 v131, 0xffff0000, v102
	v_lshlrev_b32_e32 v102, 16, v103
	v_and_b32_e32 v103, 0xffff0000, v103
	v_pk_fma_f32 v[64:65], v[64:65], v[122:123], v[100:101]
	v_pk_fma_f32 v[62:63], v[62:63], v[124:125], v[128:129]
	v_pk_fma_f32 v[100:101], v[60:61], v[126:127], v[102:103]
	v_pk_fma_f32 v[60:61], v[58:59], v[112:113], v[130:131]
	v_cvt_pk_bf16_f32 v58, v62, v63
	v_cvt_pk_bf16_f32 v59, v64, v65
	v_cvt_f32_ubyte3_e32 v63, v117
	v_cvt_pk_bf16_f32 v60, v60, v61
	v_cvt_pk_bf16_f32 v61, v100, v101
	global_store_dwordx4 v[114:115], v[58:61], off
	v_cvt_f32_ubyte2_e32 v62, v117
	v_cvt_f32_ubyte1_e32 v65, v117
	v_cvt_f32_ubyte3_e32 v59, v116
	v_cvt_f32_ubyte2_e32 v58, v116
	v_cvt_f32_ubyte0_e32 v64, v117
	v_cvt_f32_ubyte1_e32 v61, v116
	v_cvt_f32_ubyte0_e32 v60, v116
	v_pk_mul_f32 v[58:59], v[58:59], s[30:31] op_sel_hi:[1,0]
	v_pk_mul_f32 v[64:65], v[64:65], s[30:31] op_sel_hi:[1,0]
	v_pk_mul_f32 v[62:63], v[62:63], s[30:31] op_sel_hi:[1,0]
	v_lshlrev_b32_e32 v100, 16, v104
	v_and_b32_e32 v101, 0xffff0000, v104
	v_lshlrev_b32_e32 v102, 16, v105
	v_and_b32_e32 v103, 0xffff0000, v105
	v_lshlrev_b32_e32 v104, 16, v106
	v_and_b32_e32 v105, 0xffff0000, v106
	v_lshlrev_b32_e32 v106, 16, v107
	v_and_b32_e32 v107, 0xffff0000, v107
	v_pk_mul_f32 v[60:61], v[60:61], s[30:31] op_sel_hi:[1,0]
	v_pk_fma_f32 v[56:57], v[56:57], v[58:59], v[102:103]
	v_pk_fma_f32 v[58:59], v[52:53], v[62:63], v[106:107]
	v_pk_fma_f32 v[52:53], v[50:51], v[64:65], v[104:105]
	v_pk_fma_f32 v[54:55], v[54:55], v[60:61], v[100:101]
	v_lshlrev_b32_e32 v60, 16, v109
	v_cvt_pk_bf16_f32 v50, v54, v55
	v_cvt_pk_bf16_f32 v51, v56, v57
	v_cvt_pk_bf16_f32 v52, v52, v53
	v_cvt_pk_bf16_f32 v53, v58, v59
	global_store_dwordx4 v[114:115], v[50:53], off offset:256
; __device__ __forceinline__ int otid() { int t = threadIdx.x; asm volatile("" : "+v"(t)); return t; }
; #define PG8_BAR __builtin_amdgcn_s_barrier()
; __device__ __forceinline__ u32x4 pack8(f32x4 v0, f32x4 v1) { u32x4 w; w.x = cvt_pk_bf16(v0[0], v0[1]); w.y = cvt_pk_bf16(v0[2], v0[3]); w.z = cvt_pk_bf16(v1[0], v1[1]); w.w = cvt_pk_bf16(v1[2], v1[3]); return w; }
; __device__ __forceinline__ void unpack8(u32x4 w, f32x4& a, f32x4& b) { a = (f32x4){bf_lo(w.x), bf_hi(w.x), bf_lo(w.y), bf_hi(w.y)}; b = (f32x4){bf_lo(w.z), bf_hi(w.z), bf_lo(w.w), bf_hi(w.w)}; }
;     ...
;         if (wr == 0) PG8_BAR;
;         { const int t2_ = otid(), w2_ = t2_ >> 6, l2_ = t2_ & 63; E(acc, cur, w2_ >> 2, w2_ & 3, l2_ & 15, l2_ >> 4); }
;         if (!has_next) break;
; #pragma unroll
;         for (int a = 0; a < 2; ++a)
; #pragma unroll
;             for (int b = 0; b < 2; ++b)
; #pragma unroll
;                 for (int m = 0; m < 4; ++m)
; #pragma unroll
;                     for (int n = 0; n < 2; ++n) acc[a][b][m][n] = (f32x4){0.f, 0.f, 0.f, 0.f};
;         cur = nxt; cA = nA; cB = nB; ++ui;
;         if (wr == 1) PG8_BAR;
;     }
;     __device__ __forceinline__ void operator()(const f32x4 (&acc)[2][2][4][2], const Unit& u, int wr, int wc, int fr, int fq) const {
;         const unsigned char* gate_ = gate; bf16_t* mg_ = mg; const int first_ = first; const float as_ = ascale;
;         epi_perm2<LB>(acc, u, wr, wc, fr, fq,
;             [=](int row, int col) __attribute__((always_inline)) { LB L; L.g = *(const u32x2*)(gate_ + (size_t)row * (NP * 2) + col);
;                 L.m = first_ ? (u32x4){0u, 0u, 0u, 0u} : *(const u32x4*)(mg_ + (size_t)row * DM + col); return L; },
;             [=](int row, int col, f32x4 v0, f32x4 v1, const LB& L) __attribute__((always_inline)) {
;                 f32x4 g0, g1, p0, p1; gate_unpack8(L.g, g0, g1); unpack8(L.m, p0, p1);
;                 v0 = v0 * (g0 * as_) + p0; v1 = v1 * (g1 * as_) + p1;
;                 *(u32x4*)(mg_ + (size_t)row * DM + col) = pack8(v0, v1); });
;     }
	v_cvt_f32_ubyte3_e32 v55, v119
	v_cvt_f32_ubyte2_e32 v54, v119
	v_cvt_f32_ubyte3_e32 v51, v118
	v_cvt_f32_ubyte2_e32 v50, v118
	v_cvt_f32_ubyte1_e32 v53, v118
	v_cvt_f32_ubyte0_e32 v52, v118
	v_cvt_f32_ubyte1_e32 v57, v119
	v_cvt_f32_ubyte0_e32 v56, v119
	v_pk_mul_f32 v[52:53], v[52:53], s[30:31] op_sel_hi:[1,0]
	v_pk_mul_f32 v[50:51], v[50:51], s[30:31] op_sel_hi:[1,0]
	v_pk_mul_f32 v[56:57], v[56:57], s[30:31] op_sel_hi:[1,0]
	v_pk_mul_f32 v[54:55], v[54:55], s[30:31] op_sel_hi:[1,0]
	v_lshlrev_b32_e32 v58, 16, v108
	v_and_b32_e32 v59, 0xffff0000, v108
	v_and_b32_e32 v61, 0xffff0000, v109
	v_lshlrev_b32_e32 v62, 16, v110
	v_and_b32_e32 v63, 0xffff0000, v110
	v_lshlrev_b32_e32 v64, 16, v111
	v_and_b32_e32 v65, 0xffff0000, v111
	v_pk_fma_f32 v[48:49], v[48:49], v[50:51], v[60:61]
	v_pk_fma_f32 v[46:47], v[46:47], v[52:53], v[58:59]
	v_pk_fma_f32 v[50:51], v[44:45], v[54:55], v[64:65]
	v_pk_fma_f32 v[44:45], v[42:43], v[56:57], v[62:63]
	v_cvt_pk_bf16_f32 v42, v46, v47
	v_cvt_pk_bf16_f32 v43, v48, v49
	v_cvt_f32_ubyte3_e32 v47, v121
	v_cvt_pk_bf16_f32 v44, v44, v45
	v_cvt_pk_bf16_f32 v45, v50, v51
	global_store_dwordx4 v[96:97], v[42:45], off
	v_cvt_f32_ubyte2_e32 v46, v121
	v_cvt_f32_ubyte1_e32 v49, v121
	v_cvt_f32_ubyte3_e32 v43, v120
	v_cvt_f32_ubyte2_e32 v42, v120
	v_cvt_f32_ubyte0_e32 v48, v121
	v_cvt_f32_ubyte1_e32 v45, v120
	v_cvt_f32_ubyte0_e32 v44, v120
	v_pk_mul_f32 v[42:43], v[42:43], s[30:31] op_sel_hi:[1,0]
	v_pk_mul_f32 v[48:49], v[48:49], s[30:31] op_sel_hi:[1,0]
	v_pk_mul_f32 v[46:47], v[46:47], s[30:31] op_sel_hi:[1,0]
	v_lshlrev_b32_e32 v52, 16, v83
	v_and_b32_e32 v53, 0xffff0000, v83
	v_lshlrev_b32_e32 v54, 16, v84
	v_and_b32_e32 v55, 0xffff0000, v84
	v_lshlrev_b32_e32 v56, 16, v85
	v_and_b32_e32 v57, 0xffff0000, v85
	v_pk_mul_f32 v[44:45], v[44:45], s[30:31] op_sel_hi:[1,0]
	v_lshlrev_b32_e32 v50, 16, v82
	v_and_b32_e32 v51, 0xffff0000, v82
	v_pk_fma_f32 v[40:41], v[40:41], v[42:43], v[52:53]
	v_pk_fma_f32 v[42:43], v[36:37], v[46:47], v[56:57]
	v_pk_fma_f32 v[36:37], v[34:35], v[48:49], v[54:55]
	v_pk_fma_f32 v[38:39], v[38:39], v[44:45], v[50:51]
	v_lshlrev_b32_e32 v44, 16, v79
	v_cvt_pk_bf16_f32 v34, v38, v39
	v_cvt_pk_bf16_f32 v35, v40, v41
	v_cvt_pk_bf16_f32 v36, v36, v37
	v_cvt_pk_bf16_f32 v37, v42, v43
	global_store_dwordx4 v[96:97], v[34:37], off offset:256
	v_cvt_f32_ubyte3_e32 v39, v99
	v_cvt_f32_ubyte2_e32 v38, v99
	v_cvt_f32_ubyte3_e32 v35, v98
	v_cvt_f32_ubyte2_e32 v34, v98
	v_cvt_f32_ubyte1_e32 v37, v98
	v_cvt_f32_ubyte0_e32 v36, v98
	v_cvt_f32_ubyte1_e32 v41, v99
	v_cvt_f32_ubyte0_e32 v40, v99
	v_pk_mul_f32 v[36:37], v[36:37], s[30:31] op_sel_hi:[1,0]
	v_pk_mul_f32 v[34:35], v[34:35], s[30:31] op_sel_hi:[1,0]
	v_pk_mul_f32 v[40:41], v[40:41], s[30:31] op_sel_hi:[1,0]
	v_pk_mul_f32 v[38:39], v[38:39], s[30:31] op_sel_hi:[1,0]
	v_lshlrev_b32_e32 v42, 16, v78
	v_and_b32_e32 v43, 0xffff0000, v78
	v_and_b32_e32 v45, 0xffff0000, v79
	v_lshlrev_b32_e32 v46, 16, v80
	v_and_b32_e32 v47, 0xffff0000, v80
	v_lshlrev_b32_e32 v48, 16, v81
	v_and_b32_e32 v49, 0xffff0000, v81
	v_pk_fma_f32 v[32:33], v[32:33], v[34:35], v[44:45]
	v_pk_fma_f32 v[30:31], v[30:31], v[36:37], v[42:43]
	v_pk_fma_f32 v[34:35], v[28:29], v[38:39], v[48:49]
	v_pk_fma_f32 v[28:29], v[26:27], v[40:41], v[46:47]
	v_cvt_pk_bf16_f32 v26, v30, v31
	v_cvt_pk_bf16_f32 v27, v32, v33
	v_cvt_f32_ubyte3_e32 v31, v95
	v_cvt_pk_bf16_f32 v28, v28, v29
	v_cvt_pk_bf16_f32 v29, v34, v35
	global_store_dwordx4 v[90:91], v[26:29], off
	v_cvt_f32_ubyte2_e32 v30, v95
	v_cvt_f32_ubyte1_e32 v33, v95
	v_cvt_f32_ubyte3_e32 v27, v94
	v_cvt_f32_ubyte2_e32 v26, v94
	v_cvt_f32_ubyte0_e32 v32, v95
	v_cvt_f32_ubyte1_e32 v29, v94
	v_cvt_f32_ubyte0_e32 v28, v94
	v_pk_mul_f32 v[26:27], v[26:27], s[30:31] op_sel_hi:[1,0]
	v_pk_mul_f32 v[32:33], v[32:33], s[30:31] op_sel_hi:[1,0]
	v_pk_mul_f32 v[30:31], v[30:31], s[30:31] op_sel_hi:[1,0]
	v_lshlrev_b32_e32 v36, 16, v75
	v_and_b32_e32 v37, 0xffff0000, v75
	v_lshlrev_b32_e32 v38, 16, v76
	v_and_b32_e32 v39, 0xffff0000, v76
	v_lshlrev_b32_e32 v40, 16, v77
	v_and_b32_e32 v41, 0xffff0000, v77
	v_pk_mul_f32 v[28:29], v[28:29], s[30:31] op_sel_hi:[1,0]
	v_lshlrev_b32_e32 v34, 16, v74
	v_and_b32_e32 v35, 0xffff0000, v74
	v_pk_fma_f32 v[24:25], v[24:25], v[26:27], v[36:37]
	v_pk_fma_f32 v[26:27], v[20:21], v[30:31], v[40:41]
	v_pk_fma_f32 v[20:21], v[18:19], v[32:33], v[38:39]
	v_pk_fma_f32 v[22:23], v[22:23], v[28:29], v[34:35]
	v_lshlrev_b32_e32 v28, 16, v71
	v_cvt_pk_bf16_f32 v18, v22, v23
	v_cvt_pk_bf16_f32 v19, v24, v25
	v_cvt_pk_bf16_f32 v20, v20, v21
	v_cvt_pk_bf16_f32 v21, v26, v27
	global_store_dwordx4 v[90:91], v[18:21], off offset:256
	v_cvt_f32_ubyte3_e32 v23, v93
	v_cvt_f32_ubyte2_e32 v22, v93
	v_cvt_f32_ubyte3_e32 v19, v92
	v_cvt_f32_ubyte2_e32 v18, v92
	v_cvt_f32_ubyte1_e32 v21, v92
	v_cvt_f32_ubyte0_e32 v20, v92
	v_cvt_f32_ubyte1_e32 v25, v93
	v_cvt_f32_ubyte0_e32 v24, v93
	v_pk_mul_f32 v[20:21], v[20:21], s[30:31] op_sel_hi:[1,0]
	v_pk_mul_f32 v[18:19], v[18:19], s[30:31] op_sel_hi:[1,0]
	v_pk_mul_f32 v[24:25], v[24:25], s[30:31] op_sel_hi:[1,0]
	v_pk_mul_f32 v[22:23], v[22:23], s[30:31] op_sel_hi:[1,0]
	v_lshlrev_b32_e32 v26, 16, v70
	v_and_b32_e32 v27, 0xffff0000, v70
	v_and_b32_e32 v29, 0xffff0000, v71
	v_lshlrev_b32_e32 v30, 16, v72
	v_and_b32_e32 v31, 0xffff0000, v72
	v_lshlrev_b32_e32 v32, 16, v73
	v_and_b32_e32 v33, 0xffff0000, v73
	v_pk_fma_f32 v[16:17], v[16:17], v[18:19], v[28:29]
	v_pk_fma_f32 v[14:15], v[14:15], v[20:21], v[26:27]
	v_pk_fma_f32 v[18:19], v[12:13], v[22:23], v[32:33]
	v_pk_fma_f32 v[12:13], v[10:11], v[24:25], v[30:31]
	v_cvt_pk_bf16_f32 v10, v14, v15
	v_cvt_pk_bf16_f32 v11, v16, v17
	v_cvt_f32_ubyte3_e32 v15, v89
	v_cvt_pk_bf16_f32 v12, v12, v13
	v_cvt_pk_bf16_f32 v13, v18, v19
	global_store_dwordx4 v[86:87], v[10:13], off
	v_cvt_f32_ubyte2_e32 v14, v89
	v_cvt_f32_ubyte1_e32 v17, v89
	v_cvt_f32_ubyte3_e32 v11, v88
	v_cvt_f32_ubyte2_e32 v10, v88
	v_cvt_f32_ubyte0_e32 v16, v89
	v_cvt_f32_ubyte1_e32 v13, v88
	v_cvt_f32_ubyte0_e32 v12, v88
	v_pk_mul_f32 v[10:11], v[10:11], s[30:31] op_sel_hi:[1,0]
	v_pk_mul_f32 v[16:17], v[16:17], s[30:31] op_sel_hi:[1,0]
	v_pk_mul_f32 v[14:15], v[14:15], s[30:31] op_sel_hi:[1,0]
	v_lshlrev_b32_e32 v20, 16, v67
	v_and_b32_e32 v21, 0xffff0000, v67
	v_lshlrev_b32_e32 v22, 16, v68
	v_and_b32_e32 v23, 0xffff0000, v68
	v_lshlrev_b32_e32 v24, 16, v69
	v_and_b32_e32 v25, 0xffff0000, v69
	v_pk_mul_f32 v[12:13], v[12:13], s[30:31] op_sel_hi:[1,0]
	v_lshlrev_b32_e32 v18, 16, v66
	v_and_b32_e32 v19, 0xffff0000, v66
	v_pk_fma_f32 v[8:9], v[8:9], v[10:11], v[20:21]
	v_pk_fma_f32 v[10:11], v[4:5], v[14:15], v[24:25]
	v_pk_fma_f32 v[4:5], v[2:3], v[16:17], v[22:23]
	v_pk_fma_f32 v[6:7], v[6:7], v[12:13], v[18:19]
	s_nop 0
	v_cvt_pk_bf16_f32 v2, v6, v7
	v_cvt_pk_bf16_f32 v3, v8, v9
	v_cvt_pk_bf16_f32 v4, v4, v5
	v_cvt_pk_bf16_f32 v5, v10, v11
	global_store_dwordx4 v[86:87], v[2:5], off offset:256
	s_cbranch_vccnz .LBB0_300
	s_andn2_b64 vcc, exec, s[64:65]
	s_cbranch_vccnz .LBB0_299
	s_barrier
	s_branch .LBB0_299

; __device__ __forceinline__ u32x4 pack8(f32x4 v0, f32x4 v1) { u32x4 w; w.x = cvt_pk_bf16(v0[0], v0[1]); w.y = cvt_pk_bf16(v0[2], v0[3]); w.z = cvt_pk_bf16(v1[0], v1[1]); w.w = cvt_pk_bf16(v1[2], v1[3]); return w; }
;     __device__ __forceinline__ void operator()(const f32x4 (&acc)[2][2][4][2], const Unit& u, int wr, int wc, int fr, int fq) const {
;     ...
;         epi_perm2<LQ>(acc, u, wr, wc, fr, fq,
;             [=](int row, int col) __attribute__((always_inline)) { LQ L; L.rs = stat_[row * 2 + 0]; const int d = col % 192;
;                 if (d >= 128) { const int i0 = ((d - 128) >> 3) * 4; L.c = *(const f32x4*)(cs_ + (size_t)row * 32 + i0); L.s = *(const f32x4*)(sn_ + (size_t)row * 32 + i0); }
;                 else { L.c = (f32x4){1.f, 1.f, 1.f, 1.f}; L.s = (f32x4){0.f, 0.f, 0.f, 0.f}; } return L; },
;             [=](int row, int col, f32x4 v0, f32x4 v1, const LQ& L) __attribute__((always_inline)) {
;                 v0 = v0 * L.rs; v1 = v1 * L.rs; const int d = col % 192;
;                 if (d >= 128) { const f32x4 o1 = v0 * L.c - v1 * L.s; const f32x4 o2 = v1 * L.c + v0 * L.s; v0 = o1; v1 = o2; }
;                 *(u32x4*)(Q_ + (size_t)row * QW + col) = pack8(v0, v1); });
.LBB0_383:
	v_mov_b32_e32 v0, v199
	s_lshl_b32 s1, s1, 8
	v_and_b32_e32 v130, 15, v0
	v_ashrrev_i32_e32 v131, 2, v0
	v_and_or_b32 v130, v131, s61, v130
	v_add_u32_e32 v206, s1, v130
	v_lshlrev_b32_e32 v130, 1, v206
	v_ashrrev_i32_e32 v131, 31, v130
	v_lshl_add_u64 v[130:131], v[130:131], 2, s[12:13]
	global_load_dword v208, v[130:131], off
	v_lshrrev_b32_e32 v0, 1, v0
	v_and_b32_e32 v0, 0x78, v0
	v_lshl_or_b32 v210, s86, 8, v0
	v_ashrrev_i32_e32 v207, 31, v206
	s_mov_b32 s1, 0x2aaaaaab
	v_lshlrev_b64 v[130:131], 7, v[206:207]
	v_mul_hi_i32 v0, v210, s1
	v_lshl_add_u64 v[138:139], s[50:51], 0, v[130:131]
	v_lshl_add_u64 v[140:141], s[64:65], 0, v[130:131]
	v_lshrrev_b32_e32 v130, 31, v0
	v_lshrrev_b32_e32 v0, 5, v0
	v_add_u32_e32 v0, v0, v130
	s_movk_i32 s1, 0xc0
	v_mul_lo_u32 v0, v0, s1
	v_sub_u32_e32 v207, v210, v0
	s_movk_i32 s1, 0x7f
	v_cmp_lt_i32_e32 vcc, s1, v207
	v_mov_b32_e32 v134, 0
	v_mov_b32_e32 v130, 1.0
	v_mov_b32_e32 v146, 1.0
	v_mov_b32_e32 v147, 1.0
	v_mov_b32_e32 v148, 1.0
	v_mov_b32_e32 v149, 1.0
	v_mov_b32_e32 v150, 0
	v_mov_b32_e32 v151, 0
	v_mov_b32_e32 v152, 0
	v_mov_b32_e32 v153, 0
	s_and_saveexec_b64 s[42:43], vcc
	v_readlane_b32 s74, v253, 24
	s_mov_b64 s[76:77], 0x2ea60000
	v_readlane_b32 s75, v253, 25
	s_cbranch_execz .LBB0_385
	v_add_u32_e32 v0, 0xffffff80, v207
	v_lshrrev_b32_e32 v0, 1, v0
	v_lshlrev_b64 v[132:133], 2, v[0:1]
	v_lshl_add_u64 v[136:137], v[140:141], 0, v[132:133]
	v_lshl_add_u64 v[132:133], v[138:139], 0, v[132:133]
	global_load_dwordx4 v[146:149], v[132:133], off
	global_load_dwordx4 v[150:153], v[136:137], off
.LBB0_385:
	s_or_b64 exec, exec, s[42:43]
	v_or_b32_e32 v0, 0x80, v210
	s_mov_b32 s1, 0x2aaaaaab
	v_mul_hi_i32 v131, v0, s1
	v_lshrrev_b32_e32 v132, 31, v131
	v_lshrrev_b32_e32 v131, 5, v131
	v_add_u32_e32 v131, v131, v132
	s_movk_i32 s1, 0xc0
	v_mul_lo_u32 v131, v131, s1
	v_sub_u32_e32 v215, v0, v131
	s_movk_i32 s1, 0x7f
	v_cmp_lt_i32_e64 s[42:43], s1, v215
	v_mov_b32_e32 v131, 1.0
	v_mov_b32_e32 v132, 1.0
	v_mov_b32_e32 v133, 1.0
	v_mov_b32_e32 v135, 0
	v_mov_b32_e32 v136, 0
	v_mov_b32_e32 v137, 0
	s_and_saveexec_b64 s[86:87], s[42:43]
	s_cbranch_execz .LBB0_387
	v_add_u32_e32 v0, 0xffffff80, v215
	v_lshrrev_b32_e32 v0, 1, v0
	v_and_b32_e32 v0, 0x7ffffffc, v0
	v_lshlrev_b64 v[130:131], 2, v[0:1]
	v_lshl_add_u64 v[134:135], v[140:141], 0, v[130:131]
	v_lshl_add_u64 v[130:131], v[138:139], 0, v[130:131]
	global_load_dwordx4 v[130:133], v[130:131], off
	s_nop 0
	global_load_dwordx4 v[134:137], v[134:135], off
.LBB0_387:
	s_or_b64 exec, exec, s[86:87]
	v_or_b32_e32 v138, 16, v206
	v_lshlrev_b32_e32 v140, 1, v138
	v_ashrrev_i32_e32 v141, 31, v140
	v_lshl_add_u64 v[140:141], v[140:141], 2, s[12:13]
	global_load_dword v212, v[140:141], off
	v_ashrrev_i32_e32 v139, 31, v138
	v_lshlrev_b64 v[138:139], 7, v[138:139]
	v_lshl_add_u64 v[154:155], s[50:51], 0, v[138:139]
	v_lshl_add_u64 v[156:157], s[64:65], 0, v[138:139]
	v_mov_b32_e32 v142, 0
	v_mov_b32_e32 v138, 1.0
	v_mov_b32_e32 v162, 1.0
	v_mov_b32_e32 v163, 1.0
	v_mov_b32_e32 v164, 1.0
	v_mov_b32_e32 v165, 1.0
	v_mov_b32_e32 v166, 0
	v_mov_b32_e32 v167, 0
	v_mov_b32_e32 v168, 0
	v_mov_b32_e32 v169, 0
	s_and_saveexec_b64 s[86:87], vcc
	s_cbranch_execz .LBB0_389
	v_add_u32_e32 v0, 0xffffff80, v207
	v_lshrrev_b32_e32 v0, 1, v0
	v_lshlrev_b64 v[140:141], 2, v[0:1]
	v_lshl_add_u64 v[144:145], v[156:157], 0, v[140:141]
	v_lshl_add_u64 v[140:141], v[154:155], 0, v[140:141]
	global_load_dwordx4 v[162:165], v[140:141], off
	global_load_dwordx4 v[166:169], v[144:145], off
.LBB0_389:
	s_or_b64 exec, exec, s[86:87]
	v_mov_b32_e32 v139, 1.0
	v_mov_b32_e32 v140, 1.0
	v_mov_b32_e32 v141, 1.0
	v_mov_b32_e32 v143, 0
	v_mov_b32_e32 v144, 0
	v_mov_b32_e32 v145, 0
	s_and_saveexec_b64 s[86:87], s[42:43]
	s_cbranch_execz .LBB0_391
	v_add_u32_e32 v0, 0xffffff80, v215
	v_lshrrev_b32_e32 v0, 1, v0
	v_and_b32_e32 v0, 0x7ffffffc, v0
	v_lshlrev_b64 v[138:139], 2, v[0:1]
	v_lshl_add_u64 v[142:143], v[156:157], 0, v[138:139]
	v_lshl_add_u64 v[138:139], v[154:155], 0, v[138:139]
	global_load_dwordx4 v[138:141], v[138:139], off
	s_nop 0
	global_load_dwordx4 v[142:145], v[142:143], off
.LBB0_391:
	s_or_b64 exec, exec, s[86:87]
	v_or_b32_e32 v154, 32, v206
	v_lshlrev_b32_e32 v156, 1, v154
	v_ashrrev_i32_e32 v157, 31, v156
	v_lshl_add_u64 v[156:157], v[156:157], 2, s[12:13]
	global_load_dword v214, v[156:157], off
	v_ashrrev_i32_e32 v155, 31, v154
	v_lshlrev_b64 v[154:155], 7, v[154:155]
	v_lshl_add_u64 v[170:171], s[50:51], 0, v[154:155]
	v_lshl_add_u64 v[172:173], s[64:65], 0, v[154:155]
	v_mov_b32_e32 v158, 0
	v_mov_b32_e32 v154, 1.0
	v_mov_b32_e32 v178, 1.0
	v_mov_b32_e32 v179, 1.0
	v_mov_b32_e32 v180, 1.0
	v_mov_b32_e32 v181, 1.0
	v_mov_b32_e32 v182, 0
	v_mov_b32_e32 v183, 0
	v_mov_b32_e32 v184, 0
	v_mov_b32_e32 v185, 0
	s_and_saveexec_b64 s[86:87], vcc
	s_cbranch_execz .LBB0_393
	v_add_u32_e32 v0, 0xffffff80, v207
	v_lshrrev_b32_e32 v0, 1, v0
	v_lshlrev_b64 v[156:157], 2, v[0:1]
	v_lshl_add_u64 v[160:161], v[172:173], 0, v[156:157]
	v_lshl_add_u64 v[156:157], v[170:171], 0, v[156:157]
	global_load_dwordx4 v[178:181], v[156:157], off
	global_load_dwordx4 v[182:185], v[160:161], off
.LBB0_393:
	s_or_b64 exec, exec, s[86:87]
	v_mov_b32_e32 v155, 1.0
	v_mov_b32_e32 v156, 1.0
	v_mov_b32_e32 v157, 1.0
	v_mov_b32_e32 v159, 0
	v_mov_b32_e32 v160, 0
	v_mov_b32_e32 v161, 0
	s_and_saveexec_b64 s[86:87], s[42:43]
	s_cbranch_execz .LBB0_395
	v_add_u32_e32 v0, 0xffffff80, v215
	v_lshrrev_b32_e32 v0, 1, v0
	v_and_b32_e32 v0, 0x7ffffffc, v0
	v_lshlrev_b64 v[154:155], 2, v[0:1]
	v_lshl_add_u64 v[158:159], v[172:173], 0, v[154:155]
	v_lshl_add_u64 v[154:155], v[170:171], 0, v[154:155]
	global_load_dwordx4 v[154:157], v[154:155], off
	s_nop 0
	global_load_dwordx4 v[158:161], v[158:159], off
; __device__ __forceinline__ u32x4 pack8(f32x4 v0, f32x4 v1) { u32x4 w; w.x = cvt_pk_bf16(v0[0], v0[1]); w.y = cvt_pk_bf16(v0[2], v0[3]); w.z = cvt_pk_bf16(v1[0], v1[1]); w.w = cvt_pk_bf16(v1[2], v1[3]); return w; }
;     __device__ __forceinline__ void operator()(const f32x4 (&acc)[2][2][4][2], const Unit& u, int wr, int wc, int fr, int fq) const {
;     ...
;         epi_perm2<LQ>(acc, u, wr, wc, fr, fq,
;             [=](int row, int col) __attribute__((always_inline)) { LQ L; L.rs = stat_[row * 2 + 0]; const int d = col % 192;
;                 if (d >= 128) { const int i0 = ((d - 128) >> 3) * 4; L.c = *(const f32x4*)(cs_ + (size_t)row * 32 + i0); L.s = *(const f32x4*)(sn_ + (size_t)row * 32 + i0); }
;                 else { L.c = (f32x4){1.f, 1.f, 1.f, 1.f}; L.s = (f32x4){0.f, 0.f, 0.f, 0.f}; } return L; },
;             [=](int row, int col, f32x4 v0, f32x4 v1, const LQ& L) __attribute__((always_inline)) {
;                 v0 = v0 * L.rs; v1 = v1 * L.rs; const int d = col % 192;
;                 if (d >= 128) { const f32x4 o1 = v0 * L.c - v1 * L.s; const f32x4 o2 = v1 * L.c + v0 * L.s; v0 = o1; v1 = o2; }
;                 *(u32x4*)(Q_ + (size_t)row * QW + col) = pack8(v0, v1); });
.LBB0_395:
	s_or_b64 exec, exec, s[86:87]
	v_or_b32_e32 v170, 48, v206
	v_lshlrev_b32_e32 v172, 1, v170
	v_ashrrev_i32_e32 v173, 31, v172
	v_lshl_add_u64 v[172:173], v[172:173], 2, s[12:13]
	global_load_dword v216, v[172:173], off
	v_ashrrev_i32_e32 v171, 31, v170
	v_lshlrev_b64 v[170:171], 7, v[170:171]
	v_lshl_add_u64 v[218:219], s[50:51], 0, v[170:171]
	v_lshl_add_u64 v[220:221], s[64:65], 0, v[170:171]
	v_mov_b32_e32 v174, 0
	v_mov_b32_e32 v170, 1.0
	v_mov_b32_e32 v186, 1.0
	v_mov_b32_e32 v187, 1.0
	v_mov_b32_e32 v188, 1.0
	v_mov_b32_e32 v189, 1.0
	v_mov_b32_e32 v190, 0
	v_mov_b32_e32 v191, 0
	v_mov_b32_e32 v192, 0
	v_mov_b32_e32 v193, 0
	s_and_saveexec_b64 s[86:87], vcc
	s_cbranch_execz .LBB0_397
	v_add_u32_e32 v0, 0xffffff80, v207
	v_lshrrev_b32_e32 v0, 1, v0
	v_lshlrev_b64 v[172:173], 2, v[0:1]
	v_lshl_add_u64 v[176:177], v[220:221], 0, v[172:173]
	v_lshl_add_u64 v[172:173], v[218:219], 0, v[172:173]
	global_load_dwordx4 v[186:189], v[172:173], off
	global_load_dwordx4 v[190:193], v[176:177], off
.LBB0_397:
	s_or_b64 exec, exec, s[86:87]
	v_mov_b32_e32 v171, 1.0
	v_mov_b32_e32 v172, 1.0
	v_mov_b32_e32 v173, 1.0
	v_mov_b32_e32 v175, 0
	v_mov_b32_e32 v176, 0
	v_mov_b32_e32 v177, 0
	s_and_saveexec_b64 s[86:87], s[42:43]
	s_cbranch_execz .LBB0_399
	v_add_u32_e32 v0, 0xffffff80, v215
	v_lshrrev_b32_e32 v0, 1, v0
	v_and_b32_e32 v0, 0x7ffffffc, v0
	v_lshlrev_b64 v[170:171], 2, v[0:1]
	v_lshl_add_u64 v[174:175], v[220:221], 0, v[170:171]
	v_lshl_add_u64 v[170:171], v[218:219], 0, v[170:171]
	global_load_dwordx4 v[170:173], v[170:171], off
	s_nop 0
	global_load_dwordx4 v[174:177], v[174:175], off
.LBB0_399:
	s_or_b64 exec, exec, s[86:87]
	s_waitcnt vmcnt(0) lgkmcnt(0)
	v_pk_mul_f32 v[128:129], v[128:129], v[208:209] op_sel_hi:[1,0]
	v_pk_mul_f32 v[126:127], v[126:127], v[208:209] op_sel_hi:[1,0]
	v_pk_mul_f32 v[124:125], v[124:125], v[208:209] op_sel_hi:[1,0]
	v_pk_mul_f32 v[122:123], v[122:123], v[208:209] op_sel_hi:[1,0]
	v_pk_mul_f32 v[196:197], v[124:125], v[152:153]
	v_pk_mul_f32 v[194:195], v[122:123], v[150:151]
	v_pk_mul_f32 v[150:151], v[126:127], v[150:151]
	v_pk_mul_f32 v[152:153], v[128:129], v[152:153]
	v_pk_fma_f32 v[196:197], v[128:129], v[148:149], v[196:197] neg_lo:[0,0,1] neg_hi:[0,0,1]
	v_pk_fma_f32 v[194:195], v[126:127], v[146:147], v[194:195] neg_lo:[0,0,1] neg_hi:[0,0,1]
	v_pk_fma_f32 v[148:149], v[124:125], v[148:149], v[152:153]
	v_pk_fma_f32 v[146:147], v[122:123], v[146:147], v[150:151]
	v_cndmask_b32_e32 v0, v124, v148, vcc
	v_cndmask_b32_e32 v148, v125, v149, vcc
	v_cndmask_b32_e32 v122, v122, v146, vcc
	v_cndmask_b32_e32 v123, v123, v147, vcc
	v_cndmask_b32_e32 v125, v128, v196, vcc
	v_cndmask_b32_e32 v124, v126, v194, vcc
	v_cndmask_b32_e32 v126, v127, v195, vcc
	v_cndmask_b32_e32 v128, v129, v197, vcc
	v_cvt_pk_bf16_f32 v124, v124, v126
	v_cvt_pk_bf16_f32 v125, v125, v128
	v_cvt_pk_bf16_f32 v126, v122, v123
	v_mov_b64_e32 v[122:123], s[72:73]
	v_ashrrev_i32_e32 v211, 31, v210
	v_mad_i64_i32 v[128:129], s[34:35], v206, s60, v[122:123]
	v_lshlrev_b64 v[146:147], 1, v[210:211]
	v_cvt_pk_bf16_f32 v127, v0, v148
	v_lshl_add_u64 v[128:129], v[128:129], 0, v[146:147]
	v_pk_mul_f32 v[120:121], v[120:121], v[208:209] op_sel_hi:[1,0]
	v_pk_mul_f32 v[118:119], v[118:119], v[208:209] op_sel_hi:[1,0]
	v_pk_mul_f32 v[116:117], v[116:117], v[208:209] op_sel_hi:[1,0]
	v_pk_mul_f32 v[114:115], v[114:115], v[208:209] op_sel_hi:[1,0]
	global_store_dwordx4 v[128:129], v[124:127], off
	v_pk_mul_f32 v[112:113], v[112:113], v[212:213] op_sel_hi:[1,0]
	v_pk_mul_f32 v[110:111], v[110:111], v[212:213] op_sel_hi:[1,0]
	v_pk_mul_f32 v[124:125], v[114:115], v[134:135]
	v_pk_mul_f32 v[126:127], v[116:117], v[136:137]
	v_pk_mul_f32 v[134:135], v[118:119], v[134:135]
	v_pk_mul_f32 v[136:137], v[120:121], v[136:137]
	v_pk_fma_f32 v[126:127], v[120:121], v[132:133], v[126:127] neg_lo:[0,0,1] neg_hi:[0,0,1]
	v_pk_fma_f32 v[124:125], v[118:119], v[130:131], v[124:125] neg_lo:[0,0,1] neg_hi:[0,0,1]
	v_pk_fma_f32 v[132:133], v[116:117], v[132:133], v[136:137]
	v_pk_fma_f32 v[130:131], v[114:115], v[130:131], v[134:135]
	v_cndmask_b32_e64 v0, v116, v132, s[42:43]
	v_cndmask_b32_e64 v116, v114, v130, s[42:43]
	v_cndmask_b32_e64 v130, v115, v131, s[42:43]
	v_cndmask_b32_e64 v115, v120, v126, s[42:43]
	v_cndmask_b32_e64 v114, v118, v124, s[42:43]
	v_cndmask_b32_e64 v117, v117, v133, s[42:43]
	v_cndmask_b32_e64 v120, v121, v127, s[42:43]
	v_cndmask_b32_e64 v118, v119, v125, s[42:43]
	v_cvt_pk_bf16_f32 v114, v114, v118
	v_cvt_pk_bf16_f32 v115, v115, v120
	v_pk_mul_f32 v[106:107], v[106:107], v[212:213] op_sel_hi:[1,0]
	v_cvt_pk_bf16_f32 v116, v116, v130
	v_cvt_pk_bf16_f32 v117, v0, v117
	global_store_dwordx4 v[128:129], v[114:117], off offset:256
	v_pk_mul_f32 v[108:109], v[108:109], v[212:213] op_sel_hi:[1,0]
	v_pk_mul_f32 v[118:119], v[110:111], v[166:167]
	v_pk_mul_f32 v[114:115], v[106:107], v[166:167]
	v_pk_mul_f32 v[120:121], v[112:113], v[168:169]
	v_pk_mul_f32 v[116:117], v[108:109], v[168:169]
	v_pk_fma_f32 v[114:115], v[110:111], v[162:163], v[114:115] neg_lo:[0,0,1] neg_hi:[0,0,1]
	v_pk_fma_f32 v[120:121], v[108:109], v[164:165], v[120:121]
	v_pk_fma_f32 v[118:119], v[106:107], v[162:163], v[118:119]
	v_add_u32_e32 v0, 16, v206
	v_pk_fma_f32 v[116:117], v[112:113], v[164:165], v[116:117] neg_lo:[0,0,1] neg_hi:[0,0,1]
	v_cndmask_b32_e32 v120, v108, v120, vcc
	v_cndmask_b32_e32 v108, v106, v118, vcc
	v_cndmask_b32_e32 v106, v110, v114, vcc
	v_cndmask_b32_e32 v110, v111, v115, vcc
	v_cndmask_b32_e32 v109, v109, v121, vcc
	v_cndmask_b32_e32 v118, v107, v119, vcc
	v_cndmask_b32_e32 v107, v112, v116, vcc
	v_cvt_pk_bf16_f32 v106, v106, v110
; __device__ __forceinline__ u32x4 pack8(f32x4 v0, f32x4 v1) { u32x4 w; w.x = cvt_pk_bf16(v0[0], v0[1]); w.y = cvt_pk_bf16(v0[2], v0[3]); w.z = cvt_pk_bf16(v1[0], v1[1]); w.w = cvt_pk_bf16(v1[2], v1[3]); return w; }
;     __device__ __forceinline__ void operator()(const f32x4 (&acc)[2][2][4][2], const Unit& u, int wr, int wc, int fr, int fq) const {
;     ...
;             [=](int row, int col, f32x4 v0, f32x4 v1, const LQ& L) __attribute__((always_inline)) {
;                 v0 = v0 * L.rs; v1 = v1 * L.rs; const int d = col % 192;
;                 if (d >= 128) { const f32x4 o1 = v0 * L.c - v1 * L.s; const f32x4 o2 = v1 * L.c + v0 * L.s; v0 = o1; v1 = o2; }
;                 *(u32x4*)(Q_ + (size_t)row * QW + col) = pack8(v0, v1); });
	v_mad_i64_i32 v[110:111], s[34:35], v0, s60, v[122:123]
	v_cndmask_b32_e32 v112, v113, v117, vcc
	v_cvt_pk_bf16_f32 v107, v107, v112
	v_cvt_pk_bf16_f32 v108, v108, v118
	v_cvt_pk_bf16_f32 v109, v120, v109
	v_lshl_add_u64 v[110:111], v[110:111], 0, v[146:147]
	v_pk_mul_f32 v[104:105], v[104:105], v[212:213] op_sel_hi:[1,0]
	v_pk_mul_f32 v[102:103], v[102:103], v[212:213] op_sel_hi:[1,0]
	v_pk_mul_f32 v[100:101], v[100:101], v[212:213] op_sel_hi:[1,0]
	v_pk_mul_f32 v[98:99], v[98:99], v[212:213] op_sel_hi:[1,0]
	global_store_dwordx4 v[110:111], v[106:109], off
	v_pk_mul_f32 v[112:113], v[102:103], v[142:143]
	v_pk_mul_f32 v[114:115], v[104:105], v[144:145]
	v_pk_mul_f32 v[106:107], v[98:99], v[142:143]
	v_pk_mul_f32 v[108:109], v[100:101], v[144:145]
	v_pk_fma_f32 v[106:107], v[102:103], v[138:139], v[106:107] neg_lo:[0,0,1] neg_hi:[0,0,1]
	v_pk_fma_f32 v[108:109], v[104:105], v[140:141], v[108:109] neg_lo:[0,0,1] neg_hi:[0,0,1]
	v_pk_fma_f32 v[114:115], v[100:101], v[140:141], v[114:115]
	v_pk_fma_f32 v[112:113], v[98:99], v[138:139], v[112:113]
	v_cndmask_b32_e64 v0, v100, v114, s[42:43]
	v_cndmask_b32_e64 v100, v98, v112, s[42:43]
	v_cndmask_b32_e64 v112, v99, v113, s[42:43]
	v_cndmask_b32_e64 v99, v104, v108, s[42:43]
	v_cndmask_b32_e64 v98, v102, v106, s[42:43]
	v_cndmask_b32_e64 v101, v101, v115, s[42:43]
	v_cndmask_b32_e64 v104, v105, v109, s[42:43]
	v_cndmask_b32_e64 v102, v103, v107, s[42:43]
	v_cvt_pk_bf16_f32 v98, v98, v102
	v_cvt_pk_bf16_f32 v99, v99, v104
	v_pk_mul_f32 v[96:97], v[96:97], v[214:215] op_sel_hi:[1,0]
	v_pk_mul_f32 v[94:95], v[94:95], v[214:215] op_sel_hi:[1,0]
	v_pk_mul_f32 v[90:91], v[90:91], v[214:215] op_sel_hi:[1,0]
	v_cvt_pk_bf16_f32 v100, v100, v112
	v_cvt_pk_bf16_f32 v101, v0, v101
	global_store_dwordx4 v[110:111], v[98:101], off offset:256
	v_pk_mul_f32 v[92:93], v[92:93], v[214:215] op_sel_hi:[1,0]
	v_pk_mul_f32 v[102:103], v[94:95], v[182:183]
	v_pk_mul_f32 v[98:99], v[90:91], v[182:183]
	v_pk_mul_f32 v[104:105], v[96:97], v[184:185]
	v_pk_mul_f32 v[100:101], v[92:93], v[184:185]
	v_pk_fma_f32 v[98:99], v[94:95], v[178:179], v[98:99] neg_lo:[0,0,1] neg_hi:[0,0,1]
	v_pk_fma_f32 v[104:105], v[92:93], v[180:181], v[104:105]
	v_pk_fma_f32 v[102:103], v[90:91], v[178:179], v[102:103]
	v_add_u32_e32 v0, 32, v206
	v_pk_fma_f32 v[100:101], v[96:97], v[180:181], v[100:101] neg_lo:[0,0,1] neg_hi:[0,0,1]
	v_cndmask_b32_e32 v104, v92, v104, vcc
	v_cndmask_b32_e32 v92, v90, v102, vcc
	v_cndmask_b32_e32 v90, v94, v98, vcc
	v_cndmask_b32_e32 v94, v95, v99, vcc
	v_cndmask_b32_e32 v93, v93, v105, vcc
	v_cndmask_b32_e32 v102, v91, v103, vcc
	v_cndmask_b32_e32 v91, v96, v100, vcc
	v_cvt_pk_bf16_f32 v90, v90, v94
	v_mad_i64_i32 v[94:95], s[34:35], v0, s60, v[122:123]
	v_cndmask_b32_e32 v96, v97, v101, vcc
	v_cvt_pk_bf16_f32 v91, v91, v96
	v_cvt_pk_bf16_f32 v92, v92, v102
	v_cvt_pk_bf16_f32 v93, v104, v93
	v_lshl_add_u64 v[94:95], v[94:95], 0, v[146:147]
	v_pk_mul_f32 v[88:89], v[88:89], v[214:215] op_sel_hi:[1,0]
	v_pk_mul_f32 v[86:87], v[86:87], v[214:215] op_sel_hi:[1,0]
	v_pk_mul_f32 v[84:85], v[84:85], v[214:215] op_sel_hi:[1,0]
	v_pk_mul_f32 v[82:83], v[82:83], v[214:215] op_sel_hi:[1,0]
	global_store_dwordx4 v[94:95], v[90:93], off
	v_pk_mul_f32 v[96:97], v[86:87], v[158:159]
	v_pk_mul_f32 v[98:99], v[88:89], v[160:161]
	v_pk_mul_f32 v[90:91], v[82:83], v[158:159]
	v_pk_mul_f32 v[92:93], v[84:85], v[160:161]
	v_pk_fma_f32 v[90:91], v[86:87], v[154:155], v[90:91] neg_lo:[0,0,1] neg_hi:[0,0,1]
	v_pk_fma_f32 v[92:93], v[88:89], v[156:157], v[92:93] neg_lo:[0,0,1] neg_hi:[0,0,1]
	v_pk_fma_f32 v[98:99], v[84:85], v[156:157], v[98:99]
	v_pk_fma_f32 v[96:97], v[82:83], v[154:155], v[96:97]
	v_cndmask_b32_e64 v0, v84, v98, s[42:43]
	v_cndmask_b32_e64 v84, v82, v96, s[42:43]
	v_cndmask_b32_e64 v96, v83, v97, s[42:43]
	v_cndmask_b32_e64 v83, v88, v92, s[42:43]
	v_cndmask_b32_e64 v82, v86, v90, s[42:43]
	v_cndmask_b32_e64 v85, v85, v99, s[42:43]
	v_cndmask_b32_e64 v88, v89, v93, s[42:43]
	v_cndmask_b32_e64 v86, v87, v91, s[42:43]
	v_cvt_pk_bf16_f32 v82, v82, v86
	v_cvt_pk_bf16_f32 v83, v83, v88
	v_pk_mul_f32 v[80:81], v[80:81], v[216:217] op_sel_hi:[1,0]
	v_pk_mul_f32 v[78:79], v[78:79], v[216:217] op_sel_hi:[1,0]
	v_pk_mul_f32 v[74:75], v[74:75], v[216:217] op_sel_hi:[1,0]
	v_cvt_pk_bf16_f32 v84, v84, v96
	v_cvt_pk_bf16_f32 v85, v0, v85
	global_store_dwordx4 v[94:95], v[82:85], off offset:256
	v_pk_mul_f32 v[76:77], v[76:77], v[216:217] op_sel_hi:[1,0]
	v_pk_mul_f32 v[86:87], v[78:79], v[190:191]
	v_pk_mul_f32 v[82:83], v[74:75], v[190:191]
	v_pk_mul_f32 v[88:89], v[80:81], v[192:193]
	v_pk_mul_f32 v[84:85], v[76:77], v[192:193]
	v_pk_fma_f32 v[82:83], v[78:79], v[186:187], v[82:83] neg_lo:[0,0,1] neg_hi:[0,0,1]
	v_pk_fma_f32 v[88:89], v[76:77], v[188:189], v[88:89]
	v_pk_fma_f32 v[86:87], v[74:75], v[186:187], v[86:87]
	v_add_u32_e32 v0, 48, v206
	v_pk_fma_f32 v[84:85], v[80:81], v[188:189], v[84:85] neg_lo:[0,0,1] neg_hi:[0,0,1]
	v_cndmask_b32_e32 v88, v76, v88, vcc
	v_cndmask_b32_e32 v76, v74, v86, vcc
	v_cndmask_b32_e32 v74, v78, v82, vcc
	v_cndmask_b32_e32 v78, v79, v83, vcc
	v_cndmask_b32_e32 v86, v75, v87, vcc
	v_cndmask_b32_e32 v75, v80, v84, vcc
	v_cvt_pk_bf16_f32 v74, v74, v78
	v_mad_i64_i32 v[78:79], s[34:35], v0, s60, v[122:123]
	v_cndmask_b32_e32 v77, v77, v89, vcc
	v_cndmask_b32_e32 v80, v81, v85, vcc
	v_cvt_pk_bf16_f32 v75, v75, v80
	v_lshl_add_u64 v[78:79], v[78:79], 0, v[146:147]
	v_pk_mul_f32 v[72:73], v[72:73], v[216:217] op_sel_hi:[1,0]
	v_pk_mul_f32 v[70:71], v[70:71], v[216:217] op_sel_hi:[1,0]
	v_pk_mul_f32 v[66:67], v[66:67], v[216:217] op_sel_hi:[1,0]
	v_cvt_pk_bf16_f32 v76, v76, v86
; __device__ __forceinline__ u32x4 pack8(f32x4 v0, f32x4 v1) { u32x4 w; w.x = cvt_pk_bf16(v0[0], v0[1]); w.y = cvt_pk_bf16(v0[2], v0[3]); w.z = cvt_pk_bf16(v1[0], v1[1]); w.w = cvt_pk_bf16(v1[2], v1[3]); return w; }
;     __device__ __forceinline__ void operator()(const f32x4 (&acc)[2][2][4][2], const Unit& u, int wr, int wc, int fr, int fq) const {
;     ...
;         epi_perm2<LQ>(acc, u, wr, wc, fr, fq,
;             [=](int row, int col) __attribute__((always_inline)) { LQ L; L.rs = stat_[row * 2 + 0]; const int d = col % 192;
;                 if (d >= 128) { const int i0 = ((d - 128) >> 3) * 4; L.c = *(const f32x4*)(cs_ + (size_t)row * 32 + i0); L.s = *(const f32x4*)(sn_ + (size_t)row * 32 + i0); }
;                 else { L.c = (f32x4){1.f, 1.f, 1.f, 1.f}; L.s = (f32x4){0.f, 0.f, 0.f, 0.f}; } return L; },
;             [=](int row, int col, f32x4 v0, f32x4 v1, const LQ& L) __attribute__((always_inline)) {
;                 v0 = v0 * L.rs; v1 = v1 * L.rs; const int d = col % 192;
;                 if (d >= 128) { const f32x4 o1 = v0 * L.c - v1 * L.s; const f32x4 o2 = v1 * L.c + v0 * L.s; v0 = o1; v1 = o2; }
;                 *(u32x4*)(Q_ + (size_t)row * QW + col) = pack8(v0, v1); });
	v_cvt_pk_bf16_f32 v77, v88, v77
	global_store_dwordx4 v[78:79], v[74:77], off
	v_pk_mul_f32 v[68:69], v[68:69], v[216:217] op_sel_hi:[1,0]
	v_pk_mul_f32 v[80:81], v[70:71], v[174:175]
	v_pk_mul_f32 v[74:75], v[66:67], v[174:175]
	v_pk_mul_f32 v[82:83], v[72:73], v[176:177]
	v_pk_mul_f32 v[76:77], v[68:69], v[176:177]
	v_pk_fma_f32 v[74:75], v[70:71], v[170:171], v[74:75] neg_lo:[0,0,1] neg_hi:[0,0,1]
	v_pk_fma_f32 v[82:83], v[68:69], v[172:173], v[82:83]
	v_pk_fma_f32 v[80:81], v[66:67], v[170:171], v[80:81]
	v_pk_fma_f32 v[76:77], v[72:73], v[172:173], v[76:77] neg_lo:[0,0,1] neg_hi:[0,0,1]
	v_cndmask_b32_e64 v0, v68, v82, s[42:43]
	v_cndmask_b32_e64 v68, v66, v80, s[42:43]
	v_cndmask_b32_e64 v66, v70, v74, s[42:43]
	v_cndmask_b32_e64 v69, v69, v83, s[42:43]
	v_cndmask_b32_e64 v80, v67, v81, s[42:43]
	v_cndmask_b32_e64 v67, v72, v76, s[42:43]
	v_cndmask_b32_e64 v70, v71, v75, s[42:43]
	v_cvt_pk_bf16_f32 v66, v66, v70
	v_add_u32_e32 v132, 0x80, v206
	v_cndmask_b32_e64 v72, v73, v77, s[42:43]
	v_cvt_pk_bf16_f32 v67, v67, v72
	v_cvt_pk_bf16_f32 v68, v68, v80
	v_cvt_pk_bf16_f32 v69, v0, v69
	global_store_dwordx4 v[78:79], v[66:69], off offset:256
	v_ashrrev_i32_e32 v133, 31, v132
	v_mov_b32_e32 v70, 0
	v_lshlrev_b32_e32 v66, 1, v132
	v_ashrrev_i32_e32 v67, 31, v66
	v_lshl_add_u64 v[66:67], v[66:67], 2, s[12:13]
	global_load_dword v130, v[66:67], off
	v_lshlrev_b64 v[66:67], 7, v[132:133]
	v_lshl_add_u64 v[74:75], s[50:51], 0, v[66:67]
	v_lshl_add_u64 v[76:77], s[64:65], 0, v[66:67]
	v_mov_b32_e32 v66, 1.0
	v_mov_b32_e32 v82, 1.0
	v_mov_b32_e32 v83, 1.0
	v_mov_b32_e32 v84, 1.0
	v_mov_b32_e32 v85, 1.0
	v_mov_b32_e32 v86, 0
	v_mov_b32_e32 v87, 0
	v_mov_b32_e32 v88, 0
	v_mov_b32_e32 v89, 0
	s_and_saveexec_b64 s[86:87], vcc
	s_cbranch_execz .LBB0_401
	v_add_u32_e32 v0, 0xffffff80, v207
	v_lshrrev_b32_e32 v0, 1, v0
	v_lshlrev_b64 v[68:69], 2, v[0:1]
	v_lshl_add_u64 v[72:73], v[76:77], 0, v[68:69]
	v_lshl_add_u64 v[68:69], v[74:75], 0, v[68:69]
	global_load_dwordx4 v[82:85], v[68:69], off
	global_load_dwordx4 v[86:89], v[72:73], off
.LBB0_401:
	s_or_b64 exec, exec, s[86:87]
	v_mov_b32_e32 v67, 1.0
	v_mov_b32_e32 v68, 1.0
	v_mov_b32_e32 v69, 1.0
	v_mov_b32_e32 v71, 0
	v_mov_b32_e32 v72, 0
	v_mov_b32_e32 v73, 0
	s_and_saveexec_b64 s[86:87], s[42:43]
	s_cbranch_execz .LBB0_403
	v_add_u32_e32 v0, 0xffffff80, v215
	v_lshrrev_b32_e32 v0, 1, v0
	v_and_b32_e32 v0, 0x7ffffffc, v0
	v_lshlrev_b64 v[66:67], 2, v[0:1]
	v_lshl_add_u64 v[70:71], v[76:77], 0, v[66:67]
	v_lshl_add_u64 v[66:67], v[74:75], 0, v[66:67]
	global_load_dwordx4 v[66:69], v[66:67], off
	s_nop 0
	global_load_dwordx4 v[70:73], v[70:71], off
.LBB0_403:
	s_or_b64 exec, exec, s[86:87]
	v_or_b32_e32 v74, 16, v132
	v_lshlrev_b32_e32 v76, 1, v74
	v_ashrrev_i32_e32 v77, 31, v76
	v_lshl_add_u64 v[76:77], v[76:77], 2, s[12:13]
	global_load_dword v134, v[76:77], off
	v_ashrrev_i32_e32 v75, 31, v74
	v_lshlrev_b64 v[74:75], 7, v[74:75]
	v_lshl_add_u64 v[90:91], s[50:51], 0, v[74:75]
	v_lshl_add_u64 v[92:93], s[64:65], 0, v[74:75]
	v_mov_b32_e32 v78, 0
	v_mov_b32_e32 v74, 1.0
	v_mov_b32_e32 v98, 1.0
	v_mov_b32_e32 v99, 1.0
	v_mov_b32_e32 v100, 1.0
	v_mov_b32_e32 v101, 1.0
	v_mov_b32_e32 v102, 0
	v_mov_b32_e32 v103, 0
	v_mov_b32_e32 v104, 0
	v_mov_b32_e32 v105, 0
	s_and_saveexec_b64 s[86:87], vcc
	s_cbranch_execz .LBB0_405
	v_add_u32_e32 v0, 0xffffff80, v207
	v_lshrrev_b32_e32 v0, 1, v0
	v_lshlrev_b64 v[76:77], 2, v[0:1]
	v_lshl_add_u64 v[80:81], v[92:93], 0, v[76:77]
	v_lshl_add_u64 v[76:77], v[90:91], 0, v[76:77]
	global_load_dwordx4 v[98:101], v[76:77], off
	global_load_dwordx4 v[102:105], v[80:81], off
.LBB0_405:
	s_or_b64 exec, exec, s[86:87]
	v_mov_b32_e32 v75, 1.0
	v_mov_b32_e32 v76, 1.0
	v_mov_b32_e32 v77, 1.0
	v_mov_b32_e32 v79, 0
	v_mov_b32_e32 v80, 0
	v_mov_b32_e32 v81, 0
	s_and_saveexec_b64 s[86:87], s[42:43]
	s_cbranch_execz .LBB0_407
	v_add_u32_e32 v0, 0xffffff80, v215
	v_lshrrev_b32_e32 v0, 1, v0
	v_and_b32_e32 v0, 0x7ffffffc, v0
	v_lshlrev_b64 v[74:75], 2, v[0:1]
	v_lshl_add_u64 v[78:79], v[92:93], 0, v[74:75]
	v_lshl_add_u64 v[74:75], v[90:91], 0, v[74:75]
	global_load_dwordx4 v[74:77], v[74:75], off
	s_nop 0
	global_load_dwordx4 v[78:81], v[78:79], off
.LBB0_407:
	s_or_b64 exec, exec, s[86:87]
	v_or_b32_e32 v90, 32, v132
	v_lshlrev_b32_e32 v92, 1, v90
	v_ashrrev_i32_e32 v93, 31, v92
	v_lshl_add_u64 v[92:93], v[92:93], 2, s[12:13]
	global_load_dword v136, v[92:93], off
	v_ashrrev_i32_e32 v91, 31, v90
	v_lshlrev_b64 v[90:91], 7, v[90:91]
	v_lshl_add_u64 v[106:107], s[50:51], 0, v[90:91]
	v_lshl_add_u64 v[108:109], s[64:65], 0, v[90:91]
	v_mov_b32_e32 v94, 0
	v_mov_b32_e32 v90, 1.0
	v_mov_b32_e32 v114, 1.0
	v_mov_b32_e32 v115, 1.0
	v_mov_b32_e32 v116, 1.0
	v_mov_b32_e32 v117, 1.0
	v_mov_b32_e32 v118, 0
	v_mov_b32_e32 v119, 0
	v_mov_b32_e32 v120, 0
	v_mov_b32_e32 v121, 0
	s_and_saveexec_b64 s[86:87], vcc
	s_cbranch_execz .LBB0_409
	v_add_u32_e32 v0, 0xffffff80, v207
	v_lshrrev_b32_e32 v0, 1, v0
	v_lshlrev_b64 v[92:93], 2, v[0:1]
	v_lshl_add_u64 v[96:97], v[108:109], 0, v[92:93]
	v_lshl_add_u64 v[92:93], v[106:107], 0, v[92:93]
	global_load_dwordx4 v[114:117], v[92:93], off
	global_load_dwordx4 v[118:121], v[96:97], off
.LBB0_409:
	s_or_b64 exec, exec, s[86:87]
	v_mov_b32_e32 v91, 1.0
	v_mov_b32_e32 v92, 1.0
	v_mov_b32_e32 v93, 1.0
	v_mov_b32_e32 v95, 0
	v_mov_b32_e32 v96, 0
	v_mov_b32_e32 v97, 0
	s_and_saveexec_b64 s[86:87], s[42:43]
	s_cbranch_execz .LBB0_411
	v_add_u32_e32 v0, 0xffffff80, v215
	v_lshrrev_b32_e32 v0, 1, v0
	v_and_b32_e32 v0, 0x7ffffffc, v0
	v_lshlrev_b64 v[90:91], 2, v[0:1]
	v_lshl_add_u64 v[94:95], v[108:109], 0, v[90:91]
	v_lshl_add_u64 v[90:91], v[106:107], 0, v[90:91]
	global_load_dwordx4 v[90:93], v[90:91], off
	s_nop 0
	global_load_dwordx4 v[94:97], v[94:95], off
; __device__ __forceinline__ u32x4 pack8(f32x4 v0, f32x4 v1) { u32x4 w; w.x = cvt_pk_bf16(v0[0], v0[1]); w.y = cvt_pk_bf16(v0[2], v0[3]); w.z = cvt_pk_bf16(v1[0], v1[1]); w.w = cvt_pk_bf16(v1[2], v1[3]); return w; }
;     __device__ __forceinline__ void operator()(const f32x4 (&acc)[2][2][4][2], const Unit& u, int wr, int wc, int fr, int fq) const {
;     ...
;         epi_perm2<LQ>(acc, u, wr, wc, fr, fq,
;             [=](int row, int col) __attribute__((always_inline)) { LQ L; L.rs = stat_[row * 2 + 0]; const int d = col % 192;
;                 if (d >= 128) { const int i0 = ((d - 128) >> 3) * 4; L.c = *(const f32x4*)(cs_ + (size_t)row * 32 + i0); L.s = *(const f32x4*)(sn_ + (size_t)row * 32 + i0); }
;                 else { L.c = (f32x4){1.f, 1.f, 1.f, 1.f}; L.s = (f32x4){0.f, 0.f, 0.f, 0.f}; } return L; },
;             [=](int row, int col, f32x4 v0, f32x4 v1, const LQ& L) __attribute__((always_inline)) {
;                 v0 = v0 * L.rs; v1 = v1 * L.rs; const int d = col % 192;
;                 if (d >= 128) { const f32x4 o1 = v0 * L.c - v1 * L.s; const f32x4 o2 = v1 * L.c + v0 * L.s; v0 = o1; v1 = o2; }
;                 *(u32x4*)(Q_ + (size_t)row * QW + col) = pack8(v0, v1); });
.LBB0_411:
	s_or_b64 exec, exec, s[86:87]
	v_or_b32_e32 v106, 48, v132
	v_lshlrev_b32_e32 v108, 1, v106
	v_ashrrev_i32_e32 v109, 31, v108
	v_lshl_add_u64 v[108:109], v[108:109], 2, s[12:13]
	global_load_dword v138, v[108:109], off
	v_ashrrev_i32_e32 v107, 31, v106
	v_lshlrev_b64 v[106:107], 7, v[106:107]
	v_lshl_add_u64 v[140:141], s[50:51], 0, v[106:107]
	v_lshl_add_u64 v[142:143], s[64:65], 0, v[106:107]
	v_mov_b32_e32 v110, 0
	v_mov_b32_e32 v106, 1.0
	v_mov_b32_e32 v122, 1.0
	v_mov_b32_e32 v123, 1.0
	v_mov_b32_e32 v124, 1.0
	v_mov_b32_e32 v125, 1.0
	v_mov_b32_e32 v126, 0
	v_mov_b32_e32 v127, 0
	v_mov_b32_e32 v128, 0
	v_mov_b32_e32 v129, 0
	s_and_saveexec_b64 s[86:87], vcc
	s_cbranch_execz .LBB0_413
	v_add_u32_e32 v0, 0xffffff80, v207
	v_lshrrev_b32_e32 v0, 1, v0
	v_lshlrev_b64 v[108:109], 2, v[0:1]
	v_lshl_add_u64 v[112:113], v[142:143], 0, v[108:109]
	v_lshl_add_u64 v[108:109], v[140:141], 0, v[108:109]
	global_load_dwordx4 v[122:125], v[108:109], off
	global_load_dwordx4 v[126:129], v[112:113], off
.LBB0_413:
	s_or_b64 exec, exec, s[86:87]
	v_mov_b32_e32 v107, 1.0
	v_mov_b32_e32 v108, 1.0
	v_mov_b32_e32 v109, 1.0
	v_mov_b32_e32 v111, 0
	v_mov_b32_e32 v112, 0
	v_mov_b32_e32 v113, 0
	s_and_saveexec_b64 s[86:87], s[42:43]
	s_cbranch_execz .LBB0_415
	v_add_u32_e32 v0, 0xffffff80, v215
	v_lshrrev_b32_e32 v0, 1, v0
	v_and_b32_e32 v0, 0x7ffffffc, v0
	v_lshlrev_b64 v[106:107], 2, v[0:1]
	v_lshl_add_u64 v[110:111], v[142:143], 0, v[106:107]
	v_lshl_add_u64 v[106:107], v[140:141], 0, v[106:107]
	global_load_dwordx4 v[106:109], v[106:107], off
	s_nop 0
	global_load_dwordx4 v[110:113], v[110:111], off
.LBB0_415:
	s_or_b64 exec, exec, s[86:87]
	s_waitcnt vmcnt(0) lgkmcnt(0)
	v_pk_mul_f32 v[64:65], v[64:65], v[130:131] op_sel_hi:[1,0]
	v_pk_mul_f32 v[62:63], v[62:63], v[130:131] op_sel_hi:[1,0]
	v_pk_mul_f32 v[60:61], v[60:61], v[130:131] op_sel_hi:[1,0]
	v_pk_mul_f32 v[58:59], v[58:59], v[130:131] op_sel_hi:[1,0]
	v_pk_mul_f32 v[142:143], v[60:61], v[88:89]
	v_pk_mul_f32 v[140:141], v[58:59], v[86:87]
	v_pk_mul_f32 v[86:87], v[62:63], v[86:87]
	v_pk_mul_f32 v[88:89], v[64:65], v[88:89]
	v_pk_fma_f32 v[142:143], v[64:65], v[84:85], v[142:143] neg_lo:[0,0,1] neg_hi:[0,0,1]
	v_pk_fma_f32 v[140:141], v[62:63], v[82:83], v[140:141] neg_lo:[0,0,1] neg_hi:[0,0,1]
	v_pk_fma_f32 v[84:85], v[60:61], v[84:85], v[88:89]
	v_pk_fma_f32 v[82:83], v[58:59], v[82:83], v[86:87]
	v_cndmask_b32_e32 v0, v60, v84, vcc
	v_cndmask_b32_e32 v84, v61, v85, vcc
	v_cndmask_b32_e32 v58, v58, v82, vcc
	v_cndmask_b32_e32 v59, v59, v83, vcc
	v_cndmask_b32_e32 v61, v64, v142, vcc
	v_cndmask_b32_e32 v60, v62, v140, vcc
	v_cndmask_b32_e32 v62, v63, v141, vcc
	v_cndmask_b32_e32 v64, v65, v143, vcc
	v_cvt_pk_bf16_f32 v60, v60, v62
	v_cvt_pk_bf16_f32 v61, v61, v64
	v_cvt_pk_bf16_f32 v62, v58, v59
	v_mov_b64_e32 v[58:59], s[72:73]
	v_mad_i64_i32 v[64:65], s[34:35], v132, s60, v[58:59]
	v_cvt_pk_bf16_f32 v63, v0, v84
	v_lshl_add_u64 v[64:65], v[64:65], 0, v[146:147]
	v_pk_mul_f32 v[56:57], v[56:57], v[130:131] op_sel_hi:[1,0]
	v_pk_mul_f32 v[54:55], v[54:55], v[130:131] op_sel_hi:[1,0]
	v_pk_mul_f32 v[52:53], v[52:53], v[130:131] op_sel_hi:[1,0]
	v_pk_mul_f32 v[50:51], v[50:51], v[130:131] op_sel_hi:[1,0]
	global_store_dwordx4 v[64:65], v[60:63], off
	v_pk_mul_f32 v[48:49], v[48:49], v[134:135] op_sel_hi:[1,0]
	v_pk_mul_f32 v[46:47], v[46:47], v[134:135] op_sel_hi:[1,0]
	v_pk_mul_f32 v[60:61], v[50:51], v[70:71]
	v_pk_mul_f32 v[62:63], v[52:53], v[72:73]
	v_pk_mul_f32 v[70:71], v[54:55], v[70:71]
	v_pk_mul_f32 v[72:73], v[56:57], v[72:73]
	v_pk_fma_f32 v[62:63], v[56:57], v[68:69], v[62:63] neg_lo:[0,0,1] neg_hi:[0,0,1]
	v_pk_fma_f32 v[60:61], v[54:55], v[66:67], v[60:61] neg_lo:[0,0,1] neg_hi:[0,0,1]
	v_pk_fma_f32 v[68:69], v[52:53], v[68:69], v[72:73]
	v_pk_fma_f32 v[66:67], v[50:51], v[66:67], v[70:71]
	v_cndmask_b32_e64 v0, v52, v68, s[42:43]
	v_cndmask_b32_e64 v52, v50, v66, s[42:43]
	v_cndmask_b32_e64 v66, v51, v67, s[42:43]
	v_cndmask_b32_e64 v51, v56, v62, s[42:43]
	v_cndmask_b32_e64 v50, v54, v60, s[42:43]
	v_cndmask_b32_e64 v53, v53, v69, s[42:43]
	v_cndmask_b32_e64 v56, v57, v63, s[42:43]
	v_cndmask_b32_e64 v54, v55, v61, s[42:43]
	v_cvt_pk_bf16_f32 v50, v50, v54
	v_cvt_pk_bf16_f32 v51, v51, v56
	v_pk_mul_f32 v[42:43], v[42:43], v[134:135] op_sel_hi:[1,0]
	v_cvt_pk_bf16_f32 v52, v52, v66
	v_cvt_pk_bf16_f32 v53, v0, v53
	global_store_dwordx4 v[64:65], v[50:53], off offset:256
	v_pk_mul_f32 v[44:45], v[44:45], v[134:135] op_sel_hi:[1,0]
	v_pk_mul_f32 v[54:55], v[46:47], v[102:103]
	v_pk_mul_f32 v[50:51], v[42:43], v[102:103]
	v_pk_mul_f32 v[56:57], v[48:49], v[104:105]
	v_pk_mul_f32 v[52:53], v[44:45], v[104:105]
	v_pk_fma_f32 v[50:51], v[46:47], v[98:99], v[50:51] neg_lo:[0,0,1] neg_hi:[0,0,1]
	v_pk_fma_f32 v[56:57], v[44:45], v[100:101], v[56:57]
	v_pk_fma_f32 v[54:55], v[42:43], v[98:99], v[54:55]
	v_add_u32_e32 v0, 0x90, v206
	v_pk_fma_f32 v[52:53], v[48:49], v[100:101], v[52:53] neg_lo:[0,0,1] neg_hi:[0,0,1]
	v_cndmask_b32_e32 v56, v44, v56, vcc
	v_cndmask_b32_e32 v44, v42, v54, vcc
	v_cndmask_b32_e32 v42, v46, v50, vcc
	v_cndmask_b32_e32 v46, v47, v51, vcc
	v_cndmask_b32_e32 v45, v45, v57, vcc
	v_cndmask_b32_e32 v54, v43, v55, vcc
	v_cndmask_b32_e32 v43, v48, v52, vcc
	v_cvt_pk_bf16_f32 v42, v42, v46
	v_mad_i64_i32 v[46:47], s[34:35], v0, s60, v[58:59]
	v_cndmask_b32_e32 v48, v49, v53, vcc
	v_cvt_pk_bf16_f32 v43, v43, v48
	v_cvt_pk_bf16_f32 v44, v44, v54
	v_cvt_pk_bf16_f32 v45, v56, v45
	v_lshl_add_u64 v[46:47], v[46:47], 0, v[146:147]
	v_pk_mul_f32 v[40:41], v[40:41], v[134:135] op_sel_hi:[1,0]
	v_pk_mul_f32 v[38:39], v[38:39], v[134:135] op_sel_hi:[1,0]
; __device__ __forceinline__ int otid() { int t = threadIdx.x; asm volatile("" : "+v"(t)); return t; }
; #define PG8_BAR __builtin_amdgcn_s_barrier()
; __device__ __forceinline__ u32x4 pack8(f32x4 v0, f32x4 v1) { u32x4 w; w.x = cvt_pk_bf16(v0[0], v0[1]); w.y = cvt_pk_bf16(v0[2], v0[3]); w.z = cvt_pk_bf16(v1[0], v1[1]); w.w = cvt_pk_bf16(v1[2], v1[3]); return w; }
;     ...
;         if (wr == 0) PG8_BAR;
;         { const int t2_ = otid(), w2_ = t2_ >> 6, l2_ = t2_ & 63; E(acc, cur, w2_ >> 2, w2_ & 3, l2_ & 15, l2_ >> 4); }
;         if (!has_next) break;
; #pragma unroll
;         for (int a = 0; a < 2; ++a)
; #pragma unroll
;             for (int b = 0; b < 2; ++b)
; #pragma unroll
;                 for (int m = 0; m < 4; ++m)
; #pragma unroll
;                     for (int n = 0; n < 2; ++n) acc[a][b][m][n] = (f32x4){0.f, 0.f, 0.f, 0.f};
;         cur = nxt; cA = nA; cB = nB; ++ui;
;         if (wr == 1) PG8_BAR;
;     }
;     __device__ __forceinline__ void operator()(const f32x4 (&acc)[2][2][4][2], const Unit& u, int wr, int wc, int fr, int fq) const {
;     ...
;             [=](int row, int col, f32x4 v0, f32x4 v1, const LQ& L) __attribute__((always_inline)) {
;                 v0 = v0 * L.rs; v1 = v1 * L.rs; const int d = col % 192;
;                 if (d >= 128) { const f32x4 o1 = v0 * L.c - v1 * L.s; const f32x4 o2 = v1 * L.c + v0 * L.s; v0 = o1; v1 = o2; }
;                 *(u32x4*)(Q_ + (size_t)row * QW + col) = pack8(v0, v1); });
	v_pk_mul_f32 v[36:37], v[36:37], v[134:135] op_sel_hi:[1,0]
	v_pk_mul_f32 v[34:35], v[34:35], v[134:135] op_sel_hi:[1,0]
	global_store_dwordx4 v[46:47], v[42:45], off
	v_pk_mul_f32 v[48:49], v[38:39], v[78:79]
	v_pk_mul_f32 v[50:51], v[40:41], v[80:81]
	v_pk_mul_f32 v[42:43], v[34:35], v[78:79]
	v_pk_mul_f32 v[44:45], v[36:37], v[80:81]
	v_pk_fma_f32 v[42:43], v[38:39], v[74:75], v[42:43] neg_lo:[0,0,1] neg_hi:[0,0,1]
	v_pk_fma_f32 v[44:45], v[40:41], v[76:77], v[44:45] neg_lo:[0,0,1] neg_hi:[0,0,1]
	v_pk_fma_f32 v[50:51], v[36:37], v[76:77], v[50:51]
	v_pk_fma_f32 v[48:49], v[34:35], v[74:75], v[48:49]
	v_cndmask_b32_e64 v0, v36, v50, s[42:43]
	v_cndmask_b32_e64 v36, v34, v48, s[42:43]
	v_cndmask_b32_e64 v48, v35, v49, s[42:43]
	v_cndmask_b32_e64 v35, v40, v44, s[42:43]
	v_cndmask_b32_e64 v34, v38, v42, s[42:43]
	v_cndmask_b32_e64 v37, v37, v51, s[42:43]
	v_cndmask_b32_e64 v40, v41, v45, s[42:43]
	v_cndmask_b32_e64 v38, v39, v43, s[42:43]
	v_cvt_pk_bf16_f32 v34, v34, v38
	v_cvt_pk_bf16_f32 v35, v35, v40
	v_pk_mul_f32 v[32:33], v[32:33], v[136:137] op_sel_hi:[1,0]
	v_pk_mul_f32 v[30:31], v[30:31], v[136:137] op_sel_hi:[1,0]
	v_pk_mul_f32 v[26:27], v[26:27], v[136:137] op_sel_hi:[1,0]
	v_cvt_pk_bf16_f32 v36, v36, v48
	v_cvt_pk_bf16_f32 v37, v0, v37
	global_store_dwordx4 v[46:47], v[34:37], off offset:256
	v_pk_mul_f32 v[28:29], v[28:29], v[136:137] op_sel_hi:[1,0]
	v_pk_mul_f32 v[38:39], v[30:31], v[118:119]
	v_pk_mul_f32 v[34:35], v[26:27], v[118:119]
	v_pk_mul_f32 v[40:41], v[32:33], v[120:121]
	v_pk_mul_f32 v[36:37], v[28:29], v[120:121]
	v_pk_fma_f32 v[34:35], v[30:31], v[114:115], v[34:35] neg_lo:[0,0,1] neg_hi:[0,0,1]
	v_pk_fma_f32 v[40:41], v[28:29], v[116:117], v[40:41]
	v_pk_fma_f32 v[38:39], v[26:27], v[114:115], v[38:39]
	v_add_u32_e32 v0, 0xa0, v206
	v_pk_fma_f32 v[36:37], v[32:33], v[116:117], v[36:37] neg_lo:[0,0,1] neg_hi:[0,0,1]
	v_cndmask_b32_e32 v40, v28, v40, vcc
	v_cndmask_b32_e32 v28, v26, v38, vcc
	v_cndmask_b32_e32 v26, v30, v34, vcc
	v_cndmask_b32_e32 v30, v31, v35, vcc
	v_cndmask_b32_e32 v29, v29, v41, vcc
	v_cndmask_b32_e32 v38, v27, v39, vcc
	v_cndmask_b32_e32 v27, v32, v36, vcc
	v_cvt_pk_bf16_f32 v26, v26, v30
	v_mad_i64_i32 v[30:31], s[34:35], v0, s60, v[58:59]
	v_cndmask_b32_e32 v32, v33, v37, vcc
	v_cvt_pk_bf16_f32 v27, v27, v32
	v_cvt_pk_bf16_f32 v28, v28, v38
	v_cvt_pk_bf16_f32 v29, v40, v29
	v_lshl_add_u64 v[30:31], v[30:31], 0, v[146:147]
	v_pk_mul_f32 v[24:25], v[24:25], v[136:137] op_sel_hi:[1,0]
	v_pk_mul_f32 v[22:23], v[22:23], v[136:137] op_sel_hi:[1,0]
	v_pk_mul_f32 v[20:21], v[20:21], v[136:137] op_sel_hi:[1,0]
	v_pk_mul_f32 v[18:19], v[18:19], v[136:137] op_sel_hi:[1,0]
	global_store_dwordx4 v[30:31], v[26:29], off
	v_pk_mul_f32 v[32:33], v[22:23], v[94:95]
	v_pk_mul_f32 v[34:35], v[24:25], v[96:97]
	v_pk_mul_f32 v[26:27], v[18:19], v[94:95]
	v_pk_mul_f32 v[28:29], v[20:21], v[96:97]
	v_pk_fma_f32 v[26:27], v[22:23], v[90:91], v[26:27] neg_lo:[0,0,1] neg_hi:[0,0,1]
	v_pk_fma_f32 v[28:29], v[24:25], v[92:93], v[28:29] neg_lo:[0,0,1] neg_hi:[0,0,1]
	v_pk_fma_f32 v[34:35], v[20:21], v[92:93], v[34:35]
	v_pk_fma_f32 v[32:33], v[18:19], v[90:91], v[32:33]
	v_cndmask_b32_e64 v0, v20, v34, s[42:43]
	v_cndmask_b32_e64 v20, v18, v32, s[42:43]
	v_cndmask_b32_e64 v32, v19, v33, s[42:43]
	v_cndmask_b32_e64 v19, v24, v28, s[42:43]
	v_cndmask_b32_e64 v18, v22, v26, s[42:43]
	v_cndmask_b32_e64 v21, v21, v35, s[42:43]
	v_cndmask_b32_e64 v24, v25, v29, s[42:43]
	v_cndmask_b32_e64 v22, v23, v27, s[42:43]
	v_cvt_pk_bf16_f32 v18, v18, v22
	v_cvt_pk_bf16_f32 v19, v19, v24
	v_pk_mul_f32 v[16:17], v[16:17], v[138:139] op_sel_hi:[1,0]
	v_pk_mul_f32 v[14:15], v[14:15], v[138:139] op_sel_hi:[1,0]
	v_pk_mul_f32 v[10:11], v[10:11], v[138:139] op_sel_hi:[1,0]
	v_cvt_pk_bf16_f32 v20, v20, v32
	v_cvt_pk_bf16_f32 v21, v0, v21
	global_store_dwordx4 v[30:31], v[18:21], off offset:256
	v_pk_mul_f32 v[12:13], v[12:13], v[138:139] op_sel_hi:[1,0]
	v_pk_mul_f32 v[22:23], v[14:15], v[126:127]
	v_pk_mul_f32 v[18:19], v[10:11], v[126:127]
	v_pk_mul_f32 v[24:25], v[16:17], v[128:129]
	v_pk_mul_f32 v[20:21], v[12:13], v[128:129]
	v_pk_fma_f32 v[18:19], v[14:15], v[122:123], v[18:19] neg_lo:[0,0,1] neg_hi:[0,0,1]
	v_pk_fma_f32 v[24:25], v[12:13], v[124:125], v[24:25]
	v_pk_fma_f32 v[22:23], v[10:11], v[122:123], v[22:23]
	v_add_u32_e32 v0, 0xb0, v206
	v_pk_fma_f32 v[20:21], v[16:17], v[124:125], v[20:21] neg_lo:[0,0,1] neg_hi:[0,0,1]
	v_cndmask_b32_e32 v24, v12, v24, vcc
	v_cndmask_b32_e32 v12, v10, v22, vcc
	v_cndmask_b32_e32 v10, v14, v18, vcc
	v_cndmask_b32_e32 v14, v15, v19, vcc
	v_cndmask_b32_e32 v13, v13, v25, vcc
	v_cndmask_b32_e32 v22, v11, v23, vcc
	v_cndmask_b32_e32 v11, v16, v20, vcc
	v_cvt_pk_bf16_f32 v10, v10, v14
	v_mad_i64_i32 v[14:15], s[34:35], v0, s60, v[58:59]
	v_cndmask_b32_e32 v16, v17, v21, vcc
	v_cvt_pk_bf16_f32 v11, v11, v16
	v_cvt_pk_bf16_f32 v12, v12, v22
	v_cvt_pk_bf16_f32 v13, v24, v13
	v_lshl_add_u64 v[14:15], v[14:15], 0, v[146:147]
	v_pk_mul_f32 v[8:9], v[8:9], v[138:139] op_sel_hi:[1,0]
	v_pk_mul_f32 v[6:7], v[6:7], v[138:139] op_sel_hi:[1,0]
	v_pk_mul_f32 v[4:5], v[4:5], v[138:139] op_sel_hi:[1,0]
	v_pk_mul_f32 v[2:3], v[2:3], v[138:139] op_sel_hi:[1,0]
	global_store_dwordx4 v[14:15], v[10:13], off
	v_pk_mul_f32 v[16:17], v[6:7], v[110:111]
	v_pk_mul_f32 v[18:19], v[8:9], v[112:113]
	v_pk_mul_f32 v[10:11], v[2:3], v[110:111]
	v_pk_mul_f32 v[12:13], v[4:5], v[112:113]
	v_readlane_b32 s16, v253, 38
	v_pk_fma_f32 v[12:13], v[8:9], v[108:109], v[12:13] neg_lo:[0,0,1] neg_hi:[0,0,1]
	v_pk_fma_f32 v[10:11], v[6:7], v[106:107], v[10:11] neg_lo:[0,0,1] neg_hi:[0,0,1]
	v_pk_fma_f32 v[18:19], v[4:5], v[108:109], v[18:19]
	v_pk_fma_f32 v[16:17], v[2:3], v[106:107], v[16:17]
	v_readlane_b32 s17, v253, 39
	v_cndmask_b32_e64 v0, v4, v18, s[42:43]
	v_cndmask_b32_e64 v5, v5, v19, s[42:43]
	v_cndmask_b32_e64 v4, v2, v16, s[42:43]
	v_cndmask_b32_e64 v16, v3, v17, s[42:43]
	v_cndmask_b32_e64 v3, v8, v12, s[42:43]
	v_cndmask_b32_e64 v2, v6, v10, s[42:43]
	s_and_b64 vcc, exec, s[16:17]
	s_mov_b64 s[40:41], -1
	v_cndmask_b32_e64 v8, v9, v13, s[42:43]
	v_cndmask_b32_e64 v6, v7, v11, s[42:43]
	v_cvt_pk_bf16_f32 v2, v2, v6
	v_cvt_pk_bf16_f32 v3, v3, v8
	v_cvt_pk_bf16_f32 v4, v4, v16
	v_cvt_pk_bf16_f32 v5, v0, v5
	global_store_dwordx4 v[14:15], v[2:5], off offset:256
	s_cbranch_vccnz .LBB0_374
	v_readlane_b32 s16, v255, 2
	v_readlane_b32 s17, v255, 3
	s_andn2_b64 vcc, exec, s[16:17]
	s_cbranch_vccnz .LBB0_373
	s_barrier
	s_branch .LBB0_373

; __device__ __forceinline__ u32x4 pack8(f32x4 v0, f32x4 v1) { u32x4 w; w.x = cvt_pk_bf16(v0[0], v0[1]); w.y = cvt_pk_bf16(v0[2], v0[3]); w.z = cvt_pk_bf16(v1[0], v1[1]); w.w = cvt_pk_bf16(v1[2], v1[3]); return w; }
;     __device__ __forceinline__ void operator()(const f32x4 (&acc)[2][2][4][2], const Unit& u, int wr, int wc, int fr, int fq) const {
;     ...
;         epi_perm2<float>(acc, u, wr, wc, fr, fq,
;             [=](int row, int col) __attribute__((always_inline)) { return stat_[row * 2 + 1]; },
;             [=](int row, int col, f32x4 v0, f32x4 v1, const float& rs) __attribute__((always_inline)) {
;                 v0 = v0 * rs; v1 = v1 * rs; const int h = col >> 8, d = col & 255;
;                 bf16_t* dst = d < 128 ? Kb_ + (size_t)row * KW + h * 192 + d : Vb_ + (size_t)row * VW + h * 128 + (d - 128);
;                 *(u32x4*)dst = pack8(v0, v1); });
.LBB0_441:
	v_mov_b32_e32 v0, v199
	v_readlane_b32 s74, v253, 24
	v_ashrrev_i32_e32 v136, 8, v0
	v_and_b32_e32 v137, 15, v0
	v_lshl_or_b32 v138, v136, 6, v137
	v_lshlrev_b32_e32 v136, 7, v136
	v_lshl_or_b32 v136, v137, 1, v136
	v_lshl_add_u32 v140, s96, 9, v136
	v_ashrrev_i32_e32 v141, 31, v140
	v_lshl_add_u64 v[136:137], v[140:141], 2, s[12:13]
	global_load_dword v146, v[136:137], off offset:4
	global_load_dword v148, v[136:137], off offset:132
	global_load_dword v144, v[136:137], off offset:260
	global_load_dword v142, v[136:137], off offset:388
	v_lshl_add_u32 v136, s96, 8, v138
	v_mov_b64_e32 v[138:139], s[72:73]
	v_mad_i64_i32 v[150:151], s[34:35], v136, s60, v[138:139]
	s_mul_i32 s34, s97, 0xc0
	s_ashr_i32 s35, s34, 31
	s_lshl_b64 s[42:43], s[34:35], 1
	v_lshl_add_u64 v[150:151], v[150:151], 0, s[42:43]
	v_and_b32_e32 v0, 0xf0, v0
	v_ashrrev_i32_e32 v137, 31, v136
	v_lshl_add_u64 v[150:151], v[150:151], 0, v[0:1]
	s_lshl_b32 s34, s97, 7
	s_ashr_i32 s35, s34, 31
	s_lshl_b64 s[84:85], s[34:35], 1
	s_and_b64 vcc, exec, s[40:41]
	s_mov_b64 s[76:77], 0x2ea60000
	v_readlane_b32 s75, v253, 25
	v_readlane_b32 s53, v253, 15
	s_waitcnt vmcnt(0) lgkmcnt(0)
	v_pk_mul_f32 v[152:153], v[124:125], v[146:147] op_sel_hi:[1,0]
	v_pk_mul_f32 v[124:125], v[122:123], v[146:147] op_sel_hi:[1,0]
	v_pk_mul_f32 v[122:123], v[126:127], v[146:147] op_sel_hi:[1,0]
	v_pk_mul_f32 v[128:129], v[128:129], v[146:147] op_sel_hi:[1,0]
	v_cvt_pk_bf16_f32 v122, v122, v123
	v_pk_mul_f32 v[120:121], v[120:121], v[146:147] op_sel_hi:[1,0]
	v_cvt_pk_bf16_f32 v123, v128, v129
	v_cvt_pk_bf16_f32 v124, v124, v125
	v_cvt_pk_bf16_f32 v125, v152, v153
	global_store_dwordx4 v[150:151], v[122:125], off
	v_pk_mul_f32 v[112:113], v[112:113], v[148:149] op_sel_hi:[1,0]
	v_pk_mul_f32 v[104:105], v[104:105], v[148:149] op_sel_hi:[1,0]
	v_lshlrev_b64 v[122:123], 11, v[136:137]
	v_lshl_add_u64 v[122:123], s[50:51], 0, v[122:123]
	v_lshl_add_u64 v[122:123], v[122:123], 0, s[84:85]
	v_pk_mul_f32 v[124:125], v[116:117], v[146:147] op_sel_hi:[1,0]
	v_pk_mul_f32 v[116:117], v[114:115], v[146:147] op_sel_hi:[1,0]
	v_pk_mul_f32 v[114:115], v[118:119], v[146:147] op_sel_hi:[1,0]
	v_lshl_add_u64 v[122:123], v[122:123], 0, v[0:1]
	v_cvt_pk_bf16_f32 v114, v114, v115
	v_cvt_pk_bf16_f32 v115, v120, v121
	v_cvt_pk_bf16_f32 v116, v116, v117
	v_cvt_pk_bf16_f32 v117, v124, v125
	global_store_dwordx4 v[122:123], v[114:117], off
	v_pk_mul_f32 v[118:119], v[108:109], v[148:149] op_sel_hi:[1,0]
	v_pk_mul_f32 v[108:109], v[106:107], v[148:149] op_sel_hi:[1,0]
	v_or_b32_e32 v114, 16, v136
	v_mad_i64_i32 v[116:117], s[34:35], v114, s60, v[138:139]
	v_lshl_add_u64 v[116:117], v[116:117], 0, s[42:43]
	v_pk_mul_f32 v[106:107], v[110:111], v[148:149] op_sel_hi:[1,0]
	v_ashrrev_i32_e32 v115, 31, v114
	v_lshl_add_u64 v[116:117], v[116:117], 0, v[0:1]
	v_cvt_pk_bf16_f32 v106, v106, v107
	v_cvt_pk_bf16_f32 v107, v112, v113
	v_cvt_pk_bf16_f32 v108, v108, v109
	v_cvt_pk_bf16_f32 v109, v118, v119
	global_store_dwordx4 v[116:117], v[106:109], off
	v_pk_mul_f32 v[96:97], v[96:97], v[144:145] op_sel_hi:[1,0]
	v_pk_mul_f32 v[88:89], v[88:89], v[144:145] op_sel_hi:[1,0]
	v_lshlrev_b64 v[106:107], 11, v[114:115]
	v_lshl_add_u64 v[106:107], s[50:51], 0, v[106:107]
	v_lshl_add_u64 v[106:107], v[106:107], 0, s[84:85]
	v_pk_mul_f32 v[108:109], v[100:101], v[148:149] op_sel_hi:[1,0]
	v_pk_mul_f32 v[100:101], v[98:99], v[148:149] op_sel_hi:[1,0]
	v_pk_mul_f32 v[98:99], v[102:103], v[148:149] op_sel_hi:[1,0]
	v_lshl_add_u64 v[106:107], v[106:107], 0, v[0:1]
	v_cvt_pk_bf16_f32 v98, v98, v99
	v_cvt_pk_bf16_f32 v99, v104, v105
	v_cvt_pk_bf16_f32 v100, v100, v101
	v_cvt_pk_bf16_f32 v101, v108, v109
	global_store_dwordx4 v[106:107], v[98:101], off
	v_pk_mul_f32 v[102:103], v[92:93], v[144:145] op_sel_hi:[1,0]
	v_pk_mul_f32 v[92:93], v[90:91], v[144:145] op_sel_hi:[1,0]
	v_or_b32_e32 v98, 32, v136
	v_mad_i64_i32 v[100:101], s[34:35], v98, s60, v[138:139]
	v_lshl_add_u64 v[100:101], v[100:101], 0, s[42:43]
	v_pk_mul_f32 v[90:91], v[94:95], v[144:145] op_sel_hi:[1,0]
	v_ashrrev_i32_e32 v99, 31, v98
	v_lshl_add_u64 v[100:101], v[100:101], 0, v[0:1]
	v_cvt_pk_bf16_f32 v90, v90, v91
	v_cvt_pk_bf16_f32 v91, v96, v97
	v_cvt_pk_bf16_f32 v92, v92, v93
	v_cvt_pk_bf16_f32 v93, v102, v103
	global_store_dwordx4 v[100:101], v[90:93], off
	v_pk_mul_f32 v[80:81], v[80:81], v[142:143] op_sel_hi:[1,0]
	v_pk_mul_f32 v[72:73], v[72:73], v[142:143] op_sel_hi:[1,0]
	v_lshlrev_b64 v[90:91], 11, v[98:99]
	v_lshl_add_u64 v[90:91], s[50:51], 0, v[90:91]
	v_lshl_add_u64 v[90:91], v[90:91], 0, s[84:85]
	v_pk_mul_f32 v[92:93], v[84:85], v[144:145] op_sel_hi:[1,0]
	v_pk_mul_f32 v[84:85], v[82:83], v[144:145] op_sel_hi:[1,0]
	v_pk_mul_f32 v[82:83], v[86:87], v[144:145] op_sel_hi:[1,0]
	v_lshl_add_u64 v[90:91], v[90:91], 0, v[0:1]
	v_cvt_pk_bf16_f32 v82, v82, v83
	v_cvt_pk_bf16_f32 v83, v88, v89
	v_cvt_pk_bf16_f32 v84, v84, v85
	v_cvt_pk_bf16_f32 v85, v92, v93
	global_store_dwordx4 v[90:91], v[82:85], off
	v_pk_mul_f32 v[86:87], v[76:77], v[142:143] op_sel_hi:[1,0]
	v_pk_mul_f32 v[76:77], v[74:75], v[142:143] op_sel_hi:[1,0]
	v_or_b32_e32 v82, 48, v136
	v_mad_i64_i32 v[84:85], s[34:35], v82, s60, v[138:139]
	v_lshl_add_u64 v[84:85], v[84:85], 0, s[42:43]
	v_pk_mul_f32 v[74:75], v[78:79], v[142:143] op_sel_hi:[1,0]
	v_ashrrev_i32_e32 v83, 31, v82
	v_lshl_add_u64 v[84:85], v[84:85], 0, v[0:1]
	v_cvt_pk_bf16_f32 v74, v74, v75
	v_cvt_pk_bf16_f32 v75, v80, v81
	v_cvt_pk_bf16_f32 v76, v76, v77
	v_cvt_pk_bf16_f32 v77, v86, v87
	global_store_dwordx4 v[84:85], v[74:77], off
	s_nop 1
	v_lshlrev_b64 v[74:75], 11, v[82:83]
	v_lshl_add_u64 v[74:75], s[50:51], 0, v[74:75]
	v_lshl_add_u64 v[74:75], v[74:75], 0, s[84:85]
	v_pk_mul_f32 v[76:77], v[68:69], v[142:143] op_sel_hi:[1,0]
	v_pk_mul_f32 v[68:69], v[66:67], v[142:143] op_sel_hi:[1,0]
	v_pk_mul_f32 v[66:67], v[70:71], v[142:143] op_sel_hi:[1,0]
	v_lshl_add_u64 v[74:75], v[74:75], 0, v[0:1]
	v_cvt_pk_bf16_f32 v66, v66, v67
	v_cvt_pk_bf16_f32 v67, v72, v73
	v_cvt_pk_bf16_f32 v68, v68, v69
	v_cvt_pk_bf16_f32 v69, v76, v77
	global_store_dwordx4 v[74:75], v[66:69], off
	v_add_u32_e32 v74, 0x80, v136
	v_mad_i64_i32 v[76:77], s[34:35], v74, s60, v[138:139]
	v_add_u32_e32 v66, 0x100, v140
	v_ashrrev_i32_e32 v67, 31, v66
	v_lshl_add_u64 v[66:67], v[66:67], 2, s[12:13]
	global_load_dword v72, v[66:67], off offset:4
	global_load_dword v70, v[66:67], off offset:132
	global_load_dword v68, v[66:67], off offset:260
	s_nop 0
	global_load_dword v66, v[66:67], off offset:388
	v_lshl_add_u64 v[76:77], v[76:77], 0, s[42:43]
	v_ashrrev_i32_e32 v75, 31, v74
	v_lshl_add_u64 v[76:77], v[76:77], 0, v[0:1]
	s_waitcnt vmcnt(0) lgkmcnt(0)
; __device__ __forceinline__ int otid() { int t = threadIdx.x; asm volatile("" : "+v"(t)); return t; }
; #define PG8_BAR __builtin_amdgcn_s_barrier()
; __device__ __forceinline__ u32x4 pack8(f32x4 v0, f32x4 v1) { u32x4 w; w.x = cvt_pk_bf16(v0[0], v0[1]); w.y = cvt_pk_bf16(v0[2], v0[3]); w.z = cvt_pk_bf16(v1[0], v1[1]); w.w = cvt_pk_bf16(v1[2], v1[3]); return w; }
;     ...
;         if (wr == 0) PG8_BAR;
;         { const int t2_ = otid(), w2_ = t2_ >> 6, l2_ = t2_ & 63; E(acc, cur, w2_ >> 2, w2_ & 3, l2_ & 15, l2_ >> 4); }
;         if (!has_next) break;
; #pragma unroll
;         for (int a = 0; a < 2; ++a)
; #pragma unroll
;             for (int b = 0; b < 2; ++b)
; #pragma unroll
;                 for (int m = 0; m < 4; ++m)
; #pragma unroll
;                     for (int n = 0; n < 2; ++n) acc[a][b][m][n] = (f32x4){0.f, 0.f, 0.f, 0.f};
;         cur = nxt; cA = nA; cB = nB; ++ui;
;         if (wr == 1) PG8_BAR;
;     }
;     __device__ __forceinline__ void operator()(const f32x4 (&acc)[2][2][4][2], const Unit& u, int wr, int wc, int fr, int fq) const {
;     ...
;             [=](int row, int col, f32x4 v0, f32x4 v1, const float& rs) __attribute__((always_inline)) {
;                 v0 = v0 * rs; v1 = v1 * rs; const int h = col >> 8, d = col & 255;
;                 bf16_t* dst = d < 128 ? Kb_ + (size_t)row * KW + h * 192 + d : Vb_ + (size_t)row * VW + h * 128 + (d - 128);
;                 *(u32x4*)dst = pack8(v0, v1); });
	v_pk_mul_f32 v[78:79], v[60:61], v[72:73] op_sel_hi:[1,0]
	v_pk_mul_f32 v[60:61], v[58:59], v[72:73] op_sel_hi:[1,0]
	v_pk_mul_f32 v[58:59], v[62:63], v[72:73] op_sel_hi:[1,0]
	v_pk_mul_f32 v[64:65], v[64:65], v[72:73] op_sel_hi:[1,0]
	v_cvt_pk_bf16_f32 v58, v58, v59
	v_pk_mul_f32 v[56:57], v[56:57], v[72:73] op_sel_hi:[1,0]
	v_cvt_pk_bf16_f32 v59, v64, v65
	v_cvt_pk_bf16_f32 v60, v60, v61
	v_cvt_pk_bf16_f32 v61, v78, v79
	global_store_dwordx4 v[76:77], v[58:61], off
	v_pk_mul_f32 v[48:49], v[48:49], v[70:71] op_sel_hi:[1,0]
	v_pk_mul_f32 v[40:41], v[40:41], v[70:71] op_sel_hi:[1,0]
	v_lshlrev_b64 v[58:59], 11, v[74:75]
	v_lshl_add_u64 v[58:59], s[50:51], 0, v[58:59]
	v_lshl_add_u64 v[58:59], v[58:59], 0, s[84:85]
	v_pk_mul_f32 v[60:61], v[52:53], v[72:73] op_sel_hi:[1,0]
	v_pk_mul_f32 v[52:53], v[50:51], v[72:73] op_sel_hi:[1,0]
	v_pk_mul_f32 v[50:51], v[54:55], v[72:73] op_sel_hi:[1,0]
	v_lshl_add_u64 v[58:59], v[58:59], 0, v[0:1]
	v_cvt_pk_bf16_f32 v50, v50, v51
	v_cvt_pk_bf16_f32 v51, v56, v57
	v_cvt_pk_bf16_f32 v52, v52, v53
	v_cvt_pk_bf16_f32 v53, v60, v61
	global_store_dwordx4 v[58:59], v[50:53], off
	v_pk_mul_f32 v[54:55], v[44:45], v[70:71] op_sel_hi:[1,0]
	v_pk_mul_f32 v[44:45], v[42:43], v[70:71] op_sel_hi:[1,0]
	v_add_u32_e32 v50, 0x90, v136
	v_mad_i64_i32 v[52:53], s[34:35], v50, s60, v[138:139]
	v_lshl_add_u64 v[52:53], v[52:53], 0, s[42:43]
	v_pk_mul_f32 v[42:43], v[46:47], v[70:71] op_sel_hi:[1,0]
	v_ashrrev_i32_e32 v51, 31, v50
	v_lshl_add_u64 v[52:53], v[52:53], 0, v[0:1]
	v_cvt_pk_bf16_f32 v42, v42, v43
	v_cvt_pk_bf16_f32 v43, v48, v49
	v_cvt_pk_bf16_f32 v44, v44, v45
	v_cvt_pk_bf16_f32 v45, v54, v55
	global_store_dwordx4 v[52:53], v[42:45], off
	v_pk_mul_f32 v[32:33], v[32:33], v[68:69] op_sel_hi:[1,0]
	v_pk_mul_f32 v[24:25], v[24:25], v[68:69] op_sel_hi:[1,0]
	v_lshlrev_b64 v[42:43], 11, v[50:51]
	v_lshl_add_u64 v[42:43], s[50:51], 0, v[42:43]
	v_lshl_add_u64 v[42:43], v[42:43], 0, s[84:85]
	v_pk_mul_f32 v[44:45], v[36:37], v[70:71] op_sel_hi:[1,0]
	v_pk_mul_f32 v[36:37], v[34:35], v[70:71] op_sel_hi:[1,0]
	v_pk_mul_f32 v[34:35], v[38:39], v[70:71] op_sel_hi:[1,0]
	v_lshl_add_u64 v[42:43], v[42:43], 0, v[0:1]
	v_cvt_pk_bf16_f32 v34, v34, v35
	v_cvt_pk_bf16_f32 v35, v40, v41
	v_cvt_pk_bf16_f32 v36, v36, v37
	v_cvt_pk_bf16_f32 v37, v44, v45
	global_store_dwordx4 v[42:43], v[34:37], off
	v_pk_mul_f32 v[38:39], v[28:29], v[68:69] op_sel_hi:[1,0]
	v_pk_mul_f32 v[28:29], v[26:27], v[68:69] op_sel_hi:[1,0]
	v_add_u32_e32 v34, 0xa0, v136
	v_mad_i64_i32 v[36:37], s[34:35], v34, s60, v[138:139]
	v_lshl_add_u64 v[36:37], v[36:37], 0, s[42:43]
	v_pk_mul_f32 v[26:27], v[30:31], v[68:69] op_sel_hi:[1,0]
	v_ashrrev_i32_e32 v35, 31, v34
	v_lshl_add_u64 v[36:37], v[36:37], 0, v[0:1]
	v_cvt_pk_bf16_f32 v26, v26, v27
	v_cvt_pk_bf16_f32 v27, v32, v33
	v_cvt_pk_bf16_f32 v28, v28, v29
	v_cvt_pk_bf16_f32 v29, v38, v39
	global_store_dwordx4 v[36:37], v[26:29], off
	v_pk_mul_f32 v[16:17], v[16:17], v[66:67] op_sel_hi:[1,0]
	v_pk_mul_f32 v[8:9], v[8:9], v[66:67] op_sel_hi:[1,0]
	v_lshlrev_b64 v[26:27], 11, v[34:35]
	v_lshl_add_u64 v[26:27], s[50:51], 0, v[26:27]
	v_lshl_add_u64 v[26:27], v[26:27], 0, s[84:85]
	v_pk_mul_f32 v[28:29], v[20:21], v[68:69] op_sel_hi:[1,0]
	v_pk_mul_f32 v[20:21], v[18:19], v[68:69] op_sel_hi:[1,0]
	v_pk_mul_f32 v[18:19], v[22:23], v[68:69] op_sel_hi:[1,0]
	v_lshl_add_u64 v[26:27], v[26:27], 0, v[0:1]
	v_cvt_pk_bf16_f32 v18, v18, v19
	v_cvt_pk_bf16_f32 v19, v24, v25
	v_cvt_pk_bf16_f32 v20, v20, v21
	v_cvt_pk_bf16_f32 v21, v28, v29
	global_store_dwordx4 v[26:27], v[18:21], off
	v_pk_mul_f32 v[22:23], v[12:13], v[66:67] op_sel_hi:[1,0]
	v_pk_mul_f32 v[12:13], v[10:11], v[66:67] op_sel_hi:[1,0]
	v_add_u32_e32 v18, 0xb0, v136
	v_mad_i64_i32 v[20:21], s[34:35], v18, s60, v[138:139]
	v_lshl_add_u64 v[20:21], v[20:21], 0, s[42:43]
	v_pk_mul_f32 v[10:11], v[14:15], v[66:67] op_sel_hi:[1,0]
	v_ashrrev_i32_e32 v19, 31, v18
	v_lshl_add_u64 v[20:21], v[20:21], 0, v[0:1]
	v_cvt_pk_bf16_f32 v10, v10, v11
	v_cvt_pk_bf16_f32 v11, v16, v17
	v_cvt_pk_bf16_f32 v12, v12, v13
	v_cvt_pk_bf16_f32 v13, v22, v23
	global_store_dwordx4 v[20:21], v[10:13], off
	s_mov_b64 s[42:43], -1
	s_nop 0
	v_lshlrev_b64 v[10:11], 11, v[18:19]
	v_lshl_add_u64 v[10:11], s[50:51], 0, v[10:11]
	v_lshl_add_u64 v[10:11], v[10:11], 0, s[84:85]
	v_lshl_add_u64 v[10:11], v[10:11], 0, v[0:1]
	v_pk_mul_f32 v[12:13], v[4:5], v[66:67] op_sel_hi:[1,0]
	v_pk_mul_f32 v[4:5], v[2:3], v[66:67] op_sel_hi:[1,0]
	v_pk_mul_f32 v[2:3], v[6:7], v[66:67] op_sel_hi:[1,0]
	s_nop 0
	v_cvt_pk_bf16_f32 v2, v2, v3
	v_cvt_pk_bf16_f32 v3, v8, v9
	v_cvt_pk_bf16_f32 v4, v4, v5
	v_cvt_pk_bf16_f32 v5, v12, v13
	global_store_dwordx4 v[10:11], v[2:5], off
	s_cbranch_vccnz .LBB0_428
	v_readlane_b32 s16, v253, 7
	v_readlane_b32 s17, v253, 8
	s_andn2_b64 vcc, exec, s[16:17]
	s_cbranch_vccnz .LBB0_427
	s_barrier
	s_branch .LBB0_427

; __device__ __forceinline__ float siluf_(float v) { return v * sigmoidf_(v); }
; __device__ __forceinline__ u32x4 pack8(f32x4 v0, f32x4 v1) { u32x4 w; w.x = cvt_pk_bf16(v0[0], v0[1]); w.y = cvt_pk_bf16(v0[2], v0[3]); w.z = cvt_pk_bf16(v1[0], v1[1]); w.w = cvt_pk_bf16(v1[2], v1[3]); return w; }
; __device__ __forceinline__ void unpack8(u32x4 w, f32x4& a, f32x4& b) { a = (f32x4){bf_lo(w.x), bf_hi(w.x), bf_lo(w.y), bf_hi(w.y)}; b = (f32x4){bf_lo(w.z), bf_hi(w.z), bf_lo(w.w), bf_hi(w.w)}; }
;     __device__ __forceinline__ void operator()(const f32x4 (&acc)[2][2][4][2], const Unit& u, int wr, int wc, int fr, int fq) const {
;     ...
;         epi_perm2<u32x4>(acc, u, wr, wc, fr, fq,
;             [=](int row, int col) __attribute__((always_inline)) { return *(const u32x4*)(proj_ + (size_t)row * NP + C_ZB + col); },
;             [=](int row, int col, f32x4 v0, f32x4 v1, const u32x4& zz) __attribute__((always_inline)) {
;                 f32x4 z0, z1; unpack8(zz, z0, z1);
;                 const f32x4 s0 = *(const f32x4*)(ps_ + col); const f32x4 s1 = *(const f32x4*)(ps_ + col + 4);
; #pragma unroll
;                 for (int j = 0; j < 4; ++j) { v0[j] = v0[j] * s0[j] * siluf_(z0[j]); v1[j] = v1[j] * s1[j] * siluf_(z1[j]); }
;                 *(u32x4*)(proj_ + (size_t)row * NP + C_ZB + col) = pack8(v0, v1); });
.LBB0_466:
	v_mov_b32_e32 v90, v199
	v_mov_b32_e32 v197, v146
	v_and_b32_e32 v91, 15, v90
	v_ashrrev_i32_e32 v92, 2, v90
	v_lshrrev_b32_e32 v90, 1, v90
	v_and_b32_e32 v90, 0x78, v90
	v_lshl_or_b32 v162, s0, 8, v90
	v_readlane_b32 s0, v253, 13
	v_and_or_b32 v91, v92, s61, v91
	v_readlane_b32 s1, v253, 14
	v_lshl_add_u32 v214, s12, 8, v91
	v_ashrrev_i32_e32 v163, 31, v162
	v_mov_b64_e32 v[170:171], s[0:1]
	v_mad_i64_i32 v[90:91], s[0:1], v214, s31, v[170:171]
	s_mov_b64 s[12:13], 0x1880
	v_lshl_add_u64 v[90:91], v[90:91], 0, s[12:13]
	v_lshlrev_b64 v[172:173], 1, v[162:163]
	v_lshl_add_u64 v[190:191], v[90:91], 0, v[172:173]
	global_load_dwordx4 v[158:161], v[190:191], off
	v_or_b32_e32 v92, 0x80, v162
	v_ashrrev_i32_e32 v93, 31, v92
	v_lshlrev_b64 v[174:175], 1, v[92:93]
	v_lshl_add_u64 v[188:189], v[90:91], 0, v[174:175]
	v_or_b32_e32 v90, 16, v214
	v_mad_i64_i32 v[90:91], s[0:1], v90, s31, v[170:171]
	v_lshl_add_u64 v[90:91], v[90:91], 0, s[12:13]
	v_lshl_add_u64 v[186:187], v[90:91], 0, v[172:173]
	v_lshl_add_u64 v[184:185], v[90:91], 0, v[174:175]
	v_or_b32_e32 v90, 32, v214
	v_mad_i64_i32 v[90:91], s[0:1], v90, s31, v[170:171]
	v_lshl_add_u64 v[90:91], v[90:91], 0, s[12:13]
	v_lshl_add_u64 v[182:183], v[90:91], 0, v[172:173]
	v_lshl_add_u64 v[180:181], v[90:91], 0, v[174:175]
	v_or_b32_e32 v90, 48, v214
	v_mad_i64_i32 v[90:91], s[0:1], v90, s31, v[170:171]
	v_readlane_b32 s0, v255, 14
	v_lshl_add_u64 v[90:91], v[90:91], 0, s[12:13]
	v_readlane_b32 s1, v255, 15
	v_lshl_add_u64 v[178:179], v[90:91], 0, v[172:173]
	v_lshl_add_u64 v[176:177], v[90:91], 0, v[174:175]
	v_lshl_add_u64 v[168:169], v[162:163], 2, s[0:1]
	global_load_dwordx4 v[154:157], v[188:189], off
	global_load_dwordx4 v[150:153], v[186:187], off
	global_load_dwordx4 v[138:141], v[184:185], off
	global_load_dwordx4 v[122:125], v[182:183], off
	global_load_dwordx4 v[114:117], v[180:181], off
	global_load_dwordx4 v[102:105], v[178:179], off
	global_load_dwordx4 v[90:93], v[176:177], off
	s_mov_b64 s[68:69], 0x10000
	v_readlane_b32 s50, v254, 62
	v_readlane_b32 s34, v253, 38
	v_readlane_b32 s35, v253, 39
	s_waitcnt vmcnt(0) lgkmcnt(0)
	v_lshlrev_b32_e32 v194, 16, v158
	v_and_b32_e32 v208, 0xffff0000, v158
	v_lshlrev_b32_e32 v204, 16, v159
	v_and_b32_e32 v200, 0xffff0000, v159
	v_lshlrev_b32_e32 v210, 16, v160
	v_and_b32_e32 v206, 0xffff0000, v160
	v_lshlrev_b32_e32 v202, 16, v161
	v_and_b32_e32 v192, 0xffff0000, v161
	global_load_dwordx4 v[158:161], v[168:169], off offset:16
	global_load_dwordx4 v[162:165], v[168:169], off
	v_mul_f32_e32 v193, 0xbfb8aa3b, v194
	v_exp_f32_e32 v193, v193
	v_mul_f32_e32 v146, 0xbfb8aa3b, v210
	v_exp_f32_e32 v146, v146
	v_add_f32_e32 v193, 1.0, v193
	v_rcp_f32_e32 v196, v193
	v_add_f32_e32 v146, 1.0, v146
	s_waitcnt vmcnt(1)
	v_mov_b32_e32 v207, v159
	s_waitcnt vmcnt(0)
	v_mov_b32_e32 v195, v162
	v_pk_mul_f32 v[194:195], v[196:197], v[194:195]
	v_mov_b32_e32 v209, v163
	v_mul_f32_e32 v162, v194, v195
	v_mov_b32_e32 v195, v142
	v_mul_f32_e32 v142, 0xbfb8aa3b, v208
	v_exp_f32_e32 v142, v142
	v_rcp_f32_e32 v194, v146
	v_mov_b32_e32 v205, v164
	v_mov_b32_e32 v203, v160
	v_add_f32_e32 v142, 1.0, v142
	v_rcp_f32_e32 v146, v142
	v_mul_f32_e32 v142, 0xbfb8aa3b, v206
	v_exp_f32_e32 v142, v142
	v_mov_b32_e32 v201, v165
	v_pk_mul_f32 v[146:147], v[146:147], v[208:209]
	v_mov_b32_e32 v193, v161
	v_add_f32_e32 v142, 1.0, v142
	v_rcp_f32_e32 v142, v142
	v_mul_f32_e32 v146, v146, v147
	v_mov_b32_e32 v211, v158
	v_pk_mul_f32 v[194:195], v[194:195], v[210:211]
	v_pk_mul_f32 v[142:143], v[142:143], v[206:207]
	v_mul_f32_e32 v158, v194, v195
	v_mul_f32_e32 v147, v142, v143
	v_mul_f32_e32 v142, 0xbfb8aa3b, v204
	v_exp_f32_e32 v142, v142
	v_mov_b32_e32 v143, v148
	v_lshlrev_b32_e32 v164, 16, v155
	v_mov_b32_e32 v195, v134
	v_add_f32_e32 v142, 1.0, v142
	v_rcp_f32_e32 v142, v142
	s_nop 0
	v_pk_mul_f32 v[142:143], v[142:143], v[204:205]
	s_nop 0
	v_mul_f32_e32 v159, v142, v143
	v_mul_f32_e32 v142, 0xbfb8aa3b, v202
	v_exp_f32_e32 v142, v142
	v_mov_b32_e32 v143, v144
	v_add_f32_e32 v142, 1.0, v142
	v_rcp_f32_e32 v142, v142
	s_nop 0
	v_pk_mul_f32 v[142:143], v[142:143], v[202:203]
	s_nop 0
	v_mul_f32_e32 v160, v142, v143
	v_mul_f32_e32 v142, 0xbfb8aa3b, v200
	v_exp_f32_e32 v142, v142
	s_nop 0
	v_add_f32_e32 v142, 1.0, v142
	v_rcp_f32_e32 v148, v142
	s_nop 0
	v_pk_mul_f32 v[142:143], v[148:149], v[200:201]
	s_nop 0
	v_mul_f32_e32 v148, v142, v143
	v_mul_f32_e32 v142, 0xbfb8aa3b, v192
	v_exp_f32_e32 v142, v142
	s_nop 0
	v_add_f32_e32 v142, 1.0, v142
	v_rcp_f32_e32 v144, v142
	s_nop 0
	v_pk_mul_f32 v[142:143], v[144:145], v[192:193]
	s_nop 0
	v_mul_f32_e32 v145, v142, v143
	v_cvt_pk_bf16_f32 v142, v162, v146
	v_cvt_pk_bf16_f32 v143, v159, v148
	v_cvt_pk_bf16_f32 v144, v158, v147
	v_cvt_pk_bf16_f32 v145, v160, v145
	global_store_dwordx4 v[190:191], v[142:145], off
	global_load_dwordx4 v[142:145], v[168:169], off offset:528
	s_nop 0
	global_load_dwordx4 v[146:149], v[168:169], off offset:512
	v_lshlrev_b32_e32 v160, 16, v154
	v_and_b32_e32 v158, 0xffff0000, v155
	v_mul_f32_e32 v155, 0xbfb8aa3b, v160
	v_exp_f32_e32 v155, v155
	v_and_b32_e32 v162, 0xffff0000, v154
	v_lshlrev_b32_e32 v190, 16, v156
	v_mul_f32_e32 v134, 0xbfb8aa3b, v190
	v_add_f32_e32 v155, 1.0, v155
	v_rcp_f32_e32 v194, v155
	v_exp_f32_e32 v134, v134
	v_and_b32_e32 v192, 0xffff0000, v156
	v_lshlrev_b32_e32 v156, 16, v157
	v_and_b32_e32 v154, 0xffff0000, v157
	v_add_f32_e32 v134, 1.0, v134
	s_waitcnt vmcnt(0)
; __device__ __forceinline__ float siluf_(float v) { return v * sigmoidf_(v); }
; __device__ __forceinline__ u32x4 pack8(f32x4 v0, f32x4 v1) { u32x4 w; w.x = cvt_pk_bf16(v0[0], v0[1]); w.y = cvt_pk_bf16(v0[2], v0[3]); w.z = cvt_pk_bf16(v1[0], v1[1]); w.w = cvt_pk_bf16(v1[2], v1[3]); return w; }
; __device__ __forceinline__ void unpack8(u32x4 w, f32x4& a, f32x4& b) { a = (f32x4){bf_lo(w.x), bf_hi(w.x), bf_lo(w.y), bf_hi(w.y)}; b = (f32x4){bf_lo(w.z), bf_hi(w.z), bf_lo(w.w), bf_hi(w.w)}; }
;     __device__ __forceinline__ void operator()(const f32x4 (&acc)[2][2][4][2], const Unit& u, int wr, int wc, int fr, int fq) const {
;     ...
;             [=](int row, int col, f32x4 v0, f32x4 v1, const u32x4& zz) __attribute__((always_inline)) {
;                 f32x4 z0, z1; unpack8(zz, z0, z1);
;                 const f32x4 s0 = *(const f32x4*)(ps_ + col); const f32x4 s1 = *(const f32x4*)(ps_ + col + 4);
; #pragma unroll
;                 for (int j = 0; j < 4; ++j) { v0[j] = v0[j] * s0[j] * siluf_(z0[j]); v1[j] = v1[j] * s1[j] * siluf_(z1[j]); }
;                 *(u32x4*)(proj_ + (size_t)row * NP + C_ZB + col) = pack8(v0, v1); });
	v_mov_b32_e32 v193, v143
	v_mov_b32_e32 v161, v146
	v_pk_mul_f32 v[160:161], v[194:195], v[160:161]
	v_mov_b32_e32 v163, v147
	v_mul_f32_e32 v146, v160, v161
	v_mov_b32_e32 v161, v130
	v_mul_f32_e32 v130, 0xbfb8aa3b, v162
	v_exp_f32_e32 v130, v130
	v_rcp_f32_e32 v160, v134
	v_mov_b32_e32 v165, v148
	v_mov_b32_e32 v157, v144
	v_add_f32_e32 v130, 1.0, v130
	v_rcp_f32_e32 v134, v130
	v_mul_f32_e32 v130, 0xbfb8aa3b, v192
	v_exp_f32_e32 v130, v130
	v_mov_b32_e32 v159, v149
	v_pk_mul_f32 v[134:135], v[134:135], v[162:163]
	v_mov_b32_e32 v155, v145
	v_add_f32_e32 v130, 1.0, v130
	v_rcp_f32_e32 v130, v130
	v_mul_f32_e32 v134, v134, v135
	v_mov_b32_e32 v191, v142
	v_pk_mul_f32 v[160:161], v[160:161], v[190:191]
	v_pk_mul_f32 v[130:131], v[130:131], v[192:193]
	v_mul_f32_e32 v142, v160, v161
	v_mul_f32_e32 v135, v130, v131
	v_mul_f32_e32 v130, 0xbfb8aa3b, v164
	v_exp_f32_e32 v130, v130
	v_mov_b32_e32 v131, v136
	v_lshlrev_b32_e32 v148, 16, v150
	v_and_b32_e32 v150, 0xffff0000, v150
	v_add_f32_e32 v130, 1.0, v130
	v_rcp_f32_e32 v130, v130
	s_nop 0
	v_pk_mul_f32 v[130:131], v[130:131], v[164:165]
	s_nop 0
	v_mul_f32_e32 v143, v130, v131
	v_mul_f32_e32 v130, 0xbfb8aa3b, v156
	v_exp_f32_e32 v130, v130
	v_mov_b32_e32 v131, v132
	v_add_f32_e32 v130, 1.0, v130
	v_rcp_f32_e32 v130, v130
	s_nop 0
	v_pk_mul_f32 v[130:131], v[130:131], v[156:157]
	s_nop 0
	v_mul_f32_e32 v144, v130, v131
	v_mul_f32_e32 v130, 0xbfb8aa3b, v158
	v_exp_f32_e32 v130, v130
	v_lshlrev_b32_e32 v156, 16, v152
	v_and_b32_e32 v152, 0xffff0000, v152
	v_add_f32_e32 v130, 1.0, v130
	v_rcp_f32_e32 v136, v130
	s_nop 0
	v_pk_mul_f32 v[130:131], v[136:137], v[158:159]
	s_nop 0
	v_mul_f32_e32 v136, v130, v131
	v_mul_f32_e32 v130, 0xbfb8aa3b, v154
	v_exp_f32_e32 v130, v130
	v_mov_b32_e32 v159, v126
	v_mul_f32_e32 v126, 0xbfb8aa3b, v156
	v_exp_f32_e32 v126, v126
	v_add_f32_e32 v130, 1.0, v130
	v_rcp_f32_e32 v132, v130
	v_add_f32_e32 v126, 1.0, v126
	v_pk_mul_f32 v[130:131], v[132:133], v[154:155]
	s_nop 0
	v_mul_f32_e32 v133, v130, v131
	v_cvt_pk_bf16_f32 v130, v146, v134
	v_cvt_pk_bf16_f32 v131, v143, v136
	v_cvt_pk_bf16_f32 v132, v142, v135
	v_cvt_pk_bf16_f32 v133, v144, v133
	global_store_dwordx4 v[188:189], v[130:133], off
	global_load_dwordx4 v[130:133], v[168:169], off offset:16
	s_nop 0
	global_load_dwordx4 v[134:137], v[168:169], off
	v_mul_f32_e32 v143, 0xbfb8aa3b, v148
	v_exp_f32_e32 v143, v143
	v_lshlrev_b32_e32 v154, 16, v151
	v_and_b32_e32 v144, 0xffff0000, v151
	v_lshlrev_b32_e32 v146, 16, v153
	v_add_f32_e32 v143, 1.0, v143
	v_rcp_f32_e32 v158, v143
	v_and_b32_e32 v142, 0xffff0000, v153
	s_waitcnt vmcnt(0)
	v_mov_b32_e32 v153, v131
	v_mov_b32_e32 v149, v134
	v_pk_mul_f32 v[148:149], v[158:159], v[148:149]
	v_mov_b32_e32 v151, v135
	v_mul_f32_e32 v134, v148, v149
	v_mov_b32_e32 v149, v118
	v_mul_f32_e32 v118, 0xbfb8aa3b, v150
	v_exp_f32_e32 v118, v118
	v_rcp_f32_e32 v148, v126
	v_mov_b32_e32 v155, v136
	v_mov_b32_e32 v147, v132
	v_add_f32_e32 v118, 1.0, v118
	v_rcp_f32_e32 v126, v118
	v_mul_f32_e32 v118, 0xbfb8aa3b, v152
	v_exp_f32_e32 v118, v118
	v_mov_b32_e32 v145, v137
	v_pk_mul_f32 v[126:127], v[126:127], v[150:151]
	v_mov_b32_e32 v143, v133
	v_add_f32_e32 v118, 1.0, v118
	v_rcp_f32_e32 v118, v118
	v_mul_f32_e32 v126, v126, v127
	v_mov_b32_e32 v157, v130
	v_pk_mul_f32 v[148:149], v[148:149], v[156:157]
	v_pk_mul_f32 v[118:119], v[118:119], v[152:153]
	v_mul_f32_e32 v130, v148, v149
	v_mul_f32_e32 v127, v118, v119
	v_mul_f32_e32 v118, 0xbfb8aa3b, v154
	v_exp_f32_e32 v118, v118
	v_mov_b32_e32 v119, v128
	v_lshlrev_b32_e32 v136, 16, v138
	v_and_b32_e32 v138, 0xffff0000, v138
	v_add_f32_e32 v118, 1.0, v118
	v_rcp_f32_e32 v118, v118
	s_nop 0
	v_pk_mul_f32 v[118:119], v[118:119], v[154:155]
	s_nop 0
	v_mul_f32_e32 v131, v118, v119
	v_mul_f32_e32 v118, 0xbfb8aa3b, v146
	v_exp_f32_e32 v118, v118
	v_mov_b32_e32 v119, v120
	v_add_f32_e32 v118, 1.0, v118
	v_rcp_f32_e32 v118, v118
	s_nop 0
	v_pk_mul_f32 v[118:119], v[118:119], v[146:147]
	s_nop 0
	v_mul_f32_e32 v132, v118, v119
	v_mul_f32_e32 v118, 0xbfb8aa3b, v144
	v_exp_f32_e32 v118, v118
	v_mov_b32_e32 v147, v110
	v_add_f32_e32 v118, 1.0, v118
	v_rcp_f32_e32 v128, v118
	s_nop 0
	v_pk_mul_f32 v[118:119], v[128:129], v[144:145]
	s_nop 0
	v_mul_f32_e32 v128, v118, v119
	v_mul_f32_e32 v118, 0xbfb8aa3b, v142
	v_exp_f32_e32 v118, v118
	v_lshlrev_b32_e32 v144, 16, v140
	v_mul_f32_e32 v110, 0xbfb8aa3b, v144
	v_exp_f32_e32 v110, v110
	v_add_f32_e32 v118, 1.0, v118
	v_rcp_f32_e32 v120, v118
	v_and_b32_e32 v140, 0xffff0000, v140
	v_add_f32_e32 v110, 1.0, v110
	v_pk_mul_f32 v[118:119], v[120:121], v[142:143]
	s_nop 0
	v_mul_f32_e32 v121, v118, v119
	v_cvt_pk_bf16_f32 v118, v134, v126
	v_cvt_pk_bf16_f32 v119, v131, v128
	v_cvt_pk_bf16_f32 v120, v130, v127
	v_cvt_pk_bf16_f32 v121, v132, v121
	global_store_dwordx4 v[186:187], v[118:121], off
	global_load_dwordx4 v[118:121], v[168:169], off offset:528
	s_nop 0
	global_load_dwordx4 v[126:129], v[168:169], off offset:512
	v_mul_f32_e32 v131, 0xbfb8aa3b, v136
	v_exp_f32_e32 v131, v131
	v_lshlrev_b32_e32 v142, 16, v139
	v_and_b32_e32 v132, 0xffff0000, v139
	v_lshlrev_b32_e32 v134, 16, v141
	v_add_f32_e32 v131, 1.0, v131
	v_rcp_f32_e32 v146, v131
	v_and_b32_e32 v130, 0xffff0000, v141
	s_waitcnt vmcnt(0)
; __device__ __forceinline__ float siluf_(float v) { return v * sigmoidf_(v); }
; __device__ __forceinline__ u32x4 pack8(f32x4 v0, f32x4 v1) { u32x4 w; w.x = cvt_pk_bf16(v0[0], v0[1]); w.y = cvt_pk_bf16(v0[2], v0[3]); w.z = cvt_pk_bf16(v1[0], v1[1]); w.w = cvt_pk_bf16(v1[2], v1[3]); return w; }
; __device__ __forceinline__ void unpack8(u32x4 w, f32x4& a, f32x4& b) { a = (f32x4){bf_lo(w.x), bf_hi(w.x), bf_lo(w.y), bf_hi(w.y)}; b = (f32x4){bf_lo(w.z), bf_hi(w.z), bf_lo(w.w), bf_hi(w.w)}; }
;     __device__ __forceinline__ void operator()(const f32x4 (&acc)[2][2][4][2], const Unit& u, int wr, int wc, int fr, int fq) const {
;     ...
;             [=](int row, int col, f32x4 v0, f32x4 v1, const u32x4& zz) __attribute__((always_inline)) {
;                 f32x4 z0, z1; unpack8(zz, z0, z1);
;                 const f32x4 s0 = *(const f32x4*)(ps_ + col); const f32x4 s1 = *(const f32x4*)(ps_ + col + 4);
; #pragma unroll
;                 for (int j = 0; j < 4; ++j) { v0[j] = v0[j] * s0[j] * siluf_(z0[j]); v1[j] = v1[j] * s1[j] * siluf_(z1[j]); }
;                 *(u32x4*)(proj_ + (size_t)row * NP + C_ZB + col) = pack8(v0, v1); });
	v_mov_b32_e32 v141, v119
	v_mov_b32_e32 v137, v126
	v_pk_mul_f32 v[136:137], v[146:147], v[136:137]
	v_mov_b32_e32 v139, v127
	v_mul_f32_e32 v126, v136, v137
	v_mov_b32_e32 v137, v106
	v_mul_f32_e32 v106, 0xbfb8aa3b, v138
	v_exp_f32_e32 v106, v106
	v_rcp_f32_e32 v136, v110
	v_mov_b32_e32 v143, v128
	v_mov_b32_e32 v135, v120
	v_add_f32_e32 v106, 1.0, v106
	v_rcp_f32_e32 v110, v106
	v_mul_f32_e32 v106, 0xbfb8aa3b, v140
	v_exp_f32_e32 v106, v106
	v_mov_b32_e32 v133, v129
	v_pk_mul_f32 v[110:111], v[110:111], v[138:139]
	v_mov_b32_e32 v131, v121
	v_add_f32_e32 v106, 1.0, v106
	v_rcp_f32_e32 v106, v106
	v_mul_f32_e32 v110, v110, v111
	v_mov_b32_e32 v145, v118
	v_pk_mul_f32 v[136:137], v[136:137], v[144:145]
	v_pk_mul_f32 v[106:107], v[106:107], v[140:141]
	v_mul_f32_e32 v118, v136, v137
	v_mul_f32_e32 v111, v106, v107
	v_mul_f32_e32 v106, 0xbfb8aa3b, v142
	v_exp_f32_e32 v106, v106
	v_mov_b32_e32 v107, v112
	v_and_b32_e32 v128, 0xffff0000, v122
	v_add_f32_e32 v106, 1.0, v106
	v_rcp_f32_e32 v106, v106
	s_nop 0
	v_pk_mul_f32 v[106:107], v[106:107], v[142:143]
	s_nop 0
	v_mul_f32_e32 v119, v106, v107
	v_mul_f32_e32 v106, 0xbfb8aa3b, v134
	v_exp_f32_e32 v106, v106
	v_mov_b32_e32 v107, v108
	v_add_f32_e32 v106, 1.0, v106
	v_rcp_f32_e32 v106, v106
	s_nop 0
	v_pk_mul_f32 v[106:107], v[106:107], v[134:135]
	s_nop 0
	v_mul_f32_e32 v120, v106, v107
	v_mul_f32_e32 v106, 0xbfb8aa3b, v132
	v_exp_f32_e32 v106, v106
	v_mov_b32_e32 v135, v98
	v_add_f32_e32 v106, 1.0, v106
	v_rcp_f32_e32 v112, v106
	s_nop 0
	v_pk_mul_f32 v[106:107], v[112:113], v[132:133]
	s_nop 0
	v_mul_f32_e32 v112, v106, v107
	v_mul_f32_e32 v106, 0xbfb8aa3b, v130
	v_exp_f32_e32 v106, v106
	v_lshlrev_b32_e32 v132, 16, v124
	v_mul_f32_e32 v98, 0xbfb8aa3b, v132
	v_exp_f32_e32 v98, v98
	v_add_f32_e32 v106, 1.0, v106
	v_rcp_f32_e32 v108, v106
	v_and_b32_e32 v124, 0xffff0000, v124
	v_add_f32_e32 v98, 1.0, v98
	v_pk_mul_f32 v[106:107], v[108:109], v[130:131]
	s_nop 0
	v_mul_f32_e32 v109, v106, v107
	v_cvt_pk_bf16_f32 v106, v126, v110
	v_cvt_pk_bf16_f32 v107, v119, v112
	v_cvt_pk_bf16_f32 v108, v118, v111
	v_cvt_pk_bf16_f32 v109, v120, v109
	global_store_dwordx4 v[184:185], v[106:109], off
	global_load_dwordx4 v[106:109], v[168:169], off offset:16
	s_nop 0
	global_load_dwordx4 v[110:113], v[168:169], off
	v_lshlrev_b32_e32 v126, 16, v122
	v_mul_f32_e32 v119, 0xbfb8aa3b, v126
	v_exp_f32_e32 v119, v119
	v_lshlrev_b32_e32 v122, 16, v125
	v_and_b32_e32 v118, 0xffff0000, v125
	v_lshlrev_b32_e32 v130, 16, v123
	v_add_f32_e32 v119, 1.0, v119
	v_rcp_f32_e32 v134, v119
	v_and_b32_e32 v120, 0xffff0000, v123
	s_waitcnt vmcnt(0)
	v_mov_b32_e32 v125, v107
	v_mov_b32_e32 v127, v110
	v_pk_mul_f32 v[126:127], v[134:135], v[126:127]
	v_mov_b32_e32 v129, v111
	v_mul_f32_e32 v110, v126, v127
	v_mov_b32_e32 v127, v94
	v_mul_f32_e32 v94, 0xbfb8aa3b, v128
	v_exp_f32_e32 v94, v94
	v_rcp_f32_e32 v126, v98
	v_mov_b32_e32 v131, v112
	v_mov_b32_e32 v123, v108
	v_add_f32_e32 v94, 1.0, v94
	v_rcp_f32_e32 v98, v94
	v_mul_f32_e32 v94, 0xbfb8aa3b, v124
	v_exp_f32_e32 v94, v94
	v_mov_b32_e32 v121, v113
	v_pk_mul_f32 v[98:99], v[98:99], v[128:129]
	v_mov_b32_e32 v119, v109
	v_add_f32_e32 v94, 1.0, v94
	v_rcp_f32_e32 v94, v94
	v_mul_f32_e32 v98, v98, v99
	v_mov_b32_e32 v133, v106
	v_pk_mul_f32 v[126:127], v[126:127], v[132:133]
	v_pk_mul_f32 v[94:95], v[94:95], v[124:125]
	v_mul_f32_e32 v106, v126, v127
	v_mul_f32_e32 v99, v94, v95
	v_mul_f32_e32 v94, 0xbfb8aa3b, v130
	v_exp_f32_e32 v94, v94
	v_mov_b32_e32 v95, v100
	v_lshlrev_b32_e32 v112, 16, v114
	v_and_b32_e32 v114, 0xffff0000, v114
	v_add_f32_e32 v94, 1.0, v94
	v_rcp_f32_e32 v94, v94
	v_mov_b32_e32 v135, v62
	v_pk_mul_f32 v[94:95], v[94:95], v[130:131]
	s_nop 0
	v_mul_f32_e32 v107, v94, v95
	v_mul_f32_e32 v94, 0xbfb8aa3b, v122
	v_exp_f32_e32 v94, v94
	v_mov_b32_e32 v95, v96
	v_add_f32_e32 v94, 1.0, v94
	v_rcp_f32_e32 v94, v94
	s_nop 0
	v_pk_mul_f32 v[94:95], v[94:95], v[122:123]
	s_nop 0
	v_mul_f32_e32 v108, v94, v95
	v_mul_f32_e32 v94, 0xbfb8aa3b, v120
	v_exp_f32_e32 v94, v94
	v_mov_b32_e32 v123, v86
	v_add_f32_e32 v94, 1.0, v94
	v_rcp_f32_e32 v100, v94
	s_nop 0
	v_pk_mul_f32 v[94:95], v[100:101], v[120:121]
	s_nop 0
	v_mul_f32_e32 v100, v94, v95
	v_mul_f32_e32 v94, 0xbfb8aa3b, v118
	v_exp_f32_e32 v94, v94
	v_lshlrev_b32_e32 v120, 16, v116
	v_mul_f32_e32 v86, 0xbfb8aa3b, v120
	v_exp_f32_e32 v86, v86
	v_add_f32_e32 v94, 1.0, v94
	v_rcp_f32_e32 v96, v94
	v_and_b32_e32 v116, 0xffff0000, v116
	v_add_f32_e32 v86, 1.0, v86
	v_pk_mul_f32 v[94:95], v[96:97], v[118:119]
	s_nop 0
	v_mul_f32_e32 v97, v94, v95
	v_cvt_pk_bf16_f32 v94, v110, v98
	v_cvt_pk_bf16_f32 v95, v107, v100
	v_cvt_pk_bf16_f32 v96, v106, v99
	v_cvt_pk_bf16_f32 v97, v108, v97
	global_store_dwordx4 v[182:183], v[94:97], off
	global_load_dwordx4 v[94:97], v[168:169], off offset:528
	s_nop 0
	global_load_dwordx4 v[98:101], v[168:169], off offset:512
	v_mul_f32_e32 v107, 0xbfb8aa3b, v112
	v_exp_f32_e32 v107, v107
	v_lshlrev_b32_e32 v118, 16, v115
	v_and_b32_e32 v108, 0xffff0000, v115
	v_lshlrev_b32_e32 v110, 16, v117
	v_add_f32_e32 v107, 1.0, v107
	v_rcp_f32_e32 v122, v107
	v_and_b32_e32 v106, 0xffff0000, v117
	s_waitcnt vmcnt(0)
; __device__ __forceinline__ float siluf_(float v) { return v * sigmoidf_(v); }
; __device__ __forceinline__ u32x4 pack8(f32x4 v0, f32x4 v1) { u32x4 w; w.x = cvt_pk_bf16(v0[0], v0[1]); w.y = cvt_pk_bf16(v0[2], v0[3]); w.z = cvt_pk_bf16(v1[0], v1[1]); w.w = cvt_pk_bf16(v1[2], v1[3]); return w; }
; __device__ __forceinline__ void unpack8(u32x4 w, f32x4& a, f32x4& b) { a = (f32x4){bf_lo(w.x), bf_hi(w.x), bf_lo(w.y), bf_hi(w.y)}; b = (f32x4){bf_lo(w.z), bf_hi(w.z), bf_lo(w.w), bf_hi(w.w)}; }
;     __device__ __forceinline__ void operator()(const f32x4 (&acc)[2][2][4][2], const Unit& u, int wr, int wc, int fr, int fq) const {
;     ...
;             [=](int row, int col, f32x4 v0, f32x4 v1, const u32x4& zz) __attribute__((always_inline)) {
;                 f32x4 z0, z1; unpack8(zz, z0, z1);
;                 const f32x4 s0 = *(const f32x4*)(ps_ + col); const f32x4 s1 = *(const f32x4*)(ps_ + col + 4);
; #pragma unroll
;                 for (int j = 0; j < 4; ++j) { v0[j] = v0[j] * s0[j] * siluf_(z0[j]); v1[j] = v1[j] * s1[j] * siluf_(z1[j]); }
;                 *(u32x4*)(proj_ + (size_t)row * NP + C_ZB + col) = pack8(v0, v1); });
	v_mov_b32_e32 v117, v95
	v_mov_b32_e32 v113, v98
	v_pk_mul_f32 v[112:113], v[122:123], v[112:113]
	v_mov_b32_e32 v115, v99
	v_mul_f32_e32 v98, v112, v113
	v_mov_b32_e32 v113, v82
	v_mul_f32_e32 v82, 0xbfb8aa3b, v114
	v_exp_f32_e32 v82, v82
	v_rcp_f32_e32 v112, v86
	v_mov_b32_e32 v119, v100
	v_mov_b32_e32 v111, v96
	v_add_f32_e32 v82, 1.0, v82
	v_rcp_f32_e32 v86, v82
	v_mul_f32_e32 v82, 0xbfb8aa3b, v116
	v_exp_f32_e32 v82, v82
	v_mov_b32_e32 v109, v101
	v_pk_mul_f32 v[86:87], v[86:87], v[114:115]
	v_mov_b32_e32 v107, v97
	v_add_f32_e32 v82, 1.0, v82
	v_rcp_f32_e32 v82, v82
	v_mul_f32_e32 v86, v86, v87
	v_mov_b32_e32 v121, v94
	v_pk_mul_f32 v[112:113], v[112:113], v[120:121]
	v_pk_mul_f32 v[82:83], v[82:83], v[116:117]
	v_mul_f32_e32 v94, v112, v113
	v_mul_f32_e32 v87, v82, v83
	v_mul_f32_e32 v82, 0xbfb8aa3b, v118
	v_exp_f32_e32 v82, v82
	v_mov_b32_e32 v83, v88
	v_lshlrev_b32_e32 v100, 16, v102
	v_and_b32_e32 v102, 0xffff0000, v102
	v_add_f32_e32 v82, 1.0, v82
	v_rcp_f32_e32 v82, v82
	s_nop 0
	v_pk_mul_f32 v[82:83], v[82:83], v[118:119]
	s_nop 0
	v_mul_f32_e32 v95, v82, v83
	v_mul_f32_e32 v82, 0xbfb8aa3b, v110
	v_exp_f32_e32 v82, v82
	v_mov_b32_e32 v83, v84
	v_add_f32_e32 v82, 1.0, v82
	v_rcp_f32_e32 v82, v82
	s_nop 0
	v_pk_mul_f32 v[82:83], v[82:83], v[110:111]
	s_nop 0
	v_mul_f32_e32 v96, v82, v83
	v_mul_f32_e32 v82, 0xbfb8aa3b, v108
	v_exp_f32_e32 v82, v82
	v_mov_b32_e32 v111, v78
	v_add_f32_e32 v82, 1.0, v82
	v_rcp_f32_e32 v88, v82
	s_nop 0
	v_pk_mul_f32 v[82:83], v[88:89], v[108:109]
	s_nop 0
	v_mul_f32_e32 v88, v82, v83
	v_mul_f32_e32 v82, 0xbfb8aa3b, v106
	v_exp_f32_e32 v82, v82
	v_lshlrev_b32_e32 v108, 16, v104
	v_mul_f32_e32 v78, 0xbfb8aa3b, v108
	v_exp_f32_e32 v78, v78
	v_add_f32_e32 v82, 1.0, v82
	v_rcp_f32_e32 v84, v82
	v_and_b32_e32 v104, 0xffff0000, v104
	v_add_f32_e32 v78, 1.0, v78
	v_pk_mul_f32 v[82:83], v[84:85], v[106:107]
	s_nop 0
	v_mul_f32_e32 v85, v82, v83
	v_cvt_pk_bf16_f32 v82, v98, v86
	v_cvt_pk_bf16_f32 v83, v95, v88
	v_cvt_pk_bf16_f32 v84, v94, v87
	v_cvt_pk_bf16_f32 v85, v96, v85
	global_store_dwordx4 v[180:181], v[82:85], off
	global_load_dwordx4 v[82:85], v[168:169], off offset:16
	s_nop 0
	global_load_dwordx4 v[86:89], v[168:169], off
	v_mul_f32_e32 v95, 0xbfb8aa3b, v100
	v_exp_f32_e32 v95, v95
	v_lshlrev_b32_e32 v106, 16, v103
	v_and_b32_e32 v96, 0xffff0000, v103
	v_lshlrev_b32_e32 v98, 16, v105
	v_add_f32_e32 v95, 1.0, v95
	v_rcp_f32_e32 v110, v95
	v_and_b32_e32 v94, 0xffff0000, v105
	s_waitcnt vmcnt(0)
	v_mov_b32_e32 v105, v83
	v_mov_b32_e32 v101, v86
	v_pk_mul_f32 v[100:101], v[110:111], v[100:101]
	v_mov_b32_e32 v103, v87
	v_mul_f32_e32 v86, v100, v101
	v_mov_b32_e32 v101, v74
	v_mul_f32_e32 v74, 0xbfb8aa3b, v102
	v_exp_f32_e32 v74, v74
	v_rcp_f32_e32 v100, v78
	v_mov_b32_e32 v107, v88
	v_mov_b32_e32 v99, v84
	v_add_f32_e32 v74, 1.0, v74
	v_rcp_f32_e32 v78, v74
	v_mul_f32_e32 v74, 0xbfb8aa3b, v104
	v_exp_f32_e32 v74, v74
	v_mov_b32_e32 v97, v89
	v_pk_mul_f32 v[78:79], v[78:79], v[102:103]
	v_mov_b32_e32 v95, v85
	v_add_f32_e32 v74, 1.0, v74
	v_rcp_f32_e32 v74, v74
	v_mul_f32_e32 v78, v78, v79
	v_mov_b32_e32 v109, v82
	v_pk_mul_f32 v[100:101], v[100:101], v[108:109]
	v_pk_mul_f32 v[74:75], v[74:75], v[104:105]
	v_mul_f32_e32 v82, v100, v101
	v_mul_f32_e32 v79, v74, v75
	v_mul_f32_e32 v74, 0xbfb8aa3b, v106
	v_exp_f32_e32 v74, v74
	v_mov_b32_e32 v75, v80
	v_lshlrev_b32_e32 v88, 16, v90
	v_and_b32_e32 v90, 0xffff0000, v90
	v_add_f32_e32 v74, 1.0, v74
	v_rcp_f32_e32 v74, v74
	s_nop 0
	v_pk_mul_f32 v[74:75], v[74:75], v[106:107]
	s_nop 0
	v_mul_f32_e32 v83, v74, v75
	v_mul_f32_e32 v74, 0xbfb8aa3b, v98
	v_exp_f32_e32 v74, v74
	v_mov_b32_e32 v75, v76
	v_add_f32_e32 v74, 1.0, v74
	v_rcp_f32_e32 v74, v74
	s_nop 0
	v_pk_mul_f32 v[74:75], v[74:75], v[98:99]
	s_nop 0
	v_mul_f32_e32 v84, v74, v75
	v_mul_f32_e32 v74, 0xbfb8aa3b, v96
	v_exp_f32_e32 v74, v74
	v_mov_b32_e32 v99, v70
	v_add_f32_e32 v74, 1.0, v74
	v_rcp_f32_e32 v80, v74
	s_nop 0
	v_pk_mul_f32 v[74:75], v[80:81], v[96:97]
	s_nop 0
	v_mul_f32_e32 v80, v74, v75
	v_mul_f32_e32 v74, 0xbfb8aa3b, v94
	v_exp_f32_e32 v74, v74
	v_lshlrev_b32_e32 v96, 16, v92
	v_mul_f32_e32 v70, 0xbfb8aa3b, v96
	v_exp_f32_e32 v70, v70
	v_add_f32_e32 v74, 1.0, v74
	v_rcp_f32_e32 v76, v74
	v_and_b32_e32 v92, 0xffff0000, v92
	v_add_f32_e32 v70, 1.0, v70
	v_pk_mul_f32 v[74:75], v[76:77], v[94:95]
	s_nop 0
	v_mul_f32_e32 v77, v74, v75
	v_cvt_pk_bf16_f32 v74, v86, v78
	v_cvt_pk_bf16_f32 v75, v83, v80
	v_cvt_pk_bf16_f32 v76, v82, v79
	v_cvt_pk_bf16_f32 v77, v84, v77
	global_store_dwordx4 v[178:179], v[74:77], off
	global_load_dwordx4 v[74:77], v[168:169], off offset:528
	s_nop 0
	global_load_dwordx4 v[84:87], v[168:169], off offset:512
	v_mul_f32_e32 v79, 0xbfb8aa3b, v88
	v_exp_f32_e32 v79, v79
	v_lshlrev_b32_e32 v94, 16, v91
	v_and_b32_e32 v80, 0xffff0000, v91
	v_lshlrev_b32_e32 v82, 16, v93
	v_add_f32_e32 v79, 1.0, v79
	v_rcp_f32_e32 v98, v79
	v_and_b32_e32 v78, 0xffff0000, v93
	s_waitcnt vmcnt(0)
; __device__ __forceinline__ float siluf_(float v) { return v * sigmoidf_(v); }
; __device__ __forceinline__ u32x4 pack8(f32x4 v0, f32x4 v1) { u32x4 w; w.x = cvt_pk_bf16(v0[0], v0[1]); w.y = cvt_pk_bf16(v0[2], v0[3]); w.z = cvt_pk_bf16(v1[0], v1[1]); w.w = cvt_pk_bf16(v1[2], v1[3]); return w; }
; __device__ __forceinline__ void unpack8(u32x4 w, f32x4& a, f32x4& b) { a = (f32x4){bf_lo(w.x), bf_hi(w.x), bf_lo(w.y), bf_hi(w.y)}; b = (f32x4){bf_lo(w.z), bf_hi(w.z), bf_lo(w.w), bf_hi(w.w)}; }
;     __device__ __forceinline__ void operator()(const f32x4 (&acc)[2][2][4][2], const Unit& u, int wr, int wc, int fr, int fq) const {
;     ...
;         epi_perm2<u32x4>(acc, u, wr, wc, fr, fq,
;             [=](int row, int col) __attribute__((always_inline)) { return *(const u32x4*)(proj_ + (size_t)row * NP + C_ZB + col); },
;             [=](int row, int col, f32x4 v0, f32x4 v1, const u32x4& zz) __attribute__((always_inline)) {
;                 f32x4 z0, z1; unpack8(zz, z0, z1);
;                 const f32x4 s0 = *(const f32x4*)(ps_ + col); const f32x4 s1 = *(const f32x4*)(ps_ + col + 4);
; #pragma unroll
;                 for (int j = 0; j < 4; ++j) { v0[j] = v0[j] * s0[j] * siluf_(z0[j]); v1[j] = v1[j] * s1[j] * siluf_(z1[j]); }
;                 *(u32x4*)(proj_ + (size_t)row * NP + C_ZB + col) = pack8(v0, v1); });
	v_mov_b32_e32 v93, v75
	v_mov_b32_e32 v89, v84
	v_pk_mul_f32 v[88:89], v[98:99], v[88:89]
	v_mov_b32_e32 v91, v85
	v_mul_f32_e32 v84, v88, v89
	v_mov_b32_e32 v89, v66
	v_mul_f32_e32 v66, 0xbfb8aa3b, v90
	v_exp_f32_e32 v66, v66
	v_rcp_f32_e32 v88, v70
	v_mov_b32_e32 v95, v86
	v_mov_b32_e32 v83, v76
	v_add_f32_e32 v66, 1.0, v66
	v_rcp_f32_e32 v70, v66
	v_mul_f32_e32 v66, 0xbfb8aa3b, v92
	v_exp_f32_e32 v66, v66
	v_mov_b32_e32 v81, v87
	v_pk_mul_f32 v[70:71], v[70:71], v[90:91]
	v_mov_b32_e32 v79, v77
	v_add_f32_e32 v66, 1.0, v66
	v_rcp_f32_e32 v66, v66
	v_mul_f32_e32 v70, v70, v71
	v_mov_b32_e32 v97, v74
	v_pk_mul_f32 v[88:89], v[88:89], v[96:97]
	v_pk_mul_f32 v[66:67], v[66:67], v[92:93]
	v_mul_f32_e32 v74, v88, v89
	v_mul_f32_e32 v71, v66, v67
	v_mul_f32_e32 v66, 0xbfb8aa3b, v94
	v_exp_f32_e32 v66, v66
	v_mov_b32_e32 v67, v72
	v_add_f32_e32 v66, 1.0, v66
	v_rcp_f32_e32 v66, v66
	s_nop 0
	v_pk_mul_f32 v[66:67], v[66:67], v[94:95]
	s_nop 0
	v_mul_f32_e32 v75, v66, v67
	v_mul_f32_e32 v66, 0xbfb8aa3b, v82
	v_exp_f32_e32 v66, v66
	v_mov_b32_e32 v67, v68
	v_add_f32_e32 v66, 1.0, v66
	v_rcp_f32_e32 v66, v66
	s_nop 0
	v_pk_mul_f32 v[66:67], v[66:67], v[82:83]
	s_nop 0
	v_mul_f32_e32 v76, v66, v67
	v_mul_f32_e32 v66, 0xbfb8aa3b, v80
	v_exp_f32_e32 v66, v66
	s_nop 0
	v_add_f32_e32 v66, 1.0, v66
	v_rcp_f32_e32 v72, v66
	s_nop 0
	v_pk_mul_f32 v[66:67], v[72:73], v[80:81]
	s_nop 0
	v_mul_f32_e32 v72, v66, v67
	v_mul_f32_e32 v66, 0xbfb8aa3b, v78
	v_exp_f32_e32 v66, v66
	s_nop 0
	v_add_f32_e32 v66, 1.0, v66
	v_rcp_f32_e32 v68, v66
	s_nop 0
	v_pk_mul_f32 v[66:67], v[68:69], v[78:79]
	s_nop 0
	v_mul_f32_e32 v69, v66, v67
	v_cvt_pk_bf16_f32 v66, v84, v70
	v_cvt_pk_bf16_f32 v67, v75, v72
	v_cvt_pk_bf16_f32 v68, v74, v71
	v_cvt_pk_bf16_f32 v69, v76, v69
	global_store_dwordx4 v[176:177], v[66:69], off
	s_nop 1
	v_add_u32_e32 v66, 0x80, v214
	v_mad_i64_i32 v[66:67], s[0:1], v66, s31, v[170:171]
	v_lshl_add_u64 v[66:67], v[66:67], 0, s[12:13]
	v_lshl_add_u64 v[116:117], v[66:67], 0, v[172:173]
	global_load_dwordx4 v[94:97], v[116:117], off
	v_lshl_add_u64 v[114:115], v[66:67], 0, v[174:175]
	v_add_u32_e32 v66, 0x90, v214
	v_mad_i64_i32 v[66:67], s[0:1], v66, s31, v[170:171]
	v_lshl_add_u64 v[66:67], v[66:67], 0, s[12:13]
	v_lshl_add_u64 v[112:113], v[66:67], 0, v[172:173]
	v_lshl_add_u64 v[110:111], v[66:67], 0, v[174:175]
	v_add_u32_e32 v66, 0xa0, v214
	v_mad_i64_i32 v[66:67], s[0:1], v66, s31, v[170:171]
	v_lshl_add_u64 v[66:67], v[66:67], 0, s[12:13]
	v_lshl_add_u64 v[108:109], v[66:67], 0, v[172:173]
	v_lshl_add_u64 v[106:107], v[66:67], 0, v[174:175]
	v_add_u32_e32 v66, 0xb0, v214
	v_mad_i64_i32 v[66:67], s[0:1], v66, s31, v[170:171]
	v_lshl_add_u64 v[66:67], v[66:67], 0, s[12:13]
	v_lshl_add_u64 v[104:105], v[66:67], 0, v[172:173]
	v_lshl_add_u64 v[102:103], v[66:67], 0, v[174:175]
	global_load_dwordx4 v[90:93], v[114:115], off
	global_load_dwordx4 v[86:89], v[112:113], off
	global_load_dwordx4 v[82:85], v[110:111], off
	global_load_dwordx4 v[78:81], v[108:109], off
	global_load_dwordx4 v[74:77], v[106:107], off
	global_load_dwordx4 v[70:73], v[104:105], off
	global_load_dwordx4 v[66:69], v[102:103], off
	v_readlane_b32 s0, v255, 4
	v_readlane_b32 s1, v255, 5
	s_mov_b64 s[12:13], -1
	s_andn2_b64 vcc, exec, s[0:1]
	s_waitcnt vmcnt(0) lgkmcnt(0)
	v_lshlrev_b32_e32 v126, 16, v94
	v_and_b32_e32 v128, 0xffff0000, v94
	v_lshlrev_b32_e32 v124, 16, v95
	v_and_b32_e32 v120, 0xffff0000, v95
	v_lshlrev_b32_e32 v130, 16, v96
	v_and_b32_e32 v132, 0xffff0000, v96
	v_lshlrev_b32_e32 v122, 16, v97
	v_and_b32_e32 v118, 0xffff0000, v97
	global_load_dwordx4 v[94:97], v[168:169], off offset:16
	global_load_dwordx4 v[98:101], v[168:169], off
	v_mul_f32_e32 v119, 0xbfb8aa3b, v126
	v_exp_f32_e32 v119, v119
	v_mul_f32_e32 v62, 0xbfb8aa3b, v130
	v_exp_f32_e32 v62, v62
	v_add_f32_e32 v119, 1.0, v119
	v_rcp_f32_e32 v134, v119
	v_add_f32_e32 v62, 1.0, v62
	s_waitcnt vmcnt(1)
	v_mov_b32_e32 v133, v95
	s_waitcnt vmcnt(0)
	v_mov_b32_e32 v127, v98
	v_pk_mul_f32 v[126:127], v[134:135], v[126:127]
	v_mov_b32_e32 v131, v94
	v_mul_f32_e32 v98, v126, v127
	v_mov_b32_e32 v127, v58
	v_mul_f32_e32 v58, 0xbfb8aa3b, v128
	v_exp_f32_e32 v58, v58
	v_rcp_f32_e32 v126, v62
	v_mov_b32_e32 v125, v100
	v_mov_b32_e32 v129, v99
	v_add_f32_e32 v58, 1.0, v58
	v_rcp_f32_e32 v62, v58
	v_mul_f32_e32 v58, 0xbfb8aa3b, v132
	v_exp_f32_e32 v58, v58
	v_pk_mul_f32 v[126:127], v[126:127], v[130:131]
	v_pk_mul_f32 v[62:63], v[62:63], v[128:129]
	v_mul_f32_e32 v94, v126, v127
	v_add_f32_e32 v58, 1.0, v58
	v_rcp_f32_e32 v58, v58
	v_mov_b32_e32 v127, v64
	v_mul_f32_e32 v62, v62, v63
	v_mul_f32_e32 v63, 0xbfb8aa3b, v122
	v_pk_mul_f32 v[58:59], v[58:59], v[132:133]
	v_exp_f32_e32 v63, v63
	v_mul_f32_e32 v58, v58, v59
	v_mul_f32_e32 v59, 0xbfb8aa3b, v124
	v_exp_f32_e32 v59, v59
	v_add_f32_e32 v63, 1.0, v63
	v_mov_b32_e32 v123, v96
	v_mov_b32_e32 v121, v101
	v_add_f32_e32 v59, 1.0, v59
	v_rcp_f32_e32 v126, v59
	v_mov_b32_e32 v119, v97
	v_lshlrev_b32_e32 v96, 16, v90
	v_lshlrev_b32_e32 v100, 16, v91
	v_pk_mul_f32 v[124:125], v[126:127], v[124:125]
	s_nop 0
	v_mul_f32_e32 v59, v124, v125
	v_mov_b32_e32 v125, v60
	v_mul_f32_e32 v60, 0xbfb8aa3b, v120
	v_exp_f32_e32 v60, v60
	v_rcp_f32_e32 v124, v63
	v_add_f32_e32 v60, 1.0, v60
	v_rcp_f32_e32 v64, v60
	v_mul_f32_e32 v60, 0xbfb8aa3b, v118
	v_exp_f32_e32 v60, v60
	v_pk_mul_f32 v[122:123], v[124:125], v[122:123]
	v_pk_mul_f32 v[64:65], v[64:65], v[120:121]
	v_mul_f32_e32 v63, v122, v123
	v_add_f32_e32 v60, 1.0, v60
	v_rcp_f32_e32 v60, v60
	v_mul_f32_e32 v64, v64, v65
	v_mov_b32_e32 v121, v54
	v_pk_mul_f32 v[60:61], v[60:61], v[118:119]
	s_nop 0
	v_mul_f32_e32 v65, v60, v61
	v_cvt_pk_bf16_f32 v60, v98, v62
	v_cvt_pk_bf16_f32 v61, v59, v64
	v_cvt_pk_bf16_f32 v62, v94, v58
	v_cvt_pk_bf16_f32 v63, v63, v65
	global_store_dwordx4 v[116:117], v[60:63], off
	global_load_dwordx4 v[58:61], v[168:169], off offset:528
	s_nop 0
	global_load_dwordx4 v[62:65], v[168:169], off offset:512
	v_and_b32_e32 v94, 0xffff0000, v91
	v_mul_f32_e32 v91, 0xbfb8aa3b, v96
	v_exp_f32_e32 v91, v91
	v_and_b32_e32 v98, 0xffff0000, v90
	v_lshlrev_b32_e32 v116, 16, v92
	v_mul_f32_e32 v54, 0xbfb8aa3b, v116
	v_add_f32_e32 v91, 1.0, v91
	v_rcp_f32_e32 v120, v91
	v_exp_f32_e32 v54, v54
	v_and_b32_e32 v118, 0xffff0000, v92
	v_lshlrev_b32_e32 v92, 16, v93
	v_and_b32_e32 v90, 0xffff0000, v93
	v_add_f32_e32 v54, 1.0, v54
	s_waitcnt vmcnt(0)
; __device__ __forceinline__ float siluf_(float v) { return v * sigmoidf_(v); }
; __device__ __forceinline__ u32x4 pack8(f32x4 v0, f32x4 v1) { u32x4 w; w.x = cvt_pk_bf16(v0[0], v0[1]); w.y = cvt_pk_bf16(v0[2], v0[3]); w.z = cvt_pk_bf16(v1[0], v1[1]); w.w = cvt_pk_bf16(v1[2], v1[3]); return w; }
; __device__ __forceinline__ void unpack8(u32x4 w, f32x4& a, f32x4& b) { a = (f32x4){bf_lo(w.x), bf_hi(w.x), bf_lo(w.y), bf_hi(w.y)}; b = (f32x4){bf_lo(w.z), bf_hi(w.z), bf_lo(w.w), bf_hi(w.w)}; }
;     __device__ __forceinline__ void operator()(const f32x4 (&acc)[2][2][4][2], const Unit& u, int wr, int wc, int fr, int fq) const {
;     ...
;         epi_perm2<u32x4>(acc, u, wr, wc, fr, fq,
;             [=](int row, int col) __attribute__((always_inline)) { return *(const u32x4*)(proj_ + (size_t)row * NP + C_ZB + col); },
;             [=](int row, int col, f32x4 v0, f32x4 v1, const u32x4& zz) __attribute__((always_inline)) {
;                 f32x4 z0, z1; unpack8(zz, z0, z1);
;                 const f32x4 s0 = *(const f32x4*)(ps_ + col); const f32x4 s1 = *(const f32x4*)(ps_ + col + 4);
; #pragma unroll
;                 for (int j = 0; j < 4; ++j) { v0[j] = v0[j] * s0[j] * siluf_(z0[j]); v1[j] = v1[j] * s1[j] * siluf_(z1[j]); }
;                 *(u32x4*)(proj_ + (size_t)row * NP + C_ZB + col) = pack8(v0, v1); });
	v_mov_b32_e32 v119, v59
	v_mov_b32_e32 v97, v62
	v_pk_mul_f32 v[96:97], v[120:121], v[96:97]
	v_mov_b32_e32 v99, v63
	v_mul_f32_e32 v62, v96, v97
	v_mov_b32_e32 v97, v50
	v_mul_f32_e32 v50, 0xbfb8aa3b, v98
	v_exp_f32_e32 v50, v50
	v_rcp_f32_e32 v96, v54
	v_mov_b32_e32 v101, v64
	v_mov_b32_e32 v93, v60
	v_add_f32_e32 v50, 1.0, v50
	v_rcp_f32_e32 v54, v50
	v_mul_f32_e32 v50, 0xbfb8aa3b, v118
	v_exp_f32_e32 v50, v50
	v_mov_b32_e32 v95, v65
	v_pk_mul_f32 v[54:55], v[54:55], v[98:99]
	v_mov_b32_e32 v91, v61
	v_add_f32_e32 v50, 1.0, v50
	v_rcp_f32_e32 v50, v50
	v_mul_f32_e32 v54, v54, v55
	v_mov_b32_e32 v117, v58
	v_pk_mul_f32 v[96:97], v[96:97], v[116:117]
	v_pk_mul_f32 v[50:51], v[50:51], v[118:119]
	v_mul_f32_e32 v58, v96, v97
	v_mul_f32_e32 v55, v50, v51
	v_mul_f32_e32 v50, 0xbfb8aa3b, v100
	v_exp_f32_e32 v50, v50
	v_mov_b32_e32 v51, v56
	v_lshlrev_b32_e32 v64, 16, v86
	v_and_b32_e32 v86, 0xffff0000, v86
	v_add_f32_e32 v50, 1.0, v50
	v_rcp_f32_e32 v50, v50
	s_nop 0
	v_pk_mul_f32 v[50:51], v[50:51], v[100:101]
	s_nop 0
	v_mul_f32_e32 v59, v50, v51
	v_mul_f32_e32 v50, 0xbfb8aa3b, v92
	v_exp_f32_e32 v50, v50
	v_mov_b32_e32 v51, v52
	v_add_f32_e32 v50, 1.0, v50
	v_rcp_f32_e32 v50, v50
	s_nop 0
	v_pk_mul_f32 v[50:51], v[50:51], v[92:93]
	s_nop 0
	v_mul_f32_e32 v60, v50, v51
	v_mul_f32_e32 v50, 0xbfb8aa3b, v94
	v_exp_f32_e32 v50, v50
	v_lshlrev_b32_e32 v92, 16, v88
	v_and_b32_e32 v88, 0xffff0000, v88
	v_add_f32_e32 v50, 1.0, v50
	v_rcp_f32_e32 v56, v50
	s_nop 0
	v_pk_mul_f32 v[50:51], v[56:57], v[94:95]
	s_nop 0
	v_mul_f32_e32 v56, v50, v51
	v_mul_f32_e32 v50, 0xbfb8aa3b, v90
	v_exp_f32_e32 v50, v50
	v_mov_b32_e32 v95, v46
	v_mul_f32_e32 v46, 0xbfb8aa3b, v92
	v_exp_f32_e32 v46, v46
	v_add_f32_e32 v50, 1.0, v50
	v_rcp_f32_e32 v52, v50
	v_add_f32_e32 v46, 1.0, v46
	v_pk_mul_f32 v[50:51], v[52:53], v[90:91]
	s_nop 0
	v_mul_f32_e32 v53, v50, v51
	v_cvt_pk_bf16_f32 v50, v62, v54
	v_cvt_pk_bf16_f32 v51, v59, v56
	v_cvt_pk_bf16_f32 v52, v58, v55
	v_cvt_pk_bf16_f32 v53, v60, v53
	global_store_dwordx4 v[114:115], v[50:53], off
	global_load_dwordx4 v[50:53], v[168:169], off offset:16
	s_nop 0
	global_load_dwordx4 v[54:57], v[168:169], off
	v_mul_f32_e32 v59, 0xbfb8aa3b, v64
	v_exp_f32_e32 v59, v59
	v_lshlrev_b32_e32 v90, 16, v87
	v_and_b32_e32 v60, 0xffff0000, v87
	v_lshlrev_b32_e32 v62, 16, v89
	v_add_f32_e32 v59, 1.0, v59
	v_rcp_f32_e32 v94, v59
	v_and_b32_e32 v58, 0xffff0000, v89
	s_waitcnt vmcnt(0)
	v_mov_b32_e32 v89, v51
	v_mov_b32_e32 v65, v54
	v_pk_mul_f32 v[64:65], v[94:95], v[64:65]
	v_mov_b32_e32 v87, v55
	v_mul_f32_e32 v54, v64, v65
	v_mov_b32_e32 v65, v42
	v_mul_f32_e32 v42, 0xbfb8aa3b, v86
	v_exp_f32_e32 v42, v42
	v_rcp_f32_e32 v64, v46
	v_mov_b32_e32 v91, v56
	v_mov_b32_e32 v63, v52
	v_add_f32_e32 v42, 1.0, v42
	v_rcp_f32_e32 v46, v42
	v_mul_f32_e32 v42, 0xbfb8aa3b, v88
	v_exp_f32_e32 v42, v42
	v_mov_b32_e32 v61, v57
	v_pk_mul_f32 v[46:47], v[46:47], v[86:87]
	v_mov_b32_e32 v59, v53
	v_add_f32_e32 v42, 1.0, v42
	v_rcp_f32_e32 v42, v42
	v_mul_f32_e32 v46, v46, v47
	v_mov_b32_e32 v93, v50
	v_pk_mul_f32 v[64:65], v[64:65], v[92:93]
	v_pk_mul_f32 v[42:43], v[42:43], v[88:89]
	v_mul_f32_e32 v50, v64, v65
	v_mul_f32_e32 v47, v42, v43
	v_mul_f32_e32 v42, 0xbfb8aa3b, v90
	v_exp_f32_e32 v42, v42
	v_mov_b32_e32 v43, v48
	v_lshlrev_b32_e32 v56, 16, v82
	v_and_b32_e32 v64, 0xffff0000, v84
	v_add_f32_e32 v42, 1.0, v42
	v_rcp_f32_e32 v42, v42
	s_nop 0
	v_pk_mul_f32 v[42:43], v[42:43], v[90:91]
	s_nop 0
	v_mul_f32_e32 v51, v42, v43
	v_mul_f32_e32 v42, 0xbfb8aa3b, v62
	v_exp_f32_e32 v42, v42
	v_mov_b32_e32 v43, v44
	v_add_f32_e32 v42, 1.0, v42
	v_rcp_f32_e32 v42, v42
	s_nop 0
	v_pk_mul_f32 v[42:43], v[42:43], v[62:63]
	s_nop 0
	v_mul_f32_e32 v52, v42, v43
	v_mul_f32_e32 v42, 0xbfb8aa3b, v60
	v_exp_f32_e32 v42, v42
	v_lshlrev_b32_e32 v62, 16, v84
	v_add_f32_e32 v42, 1.0, v42
	v_rcp_f32_e32 v48, v42
	s_nop 0
	v_pk_mul_f32 v[42:43], v[48:49], v[60:61]
	s_nop 0
	v_mul_f32_e32 v48, v42, v43
	v_mul_f32_e32 v42, 0xbfb8aa3b, v58
	v_exp_f32_e32 v42, v42
	v_lshlrev_b32_e32 v60, 16, v83
	v_add_f32_e32 v42, 1.0, v42
	v_rcp_f32_e32 v44, v42
	s_nop 0
	v_pk_mul_f32 v[42:43], v[44:45], v[58:59]
	s_nop 0
	v_mul_f32_e32 v45, v42, v43
	v_cvt_pk_bf16_f32 v42, v54, v46
	v_cvt_pk_bf16_f32 v43, v51, v48
	v_cvt_pk_bf16_f32 v44, v50, v47
	v_cvt_pk_bf16_f32 v45, v52, v45
	global_store_dwordx4 v[112:113], v[42:45], off
	global_load_dwordx4 v[42:45], v[168:169], off offset:528
	s_nop 0
	global_load_dwordx4 v[46:49], v[168:169], off offset:512
	v_mul_f32_e32 v51, 0xbfb8aa3b, v56
	v_exp_f32_e32 v51, v51
	v_and_b32_e32 v58, 0xffff0000, v82
	v_and_b32_e32 v52, 0xffff0000, v83
	v_mov_b32_e32 v83, v38
	v_add_f32_e32 v51, 1.0, v51
	v_rcp_f32_e32 v82, v51
	v_mul_f32_e32 v38, 0xbfb8aa3b, v62
	v_exp_f32_e32 v38, v38
	v_lshlrev_b32_e32 v54, 16, v85
	v_and_b32_e32 v50, 0xffff0000, v85
	v_add_f32_e32 v38, 1.0, v38
	s_waitcnt vmcnt(0)
; __device__ __forceinline__ float siluf_(float v) { return v * sigmoidf_(v); }
; __device__ __forceinline__ u32x4 pack8(f32x4 v0, f32x4 v1) { u32x4 w; w.x = cvt_pk_bf16(v0[0], v0[1]); w.y = cvt_pk_bf16(v0[2], v0[3]); w.z = cvt_pk_bf16(v1[0], v1[1]); w.w = cvt_pk_bf16(v1[2], v1[3]); return w; }
; __device__ __forceinline__ void unpack8(u32x4 w, f32x4& a, f32x4& b) { a = (f32x4){bf_lo(w.x), bf_hi(w.x), bf_lo(w.y), bf_hi(w.y)}; b = (f32x4){bf_lo(w.z), bf_hi(w.z), bf_lo(w.w), bf_hi(w.w)}; }
;     __device__ __forceinline__ void operator()(const f32x4 (&acc)[2][2][4][2], const Unit& u, int wr, int wc, int fr, int fq) const {
;     ...
;         epi_perm2<u32x4>(acc, u, wr, wc, fr, fq,
;             [=](int row, int col) __attribute__((always_inline)) { return *(const u32x4*)(proj_ + (size_t)row * NP + C_ZB + col); },
;             [=](int row, int col, f32x4 v0, f32x4 v1, const u32x4& zz) __attribute__((always_inline)) {
;                 f32x4 z0, z1; unpack8(zz, z0, z1);
;                 const f32x4 s0 = *(const f32x4*)(ps_ + col); const f32x4 s1 = *(const f32x4*)(ps_ + col + 4);
; #pragma unroll
;                 for (int j = 0; j < 4; ++j) { v0[j] = v0[j] * s0[j] * siluf_(z0[j]); v1[j] = v1[j] * s1[j] * siluf_(z1[j]); }
;                 *(u32x4*)(proj_ + (size_t)row * NP + C_ZB + col) = pack8(v0, v1); });
	v_mov_b32_e32 v65, v43
	v_mov_b32_e32 v57, v46
	v_pk_mul_f32 v[56:57], v[82:83], v[56:57]
	v_mov_b32_e32 v59, v47
	v_mul_f32_e32 v46, v56, v57
	v_mov_b32_e32 v57, v34
	v_mul_f32_e32 v34, 0xbfb8aa3b, v58
	v_exp_f32_e32 v34, v34
	v_rcp_f32_e32 v56, v38
	v_mov_b32_e32 v61, v48
	v_mov_b32_e32 v55, v44
	v_add_f32_e32 v34, 1.0, v34
	v_rcp_f32_e32 v38, v34
	v_mul_f32_e32 v34, 0xbfb8aa3b, v64
	v_exp_f32_e32 v34, v34
	v_mov_b32_e32 v53, v49
	v_pk_mul_f32 v[38:39], v[38:39], v[58:59]
	v_mov_b32_e32 v51, v45
	v_add_f32_e32 v34, 1.0, v34
	v_rcp_f32_e32 v34, v34
	v_mul_f32_e32 v38, v38, v39
	v_mov_b32_e32 v63, v42
	v_pk_mul_f32 v[56:57], v[56:57], v[62:63]
	v_pk_mul_f32 v[34:35], v[34:35], v[64:65]
	v_mul_f32_e32 v42, v56, v57
	v_mul_f32_e32 v39, v34, v35
	v_mul_f32_e32 v34, 0xbfb8aa3b, v60
	v_exp_f32_e32 v34, v34
	v_mov_b32_e32 v35, v40
	v_lshlrev_b32_e32 v48, 16, v78
	v_mov_b32_e32 v59, v30
	v_add_f32_e32 v34, 1.0, v34
	v_rcp_f32_e32 v34, v34
	v_and_b32_e32 v56, 0xffff0000, v80
	v_pk_mul_f32 v[34:35], v[34:35], v[60:61]
	s_nop 0
	v_mul_f32_e32 v43, v34, v35
	v_mul_f32_e32 v34, 0xbfb8aa3b, v54
	v_exp_f32_e32 v34, v34
	v_mov_b32_e32 v35, v36
	v_add_f32_e32 v34, 1.0, v34
	v_rcp_f32_e32 v34, v34
	s_nop 0
	v_pk_mul_f32 v[34:35], v[34:35], v[54:55]
	s_nop 0
	v_mul_f32_e32 v44, v34, v35
	v_mul_f32_e32 v34, 0xbfb8aa3b, v52
	v_exp_f32_e32 v34, v34
	v_lshlrev_b32_e32 v54, 16, v80
	v_mul_f32_e32 v30, 0xbfb8aa3b, v54
	v_exp_f32_e32 v30, v30
	v_add_f32_e32 v34, 1.0, v34
	v_rcp_f32_e32 v40, v34
	v_add_f32_e32 v30, 1.0, v30
	v_pk_mul_f32 v[34:35], v[40:41], v[52:53]
	s_nop 0
	v_mul_f32_e32 v40, v34, v35
	v_mul_f32_e32 v34, 0xbfb8aa3b, v50
	v_exp_f32_e32 v34, v34
	v_lshlrev_b32_e32 v52, 16, v79
	v_add_f32_e32 v34, 1.0, v34
	v_rcp_f32_e32 v36, v34
	s_nop 0
	v_pk_mul_f32 v[34:35], v[36:37], v[50:51]
	s_nop 0
	v_mul_f32_e32 v37, v34, v35
	v_cvt_pk_bf16_f32 v34, v46, v38
	v_cvt_pk_bf16_f32 v35, v43, v40
	v_cvt_pk_bf16_f32 v36, v42, v39
	v_cvt_pk_bf16_f32 v37, v44, v37
	global_store_dwordx4 v[110:111], v[34:37], off
	global_load_dwordx4 v[34:37], v[168:169], off offset:16
	s_nop 0
	global_load_dwordx4 v[38:41], v[168:169], off
	v_mul_f32_e32 v43, 0xbfb8aa3b, v48
	v_exp_f32_e32 v43, v43
	v_and_b32_e32 v50, 0xffff0000, v78
	v_lshlrev_b32_e32 v46, 16, v81
	v_and_b32_e32 v44, 0xffff0000, v79
	v_add_f32_e32 v43, 1.0, v43
	v_rcp_f32_e32 v58, v43
	v_and_b32_e32 v42, 0xffff0000, v81
	s_waitcnt vmcnt(0)
	v_mov_b32_e32 v57, v35
	v_mov_b32_e32 v49, v38
	v_pk_mul_f32 v[48:49], v[58:59], v[48:49]
	v_mov_b32_e32 v51, v39
	v_mul_f32_e32 v38, v48, v49
	v_mov_b32_e32 v49, v26
	v_mul_f32_e32 v26, 0xbfb8aa3b, v50
	v_exp_f32_e32 v26, v26
	v_rcp_f32_e32 v48, v30
	v_mov_b32_e32 v53, v40
	v_mov_b32_e32 v47, v36
	v_add_f32_e32 v26, 1.0, v26
	v_rcp_f32_e32 v30, v26
	v_mul_f32_e32 v26, 0xbfb8aa3b, v56
	v_exp_f32_e32 v26, v26
	v_mov_b32_e32 v45, v41
	v_pk_mul_f32 v[30:31], v[30:31], v[50:51]
	v_mov_b32_e32 v43, v37
	v_add_f32_e32 v26, 1.0, v26
	v_rcp_f32_e32 v26, v26
	v_mul_f32_e32 v30, v30, v31
	v_mov_b32_e32 v55, v34
	v_pk_mul_f32 v[48:49], v[48:49], v[54:55]
	v_pk_mul_f32 v[26:27], v[26:27], v[56:57]
	v_mul_f32_e32 v34, v48, v49
	v_mul_f32_e32 v31, v26, v27
	v_mul_f32_e32 v26, 0xbfb8aa3b, v52
	v_exp_f32_e32 v26, v26
	v_mov_b32_e32 v27, v32
	v_lshlrev_b32_e32 v40, 16, v74
	v_mov_b32_e32 v51, v22
	v_add_f32_e32 v26, 1.0, v26
	v_rcp_f32_e32 v26, v26
	v_and_b32_e32 v48, 0xffff0000, v76
	v_pk_mul_f32 v[26:27], v[26:27], v[52:53]
	s_nop 0
	v_mul_f32_e32 v35, v26, v27
	v_mul_f32_e32 v26, 0xbfb8aa3b, v46
	v_exp_f32_e32 v26, v26
	v_mov_b32_e32 v27, v28
	v_add_f32_e32 v26, 1.0, v26
	v_rcp_f32_e32 v26, v26
	s_nop 0
	v_pk_mul_f32 v[26:27], v[26:27], v[46:47]
	s_nop 0
	v_mul_f32_e32 v36, v26, v27
	v_mul_f32_e32 v26, 0xbfb8aa3b, v44
	v_exp_f32_e32 v26, v26
	v_lshlrev_b32_e32 v46, 16, v76
	v_mul_f32_e32 v22, 0xbfb8aa3b, v46
	v_exp_f32_e32 v22, v22
	v_add_f32_e32 v26, 1.0, v26
	v_rcp_f32_e32 v32, v26
	v_add_f32_e32 v22, 1.0, v22
	v_pk_mul_f32 v[26:27], v[32:33], v[44:45]
	s_nop 0
	v_mul_f32_e32 v32, v26, v27
	v_mul_f32_e32 v26, 0xbfb8aa3b, v42
	v_exp_f32_e32 v26, v26
	v_lshlrev_b32_e32 v44, 16, v75
	v_add_f32_e32 v26, 1.0, v26
	v_rcp_f32_e32 v28, v26
	s_nop 0
	v_pk_mul_f32 v[26:27], v[28:29], v[42:43]
	s_nop 0
	v_mul_f32_e32 v29, v26, v27
	v_cvt_pk_bf16_f32 v26, v38, v30
	v_cvt_pk_bf16_f32 v27, v35, v32
	v_cvt_pk_bf16_f32 v28, v34, v31
	v_cvt_pk_bf16_f32 v29, v36, v29
	global_store_dwordx4 v[108:109], v[26:29], off
	global_load_dwordx4 v[26:29], v[168:169], off offset:528
	s_nop 0
	global_load_dwordx4 v[30:33], v[168:169], off offset:512
	v_mul_f32_e32 v35, 0xbfb8aa3b, v40
	v_exp_f32_e32 v35, v35
	v_and_b32_e32 v42, 0xffff0000, v74
	v_lshlrev_b32_e32 v38, 16, v77
	v_and_b32_e32 v36, 0xffff0000, v75
	v_add_f32_e32 v35, 1.0, v35
	v_rcp_f32_e32 v50, v35
	v_and_b32_e32 v34, 0xffff0000, v77
	s_waitcnt vmcnt(0)
; __device__ __forceinline__ float siluf_(float v) { return v * sigmoidf_(v); }
; __device__ __forceinline__ u32x4 pack8(f32x4 v0, f32x4 v1) { u32x4 w; w.x = cvt_pk_bf16(v0[0], v0[1]); w.y = cvt_pk_bf16(v0[2], v0[3]); w.z = cvt_pk_bf16(v1[0], v1[1]); w.w = cvt_pk_bf16(v1[2], v1[3]); return w; }
; __device__ __forceinline__ void unpack8(u32x4 w, f32x4& a, f32x4& b) { a = (f32x4){bf_lo(w.x), bf_hi(w.x), bf_lo(w.y), bf_hi(w.y)}; b = (f32x4){bf_lo(w.z), bf_hi(w.z), bf_lo(w.w), bf_hi(w.w)}; }
;     __device__ __forceinline__ void operator()(const f32x4 (&acc)[2][2][4][2], const Unit& u, int wr, int wc, int fr, int fq) const {
;     ...
;         epi_perm2<u32x4>(acc, u, wr, wc, fr, fq,
;             [=](int row, int col) __attribute__((always_inline)) { return *(const u32x4*)(proj_ + (size_t)row * NP + C_ZB + col); },
;             [=](int row, int col, f32x4 v0, f32x4 v1, const u32x4& zz) __attribute__((always_inline)) {
;                 f32x4 z0, z1; unpack8(zz, z0, z1);
;                 const f32x4 s0 = *(const f32x4*)(ps_ + col); const f32x4 s1 = *(const f32x4*)(ps_ + col + 4);
; #pragma unroll
;                 for (int j = 0; j < 4; ++j) { v0[j] = v0[j] * s0[j] * siluf_(z0[j]); v1[j] = v1[j] * s1[j] * siluf_(z1[j]); }
;                 *(u32x4*)(proj_ + (size_t)row * NP + C_ZB + col) = pack8(v0, v1); });
	v_mov_b32_e32 v49, v27
	v_mov_b32_e32 v41, v30
	v_pk_mul_f32 v[40:41], v[50:51], v[40:41]
	v_mov_b32_e32 v43, v31
	v_mul_f32_e32 v30, v40, v41
	v_mov_b32_e32 v41, v18
	v_mul_f32_e32 v18, 0xbfb8aa3b, v42
	v_exp_f32_e32 v18, v18
	v_rcp_f32_e32 v40, v22
	v_mov_b32_e32 v45, v32
	v_mov_b32_e32 v39, v28
	v_add_f32_e32 v18, 1.0, v18
	v_rcp_f32_e32 v22, v18
	v_mul_f32_e32 v18, 0xbfb8aa3b, v48
	v_exp_f32_e32 v18, v18
	v_mov_b32_e32 v37, v33
	v_pk_mul_f32 v[22:23], v[22:23], v[42:43]
	v_mov_b32_e32 v35, v29
	v_add_f32_e32 v18, 1.0, v18
	v_rcp_f32_e32 v18, v18
	v_mul_f32_e32 v22, v22, v23
	v_mov_b32_e32 v47, v26
	v_pk_mul_f32 v[40:41], v[40:41], v[46:47]
	v_pk_mul_f32 v[18:19], v[18:19], v[48:49]
	v_mul_f32_e32 v26, v40, v41
	v_mul_f32_e32 v23, v18, v19
	v_mul_f32_e32 v18, 0xbfb8aa3b, v44
	v_exp_f32_e32 v18, v18
	v_mov_b32_e32 v19, v24
	v_lshlrev_b32_e32 v32, 16, v70
	v_mov_b32_e32 v43, v14
	v_add_f32_e32 v18, 1.0, v18
	v_rcp_f32_e32 v18, v18
	v_and_b32_e32 v40, 0xffff0000, v72
	v_pk_mul_f32 v[18:19], v[18:19], v[44:45]
	s_nop 0
	v_mul_f32_e32 v27, v18, v19
	v_mul_f32_e32 v18, 0xbfb8aa3b, v38
	v_exp_f32_e32 v18, v18
	v_mov_b32_e32 v19, v20
	v_add_f32_e32 v18, 1.0, v18
	v_rcp_f32_e32 v18, v18
	s_nop 0
	v_pk_mul_f32 v[18:19], v[18:19], v[38:39]
	s_nop 0
	v_mul_f32_e32 v28, v18, v19
	v_mul_f32_e32 v18, 0xbfb8aa3b, v36
	v_exp_f32_e32 v18, v18
	v_lshlrev_b32_e32 v38, 16, v72
	v_mul_f32_e32 v14, 0xbfb8aa3b, v38
	v_exp_f32_e32 v14, v14
	v_add_f32_e32 v18, 1.0, v18
	v_rcp_f32_e32 v24, v18
	v_add_f32_e32 v14, 1.0, v14
	v_pk_mul_f32 v[18:19], v[24:25], v[36:37]
	s_nop 0
	v_mul_f32_e32 v24, v18, v19
	v_mul_f32_e32 v18, 0xbfb8aa3b, v34
	v_exp_f32_e32 v18, v18
	v_lshlrev_b32_e32 v36, 16, v71
	v_add_f32_e32 v18, 1.0, v18
	v_rcp_f32_e32 v20, v18
	s_nop 0
	v_pk_mul_f32 v[18:19], v[20:21], v[34:35]
	s_nop 0
	v_mul_f32_e32 v21, v18, v19
	v_cvt_pk_bf16_f32 v18, v30, v22
	v_cvt_pk_bf16_f32 v19, v27, v24
	v_cvt_pk_bf16_f32 v20, v26, v23
	v_cvt_pk_bf16_f32 v21, v28, v21
	global_store_dwordx4 v[106:107], v[18:21], off
	global_load_dwordx4 v[18:21], v[168:169], off offset:16
	s_nop 0
	global_load_dwordx4 v[22:25], v[168:169], off
	v_mul_f32_e32 v27, 0xbfb8aa3b, v32
	v_exp_f32_e32 v27, v27
	v_and_b32_e32 v34, 0xffff0000, v70
	v_lshlrev_b32_e32 v30, 16, v73
	v_and_b32_e32 v28, 0xffff0000, v71
	v_add_f32_e32 v27, 1.0, v27
	v_rcp_f32_e32 v42, v27
	v_and_b32_e32 v26, 0xffff0000, v73
	s_waitcnt vmcnt(0)
	v_mov_b32_e32 v41, v19
	v_mov_b32_e32 v33, v22
	v_pk_mul_f32 v[32:33], v[42:43], v[32:33]
	v_mov_b32_e32 v35, v23
	v_mul_f32_e32 v22, v32, v33
	v_mov_b32_e32 v33, v10
	v_mul_f32_e32 v10, 0xbfb8aa3b, v34
	v_exp_f32_e32 v10, v10
	v_rcp_f32_e32 v32, v14
	v_mov_b32_e32 v37, v24
	v_mov_b32_e32 v31, v20
	v_add_f32_e32 v10, 1.0, v10
	v_rcp_f32_e32 v14, v10
	v_mul_f32_e32 v10, 0xbfb8aa3b, v40
	v_exp_f32_e32 v10, v10
	v_mov_b32_e32 v29, v25
	v_pk_mul_f32 v[14:15], v[14:15], v[34:35]
	v_mov_b32_e32 v27, v21
	v_add_f32_e32 v10, 1.0, v10
	v_rcp_f32_e32 v10, v10
	v_mul_f32_e32 v14, v14, v15
	v_mov_b32_e32 v39, v18
	v_pk_mul_f32 v[32:33], v[32:33], v[38:39]
	v_pk_mul_f32 v[10:11], v[10:11], v[40:41]
	v_mul_f32_e32 v18, v32, v33
	v_mul_f32_e32 v15, v10, v11
	v_mul_f32_e32 v10, 0xbfb8aa3b, v36
	v_exp_f32_e32 v10, v10
	v_mov_b32_e32 v11, v16
	v_lshlrev_b32_e32 v24, 16, v66
	v_mov_b32_e32 v35, v6
	v_add_f32_e32 v10, 1.0, v10
	v_rcp_f32_e32 v10, v10
	v_and_b32_e32 v32, 0xffff0000, v68
	v_pk_mul_f32 v[10:11], v[10:11], v[36:37]
	s_nop 0
	v_mul_f32_e32 v19, v10, v11
	v_mul_f32_e32 v10, 0xbfb8aa3b, v30
	v_exp_f32_e32 v10, v10
	v_mov_b32_e32 v11, v12
	v_add_f32_e32 v10, 1.0, v10
	v_rcp_f32_e32 v10, v10
	s_nop 0
	v_pk_mul_f32 v[10:11], v[10:11], v[30:31]
	s_nop 0
	v_mul_f32_e32 v20, v10, v11
	v_mul_f32_e32 v10, 0xbfb8aa3b, v28
	v_exp_f32_e32 v10, v10
	v_lshlrev_b32_e32 v30, 16, v68
	v_mul_f32_e32 v6, 0xbfb8aa3b, v30
	v_exp_f32_e32 v6, v6
	v_add_f32_e32 v10, 1.0, v10
	v_rcp_f32_e32 v16, v10
	v_add_f32_e32 v6, 1.0, v6
	v_pk_mul_f32 v[10:11], v[16:17], v[28:29]
	s_nop 0
	v_mul_f32_e32 v16, v10, v11
	v_mul_f32_e32 v10, 0xbfb8aa3b, v26
	v_exp_f32_e32 v10, v10
	v_lshlrev_b32_e32 v28, 16, v67
	v_add_f32_e32 v10, 1.0, v10
	v_rcp_f32_e32 v12, v10
	s_nop 0
	v_pk_mul_f32 v[10:11], v[12:13], v[26:27]
	s_nop 0
	v_mul_f32_e32 v13, v10, v11
	v_cvt_pk_bf16_f32 v10, v22, v14
	v_cvt_pk_bf16_f32 v11, v19, v16
	v_cvt_pk_bf16_f32 v12, v18, v15
	v_cvt_pk_bf16_f32 v13, v20, v13
	global_store_dwordx4 v[104:105], v[10:13], off
	global_load_dwordx4 v[10:13], v[168:169], off offset:528
	s_nop 0
	global_load_dwordx4 v[20:23], v[168:169], off offset:512
	v_mul_f32_e32 v15, 0xbfb8aa3b, v24
	v_exp_f32_e32 v15, v15
	v_and_b32_e32 v26, 0xffff0000, v66
	v_lshlrev_b32_e32 v18, 16, v69
	v_and_b32_e32 v16, 0xffff0000, v67
	v_add_f32_e32 v15, 1.0, v15
	v_rcp_f32_e32 v34, v15
	v_and_b32_e32 v14, 0xffff0000, v69
	s_waitcnt vmcnt(0)
	v_mov_b32_e32 v33, v11
	v_mov_b32_e32 v25, v20
	v_pk_mul_f32 v[24:25], v[34:35], v[24:25]
	v_mov_b32_e32 v27, v21
	v_mul_f32_e32 v20, v24, v25
	v_mov_b32_e32 v25, v2
	v_mul_f32_e32 v2, 0xbfb8aa3b, v26
	v_exp_f32_e32 v2, v2
	v_rcp_f32_e32 v24, v6
	v_mov_b32_e32 v29, v22
	v_mov_b32_e32 v19, v12
	v_add_f32_e32 v2, 1.0, v2
	v_rcp_f32_e32 v6, v2
	v_mul_f32_e32 v2, 0xbfb8aa3b, v32
	v_exp_f32_e32 v2, v2
	v_mov_b32_e32 v17, v23
	v_pk_mul_f32 v[6:7], v[6:7], v[26:27]
	v_mov_b32_e32 v15, v13
	v_add_f32_e32 v2, 1.0, v2
	v_rcp_f32_e32 v2, v2
	v_mul_f32_e32 v6, v6, v7
	v_mov_b32_e32 v31, v10
	v_pk_mul_f32 v[24:25], v[24:25], v[30:31]
	v_pk_mul_f32 v[2:3], v[2:3], v[32:33]
	v_mul_f32_e32 v10, v24, v25
	v_mul_f32_e32 v7, v2, v3
	v_mul_f32_e32 v2, 0xbfb8aa3b, v28
	v_exp_f32_e32 v2, v2
	v_mov_b32_e32 v3, v8
	v_add_f32_e32 v2, 1.0, v2
	v_rcp_f32_e32 v2, v2
	s_nop 0
	v_pk_mul_f32 v[2:3], v[2:3], v[28:29]
	s_nop 0
	v_mul_f32_e32 v11, v2, v3
	v_mul_f32_e32 v2, 0xbfb8aa3b, v18
	v_exp_f32_e32 v2, v2
	v_mov_b32_e32 v3, v4
	v_add_f32_e32 v2, 1.0, v2
	v_rcp_f32_e32 v2, v2
	s_nop 0
	v_pk_mul_f32 v[2:3], v[2:3], v[18:19]
	s_nop 0
	v_mul_f32_e32 v12, v2, v3
	v_mul_f32_e32 v2, 0xbfb8aa3b, v16
	v_exp_f32_e32 v2, v2
	s_nop 0
	v_add_f32_e32 v2, 1.0, v2
	v_rcp_f32_e32 v8, v2
	s_nop 0
	v_pk_mul_f32 v[2:3], v[8:9], v[16:17]
	s_nop 0
	v_mul_f32_e32 v8, v2, v3
	v_mul_f32_e32 v2, 0xbfb8aa3b, v14
	v_exp_f32_e32 v2, v2
	s_nop 0
	v_add_f32_e32 v2, 1.0, v2
	v_rcp_f32_e32 v4, v2
	s_nop 0
	v_pk_mul_f32 v[2:3], v[4:5], v[14:15]
	s_nop 0
	v_mul_f32_e32 v5, v2, v3
	v_cvt_pk_bf16_f32 v2, v20, v6
	v_cvt_pk_bf16_f32 v3, v11, v8
	v_cvt_pk_bf16_f32 v4, v10, v7
	v_cvt_pk_bf16_f32 v5, v12, v5
	global_store_dwordx4 v[102:103], v[2:5], off
	s_cbranch_vccnz .LBB0_455
	v_readlane_b32 s0, v255, 12
	v_readlane_b32 s1, v255, 13
	s_andn2_b64 vcc, exec, s[0:1]
	s_cbranch_vccnz .LBB0_454
	s_barrier
	s_branch .LBB0_454

; __device__ __forceinline__ int otid() { int t = threadIdx.x; asm volatile("" : "+v"(t)); return t; }
; #define PG8_BAR __builtin_amdgcn_s_barrier()
; __device__ __forceinline__ u32x4 pack8(f32x4 v0, f32x4 v1) { u32x4 w; w.x = cvt_pk_bf16(v0[0], v0[1]); w.y = cvt_pk_bf16(v0[2], v0[3]); w.z = cvt_pk_bf16(v1[0], v1[1]); w.w = cvt_pk_bf16(v1[2], v1[3]); return w; }
;     ...
;         if (wr == 0) PG8_BAR;
;         { const int t2_ = otid(), w2_ = t2_ >> 6, l2_ = t2_ & 63; E(acc, cur, w2_ >> 2, w2_ & 3, l2_ & 15, l2_ >> 4); }
;         if (!has_next) break;
; #pragma unroll
;         for (int a = 0; a < 2; ++a)
; #pragma unroll
;             for (int b = 0; b < 2; ++b)
; #pragma unroll
;                 for (int m = 0; m < 4; ++m)
; #pragma unroll
;                     for (int n = 0; n < 2; ++n) acc[a][b][m][n] = (f32x4){0.f, 0.f, 0.f, 0.f};
;         cur = nxt; cA = nA; cB = nB; ++ui;
;         if (wr == 1) PG8_BAR;
;     __device__ __forceinline__ void operator()(const f32x4 (&acc)[2][2][4][2], const Unit& u, int wr, int wc, int fr, int fq) const {
;         bf16_t* O_ = O + col0;
; #pragma unroll
;         for (int ai = 0; ai < 2; ++ai)
; #pragma unroll
;             for (int m = 0; m < 4; ++m) { const int row = u.pm * BM + ai * HALF + wr * 64 + m * 16 + fr;
; #pragma unroll
;                 for (int bj = 0; bj < 2; ++bj) { const int col = u.pn * BM + bj * HALF + wc * 32 + 8 * fq;
;                     *(u32x4*)(O_ + (size_t)row * NP + col) = pack8(acc[ai][bj][m][0], acc[ai][bj][m][1]); } }
;     }
.LBB0_665:
	v_mov_b32_e32 v134, v199
	v_cvt_pk_bf16_f32 v126, v126, v127
	v_cvt_pk_bf16_f32 v127, v128, v129
	v_cvt_pk_bf16_f32 v128, v122, v123
	v_cvt_pk_bf16_f32 v129, v124, v125
	v_readlane_b32 s74, v253, 24
	v_ashrrev_i32_e32 v135, 2, v134
	v_and_b32_e32 v135, 0xffffffc0, v135
	v_lshl_add_u32 v135, s68, 8, v135
	v_and_or_b32 v142, v134, 15, v135
	v_lshrrev_b32_e32 v134, 1, v134
	v_and_b32_e32 v134, 0x78, v134
	v_lshl_or_b32 v138, s93, 8, v134
	v_mov_b64_e32 v[134:135], s[44:45]
	v_ashrrev_i32_e32 v139, 31, v138
	v_mad_i64_i32 v[140:141], s[34:35], v142, s31, v[134:135]
	v_lshlrev_b64 v[122:123], 1, v[138:139]
	v_lshl_add_u64 v[124:125], v[140:141], 0, v[122:123]
	global_store_dwordx4 v[124:125], v[126:129], off
	v_cvt_pk_bf16_f32 v114, v114, v115
	v_cvt_pk_bf16_f32 v115, v116, v117
	v_cvt_pk_bf16_f32 v116, v106, v107
	v_or_b32_e32 v106, 16, v142
	v_cvt_pk_bf16_f32 v117, v108, v109
	global_store_dwordx4 v[124:125], v[114:117], off offset:256
	s_andn2_b64 vcc, exec, s[40:41]
	s_mov_b64 s[40:41], -1
	v_mad_i64_i32 v[114:115], s[34:35], v106, s31, v[134:135]
	v_cvt_pk_bf16_f32 v106, v118, v119
	v_cvt_pk_bf16_f32 v107, v120, v121
	v_cvt_pk_bf16_f32 v108, v110, v111
	v_lshl_add_u64 v[110:111], v[114:115], 0, v[122:123]
	v_cvt_pk_bf16_f32 v109, v112, v113
	global_store_dwordx4 v[110:111], v[106:109], off
	v_cvt_pk_bf16_f32 v98, v98, v99
	v_cvt_pk_bf16_f32 v99, v100, v101
	v_cvt_pk_bf16_f32 v100, v90, v91
	v_or_b32_e32 v90, 32, v142
	v_cvt_pk_bf16_f32 v101, v92, v93
	global_store_dwordx4 v[110:111], v[98:101], off offset:256
	v_readlane_b32 s75, v253, 25
	s_nop 0
	v_mad_i64_i32 v[98:99], s[34:35], v90, s31, v[134:135]
	v_cvt_pk_bf16_f32 v90, v102, v103
	v_cvt_pk_bf16_f32 v91, v104, v105
	v_cvt_pk_bf16_f32 v92, v94, v95
	v_lshl_add_u64 v[94:95], v[98:99], 0, v[122:123]
	v_cvt_pk_bf16_f32 v93, v96, v97
	global_store_dwordx4 v[94:95], v[90:93], off
	v_cvt_pk_bf16_f32 v82, v82, v83
	v_cvt_pk_bf16_f32 v83, v84, v85
	v_cvt_pk_bf16_f32 v84, v74, v75
	v_or_b32_e32 v74, 48, v142
	v_cvt_pk_bf16_f32 v85, v76, v77
	global_store_dwordx4 v[94:95], v[82:85], off offset:256
	s_nop 1
	v_mad_i64_i32 v[82:83], s[34:35], v74, s31, v[134:135]
	v_cvt_pk_bf16_f32 v74, v86, v87
	v_cvt_pk_bf16_f32 v75, v88, v89
	v_cvt_pk_bf16_f32 v76, v78, v79
	v_lshl_add_u64 v[78:79], v[82:83], 0, v[122:123]
	v_cvt_pk_bf16_f32 v77, v80, v81
	global_store_dwordx4 v[78:79], v[74:77], off
	v_cvt_pk_bf16_f32 v70, v70, v71
	v_cvt_pk_bf16_f32 v71, v72, v73
	v_cvt_pk_bf16_f32 v72, v66, v67
	v_add_u32_e32 v66, 0x80, v142
	v_mad_i64_i32 v[66:67], s[34:35], v66, s31, v[134:135]
	v_cvt_pk_bf16_f32 v73, v68, v69
	global_store_dwordx4 v[78:79], v[70:73], off offset:256
	v_cvt_pk_bf16_f32 v62, v62, v63
	v_cvt_pk_bf16_f32 v63, v64, v65
	v_cvt_pk_bf16_f32 v64, v58, v59
	v_lshl_add_u64 v[58:59], v[66:67], 0, v[122:123]
	v_cvt_pk_bf16_f32 v65, v60, v61
	global_store_dwordx4 v[58:59], v[62:65], off
	v_cvt_pk_bf16_f32 v50, v50, v51
	v_cvt_pk_bf16_f32 v51, v52, v53
	v_cvt_pk_bf16_f32 v52, v42, v43
	v_add_u32_e32 v42, 0x90, v142
	v_cvt_pk_bf16_f32 v53, v44, v45
	global_store_dwordx4 v[58:59], v[50:53], off offset:256
	s_nop 1
	v_mad_i64_i32 v[50:51], s[34:35], v42, s31, v[134:135]
	v_cvt_pk_bf16_f32 v42, v54, v55
	v_cvt_pk_bf16_f32 v43, v56, v57
	v_cvt_pk_bf16_f32 v44, v46, v47
	v_lshl_add_u64 v[46:47], v[50:51], 0, v[122:123]
	v_cvt_pk_bf16_f32 v45, v48, v49
	global_store_dwordx4 v[46:47], v[42:45], off
	v_cvt_pk_bf16_f32 v34, v34, v35
	v_cvt_pk_bf16_f32 v35, v36, v37
	v_cvt_pk_bf16_f32 v36, v26, v27
	v_add_u32_e32 v26, 0xa0, v142
	v_cvt_pk_bf16_f32 v37, v28, v29
	global_store_dwordx4 v[46:47], v[34:37], off offset:256
	s_nop 1
	v_mad_i64_i32 v[34:35], s[34:35], v26, s31, v[134:135]
	v_cvt_pk_bf16_f32 v26, v38, v39
	v_cvt_pk_bf16_f32 v27, v40, v41
	v_cvt_pk_bf16_f32 v28, v30, v31
	v_lshl_add_u64 v[30:31], v[34:35], 0, v[122:123]
	v_cvt_pk_bf16_f32 v29, v32, v33
	global_store_dwordx4 v[30:31], v[26:29], off
	v_cvt_pk_bf16_f32 v18, v18, v19
	v_cvt_pk_bf16_f32 v19, v20, v21
	v_cvt_pk_bf16_f32 v20, v10, v11
	v_add_u32_e32 v10, 0xb0, v142
	v_cvt_pk_bf16_f32 v21, v12, v13
	global_store_dwordx4 v[30:31], v[18:21], off offset:256
	s_nop 1
	v_mad_i64_i32 v[18:19], s[34:35], v10, s31, v[134:135]
	v_cvt_pk_bf16_f32 v10, v22, v23
	v_cvt_pk_bf16_f32 v11, v24, v25
	v_cvt_pk_bf16_f32 v12, v14, v15
	v_lshl_add_u64 v[14:15], v[18:19], 0, v[122:123]
	v_readlane_b32 s34, v253, 11
	v_cvt_pk_bf16_f32 v13, v16, v17
	global_store_dwordx4 v[14:15], v[10:13], off
	v_cvt_pk_bf16_f32 v6, v6, v7
	v_cvt_pk_bf16_f32 v7, v8, v9
	v_cvt_pk_bf16_f32 v8, v2, v3
	v_cvt_pk_bf16_f32 v9, v4, v5
	global_store_dwordx4 v[14:15], v[6:9], off offset:256
	v_readlane_b32 s35, v253, 12
	s_load_dwordx2 s[96:97], s[34:35], 0x98
	s_cbranch_vccnz .LBB0_658
	v_readlane_b32 s12, v253, 38
	v_readlane_b32 s13, v253, 39
	s_andn2_b64 vcc, exec, s[12:13]
	s_cbranch_vccnz .LBB0_657
	s_barrier
	s_branch .LBB0_657

; __device__ __forceinline__ float sigmoidf_(float v) { return __builtin_amdgcn_rcpf(1.f + __expf(-v)); }
; __device__ __forceinline__ u32x4 pack8(f32x4 v0, f32x4 v1) { u32x4 w; w.x = cvt_pk_bf16(v0[0], v0[1]); w.y = cvt_pk_bf16(v0[2], v0[3]); w.z = cvt_pk_bf16(v1[0], v1[1]); w.w = cvt_pk_bf16(v1[2], v1[3]); return w; }
;     __device__ __forceinline__ void operator()(const f32x4 (&acc)[2][2][4][2], const Unit& u, int wr, int wc, int fr, int fq) const {
;         bf16_t* O_ = O; const bool gate = u.pn >= 8;
; #pragma unroll
;         for (int bj = 0; bj < 2; ++bj) { const int col = u.pn * BM + bj * HALF + wc * 32 + 8 * fq;
;             const f32x4 b0 = gate ? *(const f32x4*)(bm + col - 2048) : (f32x4){0.f, 0.f, 0.f, 0.f}, b1 = gate ? *(const f32x4*)(bm + col - 2048 + 4) : (f32x4){0.f, 0.f, 0.f, 0.f};
;             const int ocol = gate ? GATE0 + col - 2048 : col;
; #pragma unroll
;             for (int ai = 0; ai < 2; ++ai)
; #pragma unroll
;                 for (int m = 0; m < 4; ++m) { const int row = u.pm * BM + ai * HALF + wr * 64 + m * 16 + fr; f32x4 v0 = acc[ai][bj][m][0] * 0.03125f, v1 = acc[ai][bj][m][1] * 0.03125f;
;                     if (gate) {
; #pragma unroll
;                         for (int j = 0; j < 4; ++j) { v0[j] = sigmoidf_(v0[j] + b0[j]); v1[j] = sigmoidf_(v1[j] + b1[j]); }
;                         *(u32x2*)((unsigned char*)(O_ + (size_t)row * NP + GATE0) + (col - 2048)) = gate_pack8(v0, v1); }
;                     else *(u32x4*)(O_ + (size_t)row * NP + ocol) = pack8(v0, v1); } }
;     }
.LBB0_714:
	v_ashrrev_i32_e32 v145, 2, v144
	v_and_b32_e32 v145, 0xffffffc0, v145
	v_lshl_add_u32 v145, s40, 8, v145
	v_readlane_b32 s0, v253, 13
	v_and_or_b32 v150, v144, 15, v145
	v_ashrrev_i32_e32 v145, 31, v0
	v_mov_b32_e32 v144, v0
	v_readlane_b32 s1, v253, 14
	s_mov_b64 s[40:41], -1
	s_and_b64 vcc, exec, s[90:91]
	v_lshl_add_u64 v[144:145], v[144:145], 1, s[0:1]
	s_mov_b32 s0, 0x3d000000
	v_pk_mul_f32 v[136:137], v[136:137], s[0:1] op_sel_hi:[1,0]
	v_pk_mul_f32 v[134:135], v[134:135], s[0:1] op_sel_hi:[1,0]
	v_pk_mul_f32 v[132:133], v[132:133], s[0:1] op_sel_hi:[1,0]
	v_pk_mul_f32 v[146:147], v[130:131], s[0:1] op_sel_hi:[1,0]
	v_mov_b64_e32 v[250:251], 0x200
	s_cbranch_vccz .LBB0_716
	v_mad_i64_i32 v[130:131], s[0:1], v150, s31, v[144:145]
	v_cvt_pk_bf16_f32 v152, v134, v135
	v_cvt_pk_bf16_f32 v153, v136, v137
	v_cvt_pk_bf16_f32 v154, v146, v147
	v_cvt_pk_bf16_f32 v155, v132, v133
	global_store_dwordx4 v[130:131], v[152:155], off
	s_mov_b64 s[40:41], 0
.LBB0_716:
	v_readlane_b32 s0, v253, 13
	v_readlane_b32 s1, v253, 14
	s_andn2_b64 vcc, exec, s[40:41]
	s_nop 0
	v_lshl_add_u64 v[130:131], s[0:1], 0, v[0:1]
	s_cbranch_vccnz .LBB0_718
	s_waitcnt vmcnt(0)
	v_add_f32_e32 v134, v134, v118
	v_mul_f32_e32 v134, 0xbfb8aa3b, v134
	v_add_f32_e32 v146, v146, v114
	v_add_f32_e32 v135, v135, v119
	v_exp_f32_e32 v134, v134
	v_mul_f32_e32 v146, 0xbfb8aa3b, v146
	v_mul_f32_e32 v135, 0xbfb8aa3b, v135
	v_add_f32_e32 v147, v147, v115
	v_exp_f32_e32 v146, v146
	v_exp_f32_e32 v135, v135
	v_mul_f32_e32 v147, 0xbfb8aa3b, v147
	v_add_f32_e32 v136, v136, v120
	v_add_f32_e32 v132, v132, v116
	v_exp_f32_e32 v147, v147
	v_mul_f32_e32 v136, 0xbfb8aa3b, v136
	v_mul_f32_e32 v132, 0xbfb8aa3b, v132
	v_add_f32_e32 v137, v137, v121
	v_add_f32_e32 v133, v133, v117
	v_exp_f32_e32 v136, v136
	v_exp_f32_e32 v132, v132
	v_mul_f32_e32 v137, 0xbfb8aa3b, v137
	v_mul_f32_e32 v133, 0xbfb8aa3b, v133
	v_add_f32_e32 v134, 1.0, v134
	v_exp_f32_e32 v137, v137
	v_exp_f32_e32 v133, v133
	v_rcp_f32_e32 v134, v134
	v_add_f32_e32 v146, 1.0, v146
	v_add_f32_e32 v135, 1.0, v135
	v_rcp_f32_e32 v146, v146
	v_rcp_f32_e32 v135, v135
	v_add_f32_e32 v147, 1.0, v147
	v_rcp_f32_e32 v147, v147
	v_add_f32_e32 v136, 1.0, v136
	v_add_f32_e32 v132, 1.0, v132
	v_rcp_f32_e32 v136, v136
	v_rcp_f32_e32 v132, v132
	v_add_f32_e32 v137, 1.0, v137
	v_add_f32_e32 v133, 1.0, v133
	v_rcp_f32_e32 v137, v137
	v_rcp_f32_e32 v133, v133
	v_mul_f32_e32 v134, 0x437f0000, v134
	v_cvt_pk_u8_f32 v134, v134, 0, 0
	v_mul_f32_e32 v146, 0x437f0000, v146
	v_mul_f32_e32 v135, 0x437f0000, v135
	v_cvt_pk_u8_f32 v146, v146, 0, 0
	v_cvt_pk_u8_f32 v134, v135, 1, v134
	v_mul_f32_e32 v135, 0x437f0000, v147
	v_cvt_pk_u8_f32 v135, v135, 1, v146
	v_mul_f32_e32 v136, 0x437f0000, v136
	v_mul_f32_e32 v132, 0x437f0000, v132
	v_cvt_pk_u8_f32 v134, v136, 2, v134
	v_cvt_pk_u8_f32 v135, v132, 2, v135
	v_mul_f32_e32 v132, 0x437f0000, v137
	v_mul_f32_e32 v133, 0x437f0000, v133
	v_cvt_pk_u8_f32 v132, v132, 3, v134
	v_cvt_pk_u8_f32 v133, v133, 3, v135
	v_mad_i64_i32 v[134:135], s[0:1], v150, s31, v[130:131]
	v_add_co_u32_e32 v134, vcc, 0x3000, v134
	s_nop 1
	v_addc_co_u32_e32 v135, vcc, 0, v135, vcc
	global_store_dwordx2 v[134:135], v[132:133], off offset:512
.LBB0_718:
	s_mov_b32 s0, 0x3d000000
	v_cndmask_b32_e64 v133, 0, 1, s[90:91]
	v_or_b32_e32 v132, 16, v150
	v_pk_mul_f32 v[128:129], v[128:129], s[0:1] op_sel_hi:[1,0]
	v_pk_mul_f32 v[126:127], v[126:127], s[0:1] op_sel_hi:[1,0]
	v_pk_mul_f32 v[124:125], v[124:125], s[0:1] op_sel_hi:[1,0]
	v_pk_mul_f32 v[122:123], v[122:123], s[0:1] op_sel_hi:[1,0]
	v_cmp_ne_u32_e64 s[40:41], 1, v133
	s_andn2_b64 vcc, exec, s[90:91]
	s_mov_b64 s[88:89], -1
	s_cbranch_vccnz .LBB0_720
	v_mad_i64_i32 v[146:147], s[0:1], v132, s31, v[144:145]
	s_mov_b64 s[88:89], 0
	v_cvt_pk_bf16_f32 v134, v126, v127
	v_cvt_pk_bf16_f32 v135, v128, v129
	v_cvt_pk_bf16_f32 v136, v122, v123
	v_cvt_pk_bf16_f32 v137, v124, v125
	global_store_dwordx4 v[146:147], v[134:137], off
.LBB0_720:
	s_andn2_b64 vcc, exec, s[88:89]
	s_cbranch_vccnz .LBB0_722
	s_waitcnt vmcnt(0)
	v_add_f32_e32 v126, v126, v118
	v_add_f32_e32 v122, v122, v114
	v_mul_f32_e32 v126, 0xbfb8aa3b, v126
	v_mul_f32_e32 v122, 0xbfb8aa3b, v122
	v_add_f32_e32 v127, v127, v119
	v_add_f32_e32 v123, v123, v115
	v_exp_f32_e32 v126, v126
	v_exp_f32_e32 v122, v122
	v_mul_f32_e32 v127, 0xbfb8aa3b, v127
	v_mul_f32_e32 v123, 0xbfb8aa3b, v123
	v_add_f32_e32 v128, v128, v120
	v_add_f32_e32 v124, v124, v116
	v_exp_f32_e32 v127, v127
	v_exp_f32_e32 v123, v123
	v_mul_f32_e32 v128, 0xbfb8aa3b, v128
	v_mul_f32_e32 v124, 0xbfb8aa3b, v124
	v_add_f32_e32 v129, v129, v121
	v_exp_f32_e32 v128, v128
	v_exp_f32_e32 v124, v124
	v_mul_f32_e32 v129, 0xbfb8aa3b, v129
	v_add_f32_e32 v125, v125, v117
	v_exp_f32_e32 v129, v129
	v_mul_f32_e32 v125, 0xbfb8aa3b, v125
	v_add_f32_e32 v126, 1.0, v126
	v_add_f32_e32 v122, 1.0, v122
	v_exp_f32_e32 v125, v125
	v_rcp_f32_e32 v126, v126
	v_rcp_f32_e32 v122, v122
	v_add_f32_e32 v127, 1.0, v127
	v_add_f32_e32 v123, 1.0, v123
	v_rcp_f32_e32 v127, v127
	v_rcp_f32_e32 v123, v123
	v_add_f32_e32 v128, 1.0, v128
	v_add_f32_e32 v124, 1.0, v124
	v_rcp_f32_e32 v128, v128
	v_rcp_f32_e32 v124, v124
	v_add_f32_e32 v129, 1.0, v129
	v_rcp_f32_e32 v129, v129
	v_add_f32_e32 v125, 1.0, v125
	v_rcp_f32_e32 v125, v125
	v_mul_f32_e32 v126, 0x437f0000, v126
	v_mul_f32_e32 v122, 0x437f0000, v122
	v_cvt_pk_u8_f32 v126, v126, 0, 0
	v_cvt_pk_u8_f32 v122, v122, 0, 0
	v_mul_f32_e32 v127, 0x437f0000, v127
	v_mul_f32_e32 v123, 0x437f0000, v123
	v_cvt_pk_u8_f32 v126, v127, 1, v126
	v_cvt_pk_u8_f32 v122, v123, 1, v122
	v_mul_f32_e32 v123, 0x437f0000, v128
	v_mul_f32_e32 v124, 0x437f0000, v124
	v_cvt_pk_u8_f32 v123, v123, 2, v126
	v_cvt_pk_u8_f32 v124, v124, 2, v122
	v_mul_f32_e32 v122, 0x437f0000, v129
	v_cvt_pk_u8_f32 v122, v122, 3, v123
	v_mul_f32_e32 v123, 0x437f0000, v125
	v_cvt_pk_u8_f32 v123, v123, 3, v124
	v_mad_i64_i32 v[124:125], s[0:1], v132, s31, v[130:131]
	v_add_co_u32_e32 v124, vcc, 0x3000, v124
	s_nop 1
	v_addc_co_u32_e32 v125, vcc, 0, v125, vcc
	global_store_dwordx2 v[124:125], v[122:123], off offset:512
; __device__ __forceinline__ float sigmoidf_(float v) { return __builtin_amdgcn_rcpf(1.f + __expf(-v)); }
; __device__ __forceinline__ u32x4 pack8(f32x4 v0, f32x4 v1) { u32x4 w; w.x = cvt_pk_bf16(v0[0], v0[1]); w.y = cvt_pk_bf16(v0[2], v0[3]); w.z = cvt_pk_bf16(v1[0], v1[1]); w.w = cvt_pk_bf16(v1[2], v1[3]); return w; }
;     __device__ __forceinline__ void operator()(const f32x4 (&acc)[2][2][4][2], const Unit& u, int wr, int wc, int fr, int fq) const {
;         bf16_t* O_ = O; const bool gate = u.pn >= 8;
; #pragma unroll
;         for (int bj = 0; bj < 2; ++bj) { const int col = u.pn * BM + bj * HALF + wc * 32 + 8 * fq;
;             const f32x4 b0 = gate ? *(const f32x4*)(bm + col - 2048) : (f32x4){0.f, 0.f, 0.f, 0.f}, b1 = gate ? *(const f32x4*)(bm + col - 2048 + 4) : (f32x4){0.f, 0.f, 0.f, 0.f};
;             const int ocol = gate ? GATE0 + col - 2048 : col;
; #pragma unroll
;             for (int ai = 0; ai < 2; ++ai)
; #pragma unroll
;                 for (int m = 0; m < 4; ++m) { const int row = u.pm * BM + ai * HALF + wr * 64 + m * 16 + fr; f32x4 v0 = acc[ai][bj][m][0] * 0.03125f, v1 = acc[ai][bj][m][1] * 0.03125f;
;                     if (gate) {
; #pragma unroll
;                         for (int j = 0; j < 4; ++j) { v0[j] = sigmoidf_(v0[j] + b0[j]); v1[j] = sigmoidf_(v1[j] + b1[j]); }
;                         *(u32x2*)((unsigned char*)(O_ + (size_t)row * NP + GATE0) + (col - 2048)) = gate_pack8(v0, v1); }
;                     else *(u32x4*)(O_ + (size_t)row * NP + ocol) = pack8(v0, v1); } }
;     }
.LBB0_722:
	s_mov_b32 s0, 0x3d000000
	v_or_b32_e32 v122, 32, v150
	v_pk_mul_f32 v[112:113], v[112:113], s[0:1] op_sel_hi:[1,0]
	v_pk_mul_f32 v[110:111], v[110:111], s[0:1] op_sel_hi:[1,0]
	v_pk_mul_f32 v[108:109], v[108:109], s[0:1] op_sel_hi:[1,0]
	v_pk_mul_f32 v[106:107], v[106:107], s[0:1] op_sel_hi:[1,0]
	s_and_b64 vcc, exec, s[40:41]
	s_mov_b64 s[88:89], -1
	s_cbranch_vccnz .LBB0_724
	v_mad_i64_i32 v[128:129], s[0:1], v122, s31, v[144:145]
	s_mov_b64 s[88:89], 0
	v_cvt_pk_bf16_f32 v124, v110, v111
	v_cvt_pk_bf16_f32 v125, v112, v113
	v_cvt_pk_bf16_f32 v126, v106, v107
	v_cvt_pk_bf16_f32 v127, v108, v109
	global_store_dwordx4 v[128:129], v[124:127], off
.LBB0_724:
	s_andn2_b64 vcc, exec, s[88:89]
	s_cbranch_vccnz .LBB0_726
	s_waitcnt vmcnt(0)
	v_add_f32_e32 v110, v110, v118
	v_add_f32_e32 v106, v106, v114
	v_mul_f32_e32 v110, 0xbfb8aa3b, v110
	v_mul_f32_e32 v106, 0xbfb8aa3b, v106
	v_add_f32_e32 v111, v111, v119
	v_add_f32_e32 v107, v107, v115
	v_exp_f32_e32 v110, v110
	v_exp_f32_e32 v106, v106
	v_mul_f32_e32 v111, 0xbfb8aa3b, v111
	v_mul_f32_e32 v107, 0xbfb8aa3b, v107
	v_add_f32_e32 v112, v112, v120
	v_add_f32_e32 v108, v108, v116
	v_exp_f32_e32 v111, v111
	v_exp_f32_e32 v107, v107
	v_mul_f32_e32 v112, 0xbfb8aa3b, v112
	v_mul_f32_e32 v108, 0xbfb8aa3b, v108
	v_add_f32_e32 v113, v113, v121
	v_exp_f32_e32 v112, v112
	v_exp_f32_e32 v108, v108
	v_mul_f32_e32 v113, 0xbfb8aa3b, v113
	v_add_f32_e32 v109, v109, v117
	v_exp_f32_e32 v113, v113
	v_mul_f32_e32 v109, 0xbfb8aa3b, v109
	v_add_f32_e32 v110, 1.0, v110
	v_add_f32_e32 v106, 1.0, v106
	v_exp_f32_e32 v109, v109
	v_rcp_f32_e32 v110, v110
	v_rcp_f32_e32 v106, v106
	v_add_f32_e32 v111, 1.0, v111
	v_add_f32_e32 v107, 1.0, v107
	v_rcp_f32_e32 v111, v111
	v_rcp_f32_e32 v107, v107
	v_add_f32_e32 v112, 1.0, v112
	v_add_f32_e32 v108, 1.0, v108
	v_rcp_f32_e32 v112, v112
	v_rcp_f32_e32 v108, v108
	v_add_f32_e32 v113, 1.0, v113
	v_rcp_f32_e32 v113, v113
	v_add_f32_e32 v109, 1.0, v109
	v_rcp_f32_e32 v109, v109
	v_mul_f32_e32 v110, 0x437f0000, v110
	v_mul_f32_e32 v106, 0x437f0000, v106
	v_cvt_pk_u8_f32 v110, v110, 0, 0
	v_cvt_pk_u8_f32 v106, v106, 0, 0
	v_mul_f32_e32 v111, 0x437f0000, v111
	v_mul_f32_e32 v107, 0x437f0000, v107
	v_cvt_pk_u8_f32 v110, v111, 1, v110
	v_cvt_pk_u8_f32 v106, v107, 1, v106
	v_mul_f32_e32 v107, 0x437f0000, v112
	v_mul_f32_e32 v108, 0x437f0000, v108
	v_cvt_pk_u8_f32 v107, v107, 2, v110
	v_cvt_pk_u8_f32 v108, v108, 2, v106
	v_mul_f32_e32 v106, 0x437f0000, v113
	v_cvt_pk_u8_f32 v106, v106, 3, v107
	v_mul_f32_e32 v107, 0x437f0000, v109
	v_cvt_pk_u8_f32 v107, v107, 3, v108
	v_mad_i64_i32 v[108:109], s[0:1], v122, s31, v[130:131]
	v_add_co_u32_e32 v108, vcc, 0x3000, v108
	s_nop 1
	v_addc_co_u32_e32 v109, vcc, 0, v109, vcc
	global_store_dwordx2 v[108:109], v[106:107], off offset:512
.LBB0_726:
	s_mov_b32 s0, 0x3d000000
	v_or_b32_e32 v106, 48, v150
	v_pk_mul_f32 v[104:105], v[104:105], s[0:1] op_sel_hi:[1,0]
	v_pk_mul_f32 v[102:103], v[102:103], s[0:1] op_sel_hi:[1,0]
	v_pk_mul_f32 v[100:101], v[100:101], s[0:1] op_sel_hi:[1,0]
	v_pk_mul_f32 v[98:99], v[98:99], s[0:1] op_sel_hi:[1,0]
	s_and_b64 vcc, exec, s[40:41]
	s_mov_b64 s[88:89], -1
	s_cbranch_vccnz .LBB0_728
	v_mad_i64_i32 v[112:113], s[0:1], v106, s31, v[144:145]
	s_mov_b64 s[88:89], 0
	v_cvt_pk_bf16_f32 v108, v102, v103
	v_cvt_pk_bf16_f32 v109, v104, v105
	v_cvt_pk_bf16_f32 v110, v98, v99
	v_cvt_pk_bf16_f32 v111, v100, v101
	global_store_dwordx4 v[112:113], v[108:111], off
.LBB0_728:
	s_andn2_b64 vcc, exec, s[88:89]
	s_cbranch_vccnz .LBB0_730
	s_waitcnt vmcnt(0)
	v_add_f32_e32 v102, v102, v118
	v_add_f32_e32 v98, v98, v114
	v_mul_f32_e32 v102, 0xbfb8aa3b, v102
	v_mul_f32_e32 v98, 0xbfb8aa3b, v98
	v_add_f32_e32 v103, v103, v119
	v_add_f32_e32 v99, v99, v115
	v_exp_f32_e32 v102, v102
	v_exp_f32_e32 v98, v98
	v_mul_f32_e32 v103, 0xbfb8aa3b, v103
	v_mul_f32_e32 v99, 0xbfb8aa3b, v99
	v_add_f32_e32 v104, v104, v120
	v_add_f32_e32 v100, v100, v116
	v_exp_f32_e32 v103, v103
	v_exp_f32_e32 v99, v99
	v_mul_f32_e32 v104, 0xbfb8aa3b, v104
	v_mul_f32_e32 v100, 0xbfb8aa3b, v100
	v_add_f32_e32 v105, v105, v121
	v_exp_f32_e32 v104, v104
	v_exp_f32_e32 v100, v100
	v_mul_f32_e32 v105, 0xbfb8aa3b, v105
	v_add_f32_e32 v101, v101, v117
	v_exp_f32_e32 v105, v105
	v_mul_f32_e32 v101, 0xbfb8aa3b, v101
	v_add_f32_e32 v102, 1.0, v102
	v_add_f32_e32 v98, 1.0, v98
	v_exp_f32_e32 v101, v101
	v_rcp_f32_e32 v102, v102
	v_rcp_f32_e32 v98, v98
	v_add_f32_e32 v103, 1.0, v103
	v_add_f32_e32 v99, 1.0, v99
	v_rcp_f32_e32 v103, v103
	v_rcp_f32_e32 v99, v99
	v_add_f32_e32 v104, 1.0, v104
	v_add_f32_e32 v100, 1.0, v100
	v_rcp_f32_e32 v104, v104
	v_rcp_f32_e32 v100, v100
	v_add_f32_e32 v105, 1.0, v105
	v_rcp_f32_e32 v105, v105
	v_add_f32_e32 v101, 1.0, v101
	v_rcp_f32_e32 v101, v101
	v_mul_f32_e32 v102, 0x437f0000, v102
	v_mul_f32_e32 v98, 0x437f0000, v98
	v_cvt_pk_u8_f32 v102, v102, 0, 0
	v_cvt_pk_u8_f32 v98, v98, 0, 0
	v_mul_f32_e32 v103, 0x437f0000, v103
	v_mul_f32_e32 v99, 0x437f0000, v99
	v_cvt_pk_u8_f32 v102, v103, 1, v102
	v_cvt_pk_u8_f32 v98, v99, 1, v98
	v_mul_f32_e32 v99, 0x437f0000, v104
	v_mul_f32_e32 v100, 0x437f0000, v100
	v_cvt_pk_u8_f32 v99, v99, 2, v102
	v_cvt_pk_u8_f32 v100, v100, 2, v98
	v_mul_f32_e32 v98, 0x437f0000, v105
	v_cvt_pk_u8_f32 v98, v98, 3, v99
	v_mul_f32_e32 v99, 0x437f0000, v101
	v_cvt_pk_u8_f32 v99, v99, 3, v100
	v_mad_i64_i32 v[100:101], s[0:1], v106, s31, v[130:131]
	v_add_co_u32_e32 v100, vcc, 0x3000, v100
	s_nop 1
	v_addc_co_u32_e32 v101, vcc, 0, v101, vcc
	global_store_dwordx2 v[100:101], v[98:99], off offset:512
; __device__ __forceinline__ float sigmoidf_(float v) { return __builtin_amdgcn_rcpf(1.f + __expf(-v)); }
; __device__ __forceinline__ u32x4 pack8(f32x4 v0, f32x4 v1) { u32x4 w; w.x = cvt_pk_bf16(v0[0], v0[1]); w.y = cvt_pk_bf16(v0[2], v0[3]); w.z = cvt_pk_bf16(v1[0], v1[1]); w.w = cvt_pk_bf16(v1[2], v1[3]); return w; }
;     __device__ __forceinline__ void operator()(const f32x4 (&acc)[2][2][4][2], const Unit& u, int wr, int wc, int fr, int fq) const {
;         bf16_t* O_ = O; const bool gate = u.pn >= 8;
; #pragma unroll
;         for (int bj = 0; bj < 2; ++bj) { const int col = u.pn * BM + bj * HALF + wc * 32 + 8 * fq;
;             const f32x4 b0 = gate ? *(const f32x4*)(bm + col - 2048) : (f32x4){0.f, 0.f, 0.f, 0.f}, b1 = gate ? *(const f32x4*)(bm + col - 2048 + 4) : (f32x4){0.f, 0.f, 0.f, 0.f};
;             const int ocol = gate ? GATE0 + col - 2048 : col;
; #pragma unroll
;             for (int ai = 0; ai < 2; ++ai)
; #pragma unroll
;                 for (int m = 0; m < 4; ++m) { const int row = u.pm * BM + ai * HALF + wr * 64 + m * 16 + fr; f32x4 v0 = acc[ai][bj][m][0] * 0.03125f, v1 = acc[ai][bj][m][1] * 0.03125f;
;                     if (gate) {
; #pragma unroll
;                         for (int j = 0; j < 4; ++j) { v0[j] = sigmoidf_(v0[j] + b0[j]); v1[j] = sigmoidf_(v1[j] + b1[j]); }
;                         *(u32x2*)((unsigned char*)(O_ + (size_t)row * NP + GATE0) + (col - 2048)) = gate_pack8(v0, v1); }
;                     else *(u32x4*)(O_ + (size_t)row * NP + ocol) = pack8(v0, v1); } }
;     }
.LBB0_730:
	s_mov_b32 s0, 0x3d000000
	v_add_u32_e32 v98, 0x80, v150
	v_pk_mul_f32 v[96:97], v[96:97], s[0:1] op_sel_hi:[1,0]
	v_pk_mul_f32 v[94:95], v[94:95], s[0:1] op_sel_hi:[1,0]
	v_pk_mul_f32 v[92:93], v[92:93], s[0:1] op_sel_hi:[1,0]
	v_pk_mul_f32 v[90:91], v[90:91], s[0:1] op_sel_hi:[1,0]
	s_and_b64 vcc, exec, s[40:41]
	s_mov_b64 s[88:89], -1
	s_cbranch_vccnz .LBB0_732
	v_mad_i64_i32 v[104:105], s[0:1], v98, s31, v[144:145]
	s_mov_b64 s[88:89], 0
	v_cvt_pk_bf16_f32 v100, v94, v95
	v_cvt_pk_bf16_f32 v101, v96, v97
	v_cvt_pk_bf16_f32 v102, v90, v91
	v_cvt_pk_bf16_f32 v103, v92, v93
	global_store_dwordx4 v[104:105], v[100:103], off
.LBB0_732:
	s_andn2_b64 vcc, exec, s[88:89]
	s_cbranch_vccnz .LBB0_734
	s_waitcnt vmcnt(0)
	v_add_f32_e32 v94, v94, v118
	v_add_f32_e32 v90, v90, v114
	v_mul_f32_e32 v94, 0xbfb8aa3b, v94
	v_mul_f32_e32 v90, 0xbfb8aa3b, v90
	v_add_f32_e32 v95, v95, v119
	v_add_f32_e32 v91, v91, v115
	v_exp_f32_e32 v94, v94
	v_exp_f32_e32 v90, v90
	v_mul_f32_e32 v95, 0xbfb8aa3b, v95
	v_mul_f32_e32 v91, 0xbfb8aa3b, v91
	v_add_f32_e32 v96, v96, v120
	v_add_f32_e32 v92, v92, v116
	v_exp_f32_e32 v95, v95
	v_exp_f32_e32 v91, v91
	v_mul_f32_e32 v96, 0xbfb8aa3b, v96
	v_mul_f32_e32 v92, 0xbfb8aa3b, v92
	v_add_f32_e32 v97, v97, v121
	v_exp_f32_e32 v96, v96
	v_exp_f32_e32 v92, v92
	v_mul_f32_e32 v97, 0xbfb8aa3b, v97
	v_add_f32_e32 v93, v93, v117
	v_exp_f32_e32 v97, v97
	v_mul_f32_e32 v93, 0xbfb8aa3b, v93
	v_add_f32_e32 v94, 1.0, v94
	v_add_f32_e32 v90, 1.0, v90
	v_exp_f32_e32 v93, v93
	v_rcp_f32_e32 v94, v94
	v_rcp_f32_e32 v90, v90
	v_add_f32_e32 v95, 1.0, v95
	v_add_f32_e32 v91, 1.0, v91
	v_rcp_f32_e32 v95, v95
	v_rcp_f32_e32 v91, v91
	v_add_f32_e32 v96, 1.0, v96
	v_add_f32_e32 v92, 1.0, v92
	v_rcp_f32_e32 v96, v96
	v_rcp_f32_e32 v92, v92
	v_add_f32_e32 v97, 1.0, v97
	v_rcp_f32_e32 v97, v97
	v_add_f32_e32 v93, 1.0, v93
	v_rcp_f32_e32 v93, v93
	v_mul_f32_e32 v94, 0x437f0000, v94
	v_mul_f32_e32 v90, 0x437f0000, v90
	v_cvt_pk_u8_f32 v94, v94, 0, 0
	v_cvt_pk_u8_f32 v90, v90, 0, 0
	v_mul_f32_e32 v95, 0x437f0000, v95
	v_mul_f32_e32 v91, 0x437f0000, v91
	v_cvt_pk_u8_f32 v94, v95, 1, v94
	v_cvt_pk_u8_f32 v90, v91, 1, v90
	v_mul_f32_e32 v91, 0x437f0000, v96
	v_mul_f32_e32 v92, 0x437f0000, v92
	v_cvt_pk_u8_f32 v91, v91, 2, v94
	v_cvt_pk_u8_f32 v92, v92, 2, v90
	v_mul_f32_e32 v90, 0x437f0000, v97
	v_cvt_pk_u8_f32 v90, v90, 3, v91
	v_mul_f32_e32 v91, 0x437f0000, v93
	v_cvt_pk_u8_f32 v91, v91, 3, v92
	v_mad_i64_i32 v[92:93], s[0:1], v98, s31, v[130:131]
	v_add_co_u32_e32 v92, vcc, 0x3000, v92
	s_nop 1
	v_addc_co_u32_e32 v93, vcc, 0, v93, vcc
	global_store_dwordx2 v[92:93], v[90:91], off offset:512
.LBB0_734:
	s_mov_b32 s0, 0x3d000000
	v_add_u32_e32 v90, 0x90, v150
	v_pk_mul_f32 v[88:89], v[88:89], s[0:1] op_sel_hi:[1,0]
	v_pk_mul_f32 v[86:87], v[86:87], s[0:1] op_sel_hi:[1,0]
	v_pk_mul_f32 v[84:85], v[84:85], s[0:1] op_sel_hi:[1,0]
	v_pk_mul_f32 v[82:83], v[82:83], s[0:1] op_sel_hi:[1,0]
	s_and_b64 vcc, exec, s[40:41]
	s_mov_b64 s[88:89], -1
	s_cbranch_vccnz .LBB0_736
	v_mad_i64_i32 v[96:97], s[0:1], v90, s31, v[144:145]
	s_mov_b64 s[88:89], 0
	v_cvt_pk_bf16_f32 v92, v86, v87
	v_cvt_pk_bf16_f32 v93, v88, v89
	v_cvt_pk_bf16_f32 v94, v82, v83
	v_cvt_pk_bf16_f32 v95, v84, v85
	global_store_dwordx4 v[96:97], v[92:95], off
.LBB0_736:
	s_andn2_b64 vcc, exec, s[88:89]
	s_cbranch_vccnz .LBB0_738
	s_waitcnt vmcnt(0)
	v_add_f32_e32 v86, v86, v118
	v_add_f32_e32 v82, v82, v114
	v_mul_f32_e32 v86, 0xbfb8aa3b, v86
	v_mul_f32_e32 v82, 0xbfb8aa3b, v82
	v_add_f32_e32 v87, v87, v119
	v_add_f32_e32 v83, v83, v115
	v_exp_f32_e32 v86, v86
	v_exp_f32_e32 v82, v82
	v_mul_f32_e32 v87, 0xbfb8aa3b, v87
	v_mul_f32_e32 v83, 0xbfb8aa3b, v83
	v_add_f32_e32 v88, v88, v120
	v_add_f32_e32 v84, v84, v116
	v_exp_f32_e32 v87, v87
	v_exp_f32_e32 v83, v83
	v_mul_f32_e32 v88, 0xbfb8aa3b, v88
	v_mul_f32_e32 v84, 0xbfb8aa3b, v84
	v_add_f32_e32 v89, v89, v121
	v_exp_f32_e32 v88, v88
	v_exp_f32_e32 v84, v84
	v_mul_f32_e32 v89, 0xbfb8aa3b, v89
	v_add_f32_e32 v85, v85, v117
	v_exp_f32_e32 v89, v89
	v_mul_f32_e32 v85, 0xbfb8aa3b, v85
	v_add_f32_e32 v86, 1.0, v86
	v_add_f32_e32 v82, 1.0, v82
	v_exp_f32_e32 v85, v85
	v_rcp_f32_e32 v86, v86
	v_rcp_f32_e32 v82, v82
	v_add_f32_e32 v87, 1.0, v87
	v_add_f32_e32 v83, 1.0, v83
	v_rcp_f32_e32 v87, v87
	v_rcp_f32_e32 v83, v83
	v_add_f32_e32 v88, 1.0, v88
	v_add_f32_e32 v84, 1.0, v84
	v_rcp_f32_e32 v88, v88
	v_rcp_f32_e32 v84, v84
	v_add_f32_e32 v89, 1.0, v89
	v_rcp_f32_e32 v89, v89
	v_add_f32_e32 v85, 1.0, v85
	v_rcp_f32_e32 v85, v85
	v_mul_f32_e32 v86, 0x437f0000, v86
	v_mul_f32_e32 v82, 0x437f0000, v82
	v_cvt_pk_u8_f32 v86, v86, 0, 0
	v_cvt_pk_u8_f32 v82, v82, 0, 0
	v_mul_f32_e32 v87, 0x437f0000, v87
	v_mul_f32_e32 v83, 0x437f0000, v83
	v_cvt_pk_u8_f32 v86, v87, 1, v86
	v_cvt_pk_u8_f32 v82, v83, 1, v82
	v_mul_f32_e32 v83, 0x437f0000, v88
	v_mul_f32_e32 v84, 0x437f0000, v84
	v_cvt_pk_u8_f32 v83, v83, 2, v86
	v_cvt_pk_u8_f32 v84, v84, 2, v82
	v_mul_f32_e32 v82, 0x437f0000, v89
	v_cvt_pk_u8_f32 v82, v82, 3, v83
	v_mul_f32_e32 v83, 0x437f0000, v85
	v_cvt_pk_u8_f32 v83, v83, 3, v84
	v_mad_i64_i32 v[84:85], s[0:1], v90, s31, v[130:131]
	v_add_co_u32_e32 v84, vcc, 0x3000, v84
	s_nop 1
	v_addc_co_u32_e32 v85, vcc, 0, v85, vcc
	global_store_dwordx2 v[84:85], v[82:83], off offset:512
; __device__ __forceinline__ float sigmoidf_(float v) { return __builtin_amdgcn_rcpf(1.f + __expf(-v)); }
; __device__ __forceinline__ u32x4 pack8(f32x4 v0, f32x4 v1) { u32x4 w; w.x = cvt_pk_bf16(v0[0], v0[1]); w.y = cvt_pk_bf16(v0[2], v0[3]); w.z = cvt_pk_bf16(v1[0], v1[1]); w.w = cvt_pk_bf16(v1[2], v1[3]); return w; }
;     __device__ __forceinline__ void operator()(const f32x4 (&acc)[2][2][4][2], const Unit& u, int wr, int wc, int fr, int fq) const {
;         bf16_t* O_ = O; const bool gate = u.pn >= 8;
; #pragma unroll
;         for (int bj = 0; bj < 2; ++bj) { const int col = u.pn * BM + bj * HALF + wc * 32 + 8 * fq;
;             const f32x4 b0 = gate ? *(const f32x4*)(bm + col - 2048) : (f32x4){0.f, 0.f, 0.f, 0.f}, b1 = gate ? *(const f32x4*)(bm + col - 2048 + 4) : (f32x4){0.f, 0.f, 0.f, 0.f};
;             const int ocol = gate ? GATE0 + col - 2048 : col;
; #pragma unroll
;             for (int ai = 0; ai < 2; ++ai)
; #pragma unroll
;                 for (int m = 0; m < 4; ++m) { const int row = u.pm * BM + ai * HALF + wr * 64 + m * 16 + fr; f32x4 v0 = acc[ai][bj][m][0] * 0.03125f, v1 = acc[ai][bj][m][1] * 0.03125f;
;                     if (gate) {
; #pragma unroll
;                         for (int j = 0; j < 4; ++j) { v0[j] = sigmoidf_(v0[j] + b0[j]); v1[j] = sigmoidf_(v1[j] + b1[j]); }
;                         *(u32x2*)((unsigned char*)(O_ + (size_t)row * NP + GATE0) + (col - 2048)) = gate_pack8(v0, v1); }
;                     else *(u32x4*)(O_ + (size_t)row * NP + ocol) = pack8(v0, v1); } }
;     }
.LBB0_738:
	s_mov_b32 s0, 0x3d000000
	v_add_u32_e32 v82, 0xa0, v150
	v_pk_mul_f32 v[80:81], v[80:81], s[0:1] op_sel_hi:[1,0]
	v_pk_mul_f32 v[78:79], v[78:79], s[0:1] op_sel_hi:[1,0]
	v_pk_mul_f32 v[76:77], v[76:77], s[0:1] op_sel_hi:[1,0]
	v_pk_mul_f32 v[74:75], v[74:75], s[0:1] op_sel_hi:[1,0]
	s_and_b64 vcc, exec, s[40:41]
	s_mov_b64 s[88:89], -1
	s_cbranch_vccnz .LBB0_740
	v_mad_i64_i32 v[88:89], s[0:1], v82, s31, v[144:145]
	s_mov_b64 s[88:89], 0
	v_cvt_pk_bf16_f32 v84, v78, v79
	v_cvt_pk_bf16_f32 v85, v80, v81
	v_cvt_pk_bf16_f32 v86, v74, v75
	v_cvt_pk_bf16_f32 v87, v76, v77
	global_store_dwordx4 v[88:89], v[84:87], off
.LBB0_740:
	s_andn2_b64 vcc, exec, s[88:89]
	s_cbranch_vccnz .LBB0_742
	s_waitcnt vmcnt(0)
	v_add_f32_e32 v78, v78, v118
	v_add_f32_e32 v74, v74, v114
	v_mul_f32_e32 v78, 0xbfb8aa3b, v78
	v_mul_f32_e32 v74, 0xbfb8aa3b, v74
	v_add_f32_e32 v79, v79, v119
	v_add_f32_e32 v75, v75, v115
	v_exp_f32_e32 v78, v78
	v_exp_f32_e32 v74, v74
	v_mul_f32_e32 v79, 0xbfb8aa3b, v79
	v_mul_f32_e32 v75, 0xbfb8aa3b, v75
	v_add_f32_e32 v80, v80, v120
	v_add_f32_e32 v76, v76, v116
	v_exp_f32_e32 v79, v79
	v_exp_f32_e32 v75, v75
	v_mul_f32_e32 v80, 0xbfb8aa3b, v80
	v_mul_f32_e32 v76, 0xbfb8aa3b, v76
	v_add_f32_e32 v81, v81, v121
	v_exp_f32_e32 v80, v80
	v_exp_f32_e32 v76, v76
	v_mul_f32_e32 v81, 0xbfb8aa3b, v81
	v_add_f32_e32 v77, v77, v117
	v_exp_f32_e32 v81, v81
	v_mul_f32_e32 v77, 0xbfb8aa3b, v77
	v_add_f32_e32 v78, 1.0, v78
	v_add_f32_e32 v74, 1.0, v74
	v_exp_f32_e32 v77, v77
	v_rcp_f32_e32 v78, v78
	v_rcp_f32_e32 v74, v74
	v_add_f32_e32 v79, 1.0, v79
	v_add_f32_e32 v75, 1.0, v75
	v_rcp_f32_e32 v79, v79
	v_rcp_f32_e32 v75, v75
	v_add_f32_e32 v80, 1.0, v80
	v_add_f32_e32 v76, 1.0, v76
	v_rcp_f32_e32 v80, v80
	v_rcp_f32_e32 v76, v76
	v_add_f32_e32 v81, 1.0, v81
	v_rcp_f32_e32 v81, v81
	v_add_f32_e32 v77, 1.0, v77
	v_rcp_f32_e32 v77, v77
	v_mul_f32_e32 v78, 0x437f0000, v78
	v_mul_f32_e32 v74, 0x437f0000, v74
	v_cvt_pk_u8_f32 v78, v78, 0, 0
	v_cvt_pk_u8_f32 v74, v74, 0, 0
	v_mul_f32_e32 v79, 0x437f0000, v79
	v_mul_f32_e32 v75, 0x437f0000, v75
	v_cvt_pk_u8_f32 v78, v79, 1, v78
	v_cvt_pk_u8_f32 v74, v75, 1, v74
	v_mul_f32_e32 v75, 0x437f0000, v80
	v_mul_f32_e32 v76, 0x437f0000, v76
	v_cvt_pk_u8_f32 v75, v75, 2, v78
	v_cvt_pk_u8_f32 v76, v76, 2, v74
	v_mul_f32_e32 v74, 0x437f0000, v81
	v_cvt_pk_u8_f32 v74, v74, 3, v75
	v_mul_f32_e32 v75, 0x437f0000, v77
	v_cvt_pk_u8_f32 v75, v75, 3, v76
	v_mad_i64_i32 v[76:77], s[0:1], v82, s31, v[130:131]
	v_add_co_u32_e32 v76, vcc, 0x3000, v76
	s_nop 1
	v_addc_co_u32_e32 v77, vcc, 0, v77, vcc
	global_store_dwordx2 v[76:77], v[74:75], off offset:512
.LBB0_742:
	s_mov_b32 s0, 0x3d000000
	v_add_u32_e32 v76, 0xb0, v150
	v_pk_mul_f32 v[72:73], v[72:73], s[0:1] op_sel_hi:[1,0]
	v_pk_mul_f32 v[70:71], v[70:71], s[0:1] op_sel_hi:[1,0]
	v_pk_mul_f32 v[68:69], v[68:69], s[0:1] op_sel_hi:[1,0]
	v_pk_mul_f32 v[66:67], v[66:67], s[0:1] op_sel_hi:[1,0]
	s_and_b64 vcc, exec, s[40:41]
	s_mov_b64 s[88:89], -1
	s_cbranch_vccnz .LBB0_744
	v_mad_i64_i32 v[74:75], s[0:1], v76, s31, v[144:145]
	s_mov_b64 s[88:89], 0
	v_cvt_pk_bf16_f32 v78, v70, v71
	v_cvt_pk_bf16_f32 v79, v72, v73
	v_cvt_pk_bf16_f32 v80, v66, v67
	v_cvt_pk_bf16_f32 v81, v68, v69
	global_store_dwordx4 v[74:75], v[78:81], off
.LBB0_744:
	s_andn2_b64 vcc, exec, s[88:89]
	s_cbranch_vccnz .LBB0_746
	s_waitcnt vmcnt(0)
	v_add_f32_e32 v70, v70, v118
	v_add_f32_e32 v66, v66, v114
	v_mul_f32_e32 v70, 0xbfb8aa3b, v70
	v_mul_f32_e32 v66, 0xbfb8aa3b, v66
	v_add_f32_e32 v71, v71, v119
	v_add_f32_e32 v67, v67, v115
	v_exp_f32_e32 v70, v70
	v_exp_f32_e32 v66, v66
	v_mul_f32_e32 v71, 0xbfb8aa3b, v71
	v_mul_f32_e32 v67, 0xbfb8aa3b, v67
	v_add_f32_e32 v72, v72, v120
	v_add_f32_e32 v68, v68, v116
	v_exp_f32_e32 v71, v71
	v_exp_f32_e32 v67, v67
	v_mul_f32_e32 v72, 0xbfb8aa3b, v72
	v_mul_f32_e32 v68, 0xbfb8aa3b, v68
	v_add_f32_e32 v73, v73, v121
	v_exp_f32_e32 v72, v72
	v_exp_f32_e32 v68, v68
	v_mul_f32_e32 v73, 0xbfb8aa3b, v73
	v_add_f32_e32 v69, v69, v117
	v_exp_f32_e32 v73, v73
	v_mul_f32_e32 v69, 0xbfb8aa3b, v69
	v_add_f32_e32 v70, 1.0, v70
	v_add_f32_e32 v66, 1.0, v66
	v_exp_f32_e32 v69, v69
	v_rcp_f32_e32 v70, v70
	v_rcp_f32_e32 v66, v66
	v_add_f32_e32 v71, 1.0, v71
	v_add_f32_e32 v67, 1.0, v67
	v_rcp_f32_e32 v71, v71
	v_rcp_f32_e32 v67, v67
	v_add_f32_e32 v72, 1.0, v72
	v_add_f32_e32 v68, 1.0, v68
	v_rcp_f32_e32 v72, v72
	v_rcp_f32_e32 v68, v68
	v_add_f32_e32 v73, 1.0, v73
	v_rcp_f32_e32 v73, v73
	v_add_f32_e32 v69, 1.0, v69
	v_rcp_f32_e32 v69, v69
	v_mul_f32_e32 v70, 0x437f0000, v70
	v_mul_f32_e32 v66, 0x437f0000, v66
	v_cvt_pk_u8_f32 v70, v70, 0, 0
	v_cvt_pk_u8_f32 v66, v66, 0, 0
	v_mul_f32_e32 v71, 0x437f0000, v71
	v_mul_f32_e32 v67, 0x437f0000, v67
	v_cvt_pk_u8_f32 v70, v71, 1, v70
	v_cvt_pk_u8_f32 v66, v67, 1, v66
	v_mul_f32_e32 v67, 0x437f0000, v72
	v_mul_f32_e32 v68, 0x437f0000, v68
	v_cvt_pk_u8_f32 v67, v67, 2, v70
	v_cvt_pk_u8_f32 v68, v68, 2, v66
	v_mul_f32_e32 v66, 0x437f0000, v73
	v_cvt_pk_u8_f32 v66, v66, 3, v67
	v_mul_f32_e32 v67, 0x437f0000, v69
	v_cvt_pk_u8_f32 v67, v67, 3, v68
	v_mad_i64_i32 v[68:69], s[0:1], v76, s31, v[130:131]
	v_add_co_u32_e32 v68, vcc, 0x3000, v68
	s_nop 1
	v_addc_co_u32_e32 v69, vcc, 0, v69, vcc
	global_store_dwordx2 v[68:69], v[66:67], off offset:512

; __device__ __forceinline__ float sigmoidf_(float v) { return __builtin_amdgcn_rcpf(1.f + __expf(-v)); }
; __device__ __forceinline__ u32x4 pack8(f32x4 v0, f32x4 v1) { u32x4 w; w.x = cvt_pk_bf16(v0[0], v0[1]); w.y = cvt_pk_bf16(v0[2], v0[3]); w.z = cvt_pk_bf16(v1[0], v1[1]); w.w = cvt_pk_bf16(v1[2], v1[3]); return w; }
;     __device__ __forceinline__ void operator()(const f32x4 (&acc)[2][2][4][2], const Unit& u, int wr, int wc, int fr, int fq) const {
;         bf16_t* O_ = O; const bool gate = u.pn >= 8;
; #pragma unroll
;         for (int bj = 0; bj < 2; ++bj) { const int col = u.pn * BM + bj * HALF + wc * 32 + 8 * fq;
;             const f32x4 b0 = gate ? *(const f32x4*)(bm + col - 2048) : (f32x4){0.f, 0.f, 0.f, 0.f}, b1 = gate ? *(const f32x4*)(bm + col - 2048 + 4) : (f32x4){0.f, 0.f, 0.f, 0.f};
;             const int ocol = gate ? GATE0 + col - 2048 : col;
; #pragma unroll
;             for (int ai = 0; ai < 2; ++ai)
; #pragma unroll
;                 for (int m = 0; m < 4; ++m) { const int row = u.pm * BM + ai * HALF + wr * 64 + m * 16 + fr; f32x4 v0 = acc[ai][bj][m][0] * 0.03125f, v1 = acc[ai][bj][m][1] * 0.03125f;
;                     if (gate) {
; #pragma unroll
;                         for (int j = 0; j < 4; ++j) { v0[j] = sigmoidf_(v0[j] + b0[j]); v1[j] = sigmoidf_(v1[j] + b1[j]); }
;                         *(u32x2*)((unsigned char*)(O_ + (size_t)row * NP + GATE0) + (col - 2048)) = gate_pack8(v0, v1); }
;                     else *(u32x4*)(O_ + (size_t)row * NP + ocol) = pack8(v0, v1); } }
;     }
.LBB0_750:
	v_or_b32_e32 v74, 0x80, v0
	s_mov_b32 s0, 0x3d000000
	v_ashrrev_i32_e32 v75, 31, v74
	v_pk_mul_f32 v[64:65], v[64:65], s[0:1] op_sel_hi:[1,0]
	v_pk_mul_f32 v[62:63], v[62:63], s[0:1] op_sel_hi:[1,0]
	v_pk_mul_f32 v[60:61], v[60:61], s[0:1] op_sel_hi:[1,0]
	v_pk_mul_f32 v[58:59], v[58:59], s[0:1] op_sel_hi:[1,0]
	s_and_b64 vcc, exec, s[40:41]
	s_mov_b64 s[42:43], -1
	s_cbranch_vccnz .LBB0_752
	v_readlane_b32 s0, v253, 13
	v_readlane_b32 s1, v253, 14
	s_mov_b64 s[42:43], 0
	v_cvt_pk_bf16_f32 v78, v62, v63
	v_cvt_pk_bf16_f32 v79, v64, v65
	v_cvt_pk_bf16_f32 v80, v58, v59
	v_cvt_pk_bf16_f32 v81, v60, v61
	s_nop 0
	v_mov_b64_e32 v[84:85], s[0:1]
	v_mad_i64_i32 v[84:85], s[0:1], v150, s31, v[84:85]
	v_lshl_add_u64 v[84:85], v[74:75], 1, v[84:85]
	global_store_dwordx4 v[84:85], v[78:81], off
.LBB0_752:
	s_andn2_b64 vcc, exec, s[42:43]
	v_mov_b32_e32 v0, v74
	s_cbranch_vccnz .LBB0_754
	s_waitcnt vmcnt(0)
	v_add_f32_e32 v62, v62, v70
	v_add_f32_e32 v58, v58, v66
	v_mul_f32_e32 v62, 0xbfb8aa3b, v62
	v_mul_f32_e32 v58, 0xbfb8aa3b, v58
	v_add_f32_e32 v63, v63, v71
	v_add_f32_e32 v59, v59, v67
	v_exp_f32_e32 v62, v62
	v_exp_f32_e32 v58, v58
	v_mul_f32_e32 v63, 0xbfb8aa3b, v63
	v_mul_f32_e32 v59, 0xbfb8aa3b, v59
	v_add_f32_e32 v64, v64, v72
	v_add_f32_e32 v60, v60, v68
	v_exp_f32_e32 v63, v63
	v_exp_f32_e32 v59, v59
	v_mul_f32_e32 v64, 0xbfb8aa3b, v64
	v_mul_f32_e32 v60, 0xbfb8aa3b, v60
	v_add_f32_e32 v65, v65, v73
	v_exp_f32_e32 v64, v64
	v_exp_f32_e32 v60, v60
	v_mul_f32_e32 v65, 0xbfb8aa3b, v65
	v_add_f32_e32 v61, v61, v69
	v_exp_f32_e32 v65, v65
	v_mul_f32_e32 v61, 0xbfb8aa3b, v61
	v_add_f32_e32 v62, 1.0, v62
	v_add_f32_e32 v58, 1.0, v58
	v_exp_f32_e32 v61, v61
	v_rcp_f32_e32 v62, v62
	v_rcp_f32_e32 v58, v58
	v_add_f32_e32 v63, 1.0, v63
	v_add_f32_e32 v59, 1.0, v59
	v_rcp_f32_e32 v63, v63
	v_rcp_f32_e32 v59, v59
	v_add_f32_e32 v64, 1.0, v64
	v_add_f32_e32 v60, 1.0, v60
	v_rcp_f32_e32 v64, v64
	v_rcp_f32_e32 v60, v60
	v_add_f32_e32 v65, 1.0, v65
	v_rcp_f32_e32 v65, v65
	v_add_f32_e32 v61, 1.0, v61
	v_rcp_f32_e32 v61, v61
	v_mul_f32_e32 v62, 0x437f0000, v62
	v_mul_f32_e32 v58, 0x437f0000, v58
	v_cvt_pk_u8_f32 v62, v62, 0, 0
	v_cvt_pk_u8_f32 v58, v58, 0, 0
	v_mul_f32_e32 v63, 0x437f0000, v63
	v_mul_f32_e32 v59, 0x437f0000, v59
	v_cvt_pk_u8_f32 v62, v63, 1, v62
	v_cvt_pk_u8_f32 v58, v59, 1, v58
	v_mul_f32_e32 v59, 0x437f0000, v64
	v_mul_f32_e32 v60, 0x437f0000, v60
	v_cvt_pk_u8_f32 v59, v59, 2, v62
	v_cvt_pk_u8_f32 v60, v60, 2, v58
	v_mul_f32_e32 v58, 0x437f0000, v65
	v_readlane_b32 s0, v253, 13
	v_cvt_pk_u8_f32 v58, v58, 3, v59
	v_mul_f32_e32 v59, 0x437f0000, v61
	v_readlane_b32 s1, v253, 14
	v_cvt_pk_u8_f32 v59, v59, 3, v60
	s_nop 0
	v_mov_b64_e32 v[60:61], s[0:1]
	v_mad_i64_i32 v[60:61], s[0:1], v150, s31, v[60:61]
	v_lshl_add_u64 v[60:61], v[60:61], 0, v[0:1]
	v_add_co_u32_e32 v60, vcc, 0x3000, v60
	s_nop 1
	v_addc_co_u32_e32 v61, vcc, 0, v61, vcc
	global_store_dwordx2 v[60:61], v[58:59], off offset:512
.LBB0_754:
	s_mov_b32 s0, 0x3d000000
	v_pk_mul_f32 v[56:57], v[56:57], s[0:1] op_sel_hi:[1,0]
	v_pk_mul_f32 v[54:55], v[54:55], s[0:1] op_sel_hi:[1,0]
	v_pk_mul_f32 v[52:53], v[52:53], s[0:1] op_sel_hi:[1,0]
	v_pk_mul_f32 v[50:51], v[50:51], s[0:1] op_sel_hi:[1,0]
	s_and_b64 vcc, exec, s[40:41]
	s_mov_b64 s[42:43], -1
	s_cbranch_vccnz .LBB0_756
	v_readlane_b32 s0, v253, 13
	v_readlane_b32 s1, v253, 14
	s_mov_b64 s[42:43], 0
	v_cvt_pk_bf16_f32 v58, v54, v55
	v_cvt_pk_bf16_f32 v59, v56, v57
	v_cvt_pk_bf16_f32 v60, v50, v51
	v_cvt_pk_bf16_f32 v61, v52, v53
	s_nop 0
	v_mov_b64_e32 v[62:63], s[0:1]
	v_mad_i64_i32 v[62:63], s[0:1], v132, s31, v[62:63]
	v_lshl_add_u64 v[62:63], v[74:75], 1, v[62:63]
	global_store_dwordx4 v[62:63], v[58:61], off
.LBB0_756:
	s_andn2_b64 vcc, exec, s[42:43]
	s_cbranch_vccnz .LBB0_758
	s_waitcnt vmcnt(0)
	v_add_f32_e32 v54, v54, v70
	v_add_f32_e32 v50, v50, v66
	v_mul_f32_e32 v54, 0xbfb8aa3b, v54
	v_mul_f32_e32 v50, 0xbfb8aa3b, v50
	v_add_f32_e32 v55, v55, v71
	v_add_f32_e32 v51, v51, v67
	v_exp_f32_e32 v54, v54
	v_exp_f32_e32 v50, v50
	v_mul_f32_e32 v55, 0xbfb8aa3b, v55
	v_mul_f32_e32 v51, 0xbfb8aa3b, v51
	v_add_f32_e32 v56, v56, v72
	v_add_f32_e32 v52, v52, v68
	v_exp_f32_e32 v55, v55
	v_exp_f32_e32 v51, v51
	v_mul_f32_e32 v56, 0xbfb8aa3b, v56
	v_mul_f32_e32 v52, 0xbfb8aa3b, v52
	v_add_f32_e32 v57, v57, v73
	v_exp_f32_e32 v56, v56
	v_exp_f32_e32 v52, v52
	v_mul_f32_e32 v57, 0xbfb8aa3b, v57
	v_add_f32_e32 v53, v53, v69
	v_exp_f32_e32 v57, v57
	v_mul_f32_e32 v53, 0xbfb8aa3b, v53
	v_add_f32_e32 v54, 1.0, v54
	v_add_f32_e32 v50, 1.0, v50
	v_exp_f32_e32 v53, v53
	v_rcp_f32_e32 v54, v54
	v_rcp_f32_e32 v50, v50
	v_add_f32_e32 v55, 1.0, v55
	v_add_f32_e32 v51, 1.0, v51
	v_rcp_f32_e32 v55, v55
	v_rcp_f32_e32 v51, v51
	v_add_f32_e32 v56, 1.0, v56
	v_add_f32_e32 v52, 1.0, v52
	v_rcp_f32_e32 v56, v56
	v_rcp_f32_e32 v52, v52
	v_add_f32_e32 v57, 1.0, v57
	v_rcp_f32_e32 v57, v57
	v_add_f32_e32 v53, 1.0, v53
	v_rcp_f32_e32 v53, v53
	v_mul_f32_e32 v54, 0x437f0000, v54
	v_mul_f32_e32 v50, 0x437f0000, v50
	v_cvt_pk_u8_f32 v54, v54, 0, 0
	v_cvt_pk_u8_f32 v50, v50, 0, 0
	v_mul_f32_e32 v55, 0x437f0000, v55
	v_mul_f32_e32 v51, 0x437f0000, v51
	v_cvt_pk_u8_f32 v54, v55, 1, v54
	v_cvt_pk_u8_f32 v50, v51, 1, v50
	v_mul_f32_e32 v51, 0x437f0000, v56
	v_mul_f32_e32 v52, 0x437f0000, v52
	v_cvt_pk_u8_f32 v51, v51, 2, v54
	v_cvt_pk_u8_f32 v52, v52, 2, v50
	v_mul_f32_e32 v50, 0x437f0000, v57
	v_readlane_b32 s0, v253, 13
	v_cvt_pk_u8_f32 v50, v50, 3, v51
	v_mul_f32_e32 v51, 0x437f0000, v53
	v_readlane_b32 s1, v253, 14
	v_cvt_pk_u8_f32 v51, v51, 3, v52
	s_nop 0
	v_mov_b64_e32 v[52:53], s[0:1]
	v_mad_i64_i32 v[52:53], s[0:1], v132, s31, v[52:53]
	v_lshl_add_u64 v[52:53], v[52:53], 0, v[0:1]
	v_add_co_u32_e32 v52, vcc, 0x3000, v52
	s_nop 1
	v_addc_co_u32_e32 v53, vcc, 0, v53, vcc
	global_store_dwordx2 v[52:53], v[50:51], off offset:512
; __device__ __forceinline__ float sigmoidf_(float v) { return __builtin_amdgcn_rcpf(1.f + __expf(-v)); }
; __device__ __forceinline__ u32x4 pack8(f32x4 v0, f32x4 v1) { u32x4 w; w.x = cvt_pk_bf16(v0[0], v0[1]); w.y = cvt_pk_bf16(v0[2], v0[3]); w.z = cvt_pk_bf16(v1[0], v1[1]); w.w = cvt_pk_bf16(v1[2], v1[3]); return w; }
;     __device__ __forceinline__ void operator()(const f32x4 (&acc)[2][2][4][2], const Unit& u, int wr, int wc, int fr, int fq) const {
;         bf16_t* O_ = O; const bool gate = u.pn >= 8;
; #pragma unroll
;         for (int bj = 0; bj < 2; ++bj) { const int col = u.pn * BM + bj * HALF + wc * 32 + 8 * fq;
;             const f32x4 b0 = gate ? *(const f32x4*)(bm + col - 2048) : (f32x4){0.f, 0.f, 0.f, 0.f}, b1 = gate ? *(const f32x4*)(bm + col - 2048 + 4) : (f32x4){0.f, 0.f, 0.f, 0.f};
;             const int ocol = gate ? GATE0 + col - 2048 : col;
; #pragma unroll
;             for (int ai = 0; ai < 2; ++ai)
; #pragma unroll
;                 for (int m = 0; m < 4; ++m) { const int row = u.pm * BM + ai * HALF + wr * 64 + m * 16 + fr; f32x4 v0 = acc[ai][bj][m][0] * 0.03125f, v1 = acc[ai][bj][m][1] * 0.03125f;
;                     if (gate) {
; #pragma unroll
;                         for (int j = 0; j < 4; ++j) { v0[j] = sigmoidf_(v0[j] + b0[j]); v1[j] = sigmoidf_(v1[j] + b1[j]); }
;                         *(u32x2*)((unsigned char*)(O_ + (size_t)row * NP + GATE0) + (col - 2048)) = gate_pack8(v0, v1); }
;                     else *(u32x4*)(O_ + (size_t)row * NP + ocol) = pack8(v0, v1); } }
;     }
.LBB0_758:
	s_mov_b32 s0, 0x3d000000
	v_pk_mul_f32 v[48:49], v[48:49], s[0:1] op_sel_hi:[1,0]
	v_pk_mul_f32 v[46:47], v[46:47], s[0:1] op_sel_hi:[1,0]
	v_pk_mul_f32 v[44:45], v[44:45], s[0:1] op_sel_hi:[1,0]
	v_pk_mul_f32 v[42:43], v[42:43], s[0:1] op_sel_hi:[1,0]
	s_and_b64 vcc, exec, s[40:41]
	s_mov_b64 s[42:43], -1
	s_cbranch_vccnz .LBB0_760
	v_readlane_b32 s0, v253, 13
	v_readlane_b32 s1, v253, 14
	s_mov_b64 s[42:43], 0
	v_cvt_pk_bf16_f32 v50, v46, v47
	v_cvt_pk_bf16_f32 v51, v48, v49
	v_cvt_pk_bf16_f32 v52, v42, v43
	v_cvt_pk_bf16_f32 v53, v44, v45
	s_nop 0
	v_mov_b64_e32 v[54:55], s[0:1]
	v_mad_i64_i32 v[54:55], s[0:1], v122, s31, v[54:55]
	v_lshl_add_u64 v[54:55], v[74:75], 1, v[54:55]
	global_store_dwordx4 v[54:55], v[50:53], off
.LBB0_760:
	s_andn2_b64 vcc, exec, s[42:43]
	s_cbranch_vccnz .LBB0_762
	s_waitcnt vmcnt(0)
	v_add_f32_e32 v46, v46, v70
	v_add_f32_e32 v42, v42, v66
	v_mul_f32_e32 v46, 0xbfb8aa3b, v46
	v_mul_f32_e32 v42, 0xbfb8aa3b, v42
	v_add_f32_e32 v47, v47, v71
	v_add_f32_e32 v43, v43, v67
	v_exp_f32_e32 v46, v46
	v_exp_f32_e32 v42, v42
	v_mul_f32_e32 v47, 0xbfb8aa3b, v47
	v_mul_f32_e32 v43, 0xbfb8aa3b, v43
	v_add_f32_e32 v48, v48, v72
	v_add_f32_e32 v44, v44, v68
	v_exp_f32_e32 v47, v47
	v_exp_f32_e32 v43, v43
	v_mul_f32_e32 v48, 0xbfb8aa3b, v48
	v_mul_f32_e32 v44, 0xbfb8aa3b, v44
	v_add_f32_e32 v49, v49, v73
	v_exp_f32_e32 v48, v48
	v_exp_f32_e32 v44, v44
	v_mul_f32_e32 v49, 0xbfb8aa3b, v49
	v_add_f32_e32 v45, v45, v69
	v_exp_f32_e32 v49, v49
	v_mul_f32_e32 v45, 0xbfb8aa3b, v45
	v_add_f32_e32 v46, 1.0, v46
	v_add_f32_e32 v42, 1.0, v42
	v_exp_f32_e32 v45, v45
	v_rcp_f32_e32 v46, v46
	v_rcp_f32_e32 v42, v42
	v_add_f32_e32 v47, 1.0, v47
	v_add_f32_e32 v43, 1.0, v43
	v_rcp_f32_e32 v47, v47
	v_rcp_f32_e32 v43, v43
	v_add_f32_e32 v48, 1.0, v48
	v_add_f32_e32 v44, 1.0, v44
	v_rcp_f32_e32 v48, v48
	v_rcp_f32_e32 v44, v44
	v_add_f32_e32 v49, 1.0, v49
	v_rcp_f32_e32 v49, v49
	v_add_f32_e32 v45, 1.0, v45
	v_rcp_f32_e32 v45, v45
	v_mul_f32_e32 v46, 0x437f0000, v46
	v_mul_f32_e32 v42, 0x437f0000, v42
	v_cvt_pk_u8_f32 v46, v46, 0, 0
	v_cvt_pk_u8_f32 v42, v42, 0, 0
	v_mul_f32_e32 v47, 0x437f0000, v47
	v_mul_f32_e32 v43, 0x437f0000, v43
	v_cvt_pk_u8_f32 v46, v47, 1, v46
	v_cvt_pk_u8_f32 v42, v43, 1, v42
	v_mul_f32_e32 v43, 0x437f0000, v48
	v_mul_f32_e32 v44, 0x437f0000, v44
	v_cvt_pk_u8_f32 v43, v43, 2, v46
	v_cvt_pk_u8_f32 v44, v44, 2, v42
	v_mul_f32_e32 v42, 0x437f0000, v49
	v_readlane_b32 s0, v253, 13
	v_cvt_pk_u8_f32 v42, v42, 3, v43
	v_mul_f32_e32 v43, 0x437f0000, v45
	v_readlane_b32 s1, v253, 14
	v_cvt_pk_u8_f32 v43, v43, 3, v44
	s_nop 0
	v_mov_b64_e32 v[44:45], s[0:1]
	v_mad_i64_i32 v[44:45], s[0:1], v122, s31, v[44:45]
	v_lshl_add_u64 v[44:45], v[44:45], 0, v[0:1]
	v_add_co_u32_e32 v44, vcc, 0x3000, v44
	s_nop 1
	v_addc_co_u32_e32 v45, vcc, 0, v45, vcc
	global_store_dwordx2 v[44:45], v[42:43], off offset:512
.LBB0_762:
	s_mov_b32 s0, 0x3d000000
	v_pk_mul_f32 v[40:41], v[40:41], s[0:1] op_sel_hi:[1,0]
	v_pk_mul_f32 v[38:39], v[38:39], s[0:1] op_sel_hi:[1,0]
	v_pk_mul_f32 v[36:37], v[36:37], s[0:1] op_sel_hi:[1,0]
	v_pk_mul_f32 v[34:35], v[34:35], s[0:1] op_sel_hi:[1,0]
	s_and_b64 vcc, exec, s[40:41]
	s_mov_b64 s[42:43], -1
	s_cbranch_vccnz .LBB0_764
	v_readlane_b32 s0, v253, 13
	v_readlane_b32 s1, v253, 14
	s_mov_b64 s[42:43], 0
	v_cvt_pk_bf16_f32 v42, v38, v39
	v_cvt_pk_bf16_f32 v43, v40, v41
	v_cvt_pk_bf16_f32 v44, v34, v35
	v_cvt_pk_bf16_f32 v45, v36, v37
	s_nop 0
	v_mov_b64_e32 v[46:47], s[0:1]
	v_mad_i64_i32 v[46:47], s[0:1], v106, s31, v[46:47]
	v_lshl_add_u64 v[46:47], v[74:75], 1, v[46:47]
	global_store_dwordx4 v[46:47], v[42:45], off
.LBB0_764:
	s_andn2_b64 vcc, exec, s[42:43]
	s_cbranch_vccnz .LBB0_766
	s_waitcnt vmcnt(0)
	v_add_f32_e32 v38, v38, v70
	v_add_f32_e32 v34, v34, v66
	v_mul_f32_e32 v38, 0xbfb8aa3b, v38
	v_mul_f32_e32 v34, 0xbfb8aa3b, v34
	v_add_f32_e32 v39, v39, v71
	v_add_f32_e32 v35, v35, v67
	v_exp_f32_e32 v38, v38
	v_exp_f32_e32 v34, v34
	v_mul_f32_e32 v39, 0xbfb8aa3b, v39
	v_mul_f32_e32 v35, 0xbfb8aa3b, v35
	v_add_f32_e32 v40, v40, v72
	v_add_f32_e32 v36, v36, v68
	v_exp_f32_e32 v39, v39
	v_exp_f32_e32 v35, v35
	v_mul_f32_e32 v40, 0xbfb8aa3b, v40
	v_mul_f32_e32 v36, 0xbfb8aa3b, v36
	v_add_f32_e32 v41, v41, v73
	v_exp_f32_e32 v40, v40
	v_exp_f32_e32 v36, v36
	v_mul_f32_e32 v41, 0xbfb8aa3b, v41
	v_add_f32_e32 v37, v37, v69
	v_exp_f32_e32 v41, v41
	v_mul_f32_e32 v37, 0xbfb8aa3b, v37
	v_add_f32_e32 v38, 1.0, v38
	v_add_f32_e32 v34, 1.0, v34
	v_exp_f32_e32 v37, v37
	v_rcp_f32_e32 v38, v38
	v_rcp_f32_e32 v34, v34
	v_add_f32_e32 v39, 1.0, v39
	v_add_f32_e32 v35, 1.0, v35
	v_rcp_f32_e32 v39, v39
	v_rcp_f32_e32 v35, v35
	v_add_f32_e32 v40, 1.0, v40
	v_add_f32_e32 v36, 1.0, v36
	v_rcp_f32_e32 v40, v40
	v_rcp_f32_e32 v36, v36
	v_add_f32_e32 v41, 1.0, v41
	v_rcp_f32_e32 v41, v41
	v_add_f32_e32 v37, 1.0, v37
	v_rcp_f32_e32 v37, v37
	v_mul_f32_e32 v38, 0x437f0000, v38
	v_mul_f32_e32 v34, 0x437f0000, v34
	v_cvt_pk_u8_f32 v38, v38, 0, 0
	v_cvt_pk_u8_f32 v34, v34, 0, 0
	v_mul_f32_e32 v39, 0x437f0000, v39
	v_mul_f32_e32 v35, 0x437f0000, v35
	v_cvt_pk_u8_f32 v38, v39, 1, v38
	v_cvt_pk_u8_f32 v34, v35, 1, v34
	v_mul_f32_e32 v35, 0x437f0000, v40
	v_mul_f32_e32 v36, 0x437f0000, v36
	v_cvt_pk_u8_f32 v35, v35, 2, v38
	v_cvt_pk_u8_f32 v36, v36, 2, v34
	v_mul_f32_e32 v34, 0x437f0000, v41
	v_readlane_b32 s0, v253, 13
	v_cvt_pk_u8_f32 v34, v34, 3, v35
	v_mul_f32_e32 v35, 0x437f0000, v37
	v_readlane_b32 s1, v253, 14
	v_cvt_pk_u8_f32 v35, v35, 3, v36
	s_nop 0
	v_mov_b64_e32 v[36:37], s[0:1]
	v_mad_i64_i32 v[36:37], s[0:1], v106, s31, v[36:37]
	v_lshl_add_u64 v[36:37], v[36:37], 0, v[0:1]
	v_add_co_u32_e32 v36, vcc, 0x3000, v36
	s_nop 1
	v_addc_co_u32_e32 v37, vcc, 0, v37, vcc
	global_store_dwordx2 v[36:37], v[34:35], off offset:512
; __device__ __forceinline__ float sigmoidf_(float v) { return __builtin_amdgcn_rcpf(1.f + __expf(-v)); }
; __device__ __forceinline__ u32x4 pack8(f32x4 v0, f32x4 v1) { u32x4 w; w.x = cvt_pk_bf16(v0[0], v0[1]); w.y = cvt_pk_bf16(v0[2], v0[3]); w.z = cvt_pk_bf16(v1[0], v1[1]); w.w = cvt_pk_bf16(v1[2], v1[3]); return w; }
;     __device__ __forceinline__ void operator()(const f32x4 (&acc)[2][2][4][2], const Unit& u, int wr, int wc, int fr, int fq) const {
;         bf16_t* O_ = O; const bool gate = u.pn >= 8;
; #pragma unroll
;         for (int bj = 0; bj < 2; ++bj) { const int col = u.pn * BM + bj * HALF + wc * 32 + 8 * fq;
;             const f32x4 b0 = gate ? *(const f32x4*)(bm + col - 2048) : (f32x4){0.f, 0.f, 0.f, 0.f}, b1 = gate ? *(const f32x4*)(bm + col - 2048 + 4) : (f32x4){0.f, 0.f, 0.f, 0.f};
;             const int ocol = gate ? GATE0 + col - 2048 : col;
; #pragma unroll
;             for (int ai = 0; ai < 2; ++ai)
; #pragma unroll
;                 for (int m = 0; m < 4; ++m) { const int row = u.pm * BM + ai * HALF + wr * 64 + m * 16 + fr; f32x4 v0 = acc[ai][bj][m][0] * 0.03125f, v1 = acc[ai][bj][m][1] * 0.03125f;
;                     if (gate) {
; #pragma unroll
;                         for (int j = 0; j < 4; ++j) { v0[j] = sigmoidf_(v0[j] + b0[j]); v1[j] = sigmoidf_(v1[j] + b1[j]); }
;                         *(u32x2*)((unsigned char*)(O_ + (size_t)row * NP + GATE0) + (col - 2048)) = gate_pack8(v0, v1); }
;                     else *(u32x4*)(O_ + (size_t)row * NP + ocol) = pack8(v0, v1); } }
;     }
.LBB0_766:
	s_mov_b32 s0, 0x3d000000
	v_pk_mul_f32 v[32:33], v[32:33], s[0:1] op_sel_hi:[1,0]
	v_pk_mul_f32 v[30:31], v[30:31], s[0:1] op_sel_hi:[1,0]
	v_pk_mul_f32 v[28:29], v[28:29], s[0:1] op_sel_hi:[1,0]
	v_pk_mul_f32 v[26:27], v[26:27], s[0:1] op_sel_hi:[1,0]
	s_and_b64 vcc, exec, s[40:41]
	s_mov_b64 s[42:43], -1
	s_cbranch_vccnz .LBB0_768
	v_readlane_b32 s0, v253, 13
	v_readlane_b32 s1, v253, 14
	s_mov_b64 s[42:43], 0
	v_cvt_pk_bf16_f32 v34, v30, v31
	v_cvt_pk_bf16_f32 v35, v32, v33
	v_cvt_pk_bf16_f32 v36, v26, v27
	v_cvt_pk_bf16_f32 v37, v28, v29
	s_nop 0
	v_mov_b64_e32 v[38:39], s[0:1]
	v_mad_i64_i32 v[38:39], s[0:1], v98, s31, v[38:39]
	v_lshl_add_u64 v[38:39], v[74:75], 1, v[38:39]
	global_store_dwordx4 v[38:39], v[34:37], off
.LBB0_768:
	s_andn2_b64 vcc, exec, s[42:43]
	s_cbranch_vccnz .LBB0_770
	s_waitcnt vmcnt(0)
	v_add_f32_e32 v30, v30, v70
	v_add_f32_e32 v26, v26, v66
	v_mul_f32_e32 v30, 0xbfb8aa3b, v30
	v_mul_f32_e32 v26, 0xbfb8aa3b, v26
	v_add_f32_e32 v31, v31, v71
	v_add_f32_e32 v27, v27, v67
	v_exp_f32_e32 v30, v30
	v_exp_f32_e32 v26, v26
	v_mul_f32_e32 v31, 0xbfb8aa3b, v31
	v_mul_f32_e32 v27, 0xbfb8aa3b, v27
	v_add_f32_e32 v32, v32, v72
	v_add_f32_e32 v28, v28, v68
	v_exp_f32_e32 v31, v31
	v_exp_f32_e32 v27, v27
	v_mul_f32_e32 v32, 0xbfb8aa3b, v32
	v_mul_f32_e32 v28, 0xbfb8aa3b, v28
	v_add_f32_e32 v33, v33, v73
	v_exp_f32_e32 v32, v32
	v_exp_f32_e32 v28, v28
	v_mul_f32_e32 v33, 0xbfb8aa3b, v33
	v_add_f32_e32 v29, v29, v69
	v_exp_f32_e32 v33, v33
	v_mul_f32_e32 v29, 0xbfb8aa3b, v29
	v_add_f32_e32 v30, 1.0, v30
	v_add_f32_e32 v26, 1.0, v26
	v_exp_f32_e32 v29, v29
	v_rcp_f32_e32 v30, v30
	v_rcp_f32_e32 v26, v26
	v_add_f32_e32 v31, 1.0, v31
	v_add_f32_e32 v27, 1.0, v27
	v_rcp_f32_e32 v31, v31
	v_rcp_f32_e32 v27, v27
	v_add_f32_e32 v32, 1.0, v32
	v_add_f32_e32 v28, 1.0, v28
	v_rcp_f32_e32 v32, v32
	v_rcp_f32_e32 v28, v28
	v_add_f32_e32 v33, 1.0, v33
	v_rcp_f32_e32 v33, v33
	v_add_f32_e32 v29, 1.0, v29
	v_rcp_f32_e32 v29, v29
	v_mul_f32_e32 v30, 0x437f0000, v30
	v_mul_f32_e32 v26, 0x437f0000, v26
	v_cvt_pk_u8_f32 v30, v30, 0, 0
	v_cvt_pk_u8_f32 v26, v26, 0, 0
	v_mul_f32_e32 v31, 0x437f0000, v31
	v_mul_f32_e32 v27, 0x437f0000, v27
	v_cvt_pk_u8_f32 v30, v31, 1, v30
	v_cvt_pk_u8_f32 v26, v27, 1, v26
	v_mul_f32_e32 v27, 0x437f0000, v32
	v_mul_f32_e32 v28, 0x437f0000, v28
	v_cvt_pk_u8_f32 v27, v27, 2, v30
	v_cvt_pk_u8_f32 v28, v28, 2, v26
	v_mul_f32_e32 v26, 0x437f0000, v33
	v_readlane_b32 s0, v253, 13
	v_cvt_pk_u8_f32 v26, v26, 3, v27
	v_mul_f32_e32 v27, 0x437f0000, v29
	v_readlane_b32 s1, v253, 14
	v_cvt_pk_u8_f32 v27, v27, 3, v28
	s_nop 0
	v_mov_b64_e32 v[28:29], s[0:1]
	v_mad_i64_i32 v[28:29], s[0:1], v98, s31, v[28:29]
	v_lshl_add_u64 v[28:29], v[28:29], 0, v[0:1]
	v_add_co_u32_e32 v28, vcc, 0x3000, v28
	s_nop 1
	v_addc_co_u32_e32 v29, vcc, 0, v29, vcc
	global_store_dwordx2 v[28:29], v[26:27], off offset:512
.LBB0_770:
	s_mov_b32 s0, 0x3d000000
	v_pk_mul_f32 v[24:25], v[24:25], s[0:1] op_sel_hi:[1,0]
	v_pk_mul_f32 v[22:23], v[22:23], s[0:1] op_sel_hi:[1,0]
	v_pk_mul_f32 v[20:21], v[20:21], s[0:1] op_sel_hi:[1,0]
	v_pk_mul_f32 v[18:19], v[18:19], s[0:1] op_sel_hi:[1,0]
	s_and_b64 vcc, exec, s[40:41]
	s_mov_b64 s[42:43], -1
	s_cbranch_vccnz .LBB0_772
	v_readlane_b32 s0, v253, 13
	v_readlane_b32 s1, v253, 14
	s_mov_b64 s[42:43], 0
	v_cvt_pk_bf16_f32 v26, v22, v23
	v_cvt_pk_bf16_f32 v27, v24, v25
	v_cvt_pk_bf16_f32 v28, v18, v19
	v_cvt_pk_bf16_f32 v29, v20, v21
	s_nop 0
	v_mov_b64_e32 v[30:31], s[0:1]
	v_mad_i64_i32 v[30:31], s[0:1], v90, s31, v[30:31]
	v_lshl_add_u64 v[30:31], v[74:75], 1, v[30:31]
	global_store_dwordx4 v[30:31], v[26:29], off
; __device__ __forceinline__ float sigmoidf_(float v) { return __builtin_amdgcn_rcpf(1.f + __expf(-v)); }
; __device__ __forceinline__ u32x4 pack8(f32x4 v0, f32x4 v1) { u32x4 w; w.x = cvt_pk_bf16(v0[0], v0[1]); w.y = cvt_pk_bf16(v0[2], v0[3]); w.z = cvt_pk_bf16(v1[0], v1[1]); w.w = cvt_pk_bf16(v1[2], v1[3]); return w; }
;     __device__ __forceinline__ void operator()(const f32x4 (&acc)[2][2][4][2], const Unit& u, int wr, int wc, int fr, int fq) const {
;         bf16_t* O_ = O; const bool gate = u.pn >= 8;
; #pragma unroll
;         for (int bj = 0; bj < 2; ++bj) { const int col = u.pn * BM + bj * HALF + wc * 32 + 8 * fq;
;             const f32x4 b0 = gate ? *(const f32x4*)(bm + col - 2048) : (f32x4){0.f, 0.f, 0.f, 0.f}, b1 = gate ? *(const f32x4*)(bm + col - 2048 + 4) : (f32x4){0.f, 0.f, 0.f, 0.f};
;             const int ocol = gate ? GATE0 + col - 2048 : col;
; #pragma unroll
;             for (int ai = 0; ai < 2; ++ai)
; #pragma unroll
;                 for (int m = 0; m < 4; ++m) { const int row = u.pm * BM + ai * HALF + wr * 64 + m * 16 + fr; f32x4 v0 = acc[ai][bj][m][0] * 0.03125f, v1 = acc[ai][bj][m][1] * 0.03125f;
;                     if (gate) {
; #pragma unroll
;                         for (int j = 0; j < 4; ++j) { v0[j] = sigmoidf_(v0[j] + b0[j]); v1[j] = sigmoidf_(v1[j] + b1[j]); }
;                         *(u32x2*)((unsigned char*)(O_ + (size_t)row * NP + GATE0) + (col - 2048)) = gate_pack8(v0, v1); }
;                     else *(u32x4*)(O_ + (size_t)row * NP + ocol) = pack8(v0, v1); } }
;     }
.LBB0_772:
	s_andn2_b64 vcc, exec, s[42:43]
	s_cbranch_vccnz .LBB0_774
	s_waitcnt vmcnt(0)
	v_add_f32_e32 v22, v22, v70
	v_add_f32_e32 v18, v18, v66
	v_mul_f32_e32 v22, 0xbfb8aa3b, v22
	v_mul_f32_e32 v18, 0xbfb8aa3b, v18
	v_add_f32_e32 v23, v23, v71
	v_add_f32_e32 v19, v19, v67
	v_exp_f32_e32 v22, v22
	v_exp_f32_e32 v18, v18
	v_mul_f32_e32 v23, 0xbfb8aa3b, v23
	v_mul_f32_e32 v19, 0xbfb8aa3b, v19
	v_add_f32_e32 v24, v24, v72
	v_add_f32_e32 v20, v20, v68
	v_exp_f32_e32 v23, v23
	v_exp_f32_e32 v19, v19
	v_mul_f32_e32 v24, 0xbfb8aa3b, v24
	v_mul_f32_e32 v20, 0xbfb8aa3b, v20
	v_add_f32_e32 v25, v25, v73
	v_exp_f32_e32 v24, v24
	v_exp_f32_e32 v20, v20
	v_mul_f32_e32 v25, 0xbfb8aa3b, v25
	v_add_f32_e32 v21, v21, v69
	v_exp_f32_e32 v25, v25
	v_mul_f32_e32 v21, 0xbfb8aa3b, v21
	v_add_f32_e32 v22, 1.0, v22
	v_add_f32_e32 v18, 1.0, v18
	v_exp_f32_e32 v21, v21
	v_rcp_f32_e32 v22, v22
	v_rcp_f32_e32 v18, v18
	v_add_f32_e32 v23, 1.0, v23
	v_add_f32_e32 v19, 1.0, v19
	v_rcp_f32_e32 v23, v23
	v_rcp_f32_e32 v19, v19
	v_add_f32_e32 v24, 1.0, v24
	v_add_f32_e32 v20, 1.0, v20
	v_rcp_f32_e32 v24, v24
	v_rcp_f32_e32 v20, v20
	v_add_f32_e32 v25, 1.0, v25
	v_rcp_f32_e32 v25, v25
	v_add_f32_e32 v21, 1.0, v21
	v_rcp_f32_e32 v21, v21
	v_mul_f32_e32 v22, 0x437f0000, v22
	v_mul_f32_e32 v18, 0x437f0000, v18
	v_cvt_pk_u8_f32 v22, v22, 0, 0
	v_cvt_pk_u8_f32 v18, v18, 0, 0
	v_mul_f32_e32 v23, 0x437f0000, v23
	v_mul_f32_e32 v19, 0x437f0000, v19
	v_cvt_pk_u8_f32 v22, v23, 1, v22
	v_cvt_pk_u8_f32 v18, v19, 1, v18
	v_mul_f32_e32 v19, 0x437f0000, v24
	v_mul_f32_e32 v20, 0x437f0000, v20
	v_cvt_pk_u8_f32 v19, v19, 2, v22
	v_cvt_pk_u8_f32 v20, v20, 2, v18
	v_mul_f32_e32 v18, 0x437f0000, v25
	v_readlane_b32 s0, v253, 13
	v_cvt_pk_u8_f32 v18, v18, 3, v19
	v_mul_f32_e32 v19, 0x437f0000, v21
	v_readlane_b32 s1, v253, 14
	v_cvt_pk_u8_f32 v19, v19, 3, v20
	s_nop 0
	v_mov_b64_e32 v[20:21], s[0:1]
	v_mad_i64_i32 v[20:21], s[0:1], v90, s31, v[20:21]
	v_lshl_add_u64 v[20:21], v[20:21], 0, v[0:1]
	v_add_co_u32_e32 v20, vcc, 0x3000, v20
	s_nop 1
	v_addc_co_u32_e32 v21, vcc, 0, v21, vcc
	global_store_dwordx2 v[20:21], v[18:19], off offset:512
.LBB0_774:
	s_mov_b32 s0, 0x3d000000
	v_pk_mul_f32 v[16:17], v[16:17], s[0:1] op_sel_hi:[1,0]
	v_pk_mul_f32 v[14:15], v[14:15], s[0:1] op_sel_hi:[1,0]
	v_pk_mul_f32 v[12:13], v[12:13], s[0:1] op_sel_hi:[1,0]
	v_pk_mul_f32 v[10:11], v[10:11], s[0:1] op_sel_hi:[1,0]
	s_and_b64 vcc, exec, s[40:41]
	s_mov_b64 s[42:43], -1
	s_cbranch_vccnz .LBB0_776
	v_readlane_b32 s0, v253, 13
	v_readlane_b32 s1, v253, 14
	s_mov_b64 s[42:43], 0
	v_cvt_pk_bf16_f32 v18, v14, v15
	v_cvt_pk_bf16_f32 v19, v16, v17
	v_cvt_pk_bf16_f32 v20, v10, v11
	v_cvt_pk_bf16_f32 v21, v12, v13
	s_nop 0
	v_mov_b64_e32 v[22:23], s[0:1]
	v_mad_i64_i32 v[22:23], s[0:1], v82, s31, v[22:23]
	v_lshl_add_u64 v[22:23], v[74:75], 1, v[22:23]
	global_store_dwordx4 v[22:23], v[18:21], off
.LBB0_776:
	s_andn2_b64 vcc, exec, s[42:43]
	s_cbranch_vccnz .LBB0_778
	s_waitcnt vmcnt(0)
	v_add_f32_e32 v14, v14, v70
	v_add_f32_e32 v10, v10, v66
	v_mul_f32_e32 v14, 0xbfb8aa3b, v14
	v_mul_f32_e32 v10, 0xbfb8aa3b, v10
	v_add_f32_e32 v15, v15, v71
	v_add_f32_e32 v11, v11, v67
	v_exp_f32_e32 v14, v14
	v_exp_f32_e32 v10, v10
	v_mul_f32_e32 v15, 0xbfb8aa3b, v15
	v_mul_f32_e32 v11, 0xbfb8aa3b, v11
	v_add_f32_e32 v16, v16, v72
	v_add_f32_e32 v12, v12, v68
	v_exp_f32_e32 v15, v15
	v_exp_f32_e32 v11, v11
	v_mul_f32_e32 v16, 0xbfb8aa3b, v16
	v_mul_f32_e32 v12, 0xbfb8aa3b, v12
	v_add_f32_e32 v17, v17, v73
	v_exp_f32_e32 v16, v16
	v_exp_f32_e32 v12, v12
	v_mul_f32_e32 v17, 0xbfb8aa3b, v17
	v_add_f32_e32 v13, v13, v69
	v_exp_f32_e32 v17, v17
	v_mul_f32_e32 v13, 0xbfb8aa3b, v13
	v_add_f32_e32 v14, 1.0, v14
	v_add_f32_e32 v10, 1.0, v10
	v_exp_f32_e32 v13, v13
	v_rcp_f32_e32 v14, v14
	v_rcp_f32_e32 v10, v10
	v_add_f32_e32 v15, 1.0, v15
	v_add_f32_e32 v11, 1.0, v11
	v_rcp_f32_e32 v15, v15
	v_rcp_f32_e32 v11, v11
	v_add_f32_e32 v16, 1.0, v16
	v_add_f32_e32 v12, 1.0, v12
	v_rcp_f32_e32 v16, v16
	v_rcp_f32_e32 v12, v12
	v_add_f32_e32 v17, 1.0, v17
	v_rcp_f32_e32 v17, v17
	v_add_f32_e32 v13, 1.0, v13
	v_rcp_f32_e32 v13, v13
	v_mul_f32_e32 v14, 0x437f0000, v14
	v_mul_f32_e32 v10, 0x437f0000, v10
	v_cvt_pk_u8_f32 v14, v14, 0, 0
	v_cvt_pk_u8_f32 v10, v10, 0, 0
	v_mul_f32_e32 v15, 0x437f0000, v15
	v_mul_f32_e32 v11, 0x437f0000, v11
	v_cvt_pk_u8_f32 v14, v15, 1, v14
	v_cvt_pk_u8_f32 v10, v11, 1, v10
	v_mul_f32_e32 v11, 0x437f0000, v16
	v_mul_f32_e32 v12, 0x437f0000, v12
	v_cvt_pk_u8_f32 v11, v11, 2, v14
	v_cvt_pk_u8_f32 v12, v12, 2, v10
	v_mul_f32_e32 v10, 0x437f0000, v17
	v_readlane_b32 s0, v253, 13
	v_cvt_pk_u8_f32 v10, v10, 3, v11
	v_mul_f32_e32 v11, 0x437f0000, v13
	v_readlane_b32 s1, v253, 14
	v_cvt_pk_u8_f32 v11, v11, 3, v12
	s_nop 0
	v_mov_b64_e32 v[12:13], s[0:1]
	v_mad_i64_i32 v[12:13], s[0:1], v82, s31, v[12:13]
	v_lshl_add_u64 v[12:13], v[12:13], 0, v[0:1]
	v_add_co_u32_e32 v12, vcc, 0x3000, v12
	s_nop 1
	v_addc_co_u32_e32 v13, vcc, 0, v13, vcc
	global_store_dwordx2 v[12:13], v[10:11], off offset:512
.LBB0_778:
	s_mov_b32 s0, 0x3d000000
	v_pk_mul_f32 v[8:9], v[8:9], s[0:1] op_sel_hi:[1,0]
	v_pk_mul_f32 v[6:7], v[6:7], s[0:1] op_sel_hi:[1,0]
	v_pk_mul_f32 v[4:5], v[4:5], s[0:1] op_sel_hi:[1,0]
	v_pk_mul_f32 v[2:3], v[2:3], s[0:1] op_sel_hi:[1,0]
	s_and_b64 vcc, exec, s[40:41]
	s_mov_b64 s[40:41], -1
	s_cbranch_vccnz .LBB0_781
	v_readlane_b32 s0, v253, 13
	v_readlane_b32 s1, v253, 14
	v_cvt_pk_bf16_f32 v10, v6, v7
	v_cvt_pk_bf16_f32 v11, v8, v9
	v_cvt_pk_bf16_f32 v12, v2, v3
	v_cvt_pk_bf16_f32 v13, v4, v5
	s_nop 1
	v_mov_b64_e32 v[14:15], s[0:1]
	v_mad_i64_i32 v[14:15], s[0:1], v76, s31, v[14:15]
	v_lshl_add_u64 v[14:15], v[74:75], 1, v[14:15]
	global_store_dwordx4 v[14:15], v[10:13], off
	s_cbranch_execz .LBB0_782

; __device__ __forceinline__ float sigmoidf_(float v) { return __builtin_amdgcn_rcpf(1.f + __expf(-v)); }
; __device__ __forceinline__ int otid() { int t = threadIdx.x; asm volatile("" : "+v"(t)); return t; }
; #define PG8_BAR __builtin_amdgcn_s_barrier()
; __device__ __forceinline__ u32x4 pack8(f32x4 v0, f32x4 v1) { u32x4 w; w.x = cvt_pk_bf16(v0[0], v0[1]); w.y = cvt_pk_bf16(v0[2], v0[3]); w.z = cvt_pk_bf16(v1[0], v1[1]); w.w = cvt_pk_bf16(v1[2], v1[3]); return w; }
;     ...
;         if (wr == 0) PG8_BAR;
;         { const int t2_ = otid(), w2_ = t2_ >> 6, l2_ = t2_ & 63; E(acc, cur, w2_ >> 2, w2_ & 3, l2_ & 15, l2_ >> 4); }
;         if (!has_next) break;
;     __device__ __forceinline__ void operator()(const f32x4 (&acc)[2][2][4][2], const Unit& u, int wr, int wc, int fr, int fq) const {
;         bf16_t* O_ = O; const bool gate = u.pn >= 8;
; #pragma unroll
;         for (int bj = 0; bj < 2; ++bj) { const int col = u.pn * BM + bj * HALF + wc * 32 + 8 * fq;
;             const f32x4 b0 = gate ? *(const f32x4*)(bm + col - 2048) : (f32x4){0.f, 0.f, 0.f, 0.f}, b1 = gate ? *(const f32x4*)(bm + col - 2048 + 4) : (f32x4){0.f, 0.f, 0.f, 0.f};
;             const int ocol = gate ? GATE0 + col - 2048 : col;
; #pragma unroll
;             for (int ai = 0; ai < 2; ++ai)
; #pragma unroll
;                 for (int m = 0; m < 4; ++m) { const int row = u.pm * BM + ai * HALF + wr * 64 + m * 16 + fr; f32x4 v0 = acc[ai][bj][m][0] * 0.03125f, v1 = acc[ai][bj][m][1] * 0.03125f;
;                     if (gate) {
; #pragma unroll
;                         for (int j = 0; j < 4; ++j) { v0[j] = sigmoidf_(v0[j] + b0[j]); v1[j] = sigmoidf_(v1[j] + b1[j]); }
;                         *(u32x2*)((unsigned char*)(O_ + (size_t)row * NP + GATE0) + (col - 2048)) = gate_pack8(v0, v1); }
;                     else *(u32x4*)(O_ + (size_t)row * NP + ocol) = pack8(v0, v1); } }
;     }
.LBB0_782:
	s_waitcnt vmcnt(0)
	v_add_f32_e32 v6, v6, v70
	v_add_f32_e32 v2, v2, v66
	v_mul_f32_e32 v6, 0xbfb8aa3b, v6
	v_mul_f32_e32 v2, 0xbfb8aa3b, v2
	v_add_f32_e32 v7, v7, v71
	v_add_f32_e32 v3, v3, v67
	v_exp_f32_e32 v6, v6
	v_exp_f32_e32 v2, v2
	v_mul_f32_e32 v7, 0xbfb8aa3b, v7
	v_mul_f32_e32 v3, 0xbfb8aa3b, v3
	v_add_f32_e32 v8, v8, v72
	v_add_f32_e32 v4, v4, v68
	v_exp_f32_e32 v7, v7
	v_exp_f32_e32 v3, v3
	v_mul_f32_e32 v8, 0xbfb8aa3b, v8
	v_mul_f32_e32 v4, 0xbfb8aa3b, v4
	v_add_f32_e32 v9, v9, v73
	v_exp_f32_e32 v8, v8
	v_exp_f32_e32 v4, v4
	v_mul_f32_e32 v9, 0xbfb8aa3b, v9
	v_add_f32_e32 v5, v5, v69
	v_exp_f32_e32 v9, v9
	v_mul_f32_e32 v5, 0xbfb8aa3b, v5
	v_add_f32_e32 v6, 1.0, v6
	v_add_f32_e32 v2, 1.0, v2
	v_exp_f32_e32 v5, v5
	v_rcp_f32_e32 v6, v6
	v_rcp_f32_e32 v2, v2
	v_add_f32_e32 v7, 1.0, v7
	v_add_f32_e32 v3, 1.0, v3
	v_rcp_f32_e32 v7, v7
	v_rcp_f32_e32 v3, v3
	v_add_f32_e32 v8, 1.0, v8
	v_add_f32_e32 v4, 1.0, v4
	v_rcp_f32_e32 v8, v8
	v_rcp_f32_e32 v4, v4
	v_add_f32_e32 v9, 1.0, v9
	v_rcp_f32_e32 v9, v9
	v_add_f32_e32 v5, 1.0, v5
	v_rcp_f32_e32 v5, v5
	v_mul_f32_e32 v6, 0x437f0000, v6
	v_mul_f32_e32 v2, 0x437f0000, v2
	v_cvt_pk_u8_f32 v6, v6, 0, 0
	v_cvt_pk_u8_f32 v2, v2, 0, 0
	v_mul_f32_e32 v7, 0x437f0000, v7
	v_mul_f32_e32 v3, 0x437f0000, v3
	v_cvt_pk_u8_f32 v6, v7, 1, v6
	v_cvt_pk_u8_f32 v2, v3, 1, v2
	v_mul_f32_e32 v3, 0x437f0000, v8
	v_mul_f32_e32 v4, 0x437f0000, v4
	v_cvt_pk_u8_f32 v3, v3, 2, v6
	v_cvt_pk_u8_f32 v4, v4, 2, v2
	v_mul_f32_e32 v2, 0x437f0000, v9
	v_readlane_b32 s0, v253, 13
	v_cvt_pk_u8_f32 v2, v2, 3, v3
	v_mul_f32_e32 v3, 0x437f0000, v5
	v_readlane_b32 s1, v253, 14
	v_cvt_pk_u8_f32 v3, v3, 3, v4
	s_nop 0
	v_mov_b64_e32 v[4:5], s[0:1]
	v_mad_i64_i32 v[4:5], s[0:1], v76, s31, v[4:5]
	v_lshl_add_u64 v[4:5], v[4:5], 0, v[0:1]
	v_add_co_u32_e32 v4, vcc, 0x3000, v4
	s_nop 1
	v_addc_co_u32_e32 v5, vcc, 0, v5, vcc
	global_store_dwordx2 v[4:5], v[2:3], off offset:512
	s_andn2_b64 vcc, exec, s[84:85]
	s_mov_b64 s[40:41], -1
	s_cbranch_vccnz .LBB0_686

; __device__ __forceinline__ unsigned cvt_pk_bf16(float lo, float hi) { unsigned r; asm volatile("v_cvt_pk_bf16_f32 %0, %1, %2" : "=v"(r) : "v"(lo), "v"(hi)); return r; }
; __device__ __forceinline__ int otid() { int t = threadIdx.x; asm volatile("" : "+v"(t)); return t; }
; __device__ __forceinline__ int obid() { int t = blockIdx.x; asm volatile("" : "+s"(t)); return t; }
; __device__ __forceinline__ int ogdim() { int t = gridDim.x; asm volatile("" : "+s"(t)); return t; }
; __device__ __forceinline__ void rms_to_bf16(const float* __restrict__ src, bf16_t* __restrict__ dst, unsigned char* __restrict__ dst8) {
;     const int wid = otid() >> 6, lane = otid() & 63;
;     for (int row = (obid() * 8 + wid) * 2; row < TB; row += ogdim() * 16) {
;         f32x4 v[2][8];
; #pragma unroll
;         for (int q = 0; q < 2; ++q)
; #pragma unroll
;             for (int j = 0; j < 8; ++j) v[q][j] = *(const f32x4*)(src + (size_t)(row + q) * DM + j * 256 + lane * 4);
; #pragma unroll
;         for (int q = 0; q < 2; ++q) { float ss = 0.f;
; #pragma unroll
;             for (int j = 0; j < 8; ++j) ss += v[q][j][0] * v[q][j][0] + v[q][j][1] * v[q][j][1] + v[q][j][2] * v[q][j][2] + v[q][j][3] * v[q][j][3];
;             ss = wave_sum(ss); const float rs = rsqrtf(ss * (1.f / DM) + EPS);
; #pragma unroll
;             for (int j = 0; j < 8; ++j) { u32x2 w; w.x = cvt_pk_bf16(v[q][j][0] * rs, v[q][j][1] * rs); w.y = cvt_pk_bf16(v[q][j][2] * rs, v[q][j][3] * rs); *(u32x2*)(dst + (size_t)(row + q) * DM + j * 256 + lane * 4) = w;
;                 int x8 = __builtin_amdgcn_cvt_pk_fp8_f32(v[q][j][0] * rs, v[q][j][1] * rs, 0, false); x8 = __builtin_amdgcn_cvt_pk_fp8_f32(v[q][j][2] * rs, v[q][j][3] * rs, x8, true);
;                 *(int*)(dst8 + (size_t)(row + q) * DM + j * 256 + lane * 4) = x8; } }
;     }
; }
.LBB0_816:
	v_ashrrev_i32_e32 v67, 31, v66
	v_lshlrev_b64 v[2:3], 13, v[66:67]
	v_lshl_add_u64 v[2:3], v[68:69], 0, v[2:3]
	global_load_dwordx4 v[62:65], v[2:3], off
	global_load_dwordx4 v[58:61], v[2:3], off offset:1024
	global_load_dwordx4 v[54:57], v[2:3], off offset:2048
	global_load_dwordx4 v[50:53], v[2:3], off offset:3072
	v_add_co_u32_e32 v2, vcc, 0x1000, v2
	v_or_b32_e32 v74, 1, v66
	s_nop 0
	v_addc_co_u32_e32 v3, vcc, 0, v3, vcc
	global_load_dwordx4 v[30:33], v[2:3], off
	global_load_dwordx4 v[10:13], v[2:3], off offset:1024
	global_load_dwordx4 v[6:9], v[2:3], off offset:2048
	s_nop 0
	global_load_dwordx4 v[2:5], v[2:3], off offset:3072
	v_ashrrev_i32_e32 v75, 31, v74
	s_movk_i32 s0, 0x1000
	v_mov_b32_e32 v86, v1
	v_mov_b32_e32 v87, v1
	v_mov_b32_e32 v88, v1
	v_mov_b32_e32 v89, v1
	v_mov_b32_e32 v90, v1
	s_waitcnt vmcnt(0)
	v_mul_f32_e32 v0, v63, v63
	v_mul_f32_e32 v34, v59, v59
	v_mul_f32_e32 v35, v55, v55
	v_fmac_f32_e32 v0, v62, v62
	v_fmac_f32_e32 v34, v58, v58
	v_mul_f32_e32 v36, v51, v51
	v_fmac_f32_e32 v35, v54, v54
	v_fmac_f32_e32 v0, v64, v64
	v_fmac_f32_e32 v34, v60, v60
	v_mov_b32_e32 v16, v31
	v_mov_b32_e32 v17, v11
	v_fmac_f32_e32 v36, v50, v50
	v_fmac_f32_e32 v35, v56, v56
	v_mov_b32_e32 v14, v30
	v_mov_b32_e32 v15, v10
	v_fmac_f32_e32 v0, v65, v65
	v_fmac_f32_e32 v34, v61, v61
	v_pk_mul_f32 v[16:17], v[16:17], v[16:17]
	v_fmac_f32_e32 v36, v52, v52
	v_mov_b32_e32 v18, v32
	v_mov_b32_e32 v19, v12
	v_mov_b32_e32 v24, v7
	v_mov_b32_e32 v25, v3
	v_fmac_f32_e32 v35, v57, v57
	v_add_f32_e32 v0, v0, v34
	v_pk_fma_f32 v[14:15], v[14:15], v[14:15], v[16:17]
	v_mov_b32_e32 v20, v33
	v_mov_b32_e32 v21, v13
	v_mov_b32_e32 v22, v6
	v_mov_b32_e32 v23, v2
	v_fmac_f32_e32 v36, v53, v53
	v_pk_mul_f32 v[24:25], v[24:25], v[24:25]
	v_add_f32_e32 v0, v0, v35
	v_pk_fma_f32 v[14:15], v[18:19], v[18:19], v[14:15]
	v_mov_b32_e32 v26, v8
	v_mov_b32_e32 v27, v4
	v_pk_fma_f32 v[16:17], v[22:23], v[22:23], v[24:25]
	v_add_f32_e32 v0, v0, v36
	v_pk_fma_f32 v[14:15], v[20:21], v[20:21], v[14:15]
	v_mov_b32_e32 v28, v9
	v_mov_b32_e32 v29, v5
	v_pk_fma_f32 v[16:17], v[26:27], v[26:27], v[16:17]
	v_add_f32_e32 v0, v0, v14
	v_pk_fma_f32 v[16:17], v[28:29], v[28:29], v[16:17]
	v_add_f32_e32 v0, v0, v15
	v_add_f32_e32 v0, v0, v16
	v_add_f32_e32 v0, v0, v17
	ds_bpermute_b32 v14, v80, v0
	v_lshlrev_b64 v[16:17], 12, v[66:67]
	v_lshl_add_u64 v[76:77], v[70:71], 0, v[16:17]
	s_waitcnt lgkmcnt(0)
	v_add_f32_e32 v0, v0, v14
	ds_bpermute_b32 v14, v81, v0
	s_waitcnt lgkmcnt(0)
	v_add_f32_e32 v0, v0, v14
	ds_bpermute_b32 v18, v82, v0
	v_lshlrev_b64 v[14:15], 11, v[66:67]
	v_lshl_add_u64 v[78:79], v[72:73], 0, v[14:15]
	s_waitcnt lgkmcnt(0)
	v_add_f32_e32 v0, v0, v18
	ds_bpermute_b32 v20, v83, v0
	v_lshlrev_b64 v[18:19], 13, v[74:75]
	v_lshl_add_u64 v[18:19], v[68:69], 0, v[18:19]
	global_load_dwordx4 v[42:45], v[18:19], off
	global_load_dwordx4 v[34:37], v[18:19], off offset:1024
	global_load_dwordx4 v[22:25], v[18:19], off offset:2048
	global_load_dwordx4 v[14:17], v[18:19], off offset:3072
	s_waitcnt lgkmcnt(0)
	v_add_f32_e32 v0, v0, v20
	ds_bpermute_b32 v20, v84, v0
	v_add_co_u32_e32 v18, vcc, s0, v18
	s_mov_b32 s0, s96
	s_nop 0
	v_addc_co_u32_e32 v19, vcc, 0, v19, vcc
	s_waitcnt lgkmcnt(0)
	v_add_f32_e32 v0, v0, v20
	ds_bpermute_b32 v20, v85, v0
	s_waitcnt lgkmcnt(0)
	v_add_f32_e32 v0, v0, v20
	v_fmamk_f32 v0, v0, 0x3a000000, v198
	v_mul_f32_e32 v20, 0x4b800000, v0
	v_cmp_gt_f32_e32 vcc, s28, v0
	s_nop 1
	v_cndmask_b32_e32 v0, v0, v20, vcc
	global_load_dwordx4 v[46:49], v[18:19], off
	global_load_dwordx4 v[38:41], v[18:19], off offset:1024
	global_load_dwordx4 v[26:29], v[18:19], off offset:2048
	s_nop 0
	global_load_dwordx4 v[18:21], v[18:19], off offset:3072
	v_rsq_f32_e32 v0, v0
	s_nop 0
	v_mul_f32_e32 v67, 0x45800000, v0
	v_cndmask_b32_e32 v0, v0, v67, vcc
	v_mul_f32_e32 v62, v62, v0
	v_mul_f32_e32 v63, v63, v0
	v_mul_f32_e32 v58, v58, v0
	v_mul_f32_e32 v59, v59, v0
	v_cvt_pk_fp8_f32 v86, v62, v63
	v_mul_f32_e32 v54, v54, v0
	v_mul_f32_e32 v55, v55, v0
	v_cvt_pk_fp8_f32 v87, v58, v59
	v_mul_f32_e32 v50, v50, v0
	v_mul_f32_e32 v51, v51, v0
	v_cvt_pk_fp8_f32 v88, v54, v55
	v_mul_f32_e32 v64, v64, v0
	v_mul_f32_e32 v65, v65, v0
	v_cvt_pk_fp8_f32 v89, v50, v51
	v_mul_f32_e32 v60, v60, v0
	v_mul_f32_e32 v61, v61, v0
	v_cvt_pk_fp8_f32 v86, v64, v65 op_sel:[0,0,1]
	v_mul_f32_e32 v56, v56, v0
	v_mul_f32_e32 v57, v57, v0
	v_cvt_pk_fp8_f32 v87, v60, v61 op_sel:[0,0,1]
	v_mul_f32_e32 v52, v52, v0
	v_mul_f32_e32 v53, v53, v0
	v_cvt_pk_fp8_f32 v88, v56, v57 op_sel:[0,0,1]
	v_mul_f32_e32 v67, v30, v0
	v_mul_f32_e32 v91, v31, v0
	v_cvt_pk_bf16_f32 v30, v62, v63
	v_cvt_pk_bf16_f32 v31, v64, v65
	v_cvt_pk_fp8_f32 v89, v52, v53 op_sel:[0,0,1]
	v_cvt_pk_fp8_f32 v90, v67, v91
	global_store_dwordx2 v[76:77], v[30:31], off
	global_store_dword v[78:79], v86, off
	v_cvt_pk_bf16_f32 v30, v58, v59
	v_cvt_pk_bf16_f32 v31, v60, v61
	global_store_dword v[78:79], v87, off offset:256
	global_store_dwordx2 v[76:77], v[30:31], off offset:512
	v_cvt_pk_bf16_f32 v30, v54, v55
	v_cvt_pk_bf16_f32 v31, v56, v57
	global_store_dword v[78:79], v88, off offset:512
	global_store_dwordx2 v[76:77], v[30:31], off offset:1024
	v_cvt_pk_bf16_f32 v30, v50, v51
	v_cvt_pk_bf16_f32 v31, v52, v53
	v_mul_f32_e32 v32, v32, v0
	global_store_dword v[78:79], v89, off offset:768
	global_store_dwordx2 v[76:77], v[30:31], off offset:1536
	v_mul_f32_e32 v31, v33, v0
	v_cvt_pk_fp8_f32 v90, v32, v31 op_sel:[0,0,1]
	v_cvt_pk_bf16_f32 v30, v67, v91
	v_cvt_pk_bf16_f32 v31, v32, v31
	global_store_dwordx2 v[76:77], v[30:31], off offset:2048
	global_store_dword v[78:79], v90, off offset:1024
	v_mul_f32_e32 v30, v10, v0
	v_mul_f32_e32 v11, v11, v0
	v_mov_b32_e32 v50, v1
	v_cvt_pk_bf16_f32 v10, v30, v11
	v_cvt_pk_fp8_f32 v50, v30, v11
	s_waitcnt vmcnt(0)
; __device__ __forceinline__ unsigned cvt_pk_bf16(float lo, float hi) { unsigned r; asm volatile("v_cvt_pk_bf16_f32 %0, %1, %2" : "=v"(r) : "v"(lo), "v"(hi)); return r; }
; __device__ __forceinline__ int otid() { int t = threadIdx.x; asm volatile("" : "+v"(t)); return t; }
; __device__ __forceinline__ int obid() { int t = blockIdx.x; asm volatile("" : "+s"(t)); return t; }
; __device__ __forceinline__ int ogdim() { int t = gridDim.x; asm volatile("" : "+s"(t)); return t; }
; __device__ __forceinline__ void rms_to_bf16(const float* __restrict__ src, bf16_t* __restrict__ dst, unsigned char* __restrict__ dst8) {
;     const int wid = otid() >> 6, lane = otid() & 63;
;     for (int row = (obid() * 8 + wid) * 2; row < TB; row += ogdim() * 16) {
;         f32x4 v[2][8];
; #pragma unroll
;         for (int q = 0; q < 2; ++q)
; #pragma unroll
;             for (int j = 0; j < 8; ++j) v[q][j] = *(const f32x4*)(src + (size_t)(row + q) * DM + j * 256 + lane * 4);
; #pragma unroll
;         for (int q = 0; q < 2; ++q) { float ss = 0.f;
; #pragma unroll
;             for (int j = 0; j < 8; ++j) ss += v[q][j][0] * v[q][j][0] + v[q][j][1] * v[q][j][1] + v[q][j][2] * v[q][j][2] + v[q][j][3] * v[q][j][3];
;             ss = wave_sum(ss); const float rs = rsqrtf(ss * (1.f / DM) + EPS);
; #pragma unroll
;             for (int j = 0; j < 8; ++j) { u32x2 w; w.x = cvt_pk_bf16(v[q][j][0] * rs, v[q][j][1] * rs); w.y = cvt_pk_bf16(v[q][j][2] * rs, v[q][j][3] * rs); *(u32x2*)(dst + (size_t)(row + q) * DM + j * 256 + lane * 4) = w;
;                 int x8 = __builtin_amdgcn_cvt_pk_fp8_f32(v[q][j][0] * rs, v[q][j][1] * rs, 0, false); x8 = __builtin_amdgcn_cvt_pk_fp8_f32(v[q][j][2] * rs, v[q][j][3] * rs, x8, true);
;                 *(int*)(dst8 + (size_t)(row + q) * DM + j * 256 + lane * 4) = x8; } }
;     }
; }
	v_mul_f32_e32 v11, v43, v43
	v_mul_f32_e32 v30, v35, v35
	v_fmac_f32_e32 v11, v42, v42
	v_fmac_f32_e32 v30, v34, v34
	v_fmac_f32_e32 v11, v44, v44
	v_fmac_f32_e32 v30, v36, v36
	v_fmac_f32_e32 v11, v45, v45
	v_fmac_f32_e32 v30, v37, v37
	v_add_f32_e32 v11, v11, v30
	v_mul_f32_e32 v30, v23, v23
	v_fmac_f32_e32 v30, v22, v22
	v_fmac_f32_e32 v30, v24, v24
	v_fmac_f32_e32 v30, v25, v25
	v_add_f32_e32 v11, v11, v30
	v_mul_f32_e32 v30, v15, v15
	v_fmac_f32_e32 v30, v14, v14
	v_fmac_f32_e32 v30, v16, v16
	v_fmac_f32_e32 v30, v17, v17
	v_add_f32_e32 v11, v11, v30
	v_mov_b32_e32 v32, v47
	v_mov_b32_e32 v33, v39
	v_mov_b32_e32 v30, v46
	v_mov_b32_e32 v31, v38
	v_pk_mul_f32 v[32:33], v[32:33], v[32:33]
	v_mul_f32_e32 v12, v12, v0
	v_pk_fma_f32 v[30:31], v[30:31], v[30:31], v[32:33]
	v_mov_b32_e32 v32, v48
	v_mov_b32_e32 v33, v40
	v_pk_fma_f32 v[30:31], v[32:33], v[32:33], v[30:31]
	v_mov_b32_e32 v32, v49
	v_mov_b32_e32 v33, v41
	v_pk_fma_f32 v[30:31], v[32:33], v[32:33], v[30:31]
	v_mov_b32_e32 v32, v27
	v_add_f32_e32 v11, v11, v30
	v_mov_b32_e32 v33, v19
	v_add_f32_e32 v11, v11, v31
	v_mov_b32_e32 v30, v26
	v_mov_b32_e32 v31, v18
	v_pk_mul_f32 v[32:33], v[32:33], v[32:33]
	v_mul_f32_e32 v13, v13, v0
	v_pk_fma_f32 v[30:31], v[30:31], v[30:31], v[32:33]
	v_mov_b32_e32 v32, v28
	v_mov_b32_e32 v33, v20
	v_pk_fma_f32 v[30:31], v[32:33], v[32:33], v[30:31]
	v_mov_b32_e32 v32, v29
	v_mov_b32_e32 v33, v21
	v_pk_fma_f32 v[30:31], v[32:33], v[32:33], v[30:31]
	v_cvt_pk_fp8_f32 v50, v12, v13 op_sel:[0,0,1]
	v_add_f32_e32 v11, v11, v30
	v_add_f32_e32 v30, v11, v31
	ds_bpermute_b32 v31, v80, v30
	v_cvt_pk_bf16_f32 v11, v12, v13
	global_store_dwordx2 v[76:77], v[10:11], off offset:2560
	v_mul_f32_e32 v6, v6, v0
	v_mul_f32_e32 v7, v7, v0
	s_waitcnt lgkmcnt(0)
	v_add_f32_e32 v10, v30, v31
	ds_bpermute_b32 v11, v81, v10
	v_mov_b32_e32 v12, v1
	v_cvt_pk_fp8_f32 v12, v6, v7
	v_mul_f32_e32 v8, v8, v0
	v_mul_f32_e32 v9, v9, v0
	s_waitcnt lgkmcnt(0)
	v_add_f32_e32 v10, v10, v11
	ds_bpermute_b32 v11, v82, v10
	v_cvt_pk_fp8_f32 v12, v8, v9 op_sel:[0,0,1]
	global_store_dword v[78:79], v50, off offset:1280
	v_cvt_pk_bf16_f32 v6, v6, v7
	v_cvt_pk_bf16_f32 v7, v8, v9
	s_waitcnt lgkmcnt(0)
	v_add_f32_e32 v10, v10, v11
	ds_bpermute_b32 v11, v83, v10
	global_store_dwordx2 v[76:77], v[6:7], off offset:3072
	global_store_dword v[78:79], v12, off offset:1536
	v_mul_f32_e32 v2, v2, v0
	v_mul_f32_e32 v3, v3, v0
	v_mov_b32_e32 v8, v1
	s_waitcnt lgkmcnt(0)
	v_add_f32_e32 v6, v10, v11
	ds_bpermute_b32 v7, v84, v6
	v_cvt_pk_fp8_f32 v8, v2, v3
	v_cvt_pk_bf16_f32 v2, v2, v3
	v_mul_f32_e32 v3, v4, v0
	v_mul_f32_e32 v0, v5, v0
	s_waitcnt lgkmcnt(0)
	v_add_f32_e32 v6, v6, v7
	ds_bpermute_b32 v7, v85, v6
	v_cvt_pk_fp8_f32 v8, v3, v0 op_sel:[0,0,1]
	v_cvt_pk_bf16_f32 v3, v3, v0
	global_store_dwordx2 v[76:77], v[2:3], off offset:3584
	global_store_dword v[78:79], v8, off offset:1792
	s_waitcnt lgkmcnt(0)
	v_add_f32_e32 v4, v6, v7
	v_fmamk_f32 v4, v4, 0x3a000000, v198
	v_mul_f32_e32 v5, 0x4b800000, v4
	v_cmp_gt_f32_e32 vcc, s28, v4
	v_mov_b32_e32 v10, v1
	v_lshlrev_b64 v[2:3], 11, v[74:75]
	v_cndmask_b32_e32 v4, v4, v5, vcc
	v_rsq_f32_e32 v4, v4
	v_lshl_add_u64 v[2:3], v[72:73], 0, v[2:3]
	v_mul_f32_e32 v0, 0x45800000, v4
	v_cndmask_b32_e32 v0, v4, v0, vcc
	v_mul_f32_e32 v7, v42, v0
	v_mul_f32_e32 v8, v43, v0
	v_cvt_pk_fp8_f32 v10, v7, v8
	v_lshlrev_b64 v[4:5], 12, v[74:75]
	v_lshl_add_u64 v[4:5], v[70:71], 0, v[4:5]
	v_cvt_pk_bf16_f32 v6, v7, v8
	v_mul_f32_e32 v9, v44, v0
	v_mul_f32_e32 v8, v45, v0
	v_cvt_pk_bf16_f32 v7, v9, v8
	global_store_dwordx2 v[4:5], v[6:7], off
	v_cvt_pk_fp8_f32 v10, v9, v8 op_sel:[0,0,1]
	v_mul_f32_e32 v6, v34, v0
	v_mul_f32_e32 v7, v35, v0
	v_mov_b32_e32 v8, v1
	v_cvt_pk_fp8_f32 v8, v6, v7
	global_store_dword v[2:3], v10, off
	v_mul_f32_e32 v9, v36, v0
	v_mul_f32_e32 v10, v37, v0
	v_cvt_pk_fp8_f32 v8, v9, v10 op_sel:[0,0,1]
	v_cvt_pk_bf16_f32 v6, v6, v7
	v_cvt_pk_bf16_f32 v7, v9, v10
	global_store_dwordx2 v[4:5], v[6:7], off offset:512
	global_store_dword v[2:3], v8, off offset:256
	v_mul_f32_e32 v7, v22, v0
	v_mul_f32_e32 v8, v23, v0
	v_mov_b32_e32 v10, v1
	v_cvt_pk_fp8_f32 v10, v7, v8
	v_cvt_pk_bf16_f32 v6, v7, v8
	v_mul_f32_e32 v9, v24, v0
	v_mul_f32_e32 v8, v25, v0
	v_cvt_pk_bf16_f32 v7, v9, v8
	global_store_dwordx2 v[4:5], v[6:7], off offset:1024
	v_cvt_pk_fp8_f32 v10, v9, v8 op_sel:[0,0,1]
	v_mul_f32_e32 v6, v14, v0
	v_mul_f32_e32 v7, v15, v0
	v_mov_b32_e32 v8, v1
	v_cvt_pk_fp8_f32 v8, v6, v7
	global_store_dword v[2:3], v10, off offset:512
	v_mul_f32_e32 v9, v16, v0
	v_mul_f32_e32 v10, v17, v0
	v_cvt_pk_fp8_f32 v8, v9, v10 op_sel:[0,0,1]
	v_cvt_pk_bf16_f32 v6, v6, v7
	v_cvt_pk_bf16_f32 v7, v9, v10
	global_store_dwordx2 v[4:5], v[6:7], off offset:1536
	global_store_dword v[2:3], v8, off offset:768
	v_mul_f32_e32 v7, v46, v0
	v_mul_f32_e32 v8, v47, v0
	v_mov_b32_e32 v10, v1
	v_cvt_pk_fp8_f32 v10, v7, v8
	v_cvt_pk_bf16_f32 v6, v7, v8
	v_mul_f32_e32 v9, v48, v0
	v_mul_f32_e32 v8, v49, v0
	v_cvt_pk_bf16_f32 v7, v9, v8
	global_store_dwordx2 v[4:5], v[6:7], off offset:2048
	v_cvt_pk_fp8_f32 v10, v9, v8 op_sel:[0,0,1]
	v_mul_f32_e32 v6, v38, v0
	v_mul_f32_e32 v7, v39, v0
	v_mov_b32_e32 v8, v1
	v_cvt_pk_fp8_f32 v8, v6, v7
	global_store_dword v[2:3], v10, off offset:1024
	v_mul_f32_e32 v9, v40, v0
	v_mul_f32_e32 v10, v41, v0
	v_cvt_pk_fp8_f32 v8, v9, v10 op_sel:[0,0,1]
	v_cvt_pk_bf16_f32 v6, v6, v7
	v_cvt_pk_bf16_f32 v7, v9, v10
	global_store_dwordx2 v[4:5], v[6:7], off offset:2560
	global_store_dword v[2:3], v8, off offset:1280
	v_mul_f32_e32 v7, v26, v0
	v_mul_f32_e32 v8, v27, v0
	v_mov_b32_e32 v10, v1
	v_cvt_pk_fp8_f32 v10, v7, v8
	v_cvt_pk_bf16_f32 v6, v7, v8
	v_mul_f32_e32 v9, v28, v0
	v_mul_f32_e32 v8, v29, v0
	v_cvt_pk_bf16_f32 v7, v9, v8
	global_store_dwordx2 v[4:5], v[6:7], off offset:3072
	v_cvt_pk_fp8_f32 v10, v9, v8 op_sel:[0,0,1]
	v_mul_f32_e32 v6, v18, v0
	v_mul_f32_e32 v7, v19, v0
	v_mov_b32_e32 v8, v1
	v_cvt_pk_fp8_f32 v8, v6, v7
	v_mul_f32_e32 v9, v20, v0
	v_mul_f32_e32 v0, v21, v0
	global_store_dword v[2:3], v10, off offset:1536
	v_cvt_pk_fp8_f32 v8, v9, v0 op_sel:[0,0,1]
	v_cvt_pk_bf16_f32 v6, v6, v7
	v_cvt_pk_bf16_f32 v7, v9, v0
	global_store_dwordx2 v[4:5], v[6:7], off offset:3584
	global_store_dword v[2:3], v8, off offset:1792
	s_nop 0
	v_lshl_add_u32 v66, s0, 4, v66
	s_movk_i32 s0, 0x3fff
	v_cmp_lt_i32_e32 vcc, s0, v66
	s_or_b64 s[14:15], vcc, s[14:15]
	s_andn2_b64 exec, exec, s[14:15]
	s_cbranch_execnz .LBB0_816
